# speedup vs baseline: 1.1095x; 1.0042x over previous
; DEV u16 f2bf(float f) { return (u16)(pack2(f, 0.f) & 0xffffu); }
; DEV void phase_win(const Params& P, int l, const u16* __restrict__ xb, const u16* __restrict__ Wt, u16* __restrict__ h, char* smem) {
;     ...
;     const int mode = (cb >= C_HF && cb < C_HI) ? 1 : ((cb >= C_HG) ? 2 : 0);
; #pragma unroll
;     for (int ms = 0; ms < 8; ++ms) {
;       asm volatile("" ::: "memory");
; #pragma unroll
;       for (int ns = 0; ns < 4; ++ns)
; #pragma unroll
;         for (int j = 0; j < 4; ++j) {
;           int row = m0 + wm * 128 + ms * 16 + quad * 4 + j;
;           int col = cb + ns * 16 + l15;
;           float v = acc[ms][ns][j];
;           if (mode == 1) { float lbv = lbp[col - C_HF]; v = __logf(lbv + (1.f - lbv) / (1.f + __expf(-v))); }
;           else if (mode == 2) v = v / (1.f + __expf(-v));
;           h[(size_t)row * HS + col] = f2bf(v);
;         }
;     }
.Lwin_nolbp:
	v_add_u32_e32 v138, s16, v178
	v_mul_u32_u24_e32 v138, 0x1b00, v138
	v_or_b32_e32 v139, v130, v186
	v_lshl_add_u32 v138, v139, 1, v138
	s_cmp_eq_u32 s17, 1
	s_cbranch_scc1 .Lwg_m1
	s_cmp_eq_u32 s17, 2
	s_cbranch_scc1 .Lwg_m2
	v_cvt_pk_bf16_f32 v141, v38, s0
	global_store_short v138, v141, s[72:73]
	v_cvt_pk_bf16_f32 v141, v122, s0
	global_store_short v138, v141, s[72:73] offset:32
	v_cvt_pk_bf16_f32 v141, v126, s0
	global_store_short v138, v141, s[72:73] offset:64
	v_cvt_pk_bf16_f32 v141, v118, s0
	global_store_short v138, v141, s[72:73] offset:96
	v_add_u32_e32 v139, 0x1b00, v138
	v_cvt_pk_bf16_f32 v141, v39, s0
	global_store_short v139, v141, s[72:73]
	v_cvt_pk_bf16_f32 v141, v123, s0
	global_store_short v139, v141, s[72:73] offset:32
	v_cvt_pk_bf16_f32 v141, v127, s0
	global_store_short v139, v141, s[72:73] offset:64
	v_cvt_pk_bf16_f32 v141, v119, s0
	global_store_short v139, v141, s[72:73] offset:96
	v_add_u32_e32 v139, 0x3600, v138
	v_cvt_pk_bf16_f32 v141, v40, s0
	global_store_short v139, v141, s[72:73]
	v_cvt_pk_bf16_f32 v141, v124, s0
	global_store_short v139, v141, s[72:73] offset:32
	v_cvt_pk_bf16_f32 v141, v128, s0
	global_store_short v139, v141, s[72:73] offset:64
	v_cvt_pk_bf16_f32 v141, v120, s0
	global_store_short v139, v141, s[72:73] offset:96
	v_add_u32_e32 v139, 0x5100, v138
	v_cvt_pk_bf16_f32 v141, v41, s0
	global_store_short v139, v141, s[72:73]
	v_cvt_pk_bf16_f32 v141, v125, s0
	global_store_short v139, v141, s[72:73] offset:32
	v_cvt_pk_bf16_f32 v141, v129, s0
	global_store_short v139, v141, s[72:73] offset:64
	v_cvt_pk_bf16_f32 v141, v121, s0
	global_store_short v139, v141, s[72:73] offset:96
	v_add_u32_e32 v139, 0x1b000, v138
	v_cvt_pk_bf16_f32 v141, v26, s0
	global_store_short v139, v141, s[72:73]
	v_cvt_pk_bf16_f32 v141, v110, s0
	global_store_short v139, v141, s[72:73] offset:32
	v_cvt_pk_bf16_f32 v141, v114, s0
	global_store_short v139, v141, s[72:73] offset:64
	v_cvt_pk_bf16_f32 v141, v106, s0
	global_store_short v139, v141, s[72:73] offset:96
	v_add_u32_e32 v139, 0x1cb00, v138
	v_cvt_pk_bf16_f32 v141, v27, s0
	global_store_short v139, v141, s[72:73]
	v_cvt_pk_bf16_f32 v141, v111, s0
	global_store_short v139, v141, s[72:73] offset:32
	v_cvt_pk_bf16_f32 v141, v115, s0
	global_store_short v139, v141, s[72:73] offset:64
	v_cvt_pk_bf16_f32 v141, v107, s0
	global_store_short v139, v141, s[72:73] offset:96
	v_add_u32_e32 v139, 0x1e600, v138
	v_cvt_pk_bf16_f32 v141, v28, s0
	global_store_short v139, v141, s[72:73]
	v_cvt_pk_bf16_f32 v141, v112, s0
	global_store_short v139, v141, s[72:73] offset:32
	v_cvt_pk_bf16_f32 v141, v116, s0
	global_store_short v139, v141, s[72:73] offset:64
	v_cvt_pk_bf16_f32 v141, v108, s0
	global_store_short v139, v141, s[72:73] offset:96
	v_add_u32_e32 v139, 0x20100, v138
	v_cvt_pk_bf16_f32 v141, v29, s0
	global_store_short v139, v141, s[72:73]
	v_cvt_pk_bf16_f32 v141, v113, s0
	global_store_short v139, v141, s[72:73] offset:32
	v_cvt_pk_bf16_f32 v141, v117, s0
	global_store_short v139, v141, s[72:73] offset:64
	v_cvt_pk_bf16_f32 v141, v109, s0
	global_store_short v139, v141, s[72:73] offset:96
	v_add_u32_e32 v139, 0x36000, v138
	v_cvt_pk_bf16_f32 v141, v22, s0
	global_store_short v139, v141, s[72:73]
	v_cvt_pk_bf16_f32 v141, v98, s0
	global_store_short v139, v141, s[72:73] offset:32
	v_cvt_pk_bf16_f32 v141, v102, s0
	global_store_short v139, v141, s[72:73] offset:64
	v_cvt_pk_bf16_f32 v141, v94, s0
	global_store_short v139, v141, s[72:73] offset:96
	v_add_u32_e32 v139, 0x37b00, v138
	v_cvt_pk_bf16_f32 v141, v23, s0
	global_store_short v139, v141, s[72:73]
	v_cvt_pk_bf16_f32 v141, v99, s0
	global_store_short v139, v141, s[72:73] offset:32
	v_cvt_pk_bf16_f32 v141, v103, s0
	global_store_short v139, v141, s[72:73] offset:64
	v_cvt_pk_bf16_f32 v141, v95, s0
	global_store_short v139, v141, s[72:73] offset:96
	v_add_u32_e32 v139, 0x39600, v138
	v_cvt_pk_bf16_f32 v141, v24, s0
	global_store_short v139, v141, s[72:73]
	v_cvt_pk_bf16_f32 v141, v100, s0
	global_store_short v139, v141, s[72:73] offset:32
	v_cvt_pk_bf16_f32 v141, v104, s0
	global_store_short v139, v141, s[72:73] offset:64
	v_cvt_pk_bf16_f32 v141, v96, s0
	global_store_short v139, v141, s[72:73] offset:96
	v_add_u32_e32 v139, 0x3b100, v138
	v_cvt_pk_bf16_f32 v141, v25, s0
	global_store_short v139, v141, s[72:73]
	v_cvt_pk_bf16_f32 v141, v101, s0
	global_store_short v139, v141, s[72:73] offset:32
	v_cvt_pk_bf16_f32 v141, v105, s0
	global_store_short v139, v141, s[72:73] offset:64
	v_cvt_pk_bf16_f32 v141, v97, s0
	global_store_short v139, v141, s[72:73] offset:96
	v_add_u32_e32 v139, 0x51000, v138
	v_cvt_pk_bf16_f32 v141, v18, s0
	global_store_short v139, v141, s[72:73]
	v_cvt_pk_bf16_f32 v141, v86, s0
	global_store_short v139, v141, s[72:73] offset:32
	v_cvt_pk_bf16_f32 v141, v90, s0
	global_store_short v139, v141, s[72:73] offset:64
	v_cvt_pk_bf16_f32 v141, v82, s0
	global_store_short v139, v141, s[72:73] offset:96
	v_add_u32_e32 v139, 0x52b00, v138
	v_cvt_pk_bf16_f32 v141, v19, s0
	global_store_short v139, v141, s[72:73]
	v_cvt_pk_bf16_f32 v141, v87, s0
	global_store_short v139, v141, s[72:73] offset:32
	v_cvt_pk_bf16_f32 v141, v91, s0
	global_store_short v139, v141, s[72:73] offset:64
	v_cvt_pk_bf16_f32 v141, v83, s0
	global_store_short v139, v141, s[72:73] offset:96
	v_add_u32_e32 v139, 0x54600, v138
	v_cvt_pk_bf16_f32 v141, v20, s0
	global_store_short v139, v141, s[72:73]
	v_cvt_pk_bf16_f32 v141, v88, s0
	global_store_short v139, v141, s[72:73] offset:32
	v_cvt_pk_bf16_f32 v141, v92, s0
	global_store_short v139, v141, s[72:73] offset:64
	v_cvt_pk_bf16_f32 v141, v84, s0
	global_store_short v139, v141, s[72:73] offset:96
; DEV u16 f2bf(float f) { return (u16)(pack2(f, 0.f) & 0xffffu); }
; DEV void phase_win(const Params& P, int l, const u16* __restrict__ xb, const u16* __restrict__ Wt, u16* __restrict__ h, char* smem) {
;     ...
;     for (int ms = 0; ms < 8; ++ms) {
;       asm volatile("" ::: "memory");
; #pragma unroll
;       for (int ns = 0; ns < 4; ++ns)
; #pragma unroll
;         for (int j = 0; j < 4; ++j) {
;           int row = m0 + wm * 128 + ms * 16 + quad * 4 + j;
;           int col = cb + ns * 16 + l15;
;           float v = acc[ms][ns][j];
;           if (mode == 1) { float lbv = lbp[col - C_HF]; v = __logf(lbv + (1.f - lbv) / (1.f + __expf(-v))); }
;           else if (mode == 2) v = v / (1.f + __expf(-v));
;           h[(size_t)row * HS + col] = f2bf(v);
;         }
;     }
	v_add_u32_e32 v139, 0x56100, v138
	v_cvt_pk_bf16_f32 v141, v21, s0
	global_store_short v139, v141, s[72:73]
	v_cvt_pk_bf16_f32 v141, v89, s0
	global_store_short v139, v141, s[72:73] offset:32
	v_cvt_pk_bf16_f32 v141, v93, s0
	global_store_short v139, v141, s[72:73] offset:64
	v_cvt_pk_bf16_f32 v141, v85, s0
	global_store_short v139, v141, s[72:73] offset:96
	v_add_u32_e32 v139, 0x6c000, v138
	v_cvt_pk_bf16_f32 v141, v14, s0
	global_store_short v139, v141, s[72:73]
	v_cvt_pk_bf16_f32 v141, v74, s0
	global_store_short v139, v141, s[72:73] offset:32
	v_cvt_pk_bf16_f32 v141, v78, s0
	global_store_short v139, v141, s[72:73] offset:64
	v_cvt_pk_bf16_f32 v141, v70, s0
	global_store_short v139, v141, s[72:73] offset:96
	v_add_u32_e32 v139, 0x6db00, v138
	v_cvt_pk_bf16_f32 v141, v15, s0
	global_store_short v139, v141, s[72:73]
	v_cvt_pk_bf16_f32 v141, v75, s0
	global_store_short v139, v141, s[72:73] offset:32
	v_cvt_pk_bf16_f32 v141, v79, s0
	global_store_short v139, v141, s[72:73] offset:64
	v_cvt_pk_bf16_f32 v141, v71, s0
	global_store_short v139, v141, s[72:73] offset:96
	v_add_u32_e32 v139, 0x6f600, v138
	v_cvt_pk_bf16_f32 v141, v16, s0
	global_store_short v139, v141, s[72:73]
	v_cvt_pk_bf16_f32 v141, v76, s0
	global_store_short v139, v141, s[72:73] offset:32
	v_cvt_pk_bf16_f32 v141, v80, s0
	global_store_short v139, v141, s[72:73] offset:64
	v_cvt_pk_bf16_f32 v141, v72, s0
	global_store_short v139, v141, s[72:73] offset:96
	v_add_u32_e32 v139, 0x71100, v138
	v_cvt_pk_bf16_f32 v141, v17, s0
	global_store_short v139, v141, s[72:73]
	v_cvt_pk_bf16_f32 v141, v77, s0
	global_store_short v139, v141, s[72:73] offset:32
	v_cvt_pk_bf16_f32 v141, v81, s0
	global_store_short v139, v141, s[72:73] offset:64
	v_cvt_pk_bf16_f32 v141, v73, s0
	global_store_short v139, v141, s[72:73] offset:96
	v_add_u32_e32 v139, 0x87000, v138
	v_cvt_pk_bf16_f32 v141, v10, s0
	global_store_short v139, v141, s[72:73]
	v_cvt_pk_bf16_f32 v141, v62, s0
	global_store_short v139, v141, s[72:73] offset:32
	v_cvt_pk_bf16_f32 v141, v66, s0
	global_store_short v139, v141, s[72:73] offset:64
	v_cvt_pk_bf16_f32 v141, v58, s0
	global_store_short v139, v141, s[72:73] offset:96
	v_add_u32_e32 v139, 0x88b00, v138
	v_cvt_pk_bf16_f32 v141, v11, s0
	global_store_short v139, v141, s[72:73]
	v_cvt_pk_bf16_f32 v141, v63, s0
	global_store_short v139, v141, s[72:73] offset:32
	v_cvt_pk_bf16_f32 v141, v67, s0
	global_store_short v139, v141, s[72:73] offset:64
	v_cvt_pk_bf16_f32 v141, v59, s0
	global_store_short v139, v141, s[72:73] offset:96
	v_add_u32_e32 v139, 0x8a600, v138
	v_cvt_pk_bf16_f32 v141, v12, s0
	global_store_short v139, v141, s[72:73]
	v_cvt_pk_bf16_f32 v141, v64, s0
	global_store_short v139, v141, s[72:73] offset:32
	v_cvt_pk_bf16_f32 v141, v68, s0
	global_store_short v139, v141, s[72:73] offset:64
	v_cvt_pk_bf16_f32 v141, v60, s0
	global_store_short v139, v141, s[72:73] offset:96
	v_add_u32_e32 v139, 0x8c100, v138
	v_cvt_pk_bf16_f32 v141, v13, s0
	global_store_short v139, v141, s[72:73]
	v_cvt_pk_bf16_f32 v141, v65, s0
	global_store_short v139, v141, s[72:73] offset:32
	v_cvt_pk_bf16_f32 v141, v69, s0
	global_store_short v139, v141, s[72:73] offset:64
	v_cvt_pk_bf16_f32 v141, v61, s0
	global_store_short v139, v141, s[72:73] offset:96
	v_add_u32_e32 v139, 0xa2000, v138
	v_cvt_pk_bf16_f32 v141, v6, s0
	global_store_short v139, v141, s[72:73]
	v_cvt_pk_bf16_f32 v141, v50, s0
	global_store_short v139, v141, s[72:73] offset:32
	v_cvt_pk_bf16_f32 v141, v54, s0
	global_store_short v139, v141, s[72:73] offset:64
	v_cvt_pk_bf16_f32 v141, v46, s0
	global_store_short v139, v141, s[72:73] offset:96
	v_add_u32_e32 v139, 0xa3b00, v138
	v_cvt_pk_bf16_f32 v141, v7, s0
	global_store_short v139, v141, s[72:73]
	v_cvt_pk_bf16_f32 v141, v51, s0
	global_store_short v139, v141, s[72:73] offset:32
	v_cvt_pk_bf16_f32 v141, v55, s0
	global_store_short v139, v141, s[72:73] offset:64
	v_cvt_pk_bf16_f32 v141, v47, s0
	global_store_short v139, v141, s[72:73] offset:96
	v_add_u32_e32 v139, 0xa5600, v138
	v_cvt_pk_bf16_f32 v141, v8, s0
	global_store_short v139, v141, s[72:73]
	v_cvt_pk_bf16_f32 v141, v52, s0
	global_store_short v139, v141, s[72:73] offset:32
	v_cvt_pk_bf16_f32 v141, v56, s0
	global_store_short v139, v141, s[72:73] offset:64
	v_cvt_pk_bf16_f32 v141, v48, s0
	global_store_short v139, v141, s[72:73] offset:96
	v_add_u32_e32 v139, 0xa7100, v138
	v_cvt_pk_bf16_f32 v141, v9, s0
	global_store_short v139, v141, s[72:73]
	v_cvt_pk_bf16_f32 v141, v53, s0
	global_store_short v139, v141, s[72:73] offset:32
	v_cvt_pk_bf16_f32 v141, v57, s0
	global_store_short v139, v141, s[72:73] offset:64
	v_cvt_pk_bf16_f32 v141, v49, s0
	global_store_short v139, v141, s[72:73] offset:96
	v_add_u32_e32 v139, 0xbd000, v138
	v_cvt_pk_bf16_f32 v141, v2, s0
	global_store_short v139, v141, s[72:73]
	v_cvt_pk_bf16_f32 v141, v34, s0
	global_store_short v139, v141, s[72:73] offset:32
	v_cvt_pk_bf16_f32 v141, v42, s0
	global_store_short v139, v141, s[72:73] offset:64
	v_cvt_pk_bf16_f32 v141, v30, s0
	global_store_short v139, v141, s[72:73] offset:96
	v_add_u32_e32 v139, 0xbeb00, v138
	v_cvt_pk_bf16_f32 v141, v3, s0
	global_store_short v139, v141, s[72:73]
	v_cvt_pk_bf16_f32 v141, v35, s0
	global_store_short v139, v141, s[72:73] offset:32
	v_cvt_pk_bf16_f32 v141, v43, s0
	global_store_short v139, v141, s[72:73] offset:64
	v_cvt_pk_bf16_f32 v141, v31, s0
	global_store_short v139, v141, s[72:73] offset:96
	v_add_u32_e32 v139, 0xc0600, v138
	v_cvt_pk_bf16_f32 v141, v4, s0
	global_store_short v139, v141, s[72:73]
	v_cvt_pk_bf16_f32 v141, v36, s0
	global_store_short v139, v141, s[72:73] offset:32
	v_cvt_pk_bf16_f32 v141, v44, s0
	global_store_short v139, v141, s[72:73] offset:64
	v_cvt_pk_bf16_f32 v141, v32, s0
	global_store_short v139, v141, s[72:73] offset:96
	v_add_u32_e32 v139, 0xc2100, v138
	v_cvt_pk_bf16_f32 v141, v5, s0
	global_store_short v139, v141, s[72:73]
	v_cvt_pk_bf16_f32 v141, v37, s0
	global_store_short v139, v141, s[72:73] offset:32
	v_cvt_pk_bf16_f32 v141, v45, s0
	global_store_short v139, v141, s[72:73] offset:64
	v_cvt_pk_bf16_f32 v141, v33, s0
	global_store_short v139, v141, s[72:73] offset:96
	s_branch .LBB0_2075
; DEV u16 f2bf(float f) { return (u16)(pack2(f, 0.f) & 0xffffu); }
; DEV void phase_win(const Params& P, int l, const u16* __restrict__ xb, const u16* __restrict__ Wt, u16* __restrict__ h, char* smem) {
;     ...
;       for (int ns = 0; ns < 4; ++ns)
; #pragma unroll
;         for (int j = 0; j < 4; ++j) {
;           int row = m0 + wm * 128 + ms * 16 + quad * 4 + j;
;           int col = cb + ns * 16 + l15;
;           float v = acc[ms][ns][j];
;           if (mode == 1) { float lbv = lbp[col - C_HF]; v = __logf(lbv + (1.f - lbv) / (1.f + __expf(-v))); }
;           else if (mode == 2) v = v / (1.f + __expf(-v));
;           h[(size_t)row * HS + col] = f2bf(v);
.Lwg_m2:
	v_mul_f32_e32 v131, 0xbfb8aa3b, v38
	v_exp_f32_e32 v131, v131
	s_nop 0
	v_add_f32_e32 v131, 1.0, v131
	v_div_scale_f32 v132, s[4:5], v131, v131, v38
	v_rcp_f32_e32 v133, v132
	v_div_scale_f32 v134, vcc, v38, v131, v38
	v_fma_f32 v135, -v132, v133, 1.0
	v_fmac_f32_e32 v133, v135, v133
	v_mul_f32_e32 v135, v134, v133
	v_fma_f32 v136, -v132, v135, v134
	v_fmac_f32_e32 v135, v136, v133
	v_fma_f32 v132, -v132, v135, v134
	v_div_fmas_f32 v132, v132, v133, v135
	v_div_fixup_f32 v38, v132, v131, v38
	v_cvt_pk_bf16_f32 v141, v38, s0
	global_store_short v138, v141, s[72:73]
	v_mul_f32_e32 v131, 0xbfb8aa3b, v122
	v_exp_f32_e32 v131, v131
	s_nop 0
	v_add_f32_e32 v131, 1.0, v131
	v_div_scale_f32 v132, s[4:5], v131, v131, v122
	v_rcp_f32_e32 v133, v132
	v_div_scale_f32 v134, vcc, v122, v131, v122
	v_fma_f32 v135, -v132, v133, 1.0
	v_fmac_f32_e32 v133, v135, v133
	v_mul_f32_e32 v135, v134, v133
	v_fma_f32 v136, -v132, v135, v134
	v_fmac_f32_e32 v135, v136, v133
	v_fma_f32 v132, -v132, v135, v134
	v_div_fmas_f32 v132, v132, v133, v135
	v_div_fixup_f32 v122, v132, v131, v122
	v_cvt_pk_bf16_f32 v141, v122, s0
	global_store_short v138, v141, s[72:73] offset:32
	v_mul_f32_e32 v131, 0xbfb8aa3b, v126
	v_exp_f32_e32 v131, v131
	s_nop 0
	v_add_f32_e32 v131, 1.0, v131
	v_div_scale_f32 v132, s[4:5], v131, v131, v126
	v_rcp_f32_e32 v133, v132
	v_div_scale_f32 v134, vcc, v126, v131, v126
	v_fma_f32 v135, -v132, v133, 1.0
	v_fmac_f32_e32 v133, v135, v133
	v_mul_f32_e32 v135, v134, v133
	v_fma_f32 v136, -v132, v135, v134
	v_fmac_f32_e32 v135, v136, v133
	v_fma_f32 v132, -v132, v135, v134
	v_div_fmas_f32 v132, v132, v133, v135
	v_div_fixup_f32 v126, v132, v131, v126
	v_cvt_pk_bf16_f32 v141, v126, s0
	global_store_short v138, v141, s[72:73] offset:64
	v_mul_f32_e32 v131, 0xbfb8aa3b, v118
	v_exp_f32_e32 v131, v131
	s_nop 0
	v_add_f32_e32 v131, 1.0, v131
	v_div_scale_f32 v132, s[4:5], v131, v131, v118
	v_rcp_f32_e32 v133, v132
	v_div_scale_f32 v134, vcc, v118, v131, v118
	v_fma_f32 v135, -v132, v133, 1.0
	v_fmac_f32_e32 v133, v135, v133
	v_mul_f32_e32 v135, v134, v133
	v_fma_f32 v136, -v132, v135, v134
	v_fmac_f32_e32 v135, v136, v133
	v_fma_f32 v132, -v132, v135, v134
	v_div_fmas_f32 v132, v132, v133, v135
	v_div_fixup_f32 v118, v132, v131, v118
	v_cvt_pk_bf16_f32 v141, v118, s0
	global_store_short v138, v141, s[72:73] offset:96
	v_add_u32_e32 v139, 0x1b00, v138
	v_mul_f32_e32 v131, 0xbfb8aa3b, v39
	v_exp_f32_e32 v131, v131
	s_nop 0
	v_add_f32_e32 v131, 1.0, v131
	v_div_scale_f32 v132, s[4:5], v131, v131, v39
	v_rcp_f32_e32 v133, v132
	v_div_scale_f32 v134, vcc, v39, v131, v39
	v_fma_f32 v135, -v132, v133, 1.0
	v_fmac_f32_e32 v133, v135, v133
	v_mul_f32_e32 v135, v134, v133
	v_fma_f32 v136, -v132, v135, v134
	v_fmac_f32_e32 v135, v136, v133
	v_fma_f32 v132, -v132, v135, v134
	v_div_fmas_f32 v132, v132, v133, v135
	v_div_fixup_f32 v39, v132, v131, v39
	v_cvt_pk_bf16_f32 v141, v39, s0
	global_store_short v139, v141, s[72:73]
	v_mul_f32_e32 v131, 0xbfb8aa3b, v123
	v_exp_f32_e32 v131, v131
	s_nop 0
	v_add_f32_e32 v131, 1.0, v131
	v_div_scale_f32 v132, s[4:5], v131, v131, v123
	v_rcp_f32_e32 v133, v132
	v_div_scale_f32 v134, vcc, v123, v131, v123
	v_fma_f32 v135, -v132, v133, 1.0
	v_fmac_f32_e32 v133, v135, v133
	v_mul_f32_e32 v135, v134, v133
	v_fma_f32 v136, -v132, v135, v134
	v_fmac_f32_e32 v135, v136, v133
	v_fma_f32 v132, -v132, v135, v134
	v_div_fmas_f32 v132, v132, v133, v135
	v_div_fixup_f32 v123, v132, v131, v123
	v_cvt_pk_bf16_f32 v141, v123, s0
	global_store_short v139, v141, s[72:73] offset:32
	v_mul_f32_e32 v131, 0xbfb8aa3b, v127
	v_exp_f32_e32 v131, v131
	s_nop 0
	v_add_f32_e32 v131, 1.0, v131
	v_div_scale_f32 v132, s[4:5], v131, v131, v127
	v_rcp_f32_e32 v133, v132
	v_div_scale_f32 v134, vcc, v127, v131, v127
	v_fma_f32 v135, -v132, v133, 1.0
	v_fmac_f32_e32 v133, v135, v133
	v_mul_f32_e32 v135, v134, v133
	v_fma_f32 v136, -v132, v135, v134
	v_fmac_f32_e32 v135, v136, v133
	v_fma_f32 v132, -v132, v135, v134
	v_div_fmas_f32 v132, v132, v133, v135
	v_div_fixup_f32 v127, v132, v131, v127
	v_cvt_pk_bf16_f32 v141, v127, s0
	global_store_short v139, v141, s[72:73] offset:64
	v_mul_f32_e32 v131, 0xbfb8aa3b, v119
	v_exp_f32_e32 v131, v131
	s_nop 0
	v_add_f32_e32 v131, 1.0, v131
	v_div_scale_f32 v132, s[4:5], v131, v131, v119
	v_rcp_f32_e32 v133, v132
	v_div_scale_f32 v134, vcc, v119, v131, v119
	v_fma_f32 v135, -v132, v133, 1.0
	v_fmac_f32_e32 v133, v135, v133
	v_mul_f32_e32 v135, v134, v133
	v_fma_f32 v136, -v132, v135, v134
	v_fmac_f32_e32 v135, v136, v133
	v_fma_f32 v132, -v132, v135, v134
	v_div_fmas_f32 v132, v132, v133, v135
	v_div_fixup_f32 v119, v132, v131, v119
	v_cvt_pk_bf16_f32 v141, v119, s0
	global_store_short v139, v141, s[72:73] offset:96
	v_add_u32_e32 v139, 0x3600, v138
	v_mul_f32_e32 v131, 0xbfb8aa3b, v40
	v_exp_f32_e32 v131, v131
	s_nop 0
	v_add_f32_e32 v131, 1.0, v131
	v_div_scale_f32 v132, s[4:5], v131, v131, v40
	v_rcp_f32_e32 v133, v132
	v_div_scale_f32 v134, vcc, v40, v131, v40
	v_fma_f32 v135, -v132, v133, 1.0
	v_fmac_f32_e32 v133, v135, v133
	v_mul_f32_e32 v135, v134, v133
	v_fma_f32 v136, -v132, v135, v134
	v_fmac_f32_e32 v135, v136, v133
	v_fma_f32 v132, -v132, v135, v134
	v_div_fmas_f32 v132, v132, v133, v135
	v_div_fixup_f32 v40, v132, v131, v40
	v_cvt_pk_bf16_f32 v141, v40, s0
	global_store_short v139, v141, s[72:73]
	v_mul_f32_e32 v131, 0xbfb8aa3b, v124
	v_exp_f32_e32 v131, v131
	s_nop 0
	v_add_f32_e32 v131, 1.0, v131
	v_div_scale_f32 v132, s[4:5], v131, v131, v124
	v_rcp_f32_e32 v133, v132
	v_div_scale_f32 v134, vcc, v124, v131, v124
	v_fma_f32 v135, -v132, v133, 1.0
	v_fmac_f32_e32 v133, v135, v133
	v_mul_f32_e32 v135, v134, v133
; DEV u16 f2bf(float f) { return (u16)(pack2(f, 0.f) & 0xffffu); }
; DEV void phase_win(const Params& P, int l, const u16* __restrict__ xb, const u16* __restrict__ Wt, u16* __restrict__ h, char* smem) {
;     ...
;       for (int ns = 0; ns < 4; ++ns)
; #pragma unroll
;         for (int j = 0; j < 4; ++j) {
;           int row = m0 + wm * 128 + ms * 16 + quad * 4 + j;
;           int col = cb + ns * 16 + l15;
;           float v = acc[ms][ns][j];
;           if (mode == 1) { float lbv = lbp[col - C_HF]; v = __logf(lbv + (1.f - lbv) / (1.f + __expf(-v))); }
;           else if (mode == 2) v = v / (1.f + __expf(-v));
;           h[(size_t)row * HS + col] = f2bf(v);
	v_fma_f32 v136, -v132, v135, v134
	v_fmac_f32_e32 v135, v136, v133
	v_fma_f32 v132, -v132, v135, v134
	v_div_fmas_f32 v132, v132, v133, v135
	v_div_fixup_f32 v124, v132, v131, v124
	v_cvt_pk_bf16_f32 v141, v124, s0
	global_store_short v139, v141, s[72:73] offset:32
	v_mul_f32_e32 v131, 0xbfb8aa3b, v128
	v_exp_f32_e32 v131, v131
	s_nop 0
	v_add_f32_e32 v131, 1.0, v131
	v_div_scale_f32 v132, s[4:5], v131, v131, v128
	v_rcp_f32_e32 v133, v132
	v_div_scale_f32 v134, vcc, v128, v131, v128
	v_fma_f32 v135, -v132, v133, 1.0
	v_fmac_f32_e32 v133, v135, v133
	v_mul_f32_e32 v135, v134, v133
	v_fma_f32 v136, -v132, v135, v134
	v_fmac_f32_e32 v135, v136, v133
	v_fma_f32 v132, -v132, v135, v134
	v_div_fmas_f32 v132, v132, v133, v135
	v_div_fixup_f32 v128, v132, v131, v128
	v_cvt_pk_bf16_f32 v141, v128, s0
	global_store_short v139, v141, s[72:73] offset:64
	v_mul_f32_e32 v131, 0xbfb8aa3b, v120
	v_exp_f32_e32 v131, v131
	s_nop 0
	v_add_f32_e32 v131, 1.0, v131
	v_div_scale_f32 v132, s[4:5], v131, v131, v120
	v_rcp_f32_e32 v133, v132
	v_div_scale_f32 v134, vcc, v120, v131, v120
	v_fma_f32 v135, -v132, v133, 1.0
	v_fmac_f32_e32 v133, v135, v133
	v_mul_f32_e32 v135, v134, v133
	v_fma_f32 v136, -v132, v135, v134
	v_fmac_f32_e32 v135, v136, v133
	v_fma_f32 v132, -v132, v135, v134
	v_div_fmas_f32 v132, v132, v133, v135
	v_div_fixup_f32 v120, v132, v131, v120
	v_cvt_pk_bf16_f32 v141, v120, s0
	global_store_short v139, v141, s[72:73] offset:96
	v_add_u32_e32 v139, 0x5100, v138
	v_mul_f32_e32 v131, 0xbfb8aa3b, v41
	v_exp_f32_e32 v131, v131
	s_nop 0
	v_add_f32_e32 v131, 1.0, v131
	v_div_scale_f32 v132, s[4:5], v131, v131, v41
	v_rcp_f32_e32 v133, v132
	v_div_scale_f32 v134, vcc, v41, v131, v41
	v_fma_f32 v135, -v132, v133, 1.0
	v_fmac_f32_e32 v133, v135, v133
	v_mul_f32_e32 v135, v134, v133
	v_fma_f32 v136, -v132, v135, v134
	v_fmac_f32_e32 v135, v136, v133
	v_fma_f32 v132, -v132, v135, v134
	v_div_fmas_f32 v132, v132, v133, v135
	v_div_fixup_f32 v41, v132, v131, v41
	v_cvt_pk_bf16_f32 v141, v41, s0
	global_store_short v139, v141, s[72:73]
	v_mul_f32_e32 v131, 0xbfb8aa3b, v125
	v_exp_f32_e32 v131, v131
	s_nop 0
	v_add_f32_e32 v131, 1.0, v131
	v_div_scale_f32 v132, s[4:5], v131, v131, v125
	v_rcp_f32_e32 v133, v132
	v_div_scale_f32 v134, vcc, v125, v131, v125
	v_fma_f32 v135, -v132, v133, 1.0
	v_fmac_f32_e32 v133, v135, v133
	v_mul_f32_e32 v135, v134, v133
	v_fma_f32 v136, -v132, v135, v134
	v_fmac_f32_e32 v135, v136, v133
	v_fma_f32 v132, -v132, v135, v134
	v_div_fmas_f32 v132, v132, v133, v135
	v_div_fixup_f32 v125, v132, v131, v125
	v_cvt_pk_bf16_f32 v141, v125, s0
	global_store_short v139, v141, s[72:73] offset:32
	v_mul_f32_e32 v131, 0xbfb8aa3b, v129
	v_exp_f32_e32 v131, v131
	s_nop 0
	v_add_f32_e32 v131, 1.0, v131
	v_div_scale_f32 v132, s[4:5], v131, v131, v129
	v_rcp_f32_e32 v133, v132
	v_div_scale_f32 v134, vcc, v129, v131, v129
	v_fma_f32 v135, -v132, v133, 1.0
	v_fmac_f32_e32 v133, v135, v133
	v_mul_f32_e32 v135, v134, v133
	v_fma_f32 v136, -v132, v135, v134
	v_fmac_f32_e32 v135, v136, v133
	v_fma_f32 v132, -v132, v135, v134
	v_div_fmas_f32 v132, v132, v133, v135
	v_div_fixup_f32 v129, v132, v131, v129
	v_cvt_pk_bf16_f32 v141, v129, s0
	global_store_short v139, v141, s[72:73] offset:64
	v_mul_f32_e32 v131, 0xbfb8aa3b, v121
	v_exp_f32_e32 v131, v131
	s_nop 0
	v_add_f32_e32 v131, 1.0, v131
	v_div_scale_f32 v132, s[4:5], v131, v131, v121
	v_rcp_f32_e32 v133, v132
	v_div_scale_f32 v134, vcc, v121, v131, v121
	v_fma_f32 v135, -v132, v133, 1.0
	v_fmac_f32_e32 v133, v135, v133
	v_mul_f32_e32 v135, v134, v133
	v_fma_f32 v136, -v132, v135, v134
	v_fmac_f32_e32 v135, v136, v133
	v_fma_f32 v132, -v132, v135, v134
	v_div_fmas_f32 v132, v132, v133, v135
	v_div_fixup_f32 v121, v132, v131, v121
	v_cvt_pk_bf16_f32 v141, v121, s0
	global_store_short v139, v141, s[72:73] offset:96
	v_add_u32_e32 v139, 0x1b000, v138
	v_mul_f32_e32 v131, 0xbfb8aa3b, v26
	v_exp_f32_e32 v131, v131
	s_nop 0
	v_add_f32_e32 v131, 1.0, v131
	v_div_scale_f32 v132, s[4:5], v131, v131, v26
	v_rcp_f32_e32 v133, v132
	v_div_scale_f32 v134, vcc, v26, v131, v26
	v_fma_f32 v135, -v132, v133, 1.0
	v_fmac_f32_e32 v133, v135, v133
	v_mul_f32_e32 v135, v134, v133
	v_fma_f32 v136, -v132, v135, v134
	v_fmac_f32_e32 v135, v136, v133
	v_fma_f32 v132, -v132, v135, v134
	v_div_fmas_f32 v132, v132, v133, v135
	v_div_fixup_f32 v26, v132, v131, v26
	v_cvt_pk_bf16_f32 v141, v26, s0
	global_store_short v139, v141, s[72:73]
	v_mul_f32_e32 v131, 0xbfb8aa3b, v110
	v_exp_f32_e32 v131, v131
	s_nop 0
	v_add_f32_e32 v131, 1.0, v131
	v_div_scale_f32 v132, s[4:5], v131, v131, v110
	v_rcp_f32_e32 v133, v132
	v_div_scale_f32 v134, vcc, v110, v131, v110
	v_fma_f32 v135, -v132, v133, 1.0
	v_fmac_f32_e32 v133, v135, v133
	v_mul_f32_e32 v135, v134, v133
	v_fma_f32 v136, -v132, v135, v134
	v_fmac_f32_e32 v135, v136, v133
	v_fma_f32 v132, -v132, v135, v134
	v_div_fmas_f32 v132, v132, v133, v135
	v_div_fixup_f32 v110, v132, v131, v110
	v_cvt_pk_bf16_f32 v141, v110, s0
	global_store_short v139, v141, s[72:73] offset:32
	v_mul_f32_e32 v131, 0xbfb8aa3b, v114
	v_exp_f32_e32 v131, v131
	s_nop 0
	v_add_f32_e32 v131, 1.0, v131
	v_div_scale_f32 v132, s[4:5], v131, v131, v114
	v_rcp_f32_e32 v133, v132
	v_div_scale_f32 v134, vcc, v114, v131, v114
	v_fma_f32 v135, -v132, v133, 1.0
	v_fmac_f32_e32 v133, v135, v133
	v_mul_f32_e32 v135, v134, v133
	v_fma_f32 v136, -v132, v135, v134
	v_fmac_f32_e32 v135, v136, v133
	v_fma_f32 v132, -v132, v135, v134
	v_div_fmas_f32 v132, v132, v133, v135
	v_div_fixup_f32 v114, v132, v131, v114
	v_cvt_pk_bf16_f32 v141, v114, s0
	global_store_short v139, v141, s[72:73] offset:64
	v_mul_f32_e32 v131, 0xbfb8aa3b, v106
; DEV u16 f2bf(float f) { return (u16)(pack2(f, 0.f) & 0xffffu); }
; DEV void phase_win(const Params& P, int l, const u16* __restrict__ xb, const u16* __restrict__ Wt, u16* __restrict__ h, char* smem) {
;     ...
;       for (int ns = 0; ns < 4; ++ns)
; #pragma unroll
;         for (int j = 0; j < 4; ++j) {
;           int row = m0 + wm * 128 + ms * 16 + quad * 4 + j;
;           int col = cb + ns * 16 + l15;
;           float v = acc[ms][ns][j];
;           if (mode == 1) { float lbv = lbp[col - C_HF]; v = __logf(lbv + (1.f - lbv) / (1.f + __expf(-v))); }
;           else if (mode == 2) v = v / (1.f + __expf(-v));
;           h[(size_t)row * HS + col] = f2bf(v);
	v_exp_f32_e32 v131, v131
	s_nop 0
	v_add_f32_e32 v131, 1.0, v131
	v_div_scale_f32 v132, s[4:5], v131, v131, v106
	v_rcp_f32_e32 v133, v132
	v_div_scale_f32 v134, vcc, v106, v131, v106
	v_fma_f32 v135, -v132, v133, 1.0
	v_fmac_f32_e32 v133, v135, v133
	v_mul_f32_e32 v135, v134, v133
	v_fma_f32 v136, -v132, v135, v134
	v_fmac_f32_e32 v135, v136, v133
	v_fma_f32 v132, -v132, v135, v134
	v_div_fmas_f32 v132, v132, v133, v135
	v_div_fixup_f32 v106, v132, v131, v106
	v_cvt_pk_bf16_f32 v141, v106, s0
	global_store_short v139, v141, s[72:73] offset:96
	v_add_u32_e32 v139, 0x1cb00, v138
	v_mul_f32_e32 v131, 0xbfb8aa3b, v27
	v_exp_f32_e32 v131, v131
	s_nop 0
	v_add_f32_e32 v131, 1.0, v131
	v_div_scale_f32 v132, s[4:5], v131, v131, v27
	v_rcp_f32_e32 v133, v132
	v_div_scale_f32 v134, vcc, v27, v131, v27
	v_fma_f32 v135, -v132, v133, 1.0
	v_fmac_f32_e32 v133, v135, v133
	v_mul_f32_e32 v135, v134, v133
	v_fma_f32 v136, -v132, v135, v134
	v_fmac_f32_e32 v135, v136, v133
	v_fma_f32 v132, -v132, v135, v134
	v_div_fmas_f32 v132, v132, v133, v135
	v_div_fixup_f32 v27, v132, v131, v27
	v_cvt_pk_bf16_f32 v141, v27, s0
	global_store_short v139, v141, s[72:73]
	v_mul_f32_e32 v131, 0xbfb8aa3b, v111
	v_exp_f32_e32 v131, v131
	s_nop 0
	v_add_f32_e32 v131, 1.0, v131
	v_div_scale_f32 v132, s[4:5], v131, v131, v111
	v_rcp_f32_e32 v133, v132
	v_div_scale_f32 v134, vcc, v111, v131, v111
	v_fma_f32 v135, -v132, v133, 1.0
	v_fmac_f32_e32 v133, v135, v133
	v_mul_f32_e32 v135, v134, v133
	v_fma_f32 v136, -v132, v135, v134
	v_fmac_f32_e32 v135, v136, v133
	v_fma_f32 v132, -v132, v135, v134
	v_div_fmas_f32 v132, v132, v133, v135
	v_div_fixup_f32 v111, v132, v131, v111
	v_cvt_pk_bf16_f32 v141, v111, s0
	global_store_short v139, v141, s[72:73] offset:32
	v_mul_f32_e32 v131, 0xbfb8aa3b, v115
	v_exp_f32_e32 v131, v131
	s_nop 0
	v_add_f32_e32 v131, 1.0, v131
	v_div_scale_f32 v132, s[4:5], v131, v131, v115
	v_rcp_f32_e32 v133, v132
	v_div_scale_f32 v134, vcc, v115, v131, v115
	v_fma_f32 v135, -v132, v133, 1.0
	v_fmac_f32_e32 v133, v135, v133
	v_mul_f32_e32 v135, v134, v133
	v_fma_f32 v136, -v132, v135, v134
	v_fmac_f32_e32 v135, v136, v133
	v_fma_f32 v132, -v132, v135, v134
	v_div_fmas_f32 v132, v132, v133, v135
	v_div_fixup_f32 v115, v132, v131, v115
	v_cvt_pk_bf16_f32 v141, v115, s0
	global_store_short v139, v141, s[72:73] offset:64
	v_mul_f32_e32 v131, 0xbfb8aa3b, v107
	v_exp_f32_e32 v131, v131
	s_nop 0
	v_add_f32_e32 v131, 1.0, v131
	v_div_scale_f32 v132, s[4:5], v131, v131, v107
	v_rcp_f32_e32 v133, v132
	v_div_scale_f32 v134, vcc, v107, v131, v107
	v_fma_f32 v135, -v132, v133, 1.0
	v_fmac_f32_e32 v133, v135, v133
	v_mul_f32_e32 v135, v134, v133
	v_fma_f32 v136, -v132, v135, v134
	v_fmac_f32_e32 v135, v136, v133
	v_fma_f32 v132, -v132, v135, v134
	v_div_fmas_f32 v132, v132, v133, v135
	v_div_fixup_f32 v107, v132, v131, v107
	v_cvt_pk_bf16_f32 v141, v107, s0
	global_store_short v139, v141, s[72:73] offset:96
	v_add_u32_e32 v139, 0x1e600, v138
	v_mul_f32_e32 v131, 0xbfb8aa3b, v28
	v_exp_f32_e32 v131, v131
	s_nop 0
	v_add_f32_e32 v131, 1.0, v131
	v_div_scale_f32 v132, s[4:5], v131, v131, v28
	v_rcp_f32_e32 v133, v132
	v_div_scale_f32 v134, vcc, v28, v131, v28
	v_fma_f32 v135, -v132, v133, 1.0
	v_fmac_f32_e32 v133, v135, v133
	v_mul_f32_e32 v135, v134, v133
	v_fma_f32 v136, -v132, v135, v134
	v_fmac_f32_e32 v135, v136, v133
	v_fma_f32 v132, -v132, v135, v134
	v_div_fmas_f32 v132, v132, v133, v135
	v_div_fixup_f32 v28, v132, v131, v28
	v_cvt_pk_bf16_f32 v141, v28, s0
	global_store_short v139, v141, s[72:73]
	v_mul_f32_e32 v131, 0xbfb8aa3b, v112
	v_exp_f32_e32 v131, v131
	s_nop 0
	v_add_f32_e32 v131, 1.0, v131
	v_div_scale_f32 v132, s[4:5], v131, v131, v112
	v_rcp_f32_e32 v133, v132
	v_div_scale_f32 v134, vcc, v112, v131, v112
	v_fma_f32 v135, -v132, v133, 1.0
	v_fmac_f32_e32 v133, v135, v133
	v_mul_f32_e32 v135, v134, v133
	v_fma_f32 v136, -v132, v135, v134
	v_fmac_f32_e32 v135, v136, v133
	v_fma_f32 v132, -v132, v135, v134
	v_div_fmas_f32 v132, v132, v133, v135
	v_div_fixup_f32 v112, v132, v131, v112
	v_cvt_pk_bf16_f32 v141, v112, s0
	global_store_short v139, v141, s[72:73] offset:32
	v_mul_f32_e32 v131, 0xbfb8aa3b, v116
	v_exp_f32_e32 v131, v131
	s_nop 0
	v_add_f32_e32 v131, 1.0, v131
	v_div_scale_f32 v132, s[4:5], v131, v131, v116
	v_rcp_f32_e32 v133, v132
	v_div_scale_f32 v134, vcc, v116, v131, v116
	v_fma_f32 v135, -v132, v133, 1.0
	v_fmac_f32_e32 v133, v135, v133
	v_mul_f32_e32 v135, v134, v133
	v_fma_f32 v136, -v132, v135, v134
	v_fmac_f32_e32 v135, v136, v133
	v_fma_f32 v132, -v132, v135, v134
	v_div_fmas_f32 v132, v132, v133, v135
	v_div_fixup_f32 v116, v132, v131, v116
	v_cvt_pk_bf16_f32 v141, v116, s0
	global_store_short v139, v141, s[72:73] offset:64
	v_mul_f32_e32 v131, 0xbfb8aa3b, v108
	v_exp_f32_e32 v131, v131
	s_nop 0
	v_add_f32_e32 v131, 1.0, v131
	v_div_scale_f32 v132, s[4:5], v131, v131, v108
	v_rcp_f32_e32 v133, v132
	v_div_scale_f32 v134, vcc, v108, v131, v108
	v_fma_f32 v135, -v132, v133, 1.0
	v_fmac_f32_e32 v133, v135, v133
	v_mul_f32_e32 v135, v134, v133
	v_fma_f32 v136, -v132, v135, v134
	v_fmac_f32_e32 v135, v136, v133
	v_fma_f32 v132, -v132, v135, v134
	v_div_fmas_f32 v132, v132, v133, v135
	v_div_fixup_f32 v108, v132, v131, v108
	v_cvt_pk_bf16_f32 v141, v108, s0
	global_store_short v139, v141, s[72:73] offset:96
	v_add_u32_e32 v139, 0x20100, v138
	v_mul_f32_e32 v131, 0xbfb8aa3b, v29
	v_exp_f32_e32 v131, v131
	s_nop 0
	v_add_f32_e32 v131, 1.0, v131
	v_div_scale_f32 v132, s[4:5], v131, v131, v29
	v_rcp_f32_e32 v133, v132
	v_div_scale_f32 v134, vcc, v29, v131, v29
	v_fma_f32 v135, -v132, v133, 1.0
	v_fmac_f32_e32 v133, v135, v133
	v_mul_f32_e32 v135, v134, v133
; DEV u16 f2bf(float f) { return (u16)(pack2(f, 0.f) & 0xffffu); }
; DEV void phase_win(const Params& P, int l, const u16* __restrict__ xb, const u16* __restrict__ Wt, u16* __restrict__ h, char* smem) {
;     ...
;       for (int ns = 0; ns < 4; ++ns)
; #pragma unroll
;         for (int j = 0; j < 4; ++j) {
;           int row = m0 + wm * 128 + ms * 16 + quad * 4 + j;
;           int col = cb + ns * 16 + l15;
;           float v = acc[ms][ns][j];
;           if (mode == 1) { float lbv = lbp[col - C_HF]; v = __logf(lbv + (1.f - lbv) / (1.f + __expf(-v))); }
;           else if (mode == 2) v = v / (1.f + __expf(-v));
;           h[(size_t)row * HS + col] = f2bf(v);
	v_fma_f32 v136, -v132, v135, v134
	v_fmac_f32_e32 v135, v136, v133
	v_fma_f32 v132, -v132, v135, v134
	v_div_fmas_f32 v132, v132, v133, v135
	v_div_fixup_f32 v29, v132, v131, v29
	v_cvt_pk_bf16_f32 v141, v29, s0
	global_store_short v139, v141, s[72:73]
	v_mul_f32_e32 v131, 0xbfb8aa3b, v113
	v_exp_f32_e32 v131, v131
	s_nop 0
	v_add_f32_e32 v131, 1.0, v131
	v_div_scale_f32 v132, s[4:5], v131, v131, v113
	v_rcp_f32_e32 v133, v132
	v_div_scale_f32 v134, vcc, v113, v131, v113
	v_fma_f32 v135, -v132, v133, 1.0
	v_fmac_f32_e32 v133, v135, v133
	v_mul_f32_e32 v135, v134, v133
	v_fma_f32 v136, -v132, v135, v134
	v_fmac_f32_e32 v135, v136, v133
	v_fma_f32 v132, -v132, v135, v134
	v_div_fmas_f32 v132, v132, v133, v135
	v_div_fixup_f32 v113, v132, v131, v113
	v_cvt_pk_bf16_f32 v141, v113, s0
	global_store_short v139, v141, s[72:73] offset:32
	v_mul_f32_e32 v131, 0xbfb8aa3b, v117
	v_exp_f32_e32 v131, v131
	s_nop 0
	v_add_f32_e32 v131, 1.0, v131
	v_div_scale_f32 v132, s[4:5], v131, v131, v117
	v_rcp_f32_e32 v133, v132
	v_div_scale_f32 v134, vcc, v117, v131, v117
	v_fma_f32 v135, -v132, v133, 1.0
	v_fmac_f32_e32 v133, v135, v133
	v_mul_f32_e32 v135, v134, v133
	v_fma_f32 v136, -v132, v135, v134
	v_fmac_f32_e32 v135, v136, v133
	v_fma_f32 v132, -v132, v135, v134
	v_div_fmas_f32 v132, v132, v133, v135
	v_div_fixup_f32 v117, v132, v131, v117
	v_cvt_pk_bf16_f32 v141, v117, s0
	global_store_short v139, v141, s[72:73] offset:64
	v_mul_f32_e32 v131, 0xbfb8aa3b, v109
	v_exp_f32_e32 v131, v131
	s_nop 0
	v_add_f32_e32 v131, 1.0, v131
	v_div_scale_f32 v132, s[4:5], v131, v131, v109
	v_rcp_f32_e32 v133, v132
	v_div_scale_f32 v134, vcc, v109, v131, v109
	v_fma_f32 v135, -v132, v133, 1.0
	v_fmac_f32_e32 v133, v135, v133
	v_mul_f32_e32 v135, v134, v133
	v_fma_f32 v136, -v132, v135, v134
	v_fmac_f32_e32 v135, v136, v133
	v_fma_f32 v132, -v132, v135, v134
	v_div_fmas_f32 v132, v132, v133, v135
	v_div_fixup_f32 v109, v132, v131, v109
	v_cvt_pk_bf16_f32 v141, v109, s0
	global_store_short v139, v141, s[72:73] offset:96
	v_add_u32_e32 v139, 0x36000, v138
	v_mul_f32_e32 v131, 0xbfb8aa3b, v22
	v_exp_f32_e32 v131, v131
	s_nop 0
	v_add_f32_e32 v131, 1.0, v131
	v_div_scale_f32 v132, s[4:5], v131, v131, v22
	v_rcp_f32_e32 v133, v132
	v_div_scale_f32 v134, vcc, v22, v131, v22
	v_fma_f32 v135, -v132, v133, 1.0
	v_fmac_f32_e32 v133, v135, v133
	v_mul_f32_e32 v135, v134, v133
	v_fma_f32 v136, -v132, v135, v134
	v_fmac_f32_e32 v135, v136, v133
	v_fma_f32 v132, -v132, v135, v134
	v_div_fmas_f32 v132, v132, v133, v135
	v_div_fixup_f32 v22, v132, v131, v22
	v_cvt_pk_bf16_f32 v141, v22, s0
	global_store_short v139, v141, s[72:73]
	v_mul_f32_e32 v131, 0xbfb8aa3b, v98
	v_exp_f32_e32 v131, v131
	s_nop 0
	v_add_f32_e32 v131, 1.0, v131
	v_div_scale_f32 v132, s[4:5], v131, v131, v98
	v_rcp_f32_e32 v133, v132
	v_div_scale_f32 v134, vcc, v98, v131, v98
	v_fma_f32 v135, -v132, v133, 1.0
	v_fmac_f32_e32 v133, v135, v133
	v_mul_f32_e32 v135, v134, v133
	v_fma_f32 v136, -v132, v135, v134
	v_fmac_f32_e32 v135, v136, v133
	v_fma_f32 v132, -v132, v135, v134
	v_div_fmas_f32 v132, v132, v133, v135
	v_div_fixup_f32 v98, v132, v131, v98
	v_cvt_pk_bf16_f32 v141, v98, s0
	global_store_short v139, v141, s[72:73] offset:32
	v_mul_f32_e32 v131, 0xbfb8aa3b, v102
	v_exp_f32_e32 v131, v131
	s_nop 0
	v_add_f32_e32 v131, 1.0, v131
	v_div_scale_f32 v132, s[4:5], v131, v131, v102
	v_rcp_f32_e32 v133, v132
	v_div_scale_f32 v134, vcc, v102, v131, v102
	v_fma_f32 v135, -v132, v133, 1.0
	v_fmac_f32_e32 v133, v135, v133
	v_mul_f32_e32 v135, v134, v133
	v_fma_f32 v136, -v132, v135, v134
	v_fmac_f32_e32 v135, v136, v133
	v_fma_f32 v132, -v132, v135, v134
	v_div_fmas_f32 v132, v132, v133, v135
	v_div_fixup_f32 v102, v132, v131, v102
	v_cvt_pk_bf16_f32 v141, v102, s0
	global_store_short v139, v141, s[72:73] offset:64
	v_mul_f32_e32 v131, 0xbfb8aa3b, v94
	v_exp_f32_e32 v131, v131
	s_nop 0
	v_add_f32_e32 v131, 1.0, v131
	v_div_scale_f32 v132, s[4:5], v131, v131, v94
	v_rcp_f32_e32 v133, v132
	v_div_scale_f32 v134, vcc, v94, v131, v94
	v_fma_f32 v135, -v132, v133, 1.0
	v_fmac_f32_e32 v133, v135, v133
	v_mul_f32_e32 v135, v134, v133
	v_fma_f32 v136, -v132, v135, v134
	v_fmac_f32_e32 v135, v136, v133
	v_fma_f32 v132, -v132, v135, v134
	v_div_fmas_f32 v132, v132, v133, v135
	v_div_fixup_f32 v94, v132, v131, v94
	v_cvt_pk_bf16_f32 v141, v94, s0
	global_store_short v139, v141, s[72:73] offset:96
	v_add_u32_e32 v139, 0x37b00, v138
	v_mul_f32_e32 v131, 0xbfb8aa3b, v23
	v_exp_f32_e32 v131, v131
	s_nop 0
	v_add_f32_e32 v131, 1.0, v131
	v_div_scale_f32 v132, s[4:5], v131, v131, v23
	v_rcp_f32_e32 v133, v132
	v_div_scale_f32 v134, vcc, v23, v131, v23
	v_fma_f32 v135, -v132, v133, 1.0
	v_fmac_f32_e32 v133, v135, v133
	v_mul_f32_e32 v135, v134, v133
	v_fma_f32 v136, -v132, v135, v134
	v_fmac_f32_e32 v135, v136, v133
	v_fma_f32 v132, -v132, v135, v134
	v_div_fmas_f32 v132, v132, v133, v135
	v_div_fixup_f32 v23, v132, v131, v23
	v_cvt_pk_bf16_f32 v141, v23, s0
	global_store_short v139, v141, s[72:73]
	v_mul_f32_e32 v131, 0xbfb8aa3b, v99
	v_exp_f32_e32 v131, v131
	s_nop 0
	v_add_f32_e32 v131, 1.0, v131
	v_div_scale_f32 v132, s[4:5], v131, v131, v99
	v_rcp_f32_e32 v133, v132
	v_div_scale_f32 v134, vcc, v99, v131, v99
	v_fma_f32 v135, -v132, v133, 1.0
	v_fmac_f32_e32 v133, v135, v133
	v_mul_f32_e32 v135, v134, v133
	v_fma_f32 v136, -v132, v135, v134
	v_fmac_f32_e32 v135, v136, v133
	v_fma_f32 v132, -v132, v135, v134
	v_div_fmas_f32 v132, v132, v133, v135
	v_div_fixup_f32 v99, v132, v131, v99
	v_cvt_pk_bf16_f32 v141, v99, s0
	global_store_short v139, v141, s[72:73] offset:32
	v_mul_f32_e32 v131, 0xbfb8aa3b, v103
	v_exp_f32_e32 v131, v131
	s_nop 0
; DEV u16 f2bf(float f) { return (u16)(pack2(f, 0.f) & 0xffffu); }
; DEV void phase_win(const Params& P, int l, const u16* __restrict__ xb, const u16* __restrict__ Wt, u16* __restrict__ h, char* smem) {
;     ...
;       for (int ns = 0; ns < 4; ++ns)
; #pragma unroll
;         for (int j = 0; j < 4; ++j) {
;           int row = m0 + wm * 128 + ms * 16 + quad * 4 + j;
;           int col = cb + ns * 16 + l15;
;           float v = acc[ms][ns][j];
;           if (mode == 1) { float lbv = lbp[col - C_HF]; v = __logf(lbv + (1.f - lbv) / (1.f + __expf(-v))); }
;           else if (mode == 2) v = v / (1.f + __expf(-v));
;           h[(size_t)row * HS + col] = f2bf(v);
	v_add_f32_e32 v131, 1.0, v131
	v_div_scale_f32 v132, s[4:5], v131, v131, v103
	v_rcp_f32_e32 v133, v132
	v_div_scale_f32 v134, vcc, v103, v131, v103
	v_fma_f32 v135, -v132, v133, 1.0
	v_fmac_f32_e32 v133, v135, v133
	v_mul_f32_e32 v135, v134, v133
	v_fma_f32 v136, -v132, v135, v134
	v_fmac_f32_e32 v135, v136, v133
	v_fma_f32 v132, -v132, v135, v134
	v_div_fmas_f32 v132, v132, v133, v135
	v_div_fixup_f32 v103, v132, v131, v103
	v_cvt_pk_bf16_f32 v141, v103, s0
	global_store_short v139, v141, s[72:73] offset:64
	v_mul_f32_e32 v131, 0xbfb8aa3b, v95
	v_exp_f32_e32 v131, v131
	s_nop 0
	v_add_f32_e32 v131, 1.0, v131
	v_div_scale_f32 v132, s[4:5], v131, v131, v95
	v_rcp_f32_e32 v133, v132
	v_div_scale_f32 v134, vcc, v95, v131, v95
	v_fma_f32 v135, -v132, v133, 1.0
	v_fmac_f32_e32 v133, v135, v133
	v_mul_f32_e32 v135, v134, v133
	v_fma_f32 v136, -v132, v135, v134
	v_fmac_f32_e32 v135, v136, v133
	v_fma_f32 v132, -v132, v135, v134
	v_div_fmas_f32 v132, v132, v133, v135
	v_div_fixup_f32 v95, v132, v131, v95
	v_cvt_pk_bf16_f32 v141, v95, s0
	global_store_short v139, v141, s[72:73] offset:96
	v_add_u32_e32 v139, 0x39600, v138
	v_mul_f32_e32 v131, 0xbfb8aa3b, v24
	v_exp_f32_e32 v131, v131
	s_nop 0
	v_add_f32_e32 v131, 1.0, v131
	v_div_scale_f32 v132, s[4:5], v131, v131, v24
	v_rcp_f32_e32 v133, v132
	v_div_scale_f32 v134, vcc, v24, v131, v24
	v_fma_f32 v135, -v132, v133, 1.0
	v_fmac_f32_e32 v133, v135, v133
	v_mul_f32_e32 v135, v134, v133
	v_fma_f32 v136, -v132, v135, v134
	v_fmac_f32_e32 v135, v136, v133
	v_fma_f32 v132, -v132, v135, v134
	v_div_fmas_f32 v132, v132, v133, v135
	v_div_fixup_f32 v24, v132, v131, v24
	v_cvt_pk_bf16_f32 v141, v24, s0
	global_store_short v139, v141, s[72:73]
	v_mul_f32_e32 v131, 0xbfb8aa3b, v100
	v_exp_f32_e32 v131, v131
	s_nop 0
	v_add_f32_e32 v131, 1.0, v131
	v_div_scale_f32 v132, s[4:5], v131, v131, v100
	v_rcp_f32_e32 v133, v132
	v_div_scale_f32 v134, vcc, v100, v131, v100
	v_fma_f32 v135, -v132, v133, 1.0
	v_fmac_f32_e32 v133, v135, v133
	v_mul_f32_e32 v135, v134, v133
	v_fma_f32 v136, -v132, v135, v134
	v_fmac_f32_e32 v135, v136, v133
	v_fma_f32 v132, -v132, v135, v134
	v_div_fmas_f32 v132, v132, v133, v135
	v_div_fixup_f32 v100, v132, v131, v100
	v_cvt_pk_bf16_f32 v141, v100, s0
	global_store_short v139, v141, s[72:73] offset:32
	v_mul_f32_e32 v131, 0xbfb8aa3b, v104
	v_exp_f32_e32 v131, v131
	s_nop 0
	v_add_f32_e32 v131, 1.0, v131
	v_div_scale_f32 v132, s[4:5], v131, v131, v104
	v_rcp_f32_e32 v133, v132
	v_div_scale_f32 v134, vcc, v104, v131, v104
	v_fma_f32 v135, -v132, v133, 1.0
	v_fmac_f32_e32 v133, v135, v133
	v_mul_f32_e32 v135, v134, v133
	v_fma_f32 v136, -v132, v135, v134
	v_fmac_f32_e32 v135, v136, v133
	v_fma_f32 v132, -v132, v135, v134
	v_div_fmas_f32 v132, v132, v133, v135
	v_div_fixup_f32 v104, v132, v131, v104
	v_cvt_pk_bf16_f32 v141, v104, s0
	global_store_short v139, v141, s[72:73] offset:64
	v_mul_f32_e32 v131, 0xbfb8aa3b, v96
	v_exp_f32_e32 v131, v131
	s_nop 0
	v_add_f32_e32 v131, 1.0, v131
	v_div_scale_f32 v132, s[4:5], v131, v131, v96
	v_rcp_f32_e32 v133, v132
	v_div_scale_f32 v134, vcc, v96, v131, v96
	v_fma_f32 v135, -v132, v133, 1.0
	v_fmac_f32_e32 v133, v135, v133
	v_mul_f32_e32 v135, v134, v133
	v_fma_f32 v136, -v132, v135, v134
	v_fmac_f32_e32 v135, v136, v133
	v_fma_f32 v132, -v132, v135, v134
	v_div_fmas_f32 v132, v132, v133, v135
	v_div_fixup_f32 v96, v132, v131, v96
	v_cvt_pk_bf16_f32 v141, v96, s0
	global_store_short v139, v141, s[72:73] offset:96
	v_add_u32_e32 v139, 0x3b100, v138
	v_mul_f32_e32 v131, 0xbfb8aa3b, v25
	v_exp_f32_e32 v131, v131
	s_nop 0
	v_add_f32_e32 v131, 1.0, v131
	v_div_scale_f32 v132, s[4:5], v131, v131, v25
	v_rcp_f32_e32 v133, v132
	v_div_scale_f32 v134, vcc, v25, v131, v25
	v_fma_f32 v135, -v132, v133, 1.0
	v_fmac_f32_e32 v133, v135, v133
	v_mul_f32_e32 v135, v134, v133
	v_fma_f32 v136, -v132, v135, v134
	v_fmac_f32_e32 v135, v136, v133
	v_fma_f32 v132, -v132, v135, v134
	v_div_fmas_f32 v132, v132, v133, v135
	v_div_fixup_f32 v25, v132, v131, v25
	v_cvt_pk_bf16_f32 v141, v25, s0
	global_store_short v139, v141, s[72:73]
	v_mul_f32_e32 v131, 0xbfb8aa3b, v101
	v_exp_f32_e32 v131, v131
	s_nop 0
	v_add_f32_e32 v131, 1.0, v131
	v_div_scale_f32 v132, s[4:5], v131, v131, v101
	v_rcp_f32_e32 v133, v132
	v_div_scale_f32 v134, vcc, v101, v131, v101
	v_fma_f32 v135, -v132, v133, 1.0
	v_fmac_f32_e32 v133, v135, v133
	v_mul_f32_e32 v135, v134, v133
	v_fma_f32 v136, -v132, v135, v134
	v_fmac_f32_e32 v135, v136, v133
	v_fma_f32 v132, -v132, v135, v134
	v_div_fmas_f32 v132, v132, v133, v135
	v_div_fixup_f32 v101, v132, v131, v101
	v_cvt_pk_bf16_f32 v141, v101, s0
	global_store_short v139, v141, s[72:73] offset:32
	v_mul_f32_e32 v131, 0xbfb8aa3b, v105
	v_exp_f32_e32 v131, v131
	s_nop 0
	v_add_f32_e32 v131, 1.0, v131
	v_div_scale_f32 v132, s[4:5], v131, v131, v105
	v_rcp_f32_e32 v133, v132
	v_div_scale_f32 v134, vcc, v105, v131, v105
	v_fma_f32 v135, -v132, v133, 1.0
	v_fmac_f32_e32 v133, v135, v133
	v_mul_f32_e32 v135, v134, v133
	v_fma_f32 v136, -v132, v135, v134
	v_fmac_f32_e32 v135, v136, v133
	v_fma_f32 v132, -v132, v135, v134
	v_div_fmas_f32 v132, v132, v133, v135
	v_div_fixup_f32 v105, v132, v131, v105
	v_cvt_pk_bf16_f32 v141, v105, s0
	global_store_short v139, v141, s[72:73] offset:64
	v_mul_f32_e32 v131, 0xbfb8aa3b, v97
	v_exp_f32_e32 v131, v131
	s_nop 0
	v_add_f32_e32 v131, 1.0, v131
	v_div_scale_f32 v132, s[4:5], v131, v131, v97
	v_rcp_f32_e32 v133, v132
	v_div_scale_f32 v134, vcc, v97, v131, v97
	v_fma_f32 v135, -v132, v133, 1.0
	v_fmac_f32_e32 v133, v135, v133
	v_mul_f32_e32 v135, v134, v133
	v_fma_f32 v136, -v132, v135, v134
	v_fmac_f32_e32 v135, v136, v133
; DEV u16 f2bf(float f) { return (u16)(pack2(f, 0.f) & 0xffffu); }
; DEV void phase_win(const Params& P, int l, const u16* __restrict__ xb, const u16* __restrict__ Wt, u16* __restrict__ h, char* smem) {
;     ...
;       for (int ns = 0; ns < 4; ++ns)
; #pragma unroll
;         for (int j = 0; j < 4; ++j) {
;           int row = m0 + wm * 128 + ms * 16 + quad * 4 + j;
;           int col = cb + ns * 16 + l15;
;           float v = acc[ms][ns][j];
;           if (mode == 1) { float lbv = lbp[col - C_HF]; v = __logf(lbv + (1.f - lbv) / (1.f + __expf(-v))); }
;           else if (mode == 2) v = v / (1.f + __expf(-v));
;           h[(size_t)row * HS + col] = f2bf(v);
	v_fma_f32 v132, -v132, v135, v134
	v_div_fmas_f32 v132, v132, v133, v135
	v_div_fixup_f32 v97, v132, v131, v97
	v_cvt_pk_bf16_f32 v141, v97, s0
	global_store_short v139, v141, s[72:73] offset:96
	v_add_u32_e32 v139, 0x51000, v138
	v_mul_f32_e32 v131, 0xbfb8aa3b, v18
	v_exp_f32_e32 v131, v131
	s_nop 0
	v_add_f32_e32 v131, 1.0, v131
	v_div_scale_f32 v132, s[4:5], v131, v131, v18
	v_rcp_f32_e32 v133, v132
	v_div_scale_f32 v134, vcc, v18, v131, v18
	v_fma_f32 v135, -v132, v133, 1.0
	v_fmac_f32_e32 v133, v135, v133
	v_mul_f32_e32 v135, v134, v133
	v_fma_f32 v136, -v132, v135, v134
	v_fmac_f32_e32 v135, v136, v133
	v_fma_f32 v132, -v132, v135, v134
	v_div_fmas_f32 v132, v132, v133, v135
	v_div_fixup_f32 v18, v132, v131, v18
	v_cvt_pk_bf16_f32 v141, v18, s0
	global_store_short v139, v141, s[72:73]
	v_mul_f32_e32 v131, 0xbfb8aa3b, v86
	v_exp_f32_e32 v131, v131
	s_nop 0
	v_add_f32_e32 v131, 1.0, v131
	v_div_scale_f32 v132, s[4:5], v131, v131, v86
	v_rcp_f32_e32 v133, v132
	v_div_scale_f32 v134, vcc, v86, v131, v86
	v_fma_f32 v135, -v132, v133, 1.0
	v_fmac_f32_e32 v133, v135, v133
	v_mul_f32_e32 v135, v134, v133
	v_fma_f32 v136, -v132, v135, v134
	v_fmac_f32_e32 v135, v136, v133
	v_fma_f32 v132, -v132, v135, v134
	v_div_fmas_f32 v132, v132, v133, v135
	v_div_fixup_f32 v86, v132, v131, v86
	v_cvt_pk_bf16_f32 v141, v86, s0
	global_store_short v139, v141, s[72:73] offset:32
	v_mul_f32_e32 v131, 0xbfb8aa3b, v90
	v_exp_f32_e32 v131, v131
	s_nop 0
	v_add_f32_e32 v131, 1.0, v131
	v_div_scale_f32 v132, s[4:5], v131, v131, v90
	v_rcp_f32_e32 v133, v132
	v_div_scale_f32 v134, vcc, v90, v131, v90
	v_fma_f32 v135, -v132, v133, 1.0
	v_fmac_f32_e32 v133, v135, v133
	v_mul_f32_e32 v135, v134, v133
	v_fma_f32 v136, -v132, v135, v134
	v_fmac_f32_e32 v135, v136, v133
	v_fma_f32 v132, -v132, v135, v134
	v_div_fmas_f32 v132, v132, v133, v135
	v_div_fixup_f32 v90, v132, v131, v90
	v_cvt_pk_bf16_f32 v141, v90, s0
	global_store_short v139, v141, s[72:73] offset:64
	v_mul_f32_e32 v131, 0xbfb8aa3b, v82
	v_exp_f32_e32 v131, v131
	s_nop 0
	v_add_f32_e32 v131, 1.0, v131
	v_div_scale_f32 v132, s[4:5], v131, v131, v82
	v_rcp_f32_e32 v133, v132
	v_div_scale_f32 v134, vcc, v82, v131, v82
	v_fma_f32 v135, -v132, v133, 1.0
	v_fmac_f32_e32 v133, v135, v133
	v_mul_f32_e32 v135, v134, v133
	v_fma_f32 v136, -v132, v135, v134
	v_fmac_f32_e32 v135, v136, v133
	v_fma_f32 v132, -v132, v135, v134
	v_div_fmas_f32 v132, v132, v133, v135
	v_div_fixup_f32 v82, v132, v131, v82
	v_cvt_pk_bf16_f32 v141, v82, s0
	global_store_short v139, v141, s[72:73] offset:96
	v_add_u32_e32 v139, 0x52b00, v138
	v_mul_f32_e32 v131, 0xbfb8aa3b, v19
	v_exp_f32_e32 v131, v131
	s_nop 0
	v_add_f32_e32 v131, 1.0, v131
	v_div_scale_f32 v132, s[4:5], v131, v131, v19
	v_rcp_f32_e32 v133, v132
	v_div_scale_f32 v134, vcc, v19, v131, v19
	v_fma_f32 v135, -v132, v133, 1.0
	v_fmac_f32_e32 v133, v135, v133
	v_mul_f32_e32 v135, v134, v133
	v_fma_f32 v136, -v132, v135, v134
	v_fmac_f32_e32 v135, v136, v133
	v_fma_f32 v132, -v132, v135, v134
	v_div_fmas_f32 v132, v132, v133, v135
	v_div_fixup_f32 v19, v132, v131, v19
	v_cvt_pk_bf16_f32 v141, v19, s0
	global_store_short v139, v141, s[72:73]
	v_mul_f32_e32 v131, 0xbfb8aa3b, v87
	v_exp_f32_e32 v131, v131
	s_nop 0
	v_add_f32_e32 v131, 1.0, v131
	v_div_scale_f32 v132, s[4:5], v131, v131, v87
	v_rcp_f32_e32 v133, v132
	v_div_scale_f32 v134, vcc, v87, v131, v87
	v_fma_f32 v135, -v132, v133, 1.0
	v_fmac_f32_e32 v133, v135, v133
	v_mul_f32_e32 v135, v134, v133
	v_fma_f32 v136, -v132, v135, v134
	v_fmac_f32_e32 v135, v136, v133
	v_fma_f32 v132, -v132, v135, v134
	v_div_fmas_f32 v132, v132, v133, v135
	v_div_fixup_f32 v87, v132, v131, v87
	v_cvt_pk_bf16_f32 v141, v87, s0
	global_store_short v139, v141, s[72:73] offset:32
	v_mul_f32_e32 v131, 0xbfb8aa3b, v91
	v_exp_f32_e32 v131, v131
	s_nop 0
	v_add_f32_e32 v131, 1.0, v131
	v_div_scale_f32 v132, s[4:5], v131, v131, v91
	v_rcp_f32_e32 v133, v132
	v_div_scale_f32 v134, vcc, v91, v131, v91
	v_fma_f32 v135, -v132, v133, 1.0
	v_fmac_f32_e32 v133, v135, v133
	v_mul_f32_e32 v135, v134, v133
	v_fma_f32 v136, -v132, v135, v134
	v_fmac_f32_e32 v135, v136, v133
	v_fma_f32 v132, -v132, v135, v134
	v_div_fmas_f32 v132, v132, v133, v135
	v_div_fixup_f32 v91, v132, v131, v91
	v_cvt_pk_bf16_f32 v141, v91, s0
	global_store_short v139, v141, s[72:73] offset:64
	v_mul_f32_e32 v131, 0xbfb8aa3b, v83
	v_exp_f32_e32 v131, v131
	s_nop 0
	v_add_f32_e32 v131, 1.0, v131
	v_div_scale_f32 v132, s[4:5], v131, v131, v83
	v_rcp_f32_e32 v133, v132
	v_div_scale_f32 v134, vcc, v83, v131, v83
	v_fma_f32 v135, -v132, v133, 1.0
	v_fmac_f32_e32 v133, v135, v133
	v_mul_f32_e32 v135, v134, v133
	v_fma_f32 v136, -v132, v135, v134
	v_fmac_f32_e32 v135, v136, v133
	v_fma_f32 v132, -v132, v135, v134
	v_div_fmas_f32 v132, v132, v133, v135
	v_div_fixup_f32 v83, v132, v131, v83
	v_cvt_pk_bf16_f32 v141, v83, s0
	global_store_short v139, v141, s[72:73] offset:96
	v_add_u32_e32 v139, 0x54600, v138
	v_mul_f32_e32 v131, 0xbfb8aa3b, v20
	v_exp_f32_e32 v131, v131
	s_nop 0
	v_add_f32_e32 v131, 1.0, v131
	v_div_scale_f32 v132, s[4:5], v131, v131, v20
	v_rcp_f32_e32 v133, v132
	v_div_scale_f32 v134, vcc, v20, v131, v20
	v_fma_f32 v135, -v132, v133, 1.0
	v_fmac_f32_e32 v133, v135, v133
	v_mul_f32_e32 v135, v134, v133
	v_fma_f32 v136, -v132, v135, v134
	v_fmac_f32_e32 v135, v136, v133
	v_fma_f32 v132, -v132, v135, v134
	v_div_fmas_f32 v132, v132, v133, v135
	v_div_fixup_f32 v20, v132, v131, v20
	v_cvt_pk_bf16_f32 v141, v20, s0
	global_store_short v139, v141, s[72:73]
	v_mul_f32_e32 v131, 0xbfb8aa3b, v88
	v_exp_f32_e32 v131, v131
	s_nop 0
	v_add_f32_e32 v131, 1.0, v131
	v_div_scale_f32 v132, s[4:5], v131, v131, v88
; DEV u16 f2bf(float f) { return (u16)(pack2(f, 0.f) & 0xffffu); }
; DEV void phase_win(const Params& P, int l, const u16* __restrict__ xb, const u16* __restrict__ Wt, u16* __restrict__ h, char* smem) {
;     ...
;       for (int ns = 0; ns < 4; ++ns)
; #pragma unroll
;         for (int j = 0; j < 4; ++j) {
;           int row = m0 + wm * 128 + ms * 16 + quad * 4 + j;
;           int col = cb + ns * 16 + l15;
;           float v = acc[ms][ns][j];
;           if (mode == 1) { float lbv = lbp[col - C_HF]; v = __logf(lbv + (1.f - lbv) / (1.f + __expf(-v))); }
;           else if (mode == 2) v = v / (1.f + __expf(-v));
;           h[(size_t)row * HS + col] = f2bf(v);
	v_rcp_f32_e32 v133, v132
	v_div_scale_f32 v134, vcc, v88, v131, v88
	v_fma_f32 v135, -v132, v133, 1.0
	v_fmac_f32_e32 v133, v135, v133
	v_mul_f32_e32 v135, v134, v133
	v_fma_f32 v136, -v132, v135, v134
	v_fmac_f32_e32 v135, v136, v133
	v_fma_f32 v132, -v132, v135, v134
	v_div_fmas_f32 v132, v132, v133, v135
	v_div_fixup_f32 v88, v132, v131, v88
	v_cvt_pk_bf16_f32 v141, v88, s0
	global_store_short v139, v141, s[72:73] offset:32
	v_mul_f32_e32 v131, 0xbfb8aa3b, v92
	v_exp_f32_e32 v131, v131
	s_nop 0
	v_add_f32_e32 v131, 1.0, v131
	v_div_scale_f32 v132, s[4:5], v131, v131, v92
	v_rcp_f32_e32 v133, v132
	v_div_scale_f32 v134, vcc, v92, v131, v92
	v_fma_f32 v135, -v132, v133, 1.0
	v_fmac_f32_e32 v133, v135, v133
	v_mul_f32_e32 v135, v134, v133
	v_fma_f32 v136, -v132, v135, v134
	v_fmac_f32_e32 v135, v136, v133
	v_fma_f32 v132, -v132, v135, v134
	v_div_fmas_f32 v132, v132, v133, v135
	v_div_fixup_f32 v92, v132, v131, v92
	v_cvt_pk_bf16_f32 v141, v92, s0
	global_store_short v139, v141, s[72:73] offset:64
	v_mul_f32_e32 v131, 0xbfb8aa3b, v84
	v_exp_f32_e32 v131, v131
	s_nop 0
	v_add_f32_e32 v131, 1.0, v131
	v_div_scale_f32 v132, s[4:5], v131, v131, v84
	v_rcp_f32_e32 v133, v132
	v_div_scale_f32 v134, vcc, v84, v131, v84
	v_fma_f32 v135, -v132, v133, 1.0
	v_fmac_f32_e32 v133, v135, v133
	v_mul_f32_e32 v135, v134, v133
	v_fma_f32 v136, -v132, v135, v134
	v_fmac_f32_e32 v135, v136, v133
	v_fma_f32 v132, -v132, v135, v134
	v_div_fmas_f32 v132, v132, v133, v135
	v_div_fixup_f32 v84, v132, v131, v84
	v_cvt_pk_bf16_f32 v141, v84, s0
	global_store_short v139, v141, s[72:73] offset:96
	v_add_u32_e32 v139, 0x56100, v138
	v_mul_f32_e32 v131, 0xbfb8aa3b, v21
	v_exp_f32_e32 v131, v131
	s_nop 0
	v_add_f32_e32 v131, 1.0, v131
	v_div_scale_f32 v132, s[4:5], v131, v131, v21
	v_rcp_f32_e32 v133, v132
	v_div_scale_f32 v134, vcc, v21, v131, v21
	v_fma_f32 v135, -v132, v133, 1.0
	v_fmac_f32_e32 v133, v135, v133
	v_mul_f32_e32 v135, v134, v133
	v_fma_f32 v136, -v132, v135, v134
	v_fmac_f32_e32 v135, v136, v133
	v_fma_f32 v132, -v132, v135, v134
	v_div_fmas_f32 v132, v132, v133, v135
	v_div_fixup_f32 v21, v132, v131, v21
	v_cvt_pk_bf16_f32 v141, v21, s0
	global_store_short v139, v141, s[72:73]
	v_mul_f32_e32 v131, 0xbfb8aa3b, v89
	v_exp_f32_e32 v131, v131
	s_nop 0
	v_add_f32_e32 v131, 1.0, v131
	v_div_scale_f32 v132, s[4:5], v131, v131, v89
	v_rcp_f32_e32 v133, v132
	v_div_scale_f32 v134, vcc, v89, v131, v89
	v_fma_f32 v135, -v132, v133, 1.0
	v_fmac_f32_e32 v133, v135, v133
	v_mul_f32_e32 v135, v134, v133
	v_fma_f32 v136, -v132, v135, v134
	v_fmac_f32_e32 v135, v136, v133
	v_fma_f32 v132, -v132, v135, v134
	v_div_fmas_f32 v132, v132, v133, v135
	v_div_fixup_f32 v89, v132, v131, v89
	v_cvt_pk_bf16_f32 v141, v89, s0
	global_store_short v139, v141, s[72:73] offset:32
	v_mul_f32_e32 v131, 0xbfb8aa3b, v93
	v_exp_f32_e32 v131, v131
	s_nop 0
	v_add_f32_e32 v131, 1.0, v131
	v_div_scale_f32 v132, s[4:5], v131, v131, v93
	v_rcp_f32_e32 v133, v132
	v_div_scale_f32 v134, vcc, v93, v131, v93
	v_fma_f32 v135, -v132, v133, 1.0
	v_fmac_f32_e32 v133, v135, v133
	v_mul_f32_e32 v135, v134, v133
	v_fma_f32 v136, -v132, v135, v134
	v_fmac_f32_e32 v135, v136, v133
	v_fma_f32 v132, -v132, v135, v134
	v_div_fmas_f32 v132, v132, v133, v135
	v_div_fixup_f32 v93, v132, v131, v93
	v_cvt_pk_bf16_f32 v141, v93, s0
	global_store_short v139, v141, s[72:73] offset:64
	v_mul_f32_e32 v131, 0xbfb8aa3b, v85
	v_exp_f32_e32 v131, v131
	s_nop 0
	v_add_f32_e32 v131, 1.0, v131
	v_div_scale_f32 v132, s[4:5], v131, v131, v85
	v_rcp_f32_e32 v133, v132
	v_div_scale_f32 v134, vcc, v85, v131, v85
	v_fma_f32 v135, -v132, v133, 1.0
	v_fmac_f32_e32 v133, v135, v133
	v_mul_f32_e32 v135, v134, v133
	v_fma_f32 v136, -v132, v135, v134
	v_fmac_f32_e32 v135, v136, v133
	v_fma_f32 v132, -v132, v135, v134
	v_div_fmas_f32 v132, v132, v133, v135
	v_div_fixup_f32 v85, v132, v131, v85
	v_cvt_pk_bf16_f32 v141, v85, s0
	global_store_short v139, v141, s[72:73] offset:96
	v_add_u32_e32 v139, 0x6c000, v138
	v_mul_f32_e32 v131, 0xbfb8aa3b, v14
	v_exp_f32_e32 v131, v131
	s_nop 0
	v_add_f32_e32 v131, 1.0, v131
	v_div_scale_f32 v132, s[4:5], v131, v131, v14
	v_rcp_f32_e32 v133, v132
	v_div_scale_f32 v134, vcc, v14, v131, v14
	v_fma_f32 v135, -v132, v133, 1.0
	v_fmac_f32_e32 v133, v135, v133
	v_mul_f32_e32 v135, v134, v133
	v_fma_f32 v136, -v132, v135, v134
	v_fmac_f32_e32 v135, v136, v133
	v_fma_f32 v132, -v132, v135, v134
	v_div_fmas_f32 v132, v132, v133, v135
	v_div_fixup_f32 v14, v132, v131, v14
	v_cvt_pk_bf16_f32 v141, v14, s0
	global_store_short v139, v141, s[72:73]
	v_mul_f32_e32 v131, 0xbfb8aa3b, v74
	v_exp_f32_e32 v131, v131
	s_nop 0
	v_add_f32_e32 v131, 1.0, v131
	v_div_scale_f32 v132, s[4:5], v131, v131, v74
	v_rcp_f32_e32 v133, v132
	v_div_scale_f32 v134, vcc, v74, v131, v74
	v_fma_f32 v135, -v132, v133, 1.0
	v_fmac_f32_e32 v133, v135, v133
	v_mul_f32_e32 v135, v134, v133
	v_fma_f32 v136, -v132, v135, v134
	v_fmac_f32_e32 v135, v136, v133
	v_fma_f32 v132, -v132, v135, v134
	v_div_fmas_f32 v132, v132, v133, v135
	v_div_fixup_f32 v74, v132, v131, v74
	v_cvt_pk_bf16_f32 v141, v74, s0
	global_store_short v139, v141, s[72:73] offset:32
	v_mul_f32_e32 v131, 0xbfb8aa3b, v78
	v_exp_f32_e32 v131, v131
	s_nop 0
	v_add_f32_e32 v131, 1.0, v131
	v_div_scale_f32 v132, s[4:5], v131, v131, v78
	v_rcp_f32_e32 v133, v132
	v_div_scale_f32 v134, vcc, v78, v131, v78
	v_fma_f32 v135, -v132, v133, 1.0
	v_fmac_f32_e32 v133, v135, v133
	v_mul_f32_e32 v135, v134, v133
	v_fma_f32 v136, -v132, v135, v134
	v_fmac_f32_e32 v135, v136, v133
	v_fma_f32 v132, -v132, v135, v134
	v_div_fmas_f32 v132, v132, v133, v135
	v_div_fixup_f32 v78, v132, v131, v78
; DEV u16 f2bf(float f) { return (u16)(pack2(f, 0.f) & 0xffffu); }
; DEV void phase_win(const Params& P, int l, const u16* __restrict__ xb, const u16* __restrict__ Wt, u16* __restrict__ h, char* smem) {
;     ...
;       for (int ns = 0; ns < 4; ++ns)
; #pragma unroll
;         for (int j = 0; j < 4; ++j) {
;           int row = m0 + wm * 128 + ms * 16 + quad * 4 + j;
;           int col = cb + ns * 16 + l15;
;           float v = acc[ms][ns][j];
;           if (mode == 1) { float lbv = lbp[col - C_HF]; v = __logf(lbv + (1.f - lbv) / (1.f + __expf(-v))); }
;           else if (mode == 2) v = v / (1.f + __expf(-v));
;           h[(size_t)row * HS + col] = f2bf(v);
	v_cvt_pk_bf16_f32 v141, v78, s0
	global_store_short v139, v141, s[72:73] offset:64
	v_mul_f32_e32 v131, 0xbfb8aa3b, v70
	v_exp_f32_e32 v131, v131
	s_nop 0
	v_add_f32_e32 v131, 1.0, v131
	v_div_scale_f32 v132, s[4:5], v131, v131, v70
	v_rcp_f32_e32 v133, v132
	v_div_scale_f32 v134, vcc, v70, v131, v70
	v_fma_f32 v135, -v132, v133, 1.0
	v_fmac_f32_e32 v133, v135, v133
	v_mul_f32_e32 v135, v134, v133
	v_fma_f32 v136, -v132, v135, v134
	v_fmac_f32_e32 v135, v136, v133
	v_fma_f32 v132, -v132, v135, v134
	v_div_fmas_f32 v132, v132, v133, v135
	v_div_fixup_f32 v70, v132, v131, v70
	v_cvt_pk_bf16_f32 v141, v70, s0
	global_store_short v139, v141, s[72:73] offset:96
	v_add_u32_e32 v139, 0x6db00, v138
	v_mul_f32_e32 v131, 0xbfb8aa3b, v15
	v_exp_f32_e32 v131, v131
	s_nop 0
	v_add_f32_e32 v131, 1.0, v131
	v_div_scale_f32 v132, s[4:5], v131, v131, v15
	v_rcp_f32_e32 v133, v132
	v_div_scale_f32 v134, vcc, v15, v131, v15
	v_fma_f32 v135, -v132, v133, 1.0
	v_fmac_f32_e32 v133, v135, v133
	v_mul_f32_e32 v135, v134, v133
	v_fma_f32 v136, -v132, v135, v134
	v_fmac_f32_e32 v135, v136, v133
	v_fma_f32 v132, -v132, v135, v134
	v_div_fmas_f32 v132, v132, v133, v135
	v_div_fixup_f32 v15, v132, v131, v15
	v_cvt_pk_bf16_f32 v141, v15, s0
	global_store_short v139, v141, s[72:73]
	v_mul_f32_e32 v131, 0xbfb8aa3b, v75
	v_exp_f32_e32 v131, v131
	s_nop 0
	v_add_f32_e32 v131, 1.0, v131
	v_div_scale_f32 v132, s[4:5], v131, v131, v75
	v_rcp_f32_e32 v133, v132
	v_div_scale_f32 v134, vcc, v75, v131, v75
	v_fma_f32 v135, -v132, v133, 1.0
	v_fmac_f32_e32 v133, v135, v133
	v_mul_f32_e32 v135, v134, v133
	v_fma_f32 v136, -v132, v135, v134
	v_fmac_f32_e32 v135, v136, v133
	v_fma_f32 v132, -v132, v135, v134
	v_div_fmas_f32 v132, v132, v133, v135
	v_div_fixup_f32 v75, v132, v131, v75
	v_cvt_pk_bf16_f32 v141, v75, s0
	global_store_short v139, v141, s[72:73] offset:32
	v_mul_f32_e32 v131, 0xbfb8aa3b, v79
	v_exp_f32_e32 v131, v131
	s_nop 0
	v_add_f32_e32 v131, 1.0, v131
	v_div_scale_f32 v132, s[4:5], v131, v131, v79
	v_rcp_f32_e32 v133, v132
	v_div_scale_f32 v134, vcc, v79, v131, v79
	v_fma_f32 v135, -v132, v133, 1.0
	v_fmac_f32_e32 v133, v135, v133
	v_mul_f32_e32 v135, v134, v133
	v_fma_f32 v136, -v132, v135, v134
	v_fmac_f32_e32 v135, v136, v133
	v_fma_f32 v132, -v132, v135, v134
	v_div_fmas_f32 v132, v132, v133, v135
	v_div_fixup_f32 v79, v132, v131, v79
	v_cvt_pk_bf16_f32 v141, v79, s0
	global_store_short v139, v141, s[72:73] offset:64
	v_mul_f32_e32 v131, 0xbfb8aa3b, v71
	v_exp_f32_e32 v131, v131
	s_nop 0
	v_add_f32_e32 v131, 1.0, v131
	v_div_scale_f32 v132, s[4:5], v131, v131, v71
	v_rcp_f32_e32 v133, v132
	v_div_scale_f32 v134, vcc, v71, v131, v71
	v_fma_f32 v135, -v132, v133, 1.0
	v_fmac_f32_e32 v133, v135, v133
	v_mul_f32_e32 v135, v134, v133
	v_fma_f32 v136, -v132, v135, v134
	v_fmac_f32_e32 v135, v136, v133
	v_fma_f32 v132, -v132, v135, v134
	v_div_fmas_f32 v132, v132, v133, v135
	v_div_fixup_f32 v71, v132, v131, v71
	v_cvt_pk_bf16_f32 v141, v71, s0
	global_store_short v139, v141, s[72:73] offset:96
	v_add_u32_e32 v139, 0x6f600, v138
	v_mul_f32_e32 v131, 0xbfb8aa3b, v16
	v_exp_f32_e32 v131, v131
	s_nop 0
	v_add_f32_e32 v131, 1.0, v131
	v_div_scale_f32 v132, s[4:5], v131, v131, v16
	v_rcp_f32_e32 v133, v132
	v_div_scale_f32 v134, vcc, v16, v131, v16
	v_fma_f32 v135, -v132, v133, 1.0
	v_fmac_f32_e32 v133, v135, v133
	v_mul_f32_e32 v135, v134, v133
	v_fma_f32 v136, -v132, v135, v134
	v_fmac_f32_e32 v135, v136, v133
	v_fma_f32 v132, -v132, v135, v134
	v_div_fmas_f32 v132, v132, v133, v135
	v_div_fixup_f32 v16, v132, v131, v16
	v_cvt_pk_bf16_f32 v141, v16, s0
	global_store_short v139, v141, s[72:73]
	v_mul_f32_e32 v131, 0xbfb8aa3b, v76
	v_exp_f32_e32 v131, v131
	s_nop 0
	v_add_f32_e32 v131, 1.0, v131
	v_div_scale_f32 v132, s[4:5], v131, v131, v76
	v_rcp_f32_e32 v133, v132
	v_div_scale_f32 v134, vcc, v76, v131, v76
	v_fma_f32 v135, -v132, v133, 1.0
	v_fmac_f32_e32 v133, v135, v133
	v_mul_f32_e32 v135, v134, v133
	v_fma_f32 v136, -v132, v135, v134
	v_fmac_f32_e32 v135, v136, v133
	v_fma_f32 v132, -v132, v135, v134
	v_div_fmas_f32 v132, v132, v133, v135
	v_div_fixup_f32 v76, v132, v131, v76
	v_cvt_pk_bf16_f32 v141, v76, s0
	global_store_short v139, v141, s[72:73] offset:32
	v_mul_f32_e32 v131, 0xbfb8aa3b, v80
	v_exp_f32_e32 v131, v131
	s_nop 0
	v_add_f32_e32 v131, 1.0, v131
	v_div_scale_f32 v132, s[4:5], v131, v131, v80
	v_rcp_f32_e32 v133, v132
	v_div_scale_f32 v134, vcc, v80, v131, v80
	v_fma_f32 v135, -v132, v133, 1.0
	v_fmac_f32_e32 v133, v135, v133
	v_mul_f32_e32 v135, v134, v133
	v_fma_f32 v136, -v132, v135, v134
	v_fmac_f32_e32 v135, v136, v133
	v_fma_f32 v132, -v132, v135, v134
	v_div_fmas_f32 v132, v132, v133, v135
	v_div_fixup_f32 v80, v132, v131, v80
	v_cvt_pk_bf16_f32 v141, v80, s0
	global_store_short v139, v141, s[72:73] offset:64
	v_mul_f32_e32 v131, 0xbfb8aa3b, v72
	v_exp_f32_e32 v131, v131
	s_nop 0
	v_add_f32_e32 v131, 1.0, v131
	v_div_scale_f32 v132, s[4:5], v131, v131, v72
	v_rcp_f32_e32 v133, v132
	v_div_scale_f32 v134, vcc, v72, v131, v72
	v_fma_f32 v135, -v132, v133, 1.0
	v_fmac_f32_e32 v133, v135, v133
	v_mul_f32_e32 v135, v134, v133
	v_fma_f32 v136, -v132, v135, v134
	v_fmac_f32_e32 v135, v136, v133
	v_fma_f32 v132, -v132, v135, v134
	v_div_fmas_f32 v132, v132, v133, v135
	v_div_fixup_f32 v72, v132, v131, v72
	v_cvt_pk_bf16_f32 v141, v72, s0
	global_store_short v139, v141, s[72:73] offset:96
	v_add_u32_e32 v139, 0x71100, v138
	v_mul_f32_e32 v131, 0xbfb8aa3b, v17
	v_exp_f32_e32 v131, v131
	s_nop 0
	v_add_f32_e32 v131, 1.0, v131
	v_div_scale_f32 v132, s[4:5], v131, v131, v17
	v_rcp_f32_e32 v133, v132
	v_div_scale_f32 v134, vcc, v17, v131, v17
; DEV u16 f2bf(float f) { return (u16)(pack2(f, 0.f) & 0xffffu); }
; DEV void phase_win(const Params& P, int l, const u16* __restrict__ xb, const u16* __restrict__ Wt, u16* __restrict__ h, char* smem) {
;     ...
;       for (int ns = 0; ns < 4; ++ns)
; #pragma unroll
;         for (int j = 0; j < 4; ++j) {
;           int row = m0 + wm * 128 + ms * 16 + quad * 4 + j;
;           int col = cb + ns * 16 + l15;
;           float v = acc[ms][ns][j];
;           if (mode == 1) { float lbv = lbp[col - C_HF]; v = __logf(lbv + (1.f - lbv) / (1.f + __expf(-v))); }
;           else if (mode == 2) v = v / (1.f + __expf(-v));
;           h[(size_t)row * HS + col] = f2bf(v);
	v_fma_f32 v135, -v132, v133, 1.0
	v_fmac_f32_e32 v133, v135, v133
	v_mul_f32_e32 v135, v134, v133
	v_fma_f32 v136, -v132, v135, v134
	v_fmac_f32_e32 v135, v136, v133
	v_fma_f32 v132, -v132, v135, v134
	v_div_fmas_f32 v132, v132, v133, v135
	v_div_fixup_f32 v17, v132, v131, v17
	v_cvt_pk_bf16_f32 v141, v17, s0
	global_store_short v139, v141, s[72:73]
	v_mul_f32_e32 v131, 0xbfb8aa3b, v77
	v_exp_f32_e32 v131, v131
	s_nop 0
	v_add_f32_e32 v131, 1.0, v131
	v_div_scale_f32 v132, s[4:5], v131, v131, v77
	v_rcp_f32_e32 v133, v132
	v_div_scale_f32 v134, vcc, v77, v131, v77
	v_fma_f32 v135, -v132, v133, 1.0
	v_fmac_f32_e32 v133, v135, v133
	v_mul_f32_e32 v135, v134, v133
	v_fma_f32 v136, -v132, v135, v134
	v_fmac_f32_e32 v135, v136, v133
	v_fma_f32 v132, -v132, v135, v134
	v_div_fmas_f32 v132, v132, v133, v135
	v_div_fixup_f32 v77, v132, v131, v77
	v_cvt_pk_bf16_f32 v141, v77, s0
	global_store_short v139, v141, s[72:73] offset:32
	v_mul_f32_e32 v131, 0xbfb8aa3b, v81
	v_exp_f32_e32 v131, v131
	s_nop 0
	v_add_f32_e32 v131, 1.0, v131
	v_div_scale_f32 v132, s[4:5], v131, v131, v81
	v_rcp_f32_e32 v133, v132
	v_div_scale_f32 v134, vcc, v81, v131, v81
	v_fma_f32 v135, -v132, v133, 1.0
	v_fmac_f32_e32 v133, v135, v133
	v_mul_f32_e32 v135, v134, v133
	v_fma_f32 v136, -v132, v135, v134
	v_fmac_f32_e32 v135, v136, v133
	v_fma_f32 v132, -v132, v135, v134
	v_div_fmas_f32 v132, v132, v133, v135
	v_div_fixup_f32 v81, v132, v131, v81
	v_cvt_pk_bf16_f32 v141, v81, s0
	global_store_short v139, v141, s[72:73] offset:64
	v_mul_f32_e32 v131, 0xbfb8aa3b, v73
	v_exp_f32_e32 v131, v131
	s_nop 0
	v_add_f32_e32 v131, 1.0, v131
	v_div_scale_f32 v132, s[4:5], v131, v131, v73
	v_rcp_f32_e32 v133, v132
	v_div_scale_f32 v134, vcc, v73, v131, v73
	v_fma_f32 v135, -v132, v133, 1.0
	v_fmac_f32_e32 v133, v135, v133
	v_mul_f32_e32 v135, v134, v133
	v_fma_f32 v136, -v132, v135, v134
	v_fmac_f32_e32 v135, v136, v133
	v_fma_f32 v132, -v132, v135, v134
	v_div_fmas_f32 v132, v132, v133, v135
	v_div_fixup_f32 v73, v132, v131, v73
	v_cvt_pk_bf16_f32 v141, v73, s0
	global_store_short v139, v141, s[72:73] offset:96
	v_add_u32_e32 v139, 0x87000, v138
	v_mul_f32_e32 v131, 0xbfb8aa3b, v10
	v_exp_f32_e32 v131, v131
	s_nop 0
	v_add_f32_e32 v131, 1.0, v131
	v_div_scale_f32 v132, s[4:5], v131, v131, v10
	v_rcp_f32_e32 v133, v132
	v_div_scale_f32 v134, vcc, v10, v131, v10
	v_fma_f32 v135, -v132, v133, 1.0
	v_fmac_f32_e32 v133, v135, v133
	v_mul_f32_e32 v135, v134, v133
	v_fma_f32 v136, -v132, v135, v134
	v_fmac_f32_e32 v135, v136, v133
	v_fma_f32 v132, -v132, v135, v134
	v_div_fmas_f32 v132, v132, v133, v135
	v_div_fixup_f32 v10, v132, v131, v10
	v_cvt_pk_bf16_f32 v141, v10, s0
	global_store_short v139, v141, s[72:73]
	v_mul_f32_e32 v131, 0xbfb8aa3b, v62
	v_exp_f32_e32 v131, v131
	s_nop 0
	v_add_f32_e32 v131, 1.0, v131
	v_div_scale_f32 v132, s[4:5], v131, v131, v62
	v_rcp_f32_e32 v133, v132
	v_div_scale_f32 v134, vcc, v62, v131, v62
	v_fma_f32 v135, -v132, v133, 1.0
	v_fmac_f32_e32 v133, v135, v133
	v_mul_f32_e32 v135, v134, v133
	v_fma_f32 v136, -v132, v135, v134
	v_fmac_f32_e32 v135, v136, v133
	v_fma_f32 v132, -v132, v135, v134
	v_div_fmas_f32 v132, v132, v133, v135
	v_div_fixup_f32 v62, v132, v131, v62
	v_cvt_pk_bf16_f32 v141, v62, s0
	global_store_short v139, v141, s[72:73] offset:32
	v_mul_f32_e32 v131, 0xbfb8aa3b, v66
	v_exp_f32_e32 v131, v131
	s_nop 0
	v_add_f32_e32 v131, 1.0, v131
	v_div_scale_f32 v132, s[4:5], v131, v131, v66
	v_rcp_f32_e32 v133, v132
	v_div_scale_f32 v134, vcc, v66, v131, v66
	v_fma_f32 v135, -v132, v133, 1.0
	v_fmac_f32_e32 v133, v135, v133
	v_mul_f32_e32 v135, v134, v133
	v_fma_f32 v136, -v132, v135, v134
	v_fmac_f32_e32 v135, v136, v133
	v_fma_f32 v132, -v132, v135, v134
	v_div_fmas_f32 v132, v132, v133, v135
	v_div_fixup_f32 v66, v132, v131, v66
	v_cvt_pk_bf16_f32 v141, v66, s0
	global_store_short v139, v141, s[72:73] offset:64
	v_mul_f32_e32 v131, 0xbfb8aa3b, v58
	v_exp_f32_e32 v131, v131
	s_nop 0
	v_add_f32_e32 v131, 1.0, v131
	v_div_scale_f32 v132, s[4:5], v131, v131, v58
	v_rcp_f32_e32 v133, v132
	v_div_scale_f32 v134, vcc, v58, v131, v58
	v_fma_f32 v135, -v132, v133, 1.0
	v_fmac_f32_e32 v133, v135, v133
	v_mul_f32_e32 v135, v134, v133
	v_fma_f32 v136, -v132, v135, v134
	v_fmac_f32_e32 v135, v136, v133
	v_fma_f32 v132, -v132, v135, v134
	v_div_fmas_f32 v132, v132, v133, v135
	v_div_fixup_f32 v58, v132, v131, v58
	v_cvt_pk_bf16_f32 v141, v58, s0
	global_store_short v139, v141, s[72:73] offset:96
	v_add_u32_e32 v139, 0x88b00, v138
	v_mul_f32_e32 v131, 0xbfb8aa3b, v11
	v_exp_f32_e32 v131, v131
	s_nop 0
	v_add_f32_e32 v131, 1.0, v131
	v_div_scale_f32 v132, s[4:5], v131, v131, v11
	v_rcp_f32_e32 v133, v132
	v_div_scale_f32 v134, vcc, v11, v131, v11
	v_fma_f32 v135, -v132, v133, 1.0
	v_fmac_f32_e32 v133, v135, v133
	v_mul_f32_e32 v135, v134, v133
	v_fma_f32 v136, -v132, v135, v134
	v_fmac_f32_e32 v135, v136, v133
	v_fma_f32 v132, -v132, v135, v134
	v_div_fmas_f32 v132, v132, v133, v135
	v_div_fixup_f32 v11, v132, v131, v11
	v_cvt_pk_bf16_f32 v141, v11, s0
	global_store_short v139, v141, s[72:73]
	v_mul_f32_e32 v131, 0xbfb8aa3b, v63
	v_exp_f32_e32 v131, v131
	s_nop 0
	v_add_f32_e32 v131, 1.0, v131
	v_div_scale_f32 v132, s[4:5], v131, v131, v63
	v_rcp_f32_e32 v133, v132
	v_div_scale_f32 v134, vcc, v63, v131, v63
	v_fma_f32 v135, -v132, v133, 1.0
	v_fmac_f32_e32 v133, v135, v133
	v_mul_f32_e32 v135, v134, v133
	v_fma_f32 v136, -v132, v135, v134
	v_fmac_f32_e32 v135, v136, v133
	v_fma_f32 v132, -v132, v135, v134
	v_div_fmas_f32 v132, v132, v133, v135
	v_div_fixup_f32 v63, v132, v131, v63
	v_cvt_pk_bf16_f32 v141, v63, s0
	global_store_short v139, v141, s[72:73] offset:32
; DEV u16 f2bf(float f) { return (u16)(pack2(f, 0.f) & 0xffffu); }
; DEV void phase_win(const Params& P, int l, const u16* __restrict__ xb, const u16* __restrict__ Wt, u16* __restrict__ h, char* smem) {
;     ...
;       for (int ns = 0; ns < 4; ++ns)
; #pragma unroll
;         for (int j = 0; j < 4; ++j) {
;           int row = m0 + wm * 128 + ms * 16 + quad * 4 + j;
;           int col = cb + ns * 16 + l15;
;           float v = acc[ms][ns][j];
;           if (mode == 1) { float lbv = lbp[col - C_HF]; v = __logf(lbv + (1.f - lbv) / (1.f + __expf(-v))); }
;           else if (mode == 2) v = v / (1.f + __expf(-v));
;           h[(size_t)row * HS + col] = f2bf(v);
	v_mul_f32_e32 v131, 0xbfb8aa3b, v67
	v_exp_f32_e32 v131, v131
	s_nop 0
	v_add_f32_e32 v131, 1.0, v131
	v_div_scale_f32 v132, s[4:5], v131, v131, v67
	v_rcp_f32_e32 v133, v132
	v_div_scale_f32 v134, vcc, v67, v131, v67
	v_fma_f32 v135, -v132, v133, 1.0
	v_fmac_f32_e32 v133, v135, v133
	v_mul_f32_e32 v135, v134, v133
	v_fma_f32 v136, -v132, v135, v134
	v_fmac_f32_e32 v135, v136, v133
	v_fma_f32 v132, -v132, v135, v134
	v_div_fmas_f32 v132, v132, v133, v135
	v_div_fixup_f32 v67, v132, v131, v67
	v_cvt_pk_bf16_f32 v141, v67, s0
	global_store_short v139, v141, s[72:73] offset:64
	v_mul_f32_e32 v131, 0xbfb8aa3b, v59
	v_exp_f32_e32 v131, v131
	s_nop 0
	v_add_f32_e32 v131, 1.0, v131
	v_div_scale_f32 v132, s[4:5], v131, v131, v59
	v_rcp_f32_e32 v133, v132
	v_div_scale_f32 v134, vcc, v59, v131, v59
	v_fma_f32 v135, -v132, v133, 1.0
	v_fmac_f32_e32 v133, v135, v133
	v_mul_f32_e32 v135, v134, v133
	v_fma_f32 v136, -v132, v135, v134
	v_fmac_f32_e32 v135, v136, v133
	v_fma_f32 v132, -v132, v135, v134
	v_div_fmas_f32 v132, v132, v133, v135
	v_div_fixup_f32 v59, v132, v131, v59
	v_cvt_pk_bf16_f32 v141, v59, s0
	global_store_short v139, v141, s[72:73] offset:96
	v_add_u32_e32 v139, 0x8a600, v138
	v_mul_f32_e32 v131, 0xbfb8aa3b, v12
	v_exp_f32_e32 v131, v131
	s_nop 0
	v_add_f32_e32 v131, 1.0, v131
	v_div_scale_f32 v132, s[4:5], v131, v131, v12
	v_rcp_f32_e32 v133, v132
	v_div_scale_f32 v134, vcc, v12, v131, v12
	v_fma_f32 v135, -v132, v133, 1.0
	v_fmac_f32_e32 v133, v135, v133
	v_mul_f32_e32 v135, v134, v133
	v_fma_f32 v136, -v132, v135, v134
	v_fmac_f32_e32 v135, v136, v133
	v_fma_f32 v132, -v132, v135, v134
	v_div_fmas_f32 v132, v132, v133, v135
	v_div_fixup_f32 v12, v132, v131, v12
	v_cvt_pk_bf16_f32 v141, v12, s0
	global_store_short v139, v141, s[72:73]
	v_mul_f32_e32 v131, 0xbfb8aa3b, v64
	v_exp_f32_e32 v131, v131
	s_nop 0
	v_add_f32_e32 v131, 1.0, v131
	v_div_scale_f32 v132, s[4:5], v131, v131, v64
	v_rcp_f32_e32 v133, v132
	v_div_scale_f32 v134, vcc, v64, v131, v64
	v_fma_f32 v135, -v132, v133, 1.0
	v_fmac_f32_e32 v133, v135, v133
	v_mul_f32_e32 v135, v134, v133
	v_fma_f32 v136, -v132, v135, v134
	v_fmac_f32_e32 v135, v136, v133
	v_fma_f32 v132, -v132, v135, v134
	v_div_fmas_f32 v132, v132, v133, v135
	v_div_fixup_f32 v64, v132, v131, v64
	v_cvt_pk_bf16_f32 v141, v64, s0
	global_store_short v139, v141, s[72:73] offset:32
	v_mul_f32_e32 v131, 0xbfb8aa3b, v68
	v_exp_f32_e32 v131, v131
	s_nop 0
	v_add_f32_e32 v131, 1.0, v131
	v_div_scale_f32 v132, s[4:5], v131, v131, v68
	v_rcp_f32_e32 v133, v132
	v_div_scale_f32 v134, vcc, v68, v131, v68
	v_fma_f32 v135, -v132, v133, 1.0
	v_fmac_f32_e32 v133, v135, v133
	v_mul_f32_e32 v135, v134, v133
	v_fma_f32 v136, -v132, v135, v134
	v_fmac_f32_e32 v135, v136, v133
	v_fma_f32 v132, -v132, v135, v134
	v_div_fmas_f32 v132, v132, v133, v135
	v_div_fixup_f32 v68, v132, v131, v68
	v_cvt_pk_bf16_f32 v141, v68, s0
	global_store_short v139, v141, s[72:73] offset:64
	v_mul_f32_e32 v131, 0xbfb8aa3b, v60
	v_exp_f32_e32 v131, v131
	s_nop 0
	v_add_f32_e32 v131, 1.0, v131
	v_div_scale_f32 v132, s[4:5], v131, v131, v60
	v_rcp_f32_e32 v133, v132
	v_div_scale_f32 v134, vcc, v60, v131, v60
	v_fma_f32 v135, -v132, v133, 1.0
	v_fmac_f32_e32 v133, v135, v133
	v_mul_f32_e32 v135, v134, v133
	v_fma_f32 v136, -v132, v135, v134
	v_fmac_f32_e32 v135, v136, v133
	v_fma_f32 v132, -v132, v135, v134
	v_div_fmas_f32 v132, v132, v133, v135
	v_div_fixup_f32 v60, v132, v131, v60
	v_cvt_pk_bf16_f32 v141, v60, s0
	global_store_short v139, v141, s[72:73] offset:96
	v_add_u32_e32 v139, 0x8c100, v138
	v_mul_f32_e32 v131, 0xbfb8aa3b, v13
	v_exp_f32_e32 v131, v131
	s_nop 0
	v_add_f32_e32 v131, 1.0, v131
	v_div_scale_f32 v132, s[4:5], v131, v131, v13
	v_rcp_f32_e32 v133, v132
	v_div_scale_f32 v134, vcc, v13, v131, v13
	v_fma_f32 v135, -v132, v133, 1.0
	v_fmac_f32_e32 v133, v135, v133
	v_mul_f32_e32 v135, v134, v133
	v_fma_f32 v136, -v132, v135, v134
	v_fmac_f32_e32 v135, v136, v133
	v_fma_f32 v132, -v132, v135, v134
	v_div_fmas_f32 v132, v132, v133, v135
	v_div_fixup_f32 v13, v132, v131, v13
	v_cvt_pk_bf16_f32 v141, v13, s0
	global_store_short v139, v141, s[72:73]
	v_mul_f32_e32 v131, 0xbfb8aa3b, v65
	v_exp_f32_e32 v131, v131
	s_nop 0
	v_add_f32_e32 v131, 1.0, v131
	v_div_scale_f32 v132, s[4:5], v131, v131, v65
	v_rcp_f32_e32 v133, v132
	v_div_scale_f32 v134, vcc, v65, v131, v65
	v_fma_f32 v135, -v132, v133, 1.0
	v_fmac_f32_e32 v133, v135, v133
	v_mul_f32_e32 v135, v134, v133
	v_fma_f32 v136, -v132, v135, v134
	v_fmac_f32_e32 v135, v136, v133
	v_fma_f32 v132, -v132, v135, v134
	v_div_fmas_f32 v132, v132, v133, v135
	v_div_fixup_f32 v65, v132, v131, v65
	v_cvt_pk_bf16_f32 v141, v65, s0
	global_store_short v139, v141, s[72:73] offset:32
	v_mul_f32_e32 v131, 0xbfb8aa3b, v69
	v_exp_f32_e32 v131, v131
	s_nop 0
	v_add_f32_e32 v131, 1.0, v131
	v_div_scale_f32 v132, s[4:5], v131, v131, v69
	v_rcp_f32_e32 v133, v132
	v_div_scale_f32 v134, vcc, v69, v131, v69
	v_fma_f32 v135, -v132, v133, 1.0
	v_fmac_f32_e32 v133, v135, v133
	v_mul_f32_e32 v135, v134, v133
	v_fma_f32 v136, -v132, v135, v134
	v_fmac_f32_e32 v135, v136, v133
	v_fma_f32 v132, -v132, v135, v134
	v_div_fmas_f32 v132, v132, v133, v135
	v_div_fixup_f32 v69, v132, v131, v69
	v_cvt_pk_bf16_f32 v141, v69, s0
	global_store_short v139, v141, s[72:73] offset:64
	v_mul_f32_e32 v131, 0xbfb8aa3b, v61
	v_exp_f32_e32 v131, v131
	s_nop 0
	v_add_f32_e32 v131, 1.0, v131
	v_div_scale_f32 v132, s[4:5], v131, v131, v61
	v_rcp_f32_e32 v133, v132
	v_div_scale_f32 v134, vcc, v61, v131, v61
	v_fma_f32 v135, -v132, v133, 1.0
	v_fmac_f32_e32 v133, v135, v133
	v_mul_f32_e32 v135, v134, v133
	v_fma_f32 v136, -v132, v135, v134
; DEV u16 f2bf(float f) { return (u16)(pack2(f, 0.f) & 0xffffu); }
; DEV void phase_win(const Params& P, int l, const u16* __restrict__ xb, const u16* __restrict__ Wt, u16* __restrict__ h, char* smem) {
;     ...
;       for (int ns = 0; ns < 4; ++ns)
; #pragma unroll
;         for (int j = 0; j < 4; ++j) {
;           int row = m0 + wm * 128 + ms * 16 + quad * 4 + j;
;           int col = cb + ns * 16 + l15;
;           float v = acc[ms][ns][j];
;           if (mode == 1) { float lbv = lbp[col - C_HF]; v = __logf(lbv + (1.f - lbv) / (1.f + __expf(-v))); }
;           else if (mode == 2) v = v / (1.f + __expf(-v));
;           h[(size_t)row * HS + col] = f2bf(v);
	v_fmac_f32_e32 v135, v136, v133
	v_fma_f32 v132, -v132, v135, v134
	v_div_fmas_f32 v132, v132, v133, v135
	v_div_fixup_f32 v61, v132, v131, v61
	v_cvt_pk_bf16_f32 v141, v61, s0
	global_store_short v139, v141, s[72:73] offset:96
	v_add_u32_e32 v139, 0xa2000, v138
	v_mul_f32_e32 v131, 0xbfb8aa3b, v6
	v_exp_f32_e32 v131, v131
	s_nop 0
	v_add_f32_e32 v131, 1.0, v131
	v_div_scale_f32 v132, s[4:5], v131, v131, v6
	v_rcp_f32_e32 v133, v132
	v_div_scale_f32 v134, vcc, v6, v131, v6
	v_fma_f32 v135, -v132, v133, 1.0
	v_fmac_f32_e32 v133, v135, v133
	v_mul_f32_e32 v135, v134, v133
	v_fma_f32 v136, -v132, v135, v134
	v_fmac_f32_e32 v135, v136, v133
	v_fma_f32 v132, -v132, v135, v134
	v_div_fmas_f32 v132, v132, v133, v135
	v_div_fixup_f32 v6, v132, v131, v6
	v_cvt_pk_bf16_f32 v141, v6, s0
	global_store_short v139, v141, s[72:73]
	v_mul_f32_e32 v131, 0xbfb8aa3b, v50
	v_exp_f32_e32 v131, v131
	s_nop 0
	v_add_f32_e32 v131, 1.0, v131
	v_div_scale_f32 v132, s[4:5], v131, v131, v50
	v_rcp_f32_e32 v133, v132
	v_div_scale_f32 v134, vcc, v50, v131, v50
	v_fma_f32 v135, -v132, v133, 1.0
	v_fmac_f32_e32 v133, v135, v133
	v_mul_f32_e32 v135, v134, v133
	v_fma_f32 v136, -v132, v135, v134
	v_fmac_f32_e32 v135, v136, v133
	v_fma_f32 v132, -v132, v135, v134
	v_div_fmas_f32 v132, v132, v133, v135
	v_div_fixup_f32 v50, v132, v131, v50
	v_cvt_pk_bf16_f32 v141, v50, s0
	global_store_short v139, v141, s[72:73] offset:32
	v_mul_f32_e32 v131, 0xbfb8aa3b, v54
	v_exp_f32_e32 v131, v131
	s_nop 0
	v_add_f32_e32 v131, 1.0, v131
	v_div_scale_f32 v132, s[4:5], v131, v131, v54
	v_rcp_f32_e32 v133, v132
	v_div_scale_f32 v134, vcc, v54, v131, v54
	v_fma_f32 v135, -v132, v133, 1.0
	v_fmac_f32_e32 v133, v135, v133
	v_mul_f32_e32 v135, v134, v133
	v_fma_f32 v136, -v132, v135, v134
	v_fmac_f32_e32 v135, v136, v133
	v_fma_f32 v132, -v132, v135, v134
	v_div_fmas_f32 v132, v132, v133, v135
	v_div_fixup_f32 v54, v132, v131, v54
	v_cvt_pk_bf16_f32 v141, v54, s0
	global_store_short v139, v141, s[72:73] offset:64
	v_mul_f32_e32 v131, 0xbfb8aa3b, v46
	v_exp_f32_e32 v131, v131
	s_nop 0
	v_add_f32_e32 v131, 1.0, v131
	v_div_scale_f32 v132, s[4:5], v131, v131, v46
	v_rcp_f32_e32 v133, v132
	v_div_scale_f32 v134, vcc, v46, v131, v46
	v_fma_f32 v135, -v132, v133, 1.0
	v_fmac_f32_e32 v133, v135, v133
	v_mul_f32_e32 v135, v134, v133
	v_fma_f32 v136, -v132, v135, v134
	v_fmac_f32_e32 v135, v136, v133
	v_fma_f32 v132, -v132, v135, v134
	v_div_fmas_f32 v132, v132, v133, v135
	v_div_fixup_f32 v46, v132, v131, v46
	v_cvt_pk_bf16_f32 v141, v46, s0
	global_store_short v139, v141, s[72:73] offset:96
	v_add_u32_e32 v139, 0xa3b00, v138
	v_mul_f32_e32 v131, 0xbfb8aa3b, v7
	v_exp_f32_e32 v131, v131
	s_nop 0
	v_add_f32_e32 v131, 1.0, v131
	v_div_scale_f32 v132, s[4:5], v131, v131, v7
	v_rcp_f32_e32 v133, v132
	v_div_scale_f32 v134, vcc, v7, v131, v7
	v_fma_f32 v135, -v132, v133, 1.0
	v_fmac_f32_e32 v133, v135, v133
	v_mul_f32_e32 v135, v134, v133
	v_fma_f32 v136, -v132, v135, v134
	v_fmac_f32_e32 v135, v136, v133
	v_fma_f32 v132, -v132, v135, v134
	v_div_fmas_f32 v132, v132, v133, v135
	v_div_fixup_f32 v7, v132, v131, v7
	v_cvt_pk_bf16_f32 v141, v7, s0
	global_store_short v139, v141, s[72:73]
	v_mul_f32_e32 v131, 0xbfb8aa3b, v51
	v_exp_f32_e32 v131, v131
	s_nop 0
	v_add_f32_e32 v131, 1.0, v131
	v_div_scale_f32 v132, s[4:5], v131, v131, v51
	v_rcp_f32_e32 v133, v132
	v_div_scale_f32 v134, vcc, v51, v131, v51
	v_fma_f32 v135, -v132, v133, 1.0
	v_fmac_f32_e32 v133, v135, v133
	v_mul_f32_e32 v135, v134, v133
	v_fma_f32 v136, -v132, v135, v134
	v_fmac_f32_e32 v135, v136, v133
	v_fma_f32 v132, -v132, v135, v134
	v_div_fmas_f32 v132, v132, v133, v135
	v_div_fixup_f32 v51, v132, v131, v51
	v_cvt_pk_bf16_f32 v141, v51, s0
	global_store_short v139, v141, s[72:73] offset:32
	v_mul_f32_e32 v131, 0xbfb8aa3b, v55
	v_exp_f32_e32 v131, v131
	s_nop 0
	v_add_f32_e32 v131, 1.0, v131
	v_div_scale_f32 v132, s[4:5], v131, v131, v55
	v_rcp_f32_e32 v133, v132
	v_div_scale_f32 v134, vcc, v55, v131, v55
	v_fma_f32 v135, -v132, v133, 1.0
	v_fmac_f32_e32 v133, v135, v133
	v_mul_f32_e32 v135, v134, v133
	v_fma_f32 v136, -v132, v135, v134
	v_fmac_f32_e32 v135, v136, v133
	v_fma_f32 v132, -v132, v135, v134
	v_div_fmas_f32 v132, v132, v133, v135
	v_div_fixup_f32 v55, v132, v131, v55
	v_cvt_pk_bf16_f32 v141, v55, s0
	global_store_short v139, v141, s[72:73] offset:64
	v_mul_f32_e32 v131, 0xbfb8aa3b, v47
	v_exp_f32_e32 v131, v131
	s_nop 0
	v_add_f32_e32 v131, 1.0, v131
	v_div_scale_f32 v132, s[4:5], v131, v131, v47
	v_rcp_f32_e32 v133, v132
	v_div_scale_f32 v134, vcc, v47, v131, v47
	v_fma_f32 v135, -v132, v133, 1.0
	v_fmac_f32_e32 v133, v135, v133
	v_mul_f32_e32 v135, v134, v133
	v_fma_f32 v136, -v132, v135, v134
	v_fmac_f32_e32 v135, v136, v133
	v_fma_f32 v132, -v132, v135, v134
	v_div_fmas_f32 v132, v132, v133, v135
	v_div_fixup_f32 v47, v132, v131, v47
	v_cvt_pk_bf16_f32 v141, v47, s0
	global_store_short v139, v141, s[72:73] offset:96
	v_add_u32_e32 v139, 0xa5600, v138
	v_mul_f32_e32 v131, 0xbfb8aa3b, v8
	v_exp_f32_e32 v131, v131
	s_nop 0
	v_add_f32_e32 v131, 1.0, v131
	v_div_scale_f32 v132, s[4:5], v131, v131, v8
	v_rcp_f32_e32 v133, v132
	v_div_scale_f32 v134, vcc, v8, v131, v8
	v_fma_f32 v135, -v132, v133, 1.0
	v_fmac_f32_e32 v133, v135, v133
	v_mul_f32_e32 v135, v134, v133
	v_fma_f32 v136, -v132, v135, v134
	v_fmac_f32_e32 v135, v136, v133
	v_fma_f32 v132, -v132, v135, v134
	v_div_fmas_f32 v132, v132, v133, v135
	v_div_fixup_f32 v8, v132, v131, v8
	v_cvt_pk_bf16_f32 v141, v8, s0
	global_store_short v139, v141, s[72:73]
	v_mul_f32_e32 v131, 0xbfb8aa3b, v52
	v_exp_f32_e32 v131, v131
	s_nop 0
	v_add_f32_e32 v131, 1.0, v131
; DEV u16 f2bf(float f) { return (u16)(pack2(f, 0.f) & 0xffffu); }
; DEV void phase_win(const Params& P, int l, const u16* __restrict__ xb, const u16* __restrict__ Wt, u16* __restrict__ h, char* smem) {
;     ...
;       for (int ns = 0; ns < 4; ++ns)
; #pragma unroll
;         for (int j = 0; j < 4; ++j) {
;           int row = m0 + wm * 128 + ms * 16 + quad * 4 + j;
;           int col = cb + ns * 16 + l15;
;           float v = acc[ms][ns][j];
;           if (mode == 1) { float lbv = lbp[col - C_HF]; v = __logf(lbv + (1.f - lbv) / (1.f + __expf(-v))); }
;           else if (mode == 2) v = v / (1.f + __expf(-v));
;           h[(size_t)row * HS + col] = f2bf(v);
	v_div_scale_f32 v132, s[4:5], v131, v131, v52
	v_rcp_f32_e32 v133, v132
	v_div_scale_f32 v134, vcc, v52, v131, v52
	v_fma_f32 v135, -v132, v133, 1.0
	v_fmac_f32_e32 v133, v135, v133
	v_mul_f32_e32 v135, v134, v133
	v_fma_f32 v136, -v132, v135, v134
	v_fmac_f32_e32 v135, v136, v133
	v_fma_f32 v132, -v132, v135, v134
	v_div_fmas_f32 v132, v132, v133, v135
	v_div_fixup_f32 v52, v132, v131, v52
	v_cvt_pk_bf16_f32 v141, v52, s0
	global_store_short v139, v141, s[72:73] offset:32
	v_mul_f32_e32 v131, 0xbfb8aa3b, v56
	v_exp_f32_e32 v131, v131
	s_nop 0
	v_add_f32_e32 v131, 1.0, v131
	v_div_scale_f32 v132, s[4:5], v131, v131, v56
	v_rcp_f32_e32 v133, v132
	v_div_scale_f32 v134, vcc, v56, v131, v56
	v_fma_f32 v135, -v132, v133, 1.0
	v_fmac_f32_e32 v133, v135, v133
	v_mul_f32_e32 v135, v134, v133
	v_fma_f32 v136, -v132, v135, v134
	v_fmac_f32_e32 v135, v136, v133
	v_fma_f32 v132, -v132, v135, v134
	v_div_fmas_f32 v132, v132, v133, v135
	v_div_fixup_f32 v56, v132, v131, v56
	v_cvt_pk_bf16_f32 v141, v56, s0
	global_store_short v139, v141, s[72:73] offset:64
	v_mul_f32_e32 v131, 0xbfb8aa3b, v48
	v_exp_f32_e32 v131, v131
	s_nop 0
	v_add_f32_e32 v131, 1.0, v131
	v_div_scale_f32 v132, s[4:5], v131, v131, v48
	v_rcp_f32_e32 v133, v132
	v_div_scale_f32 v134, vcc, v48, v131, v48
	v_fma_f32 v135, -v132, v133, 1.0
	v_fmac_f32_e32 v133, v135, v133
	v_mul_f32_e32 v135, v134, v133
	v_fma_f32 v136, -v132, v135, v134
	v_fmac_f32_e32 v135, v136, v133
	v_fma_f32 v132, -v132, v135, v134
	v_div_fmas_f32 v132, v132, v133, v135
	v_div_fixup_f32 v48, v132, v131, v48
	v_cvt_pk_bf16_f32 v141, v48, s0
	global_store_short v139, v141, s[72:73] offset:96
	v_add_u32_e32 v139, 0xa7100, v138
	v_mul_f32_e32 v131, 0xbfb8aa3b, v9
	v_exp_f32_e32 v131, v131
	s_nop 0
	v_add_f32_e32 v131, 1.0, v131
	v_div_scale_f32 v132, s[4:5], v131, v131, v9
	v_rcp_f32_e32 v133, v132
	v_div_scale_f32 v134, vcc, v9, v131, v9
	v_fma_f32 v135, -v132, v133, 1.0
	v_fmac_f32_e32 v133, v135, v133
	v_mul_f32_e32 v135, v134, v133
	v_fma_f32 v136, -v132, v135, v134
	v_fmac_f32_e32 v135, v136, v133
	v_fma_f32 v132, -v132, v135, v134
	v_div_fmas_f32 v132, v132, v133, v135
	v_div_fixup_f32 v9, v132, v131, v9
	v_cvt_pk_bf16_f32 v141, v9, s0
	global_store_short v139, v141, s[72:73]
	v_mul_f32_e32 v131, 0xbfb8aa3b, v53
	v_exp_f32_e32 v131, v131
	s_nop 0
	v_add_f32_e32 v131, 1.0, v131
	v_div_scale_f32 v132, s[4:5], v131, v131, v53
	v_rcp_f32_e32 v133, v132
	v_div_scale_f32 v134, vcc, v53, v131, v53
	v_fma_f32 v135, -v132, v133, 1.0
	v_fmac_f32_e32 v133, v135, v133
	v_mul_f32_e32 v135, v134, v133
	v_fma_f32 v136, -v132, v135, v134
	v_fmac_f32_e32 v135, v136, v133
	v_fma_f32 v132, -v132, v135, v134
	v_div_fmas_f32 v132, v132, v133, v135
	v_div_fixup_f32 v53, v132, v131, v53
	v_cvt_pk_bf16_f32 v141, v53, s0
	global_store_short v139, v141, s[72:73] offset:32
	v_mul_f32_e32 v131, 0xbfb8aa3b, v57
	v_exp_f32_e32 v131, v131
	s_nop 0
	v_add_f32_e32 v131, 1.0, v131
	v_div_scale_f32 v132, s[4:5], v131, v131, v57
	v_rcp_f32_e32 v133, v132
	v_div_scale_f32 v134, vcc, v57, v131, v57
	v_fma_f32 v135, -v132, v133, 1.0
	v_fmac_f32_e32 v133, v135, v133
	v_mul_f32_e32 v135, v134, v133
	v_fma_f32 v136, -v132, v135, v134
	v_fmac_f32_e32 v135, v136, v133
	v_fma_f32 v132, -v132, v135, v134
	v_div_fmas_f32 v132, v132, v133, v135
	v_div_fixup_f32 v57, v132, v131, v57
	v_cvt_pk_bf16_f32 v141, v57, s0
	global_store_short v139, v141, s[72:73] offset:64
	v_mul_f32_e32 v131, 0xbfb8aa3b, v49
	v_exp_f32_e32 v131, v131
	s_nop 0
	v_add_f32_e32 v131, 1.0, v131
	v_div_scale_f32 v132, s[4:5], v131, v131, v49
	v_rcp_f32_e32 v133, v132
	v_div_scale_f32 v134, vcc, v49, v131, v49
	v_fma_f32 v135, -v132, v133, 1.0
	v_fmac_f32_e32 v133, v135, v133
	v_mul_f32_e32 v135, v134, v133
	v_fma_f32 v136, -v132, v135, v134
	v_fmac_f32_e32 v135, v136, v133
	v_fma_f32 v132, -v132, v135, v134
	v_div_fmas_f32 v132, v132, v133, v135
	v_div_fixup_f32 v49, v132, v131, v49
	v_cvt_pk_bf16_f32 v141, v49, s0
	global_store_short v139, v141, s[72:73] offset:96
	v_add_u32_e32 v139, 0xbd000, v138
	v_mul_f32_e32 v131, 0xbfb8aa3b, v2
	v_exp_f32_e32 v131, v131
	s_nop 0
	v_add_f32_e32 v131, 1.0, v131
	v_div_scale_f32 v132, s[4:5], v131, v131, v2
	v_rcp_f32_e32 v133, v132
	v_div_scale_f32 v134, vcc, v2, v131, v2
	v_fma_f32 v135, -v132, v133, 1.0
	v_fmac_f32_e32 v133, v135, v133
	v_mul_f32_e32 v135, v134, v133
	v_fma_f32 v136, -v132, v135, v134
	v_fmac_f32_e32 v135, v136, v133
	v_fma_f32 v132, -v132, v135, v134
	v_div_fmas_f32 v132, v132, v133, v135
	v_div_fixup_f32 v2, v132, v131, v2
	v_cvt_pk_bf16_f32 v141, v2, s0
	global_store_short v139, v141, s[72:73]
	v_mul_f32_e32 v131, 0xbfb8aa3b, v34
	v_exp_f32_e32 v131, v131
	s_nop 0
	v_add_f32_e32 v131, 1.0, v131
	v_div_scale_f32 v132, s[4:5], v131, v131, v34
	v_rcp_f32_e32 v133, v132
	v_div_scale_f32 v134, vcc, v34, v131, v34
	v_fma_f32 v135, -v132, v133, 1.0
	v_fmac_f32_e32 v133, v135, v133
	v_mul_f32_e32 v135, v134, v133
	v_fma_f32 v136, -v132, v135, v134
	v_fmac_f32_e32 v135, v136, v133
	v_fma_f32 v132, -v132, v135, v134
	v_div_fmas_f32 v132, v132, v133, v135
	v_div_fixup_f32 v34, v132, v131, v34
	v_cvt_pk_bf16_f32 v141, v34, s0
	global_store_short v139, v141, s[72:73] offset:32
	v_mul_f32_e32 v131, 0xbfb8aa3b, v42
	v_exp_f32_e32 v131, v131
	s_nop 0
	v_add_f32_e32 v131, 1.0, v131
	v_div_scale_f32 v132, s[4:5], v131, v131, v42
	v_rcp_f32_e32 v133, v132
	v_div_scale_f32 v134, vcc, v42, v131, v42
	v_fma_f32 v135, -v132, v133, 1.0
	v_fmac_f32_e32 v133, v135, v133
	v_mul_f32_e32 v135, v134, v133
	v_fma_f32 v136, -v132, v135, v134
	v_fmac_f32_e32 v135, v136, v133
	v_fma_f32 v132, -v132, v135, v134
	v_div_fmas_f32 v132, v132, v133, v135
; DEV u16 f2bf(float f) { return (u16)(pack2(f, 0.f) & 0xffffu); }
; DEV void phase_win(const Params& P, int l, const u16* __restrict__ xb, const u16* __restrict__ Wt, u16* __restrict__ h, char* smem) {
;     ...
;       for (int ns = 0; ns < 4; ++ns)
; #pragma unroll
;         for (int j = 0; j < 4; ++j) {
;           int row = m0 + wm * 128 + ms * 16 + quad * 4 + j;
;           int col = cb + ns * 16 + l15;
;           float v = acc[ms][ns][j];
;           if (mode == 1) { float lbv = lbp[col - C_HF]; v = __logf(lbv + (1.f - lbv) / (1.f + __expf(-v))); }
;           else if (mode == 2) v = v / (1.f + __expf(-v));
;           h[(size_t)row * HS + col] = f2bf(v);
	v_div_fixup_f32 v42, v132, v131, v42
	v_cvt_pk_bf16_f32 v141, v42, s0
	global_store_short v139, v141, s[72:73] offset:64
	v_mul_f32_e32 v131, 0xbfb8aa3b, v30
	v_exp_f32_e32 v131, v131
	s_nop 0
	v_add_f32_e32 v131, 1.0, v131
	v_div_scale_f32 v132, s[4:5], v131, v131, v30
	v_rcp_f32_e32 v133, v132
	v_div_scale_f32 v134, vcc, v30, v131, v30
	v_fma_f32 v135, -v132, v133, 1.0
	v_fmac_f32_e32 v133, v135, v133
	v_mul_f32_e32 v135, v134, v133
	v_fma_f32 v136, -v132, v135, v134
	v_fmac_f32_e32 v135, v136, v133
	v_fma_f32 v132, -v132, v135, v134
	v_div_fmas_f32 v132, v132, v133, v135
	v_div_fixup_f32 v30, v132, v131, v30
	v_cvt_pk_bf16_f32 v141, v30, s0
	global_store_short v139, v141, s[72:73] offset:96
	v_add_u32_e32 v139, 0xbeb00, v138
	v_mul_f32_e32 v131, 0xbfb8aa3b, v3
	v_exp_f32_e32 v131, v131
	s_nop 0
	v_add_f32_e32 v131, 1.0, v131
	v_div_scale_f32 v132, s[4:5], v131, v131, v3
	v_rcp_f32_e32 v133, v132
	v_div_scale_f32 v134, vcc, v3, v131, v3
	v_fma_f32 v135, -v132, v133, 1.0
	v_fmac_f32_e32 v133, v135, v133
	v_mul_f32_e32 v135, v134, v133
	v_fma_f32 v136, -v132, v135, v134
	v_fmac_f32_e32 v135, v136, v133
	v_fma_f32 v132, -v132, v135, v134
	v_div_fmas_f32 v132, v132, v133, v135
	v_div_fixup_f32 v3, v132, v131, v3
	v_cvt_pk_bf16_f32 v141, v3, s0
	global_store_short v139, v141, s[72:73]
	v_mul_f32_e32 v131, 0xbfb8aa3b, v35
	v_exp_f32_e32 v131, v131
	s_nop 0
	v_add_f32_e32 v131, 1.0, v131
	v_div_scale_f32 v132, s[4:5], v131, v131, v35
	v_rcp_f32_e32 v133, v132
	v_div_scale_f32 v134, vcc, v35, v131, v35
	v_fma_f32 v135, -v132, v133, 1.0
	v_fmac_f32_e32 v133, v135, v133
	v_mul_f32_e32 v135, v134, v133
	v_fma_f32 v136, -v132, v135, v134
	v_fmac_f32_e32 v135, v136, v133
	v_fma_f32 v132, -v132, v135, v134
	v_div_fmas_f32 v132, v132, v133, v135
	v_div_fixup_f32 v35, v132, v131, v35
	v_cvt_pk_bf16_f32 v141, v35, s0
	global_store_short v139, v141, s[72:73] offset:32
	v_mul_f32_e32 v131, 0xbfb8aa3b, v43
	v_exp_f32_e32 v131, v131
	s_nop 0
	v_add_f32_e32 v131, 1.0, v131
	v_div_scale_f32 v132, s[4:5], v131, v131, v43
	v_rcp_f32_e32 v133, v132
	v_div_scale_f32 v134, vcc, v43, v131, v43
	v_fma_f32 v135, -v132, v133, 1.0
	v_fmac_f32_e32 v133, v135, v133
	v_mul_f32_e32 v135, v134, v133
	v_fma_f32 v136, -v132, v135, v134
	v_fmac_f32_e32 v135, v136, v133
	v_fma_f32 v132, -v132, v135, v134
	v_div_fmas_f32 v132, v132, v133, v135
	v_div_fixup_f32 v43, v132, v131, v43
	v_cvt_pk_bf16_f32 v141, v43, s0
	global_store_short v139, v141, s[72:73] offset:64
	v_mul_f32_e32 v131, 0xbfb8aa3b, v31
	v_exp_f32_e32 v131, v131
	s_nop 0
	v_add_f32_e32 v131, 1.0, v131
	v_div_scale_f32 v132, s[4:5], v131, v131, v31
	v_rcp_f32_e32 v133, v132
	v_div_scale_f32 v134, vcc, v31, v131, v31
	v_fma_f32 v135, -v132, v133, 1.0
	v_fmac_f32_e32 v133, v135, v133
	v_mul_f32_e32 v135, v134, v133
	v_fma_f32 v136, -v132, v135, v134
	v_fmac_f32_e32 v135, v136, v133
	v_fma_f32 v132, -v132, v135, v134
	v_div_fmas_f32 v132, v132, v133, v135
	v_div_fixup_f32 v31, v132, v131, v31
	v_cvt_pk_bf16_f32 v141, v31, s0
	global_store_short v139, v141, s[72:73] offset:96
	v_add_u32_e32 v139, 0xc0600, v138
	v_mul_f32_e32 v131, 0xbfb8aa3b, v4
	v_exp_f32_e32 v131, v131
	s_nop 0
	v_add_f32_e32 v131, 1.0, v131
	v_div_scale_f32 v132, s[4:5], v131, v131, v4
	v_rcp_f32_e32 v133, v132
	v_div_scale_f32 v134, vcc, v4, v131, v4
	v_fma_f32 v135, -v132, v133, 1.0
	v_fmac_f32_e32 v133, v135, v133
	v_mul_f32_e32 v135, v134, v133
	v_fma_f32 v136, -v132, v135, v134
	v_fmac_f32_e32 v135, v136, v133
	v_fma_f32 v132, -v132, v135, v134
	v_div_fmas_f32 v132, v132, v133, v135
	v_div_fixup_f32 v4, v132, v131, v4
	v_cvt_pk_bf16_f32 v141, v4, s0
	global_store_short v139, v141, s[72:73]
	v_mul_f32_e32 v131, 0xbfb8aa3b, v36
	v_exp_f32_e32 v131, v131
	s_nop 0
	v_add_f32_e32 v131, 1.0, v131
	v_div_scale_f32 v132, s[4:5], v131, v131, v36
	v_rcp_f32_e32 v133, v132
	v_div_scale_f32 v134, vcc, v36, v131, v36
	v_fma_f32 v135, -v132, v133, 1.0
	v_fmac_f32_e32 v133, v135, v133
	v_mul_f32_e32 v135, v134, v133
	v_fma_f32 v136, -v132, v135, v134
	v_fmac_f32_e32 v135, v136, v133
	v_fma_f32 v132, -v132, v135, v134
	v_div_fmas_f32 v132, v132, v133, v135
	v_div_fixup_f32 v36, v132, v131, v36
	v_cvt_pk_bf16_f32 v141, v36, s0
	global_store_short v139, v141, s[72:73] offset:32
	v_mul_f32_e32 v131, 0xbfb8aa3b, v44
	v_exp_f32_e32 v131, v131
	s_nop 0
	v_add_f32_e32 v131, 1.0, v131
	v_div_scale_f32 v132, s[4:5], v131, v131, v44
	v_rcp_f32_e32 v133, v132
	v_div_scale_f32 v134, vcc, v44, v131, v44
	v_fma_f32 v135, -v132, v133, 1.0
	v_fmac_f32_e32 v133, v135, v133
	v_mul_f32_e32 v135, v134, v133
	v_fma_f32 v136, -v132, v135, v134
	v_fmac_f32_e32 v135, v136, v133
	v_fma_f32 v132, -v132, v135, v134
	v_div_fmas_f32 v132, v132, v133, v135
	v_div_fixup_f32 v44, v132, v131, v44
	v_cvt_pk_bf16_f32 v141, v44, s0
	global_store_short v139, v141, s[72:73] offset:64
	v_mul_f32_e32 v131, 0xbfb8aa3b, v32
	v_exp_f32_e32 v131, v131
	s_nop 0
	v_add_f32_e32 v131, 1.0, v131
	v_div_scale_f32 v132, s[4:5], v131, v131, v32
	v_rcp_f32_e32 v133, v132
	v_div_scale_f32 v134, vcc, v32, v131, v32
	v_fma_f32 v135, -v132, v133, 1.0
	v_fmac_f32_e32 v133, v135, v133
	v_mul_f32_e32 v135, v134, v133
	v_fma_f32 v136, -v132, v135, v134
	v_fmac_f32_e32 v135, v136, v133
	v_fma_f32 v132, -v132, v135, v134
	v_div_fmas_f32 v132, v132, v133, v135
	v_div_fixup_f32 v32, v132, v131, v32
	v_cvt_pk_bf16_f32 v141, v32, s0
	global_store_short v139, v141, s[72:73] offset:96
	v_add_u32_e32 v139, 0xc2100, v138
	v_mul_f32_e32 v131, 0xbfb8aa3b, v5
	v_exp_f32_e32 v131, v131
	s_nop 0
	v_add_f32_e32 v131, 1.0, v131
	v_div_scale_f32 v132, s[4:5], v131, v131, v5
	v_rcp_f32_e32 v133, v132
	v_div_scale_f32 v134, vcc, v5, v131, v5
; DEV u16 f2bf(float f) { return (u16)(pack2(f, 0.f) & 0xffffu); }
; DEV void phase_win(const Params& P, int l, const u16* __restrict__ xb, const u16* __restrict__ Wt, u16* __restrict__ h, char* smem) {
;     ...
;       for (int ns = 0; ns < 4; ++ns)
; #pragma unroll
;         for (int j = 0; j < 4; ++j) {
;           int row = m0 + wm * 128 + ms * 16 + quad * 4 + j;
;           int col = cb + ns * 16 + l15;
;           float v = acc[ms][ns][j];
;           if (mode == 1) { float lbv = lbp[col - C_HF]; v = __logf(lbv + (1.f - lbv) / (1.f + __expf(-v))); }
;           else if (mode == 2) v = v / (1.f + __expf(-v));
;           h[(size_t)row * HS + col] = f2bf(v);
	v_fma_f32 v135, -v132, v133, 1.0
	v_fmac_f32_e32 v133, v135, v133
	v_mul_f32_e32 v135, v134, v133
	v_fma_f32 v136, -v132, v135, v134
	v_fmac_f32_e32 v135, v136, v133
	v_fma_f32 v132, -v132, v135, v134
	v_div_fmas_f32 v132, v132, v133, v135
	v_div_fixup_f32 v5, v132, v131, v5
	v_cvt_pk_bf16_f32 v141, v5, s0
	global_store_short v139, v141, s[72:73]
	v_mul_f32_e32 v131, 0xbfb8aa3b, v37
	v_exp_f32_e32 v131, v131
	s_nop 0
	v_add_f32_e32 v131, 1.0, v131
	v_div_scale_f32 v132, s[4:5], v131, v131, v37
	v_rcp_f32_e32 v133, v132
	v_div_scale_f32 v134, vcc, v37, v131, v37
	v_fma_f32 v135, -v132, v133, 1.0
	v_fmac_f32_e32 v133, v135, v133
	v_mul_f32_e32 v135, v134, v133
	v_fma_f32 v136, -v132, v135, v134
	v_fmac_f32_e32 v135, v136, v133
	v_fma_f32 v132, -v132, v135, v134
	v_div_fmas_f32 v132, v132, v133, v135
	v_div_fixup_f32 v37, v132, v131, v37
	v_cvt_pk_bf16_f32 v141, v37, s0
	global_store_short v139, v141, s[72:73] offset:32
	v_mul_f32_e32 v131, 0xbfb8aa3b, v45
	v_exp_f32_e32 v131, v131
	s_nop 0
	v_add_f32_e32 v131, 1.0, v131
	v_div_scale_f32 v132, s[4:5], v131, v131, v45
	v_rcp_f32_e32 v133, v132
	v_div_scale_f32 v134, vcc, v45, v131, v45
	v_fma_f32 v135, -v132, v133, 1.0
	v_fmac_f32_e32 v133, v135, v133
	v_mul_f32_e32 v135, v134, v133
	v_fma_f32 v136, -v132, v135, v134
	v_fmac_f32_e32 v135, v136, v133
	v_fma_f32 v132, -v132, v135, v134
	v_div_fmas_f32 v132, v132, v133, v135
	v_div_fixup_f32 v45, v132, v131, v45
	v_cvt_pk_bf16_f32 v141, v45, s0
	global_store_short v139, v141, s[72:73] offset:64
	v_mul_f32_e32 v131, 0xbfb8aa3b, v33
	v_exp_f32_e32 v131, v131
	s_nop 0
	v_add_f32_e32 v131, 1.0, v131
	v_div_scale_f32 v132, s[4:5], v131, v131, v33
	v_rcp_f32_e32 v133, v132
	v_div_scale_f32 v134, vcc, v33, v131, v33
	v_fma_f32 v135, -v132, v133, 1.0
	v_fmac_f32_e32 v133, v135, v133
	v_mul_f32_e32 v135, v134, v133
	v_fma_f32 v136, -v132, v135, v134
	v_fmac_f32_e32 v135, v136, v133
	v_fma_f32 v132, -v132, v135, v134
	v_div_fmas_f32 v132, v132, v133, v135
	v_div_fixup_f32 v33, v132, v131, v33
	v_cvt_pk_bf16_f32 v141, v33, s0
	global_store_short v139, v141, s[72:73] offset:96
	s_branch .LBB0_2075
.Lwg_m1:
	v_mul_f32_e32 v132, 0xbfb8aa3b, v38
	v_exp_f32_e32 v132, v132
	v_sub_f32_e32 v133, 1.0, v160
	v_add_f32_e32 v132, 1.0, v132
	v_div_scale_f32 v134, s[4:5], v132, v132, v133
	v_rcp_f32_e32 v135, v134
	v_div_scale_f32 v136, vcc, v133, v132, v133
	s_mov_b32 s4, 0x800000
	v_fma_f32 v137, -v134, v135, 1.0
	v_fmac_f32_e32 v135, v137, v135
	v_mul_f32_e32 v137, v136, v135
	v_fma_f32 v140, -v134, v137, v136
	v_fmac_f32_e32 v137, v140, v135
	v_fma_f32 v134, -v134, v137, v136
	v_div_fmas_f32 v134, v134, v135, v137
	v_div_fixup_f32 v132, v134, v132, v133
	v_add_f32_e32 v131, v160, v132
	v_cmp_gt_f32_e32 vcc, s4, v131
	s_mov_b32 s4, 0x3f317217
	s_nop 0
	v_cndmask_b32_e64 v132, 0, 32, vcc
	v_ldexp_f32 v131, v131, v132
	v_log_f32_e32 v131, v131
	s_nop 0
	v_mul_f32_e32 v132, 0x3f317217, v131
	v_fma_f32 v132, v131, s4, -v132
	v_fmac_f32_e32 v132, 0x3377d1cf, v131
	s_mov_b32 s4, 0x7f800000
	v_fmac_f32_e32 v132, 0x3f317217, v131
	v_cmp_lt_f32_e64 s[12:13], |v131|, s4
	s_nop 1
	v_cndmask_b32_e64 v131, v131, v132, s[12:13]
	v_cndmask_b32_e32 v132, 0, v227, vcc
	v_sub_f32_e32 v131, v131, v132
	v_cvt_pk_bf16_f32 v141, v131, s0
	global_store_short v138, v141, s[72:73]
	v_mul_f32_e32 v132, 0xbfb8aa3b, v122
	v_exp_f32_e32 v132, v132
	v_sub_f32_e32 v133, 1.0, v161
	v_add_f32_e32 v132, 1.0, v132
	v_div_scale_f32 v134, s[4:5], v132, v132, v133
	v_rcp_f32_e32 v135, v134
	v_div_scale_f32 v136, vcc, v133, v132, v133
	s_mov_b32 s4, 0x800000
	v_fma_f32 v137, -v134, v135, 1.0
	v_fmac_f32_e32 v135, v137, v135
	v_mul_f32_e32 v137, v136, v135
	v_fma_f32 v140, -v134, v137, v136
	v_fmac_f32_e32 v137, v140, v135
	v_fma_f32 v134, -v134, v137, v136
	v_div_fmas_f32 v134, v134, v135, v137
	v_div_fixup_f32 v132, v134, v132, v133
	v_add_f32_e32 v131, v161, v132
	v_cmp_gt_f32_e32 vcc, s4, v131
	s_mov_b32 s4, 0x3f317217
	s_nop 0
	v_cndmask_b32_e64 v132, 0, 32, vcc
	v_ldexp_f32 v131, v131, v132
	v_log_f32_e32 v131, v131
	s_nop 0
	v_mul_f32_e32 v132, 0x3f317217, v131
	v_fma_f32 v132, v131, s4, -v132
	v_fmac_f32_e32 v132, 0x3377d1cf, v131
	s_mov_b32 s4, 0x7f800000
	v_fmac_f32_e32 v132, 0x3f317217, v131
	v_cmp_lt_f32_e64 s[12:13], |v131|, s4
	s_nop 1
	v_cndmask_b32_e64 v131, v131, v132, s[12:13]
	v_cndmask_b32_e32 v132, 0, v227, vcc
	v_sub_f32_e32 v131, v131, v132
	v_cvt_pk_bf16_f32 v141, v131, s0
	global_store_short v138, v141, s[72:73] offset:32
	v_mul_f32_e32 v132, 0xbfb8aa3b, v126
	v_exp_f32_e32 v132, v132
	v_sub_f32_e32 v133, 1.0, v162
	v_add_f32_e32 v132, 1.0, v132
	v_div_scale_f32 v134, s[4:5], v132, v132, v133
	v_rcp_f32_e32 v135, v134
	v_div_scale_f32 v136, vcc, v133, v132, v133
	s_mov_b32 s4, 0x800000
	v_fma_f32 v137, -v134, v135, 1.0
	v_fmac_f32_e32 v135, v137, v135
	v_mul_f32_e32 v137, v136, v135
	v_fma_f32 v140, -v134, v137, v136
	v_fmac_f32_e32 v137, v140, v135
	v_fma_f32 v134, -v134, v137, v136
	v_div_fmas_f32 v134, v134, v135, v137
	v_div_fixup_f32 v132, v134, v132, v133
	v_add_f32_e32 v131, v162, v132
	v_cmp_gt_f32_e32 vcc, s4, v131
	s_mov_b32 s4, 0x3f317217
	s_nop 0
	v_cndmask_b32_e64 v132, 0, 32, vcc
	v_ldexp_f32 v131, v131, v132
	v_log_f32_e32 v131, v131
	s_nop 0
	v_mul_f32_e32 v132, 0x3f317217, v131
	v_fma_f32 v132, v131, s4, -v132
	v_fmac_f32_e32 v132, 0x3377d1cf, v131
	s_mov_b32 s4, 0x7f800000
	v_fmac_f32_e32 v132, 0x3f317217, v131
	v_cmp_lt_f32_e64 s[12:13], |v131|, s4
	s_nop 1
	v_cndmask_b32_e64 v131, v131, v132, s[12:13]
	v_cndmask_b32_e32 v132, 0, v227, vcc
	v_sub_f32_e32 v131, v131, v132
	v_cvt_pk_bf16_f32 v141, v131, s0
	global_store_short v138, v141, s[72:73] offset:64
; DEV u16 f2bf(float f) { return (u16)(pack2(f, 0.f) & 0xffffu); }
; DEV void phase_win(const Params& P, int l, const u16* __restrict__ xb, const u16* __restrict__ Wt, u16* __restrict__ h, char* smem) {
;     ...
;       for (int ns = 0; ns < 4; ++ns)
; #pragma unroll
;         for (int j = 0; j < 4; ++j) {
;           int row = m0 + wm * 128 + ms * 16 + quad * 4 + j;
;           int col = cb + ns * 16 + l15;
;           float v = acc[ms][ns][j];
;           if (mode == 1) { float lbv = lbp[col - C_HF]; v = __logf(lbv + (1.f - lbv) / (1.f + __expf(-v))); }
;           else if (mode == 2) v = v / (1.f + __expf(-v));
;           h[(size_t)row * HS + col] = f2bf(v);
	v_mul_f32_e32 v132, 0xbfb8aa3b, v118
	v_exp_f32_e32 v132, v132
	v_sub_f32_e32 v133, 1.0, v163
	v_add_f32_e32 v132, 1.0, v132
	v_div_scale_f32 v134, s[4:5], v132, v132, v133
	v_rcp_f32_e32 v135, v134
	v_div_scale_f32 v136, vcc, v133, v132, v133
	s_mov_b32 s4, 0x800000
	v_fma_f32 v137, -v134, v135, 1.0
	v_fmac_f32_e32 v135, v137, v135
	v_mul_f32_e32 v137, v136, v135
	v_fma_f32 v140, -v134, v137, v136
	v_fmac_f32_e32 v137, v140, v135
	v_fma_f32 v134, -v134, v137, v136
	v_div_fmas_f32 v134, v134, v135, v137
	v_div_fixup_f32 v132, v134, v132, v133
	v_add_f32_e32 v131, v163, v132
	v_cmp_gt_f32_e32 vcc, s4, v131
	s_mov_b32 s4, 0x3f317217
	s_nop 0
	v_cndmask_b32_e64 v132, 0, 32, vcc
	v_ldexp_f32 v131, v131, v132
	v_log_f32_e32 v131, v131
	s_nop 0
	v_mul_f32_e32 v132, 0x3f317217, v131
	v_fma_f32 v132, v131, s4, -v132
	v_fmac_f32_e32 v132, 0x3377d1cf, v131
	s_mov_b32 s4, 0x7f800000
	v_fmac_f32_e32 v132, 0x3f317217, v131
	v_cmp_lt_f32_e64 s[12:13], |v131|, s4
	s_nop 1
	v_cndmask_b32_e64 v131, v131, v132, s[12:13]
	v_cndmask_b32_e32 v132, 0, v227, vcc
	v_sub_f32_e32 v131, v131, v132
	v_cvt_pk_bf16_f32 v141, v131, s0
	global_store_short v138, v141, s[72:73] offset:96
	v_add_u32_e32 v139, 0x1b00, v138
	v_mul_f32_e32 v132, 0xbfb8aa3b, v39
	v_exp_f32_e32 v132, v132
	v_sub_f32_e32 v133, 1.0, v160
	v_add_f32_e32 v132, 1.0, v132
	v_div_scale_f32 v134, s[4:5], v132, v132, v133
	v_rcp_f32_e32 v135, v134
	v_div_scale_f32 v136, vcc, v133, v132, v133
	s_mov_b32 s4, 0x800000
	v_fma_f32 v137, -v134, v135, 1.0
	v_fmac_f32_e32 v135, v137, v135
	v_mul_f32_e32 v137, v136, v135
	v_fma_f32 v140, -v134, v137, v136
	v_fmac_f32_e32 v137, v140, v135
	v_fma_f32 v134, -v134, v137, v136
	v_div_fmas_f32 v134, v134, v135, v137
	v_div_fixup_f32 v132, v134, v132, v133
	v_add_f32_e32 v131, v160, v132
	v_cmp_gt_f32_e32 vcc, s4, v131
	s_mov_b32 s4, 0x3f317217
	s_nop 0
	v_cndmask_b32_e64 v132, 0, 32, vcc
	v_ldexp_f32 v131, v131, v132
	v_log_f32_e32 v131, v131
	s_nop 0
	v_mul_f32_e32 v132, 0x3f317217, v131
	v_fma_f32 v132, v131, s4, -v132
	v_fmac_f32_e32 v132, 0x3377d1cf, v131
	s_mov_b32 s4, 0x7f800000
	v_fmac_f32_e32 v132, 0x3f317217, v131
	v_cmp_lt_f32_e64 s[12:13], |v131|, s4
	s_nop 1
	v_cndmask_b32_e64 v131, v131, v132, s[12:13]
	v_cndmask_b32_e32 v132, 0, v227, vcc
	v_sub_f32_e32 v131, v131, v132
	v_cvt_pk_bf16_f32 v141, v131, s0
	global_store_short v139, v141, s[72:73]
	v_mul_f32_e32 v132, 0xbfb8aa3b, v123
	v_exp_f32_e32 v132, v132
	v_sub_f32_e32 v133, 1.0, v161
	v_add_f32_e32 v132, 1.0, v132
	v_div_scale_f32 v134, s[4:5], v132, v132, v133
	v_rcp_f32_e32 v135, v134
	v_div_scale_f32 v136, vcc, v133, v132, v133
	s_mov_b32 s4, 0x800000
	v_fma_f32 v137, -v134, v135, 1.0
	v_fmac_f32_e32 v135, v137, v135
	v_mul_f32_e32 v137, v136, v135
	v_fma_f32 v140, -v134, v137, v136
	v_fmac_f32_e32 v137, v140, v135
	v_fma_f32 v134, -v134, v137, v136
	v_div_fmas_f32 v134, v134, v135, v137
	v_div_fixup_f32 v132, v134, v132, v133
	v_add_f32_e32 v131, v161, v132
	v_cmp_gt_f32_e32 vcc, s4, v131
	s_mov_b32 s4, 0x3f317217
	s_nop 0
	v_cndmask_b32_e64 v132, 0, 32, vcc
	v_ldexp_f32 v131, v131, v132
	v_log_f32_e32 v131, v131
	s_nop 0
	v_mul_f32_e32 v132, 0x3f317217, v131
	v_fma_f32 v132, v131, s4, -v132
	v_fmac_f32_e32 v132, 0x3377d1cf, v131
	s_mov_b32 s4, 0x7f800000
	v_fmac_f32_e32 v132, 0x3f317217, v131
	v_cmp_lt_f32_e64 s[12:13], |v131|, s4
	s_nop 1
	v_cndmask_b32_e64 v131, v131, v132, s[12:13]
	v_cndmask_b32_e32 v132, 0, v227, vcc
	v_sub_f32_e32 v131, v131, v132
	v_cvt_pk_bf16_f32 v141, v131, s0
	global_store_short v139, v141, s[72:73] offset:32
	v_mul_f32_e32 v132, 0xbfb8aa3b, v127
	v_exp_f32_e32 v132, v132
	v_sub_f32_e32 v133, 1.0, v162
	v_add_f32_e32 v132, 1.0, v132
	v_div_scale_f32 v134, s[4:5], v132, v132, v133
	v_rcp_f32_e32 v135, v134
	v_div_scale_f32 v136, vcc, v133, v132, v133
	s_mov_b32 s4, 0x800000
	v_fma_f32 v137, -v134, v135, 1.0
	v_fmac_f32_e32 v135, v137, v135
	v_mul_f32_e32 v137, v136, v135
	v_fma_f32 v140, -v134, v137, v136
	v_fmac_f32_e32 v137, v140, v135
	v_fma_f32 v134, -v134, v137, v136
	v_div_fmas_f32 v134, v134, v135, v137
	v_div_fixup_f32 v132, v134, v132, v133
	v_add_f32_e32 v131, v162, v132
	v_cmp_gt_f32_e32 vcc, s4, v131
	s_mov_b32 s4, 0x3f317217
	s_nop 0
	v_cndmask_b32_e64 v132, 0, 32, vcc
	v_ldexp_f32 v131, v131, v132
	v_log_f32_e32 v131, v131
	s_nop 0
	v_mul_f32_e32 v132, 0x3f317217, v131
	v_fma_f32 v132, v131, s4, -v132
	v_fmac_f32_e32 v132, 0x3377d1cf, v131
	s_mov_b32 s4, 0x7f800000
	v_fmac_f32_e32 v132, 0x3f317217, v131
	v_cmp_lt_f32_e64 s[12:13], |v131|, s4
	s_nop 1
	v_cndmask_b32_e64 v131, v131, v132, s[12:13]
	v_cndmask_b32_e32 v132, 0, v227, vcc
	v_sub_f32_e32 v131, v131, v132
	v_cvt_pk_bf16_f32 v141, v131, s0
	global_store_short v139, v141, s[72:73] offset:64
	v_mul_f32_e32 v132, 0xbfb8aa3b, v119
	v_exp_f32_e32 v132, v132
	v_sub_f32_e32 v133, 1.0, v163
	v_add_f32_e32 v132, 1.0, v132
	v_div_scale_f32 v134, s[4:5], v132, v132, v133
	v_rcp_f32_e32 v135, v134
	v_div_scale_f32 v136, vcc, v133, v132, v133
	s_mov_b32 s4, 0x800000
	v_fma_f32 v137, -v134, v135, 1.0
	v_fmac_f32_e32 v135, v137, v135
	v_mul_f32_e32 v137, v136, v135
	v_fma_f32 v140, -v134, v137, v136
	v_fmac_f32_e32 v137, v140, v135
	v_fma_f32 v134, -v134, v137, v136
	v_div_fmas_f32 v134, v134, v135, v137
	v_div_fixup_f32 v132, v134, v132, v133
	v_add_f32_e32 v131, v163, v132
	v_cmp_gt_f32_e32 vcc, s4, v131
	s_mov_b32 s4, 0x3f317217
	s_nop 0
	v_cndmask_b32_e64 v132, 0, 32, vcc
	v_ldexp_f32 v131, v131, v132
	v_log_f32_e32 v131, v131
	s_nop 0
	v_mul_f32_e32 v132, 0x3f317217, v131
	v_fma_f32 v132, v131, s4, -v132
	v_fmac_f32_e32 v132, 0x3377d1cf, v131
	s_mov_b32 s4, 0x7f800000
	v_fmac_f32_e32 v132, 0x3f317217, v131
; DEV u16 f2bf(float f) { return (u16)(pack2(f, 0.f) & 0xffffu); }
; DEV void phase_win(const Params& P, int l, const u16* __restrict__ xb, const u16* __restrict__ Wt, u16* __restrict__ h, char* smem) {
;     ...
;       for (int ns = 0; ns < 4; ++ns)
; #pragma unroll
;         for (int j = 0; j < 4; ++j) {
;           int row = m0 + wm * 128 + ms * 16 + quad * 4 + j;
;           int col = cb + ns * 16 + l15;
;           float v = acc[ms][ns][j];
;           if (mode == 1) { float lbv = lbp[col - C_HF]; v = __logf(lbv + (1.f - lbv) / (1.f + __expf(-v))); }
;           else if (mode == 2) v = v / (1.f + __expf(-v));
;           h[(size_t)row * HS + col] = f2bf(v);
	v_cmp_lt_f32_e64 s[12:13], |v131|, s4
	s_nop 1
	v_cndmask_b32_e64 v131, v131, v132, s[12:13]
	v_cndmask_b32_e32 v132, 0, v227, vcc
	v_sub_f32_e32 v131, v131, v132
	v_cvt_pk_bf16_f32 v141, v131, s0
	global_store_short v139, v141, s[72:73] offset:96
	v_add_u32_e32 v139, 0x3600, v138
	v_mul_f32_e32 v132, 0xbfb8aa3b, v40
	v_exp_f32_e32 v132, v132
	v_sub_f32_e32 v133, 1.0, v160
	v_add_f32_e32 v132, 1.0, v132
	v_div_scale_f32 v134, s[4:5], v132, v132, v133
	v_rcp_f32_e32 v135, v134
	v_div_scale_f32 v136, vcc, v133, v132, v133
	s_mov_b32 s4, 0x800000
	v_fma_f32 v137, -v134, v135, 1.0
	v_fmac_f32_e32 v135, v137, v135
	v_mul_f32_e32 v137, v136, v135
	v_fma_f32 v140, -v134, v137, v136
	v_fmac_f32_e32 v137, v140, v135
	v_fma_f32 v134, -v134, v137, v136
	v_div_fmas_f32 v134, v134, v135, v137
	v_div_fixup_f32 v132, v134, v132, v133
	v_add_f32_e32 v131, v160, v132
	v_cmp_gt_f32_e32 vcc, s4, v131
	s_mov_b32 s4, 0x3f317217
	s_nop 0
	v_cndmask_b32_e64 v132, 0, 32, vcc
	v_ldexp_f32 v131, v131, v132
	v_log_f32_e32 v131, v131
	s_nop 0
	v_mul_f32_e32 v132, 0x3f317217, v131
	v_fma_f32 v132, v131, s4, -v132
	v_fmac_f32_e32 v132, 0x3377d1cf, v131
	s_mov_b32 s4, 0x7f800000
	v_fmac_f32_e32 v132, 0x3f317217, v131
	v_cmp_lt_f32_e64 s[12:13], |v131|, s4
	s_nop 1
	v_cndmask_b32_e64 v131, v131, v132, s[12:13]
	v_cndmask_b32_e32 v132, 0, v227, vcc
	v_sub_f32_e32 v131, v131, v132
	v_cvt_pk_bf16_f32 v141, v131, s0
	global_store_short v139, v141, s[72:73]
	v_mul_f32_e32 v132, 0xbfb8aa3b, v124
	v_exp_f32_e32 v132, v132
	v_sub_f32_e32 v133, 1.0, v161
	v_add_f32_e32 v132, 1.0, v132
	v_div_scale_f32 v134, s[4:5], v132, v132, v133
	v_rcp_f32_e32 v135, v134
	v_div_scale_f32 v136, vcc, v133, v132, v133
	s_mov_b32 s4, 0x800000
	v_fma_f32 v137, -v134, v135, 1.0
	v_fmac_f32_e32 v135, v137, v135
	v_mul_f32_e32 v137, v136, v135
	v_fma_f32 v140, -v134, v137, v136
	v_fmac_f32_e32 v137, v140, v135
	v_fma_f32 v134, -v134, v137, v136
	v_div_fmas_f32 v134, v134, v135, v137
	v_div_fixup_f32 v132, v134, v132, v133
	v_add_f32_e32 v131, v161, v132
	v_cmp_gt_f32_e32 vcc, s4, v131
	s_mov_b32 s4, 0x3f317217
	s_nop 0
	v_cndmask_b32_e64 v132, 0, 32, vcc
	v_ldexp_f32 v131, v131, v132
	v_log_f32_e32 v131, v131
	s_nop 0
	v_mul_f32_e32 v132, 0x3f317217, v131
	v_fma_f32 v132, v131, s4, -v132
	v_fmac_f32_e32 v132, 0x3377d1cf, v131
	s_mov_b32 s4, 0x7f800000
	v_fmac_f32_e32 v132, 0x3f317217, v131
	v_cmp_lt_f32_e64 s[12:13], |v131|, s4
	s_nop 1
	v_cndmask_b32_e64 v131, v131, v132, s[12:13]
	v_cndmask_b32_e32 v132, 0, v227, vcc
	v_sub_f32_e32 v131, v131, v132
	v_cvt_pk_bf16_f32 v141, v131, s0
	global_store_short v139, v141, s[72:73] offset:32
	v_mul_f32_e32 v132, 0xbfb8aa3b, v128
	v_exp_f32_e32 v132, v132
	v_sub_f32_e32 v133, 1.0, v162
	v_add_f32_e32 v132, 1.0, v132
	v_div_scale_f32 v134, s[4:5], v132, v132, v133
	v_rcp_f32_e32 v135, v134
	v_div_scale_f32 v136, vcc, v133, v132, v133
	s_mov_b32 s4, 0x800000
	v_fma_f32 v137, -v134, v135, 1.0
	v_fmac_f32_e32 v135, v137, v135
	v_mul_f32_e32 v137, v136, v135
	v_fma_f32 v140, -v134, v137, v136
	v_fmac_f32_e32 v137, v140, v135
	v_fma_f32 v134, -v134, v137, v136
	v_div_fmas_f32 v134, v134, v135, v137
	v_div_fixup_f32 v132, v134, v132, v133
	v_add_f32_e32 v131, v162, v132
	v_cmp_gt_f32_e32 vcc, s4, v131
	s_mov_b32 s4, 0x3f317217
	s_nop 0
	v_cndmask_b32_e64 v132, 0, 32, vcc
	v_ldexp_f32 v131, v131, v132
	v_log_f32_e32 v131, v131
	s_nop 0
	v_mul_f32_e32 v132, 0x3f317217, v131
	v_fma_f32 v132, v131, s4, -v132
	v_fmac_f32_e32 v132, 0x3377d1cf, v131
	s_mov_b32 s4, 0x7f800000
	v_fmac_f32_e32 v132, 0x3f317217, v131
	v_cmp_lt_f32_e64 s[12:13], |v131|, s4
	s_nop 1
	v_cndmask_b32_e64 v131, v131, v132, s[12:13]
	v_cndmask_b32_e32 v132, 0, v227, vcc
	v_sub_f32_e32 v131, v131, v132
	v_cvt_pk_bf16_f32 v141, v131, s0
	global_store_short v139, v141, s[72:73] offset:64
	v_mul_f32_e32 v132, 0xbfb8aa3b, v120
	v_exp_f32_e32 v132, v132
	v_sub_f32_e32 v133, 1.0, v163
	v_add_f32_e32 v132, 1.0, v132
	v_div_scale_f32 v134, s[4:5], v132, v132, v133
	v_rcp_f32_e32 v135, v134
	v_div_scale_f32 v136, vcc, v133, v132, v133
	s_mov_b32 s4, 0x800000
	v_fma_f32 v137, -v134, v135, 1.0
	v_fmac_f32_e32 v135, v137, v135
	v_mul_f32_e32 v137, v136, v135
	v_fma_f32 v140, -v134, v137, v136
	v_fmac_f32_e32 v137, v140, v135
	v_fma_f32 v134, -v134, v137, v136
	v_div_fmas_f32 v134, v134, v135, v137
	v_div_fixup_f32 v132, v134, v132, v133
	v_add_f32_e32 v131, v163, v132
	v_cmp_gt_f32_e32 vcc, s4, v131
	s_mov_b32 s4, 0x3f317217
	s_nop 0
	v_cndmask_b32_e64 v132, 0, 32, vcc
	v_ldexp_f32 v131, v131, v132
	v_log_f32_e32 v131, v131
	s_nop 0
	v_mul_f32_e32 v132, 0x3f317217, v131
	v_fma_f32 v132, v131, s4, -v132
	v_fmac_f32_e32 v132, 0x3377d1cf, v131
	s_mov_b32 s4, 0x7f800000
	v_fmac_f32_e32 v132, 0x3f317217, v131
	v_cmp_lt_f32_e64 s[12:13], |v131|, s4
	s_nop 1
	v_cndmask_b32_e64 v131, v131, v132, s[12:13]
	v_cndmask_b32_e32 v132, 0, v227, vcc
	v_sub_f32_e32 v131, v131, v132
	v_cvt_pk_bf16_f32 v141, v131, s0
	global_store_short v139, v141, s[72:73] offset:96
	v_add_u32_e32 v139, 0x5100, v138
	v_mul_f32_e32 v132, 0xbfb8aa3b, v41
	v_exp_f32_e32 v132, v132
	v_sub_f32_e32 v133, 1.0, v160
	v_add_f32_e32 v132, 1.0, v132
	v_div_scale_f32 v134, s[4:5], v132, v132, v133
	v_rcp_f32_e32 v135, v134
	v_div_scale_f32 v136, vcc, v133, v132, v133
	s_mov_b32 s4, 0x800000
	v_fma_f32 v137, -v134, v135, 1.0
	v_fmac_f32_e32 v135, v137, v135
	v_mul_f32_e32 v137, v136, v135
	v_fma_f32 v140, -v134, v137, v136
	v_fmac_f32_e32 v137, v140, v135
	v_fma_f32 v134, -v134, v137, v136
	v_div_fmas_f32 v134, v134, v135, v137
	v_div_fixup_f32 v132, v134, v132, v133
	v_add_f32_e32 v131, v160, v132
	v_cmp_gt_f32_e32 vcc, s4, v131
	s_mov_b32 s4, 0x3f317217
; DEV u16 f2bf(float f) { return (u16)(pack2(f, 0.f) & 0xffffu); }
; DEV void phase_win(const Params& P, int l, const u16* __restrict__ xb, const u16* __restrict__ Wt, u16* __restrict__ h, char* smem) {
;     ...
;       for (int ns = 0; ns < 4; ++ns)
; #pragma unroll
;         for (int j = 0; j < 4; ++j) {
;           int row = m0 + wm * 128 + ms * 16 + quad * 4 + j;
;           int col = cb + ns * 16 + l15;
;           float v = acc[ms][ns][j];
;           if (mode == 1) { float lbv = lbp[col - C_HF]; v = __logf(lbv + (1.f - lbv) / (1.f + __expf(-v))); }
;           else if (mode == 2) v = v / (1.f + __expf(-v));
;           h[(size_t)row * HS + col] = f2bf(v);
	s_nop 0
	v_cndmask_b32_e64 v132, 0, 32, vcc
	v_ldexp_f32 v131, v131, v132
	v_log_f32_e32 v131, v131
	s_nop 0
	v_mul_f32_e32 v132, 0x3f317217, v131
	v_fma_f32 v132, v131, s4, -v132
	v_fmac_f32_e32 v132, 0x3377d1cf, v131
	s_mov_b32 s4, 0x7f800000
	v_fmac_f32_e32 v132, 0x3f317217, v131
	v_cmp_lt_f32_e64 s[12:13], |v131|, s4
	s_nop 1
	v_cndmask_b32_e64 v131, v131, v132, s[12:13]
	v_cndmask_b32_e32 v132, 0, v227, vcc
	v_sub_f32_e32 v131, v131, v132
	v_cvt_pk_bf16_f32 v141, v131, s0
	global_store_short v139, v141, s[72:73]
	v_mul_f32_e32 v132, 0xbfb8aa3b, v125
	v_exp_f32_e32 v132, v132
	v_sub_f32_e32 v133, 1.0, v161
	v_add_f32_e32 v132, 1.0, v132
	v_div_scale_f32 v134, s[4:5], v132, v132, v133
	v_rcp_f32_e32 v135, v134
	v_div_scale_f32 v136, vcc, v133, v132, v133
	s_mov_b32 s4, 0x800000
	v_fma_f32 v137, -v134, v135, 1.0
	v_fmac_f32_e32 v135, v137, v135
	v_mul_f32_e32 v137, v136, v135
	v_fma_f32 v140, -v134, v137, v136
	v_fmac_f32_e32 v137, v140, v135
	v_fma_f32 v134, -v134, v137, v136
	v_div_fmas_f32 v134, v134, v135, v137
	v_div_fixup_f32 v132, v134, v132, v133
	v_add_f32_e32 v131, v161, v132
	v_cmp_gt_f32_e32 vcc, s4, v131
	s_mov_b32 s4, 0x3f317217
	s_nop 0
	v_cndmask_b32_e64 v132, 0, 32, vcc
	v_ldexp_f32 v131, v131, v132
	v_log_f32_e32 v131, v131
	s_nop 0
	v_mul_f32_e32 v132, 0x3f317217, v131
	v_fma_f32 v132, v131, s4, -v132
	v_fmac_f32_e32 v132, 0x3377d1cf, v131
	s_mov_b32 s4, 0x7f800000
	v_fmac_f32_e32 v132, 0x3f317217, v131
	v_cmp_lt_f32_e64 s[12:13], |v131|, s4
	s_nop 1
	v_cndmask_b32_e64 v131, v131, v132, s[12:13]
	v_cndmask_b32_e32 v132, 0, v227, vcc
	v_sub_f32_e32 v131, v131, v132
	v_cvt_pk_bf16_f32 v141, v131, s0
	global_store_short v139, v141, s[72:73] offset:32
	v_mul_f32_e32 v132, 0xbfb8aa3b, v129
	v_exp_f32_e32 v132, v132
	v_sub_f32_e32 v133, 1.0, v162
	v_add_f32_e32 v132, 1.0, v132
	v_div_scale_f32 v134, s[4:5], v132, v132, v133
	v_rcp_f32_e32 v135, v134
	v_div_scale_f32 v136, vcc, v133, v132, v133
	s_mov_b32 s4, 0x800000
	v_fma_f32 v137, -v134, v135, 1.0
	v_fmac_f32_e32 v135, v137, v135
	v_mul_f32_e32 v137, v136, v135
	v_fma_f32 v140, -v134, v137, v136
	v_fmac_f32_e32 v137, v140, v135
	v_fma_f32 v134, -v134, v137, v136
	v_div_fmas_f32 v134, v134, v135, v137
	v_div_fixup_f32 v132, v134, v132, v133
	v_add_f32_e32 v131, v162, v132
	v_cmp_gt_f32_e32 vcc, s4, v131
	s_mov_b32 s4, 0x3f317217
	s_nop 0
	v_cndmask_b32_e64 v132, 0, 32, vcc
	v_ldexp_f32 v131, v131, v132
	v_log_f32_e32 v131, v131
	s_nop 0
	v_mul_f32_e32 v132, 0x3f317217, v131
	v_fma_f32 v132, v131, s4, -v132
	v_fmac_f32_e32 v132, 0x3377d1cf, v131
	s_mov_b32 s4, 0x7f800000
	v_fmac_f32_e32 v132, 0x3f317217, v131
	v_cmp_lt_f32_e64 s[12:13], |v131|, s4
	s_nop 1
	v_cndmask_b32_e64 v131, v131, v132, s[12:13]
	v_cndmask_b32_e32 v132, 0, v227, vcc
	v_sub_f32_e32 v131, v131, v132
	v_cvt_pk_bf16_f32 v141, v131, s0
	global_store_short v139, v141, s[72:73] offset:64
	v_mul_f32_e32 v132, 0xbfb8aa3b, v121
	v_exp_f32_e32 v132, v132
	v_sub_f32_e32 v133, 1.0, v163
	v_add_f32_e32 v132, 1.0, v132
	v_div_scale_f32 v134, s[4:5], v132, v132, v133
	v_rcp_f32_e32 v135, v134
	v_div_scale_f32 v136, vcc, v133, v132, v133
	s_mov_b32 s4, 0x800000
	v_fma_f32 v137, -v134, v135, 1.0
	v_fmac_f32_e32 v135, v137, v135
	v_mul_f32_e32 v137, v136, v135
	v_fma_f32 v140, -v134, v137, v136
	v_fmac_f32_e32 v137, v140, v135
	v_fma_f32 v134, -v134, v137, v136
	v_div_fmas_f32 v134, v134, v135, v137
	v_div_fixup_f32 v132, v134, v132, v133
	v_add_f32_e32 v131, v163, v132
	v_cmp_gt_f32_e32 vcc, s4, v131
	s_mov_b32 s4, 0x3f317217
	s_nop 0
	v_cndmask_b32_e64 v132, 0, 32, vcc
	v_ldexp_f32 v131, v131, v132
	v_log_f32_e32 v131, v131
	s_nop 0
	v_mul_f32_e32 v132, 0x3f317217, v131
	v_fma_f32 v132, v131, s4, -v132
	v_fmac_f32_e32 v132, 0x3377d1cf, v131
	s_mov_b32 s4, 0x7f800000
	v_fmac_f32_e32 v132, 0x3f317217, v131
	v_cmp_lt_f32_e64 s[12:13], |v131|, s4
	s_nop 1
	v_cndmask_b32_e64 v131, v131, v132, s[12:13]
	v_cndmask_b32_e32 v132, 0, v227, vcc
	v_sub_f32_e32 v131, v131, v132
	v_cvt_pk_bf16_f32 v141, v131, s0
	global_store_short v139, v141, s[72:73] offset:96
	v_add_u32_e32 v139, 0x1b000, v138
	v_mul_f32_e32 v132, 0xbfb8aa3b, v26
	v_exp_f32_e32 v132, v132
	v_sub_f32_e32 v133, 1.0, v160
	v_add_f32_e32 v132, 1.0, v132
	v_div_scale_f32 v134, s[4:5], v132, v132, v133
	v_rcp_f32_e32 v135, v134
	v_div_scale_f32 v136, vcc, v133, v132, v133
	s_mov_b32 s4, 0x800000
	v_fma_f32 v137, -v134, v135, 1.0
	v_fmac_f32_e32 v135, v137, v135
	v_mul_f32_e32 v137, v136, v135
	v_fma_f32 v140, -v134, v137, v136
	v_fmac_f32_e32 v137, v140, v135
	v_fma_f32 v134, -v134, v137, v136
	v_div_fmas_f32 v134, v134, v135, v137
	v_div_fixup_f32 v132, v134, v132, v133
	v_add_f32_e32 v131, v160, v132
	v_cmp_gt_f32_e32 vcc, s4, v131
	s_mov_b32 s4, 0x3f317217
	s_nop 0
	v_cndmask_b32_e64 v132, 0, 32, vcc
	v_ldexp_f32 v131, v131, v132
	v_log_f32_e32 v131, v131
	s_nop 0
	v_mul_f32_e32 v132, 0x3f317217, v131
	v_fma_f32 v132, v131, s4, -v132
	v_fmac_f32_e32 v132, 0x3377d1cf, v131
	s_mov_b32 s4, 0x7f800000
	v_fmac_f32_e32 v132, 0x3f317217, v131
	v_cmp_lt_f32_e64 s[12:13], |v131|, s4
	s_nop 1
	v_cndmask_b32_e64 v131, v131, v132, s[12:13]
	v_cndmask_b32_e32 v132, 0, v227, vcc
	v_sub_f32_e32 v131, v131, v132
	v_cvt_pk_bf16_f32 v141, v131, s0
	global_store_short v139, v141, s[72:73]
	v_mul_f32_e32 v132, 0xbfb8aa3b, v110
	v_exp_f32_e32 v132, v132
	v_sub_f32_e32 v133, 1.0, v161
	v_add_f32_e32 v132, 1.0, v132
	v_div_scale_f32 v134, s[4:5], v132, v132, v133
	v_rcp_f32_e32 v135, v134
	v_div_scale_f32 v136, vcc, v133, v132, v133
	s_mov_b32 s4, 0x800000
	v_fma_f32 v137, -v134, v135, 1.0
	v_fmac_f32_e32 v135, v137, v135
	v_mul_f32_e32 v137, v136, v135
	v_fma_f32 v140, -v134, v137, v136
; DEV u16 f2bf(float f) { return (u16)(pack2(f, 0.f) & 0xffffu); }
; DEV void phase_win(const Params& P, int l, const u16* __restrict__ xb, const u16* __restrict__ Wt, u16* __restrict__ h, char* smem) {
;     ...
;       for (int ns = 0; ns < 4; ++ns)
; #pragma unroll
;         for (int j = 0; j < 4; ++j) {
;           int row = m0 + wm * 128 + ms * 16 + quad * 4 + j;
;           int col = cb + ns * 16 + l15;
;           float v = acc[ms][ns][j];
;           if (mode == 1) { float lbv = lbp[col - C_HF]; v = __logf(lbv + (1.f - lbv) / (1.f + __expf(-v))); }
;           else if (mode == 2) v = v / (1.f + __expf(-v));
;           h[(size_t)row * HS + col] = f2bf(v);
	v_fmac_f32_e32 v137, v140, v135
	v_fma_f32 v134, -v134, v137, v136
	v_div_fmas_f32 v134, v134, v135, v137
	v_div_fixup_f32 v132, v134, v132, v133
	v_add_f32_e32 v131, v161, v132
	v_cmp_gt_f32_e32 vcc, s4, v131
	s_mov_b32 s4, 0x3f317217
	s_nop 0
	v_cndmask_b32_e64 v132, 0, 32, vcc
	v_ldexp_f32 v131, v131, v132
	v_log_f32_e32 v131, v131
	s_nop 0
	v_mul_f32_e32 v132, 0x3f317217, v131
	v_fma_f32 v132, v131, s4, -v132
	v_fmac_f32_e32 v132, 0x3377d1cf, v131
	s_mov_b32 s4, 0x7f800000
	v_fmac_f32_e32 v132, 0x3f317217, v131
	v_cmp_lt_f32_e64 s[12:13], |v131|, s4
	s_nop 1
	v_cndmask_b32_e64 v131, v131, v132, s[12:13]
	v_cndmask_b32_e32 v132, 0, v227, vcc
	v_sub_f32_e32 v131, v131, v132
	v_cvt_pk_bf16_f32 v141, v131, s0
	global_store_short v139, v141, s[72:73] offset:32
	v_mul_f32_e32 v132, 0xbfb8aa3b, v114
	v_exp_f32_e32 v132, v132
	v_sub_f32_e32 v133, 1.0, v162
	v_add_f32_e32 v132, 1.0, v132
	v_div_scale_f32 v134, s[4:5], v132, v132, v133
	v_rcp_f32_e32 v135, v134
	v_div_scale_f32 v136, vcc, v133, v132, v133
	s_mov_b32 s4, 0x800000
	v_fma_f32 v137, -v134, v135, 1.0
	v_fmac_f32_e32 v135, v137, v135
	v_mul_f32_e32 v137, v136, v135
	v_fma_f32 v140, -v134, v137, v136
	v_fmac_f32_e32 v137, v140, v135
	v_fma_f32 v134, -v134, v137, v136
	v_div_fmas_f32 v134, v134, v135, v137
	v_div_fixup_f32 v132, v134, v132, v133
	v_add_f32_e32 v131, v162, v132
	v_cmp_gt_f32_e32 vcc, s4, v131
	s_mov_b32 s4, 0x3f317217
	s_nop 0
	v_cndmask_b32_e64 v132, 0, 32, vcc
	v_ldexp_f32 v131, v131, v132
	v_log_f32_e32 v131, v131
	s_nop 0
	v_mul_f32_e32 v132, 0x3f317217, v131
	v_fma_f32 v132, v131, s4, -v132
	v_fmac_f32_e32 v132, 0x3377d1cf, v131
	s_mov_b32 s4, 0x7f800000
	v_fmac_f32_e32 v132, 0x3f317217, v131
	v_cmp_lt_f32_e64 s[12:13], |v131|, s4
	s_nop 1
	v_cndmask_b32_e64 v131, v131, v132, s[12:13]
	v_cndmask_b32_e32 v132, 0, v227, vcc
	v_sub_f32_e32 v131, v131, v132
	v_cvt_pk_bf16_f32 v141, v131, s0
	global_store_short v139, v141, s[72:73] offset:64
	v_mul_f32_e32 v132, 0xbfb8aa3b, v106
	v_exp_f32_e32 v132, v132
	v_sub_f32_e32 v133, 1.0, v163
	v_add_f32_e32 v132, 1.0, v132
	v_div_scale_f32 v134, s[4:5], v132, v132, v133
	v_rcp_f32_e32 v135, v134
	v_div_scale_f32 v136, vcc, v133, v132, v133
	s_mov_b32 s4, 0x800000
	v_fma_f32 v137, -v134, v135, 1.0
	v_fmac_f32_e32 v135, v137, v135
	v_mul_f32_e32 v137, v136, v135
	v_fma_f32 v140, -v134, v137, v136
	v_fmac_f32_e32 v137, v140, v135
	v_fma_f32 v134, -v134, v137, v136
	v_div_fmas_f32 v134, v134, v135, v137
	v_div_fixup_f32 v132, v134, v132, v133
	v_add_f32_e32 v131, v163, v132
	v_cmp_gt_f32_e32 vcc, s4, v131
	s_mov_b32 s4, 0x3f317217
	s_nop 0
	v_cndmask_b32_e64 v132, 0, 32, vcc
	v_ldexp_f32 v131, v131, v132
	v_log_f32_e32 v131, v131
	s_nop 0
	v_mul_f32_e32 v132, 0x3f317217, v131
	v_fma_f32 v132, v131, s4, -v132
	v_fmac_f32_e32 v132, 0x3377d1cf, v131
	s_mov_b32 s4, 0x7f800000
	v_fmac_f32_e32 v132, 0x3f317217, v131
	v_cmp_lt_f32_e64 s[12:13], |v131|, s4
	s_nop 1
	v_cndmask_b32_e64 v131, v131, v132, s[12:13]
	v_cndmask_b32_e32 v132, 0, v227, vcc
	v_sub_f32_e32 v131, v131, v132
	v_cvt_pk_bf16_f32 v141, v131, s0
	global_store_short v139, v141, s[72:73] offset:96
	v_add_u32_e32 v139, 0x1cb00, v138
	v_mul_f32_e32 v132, 0xbfb8aa3b, v27
	v_exp_f32_e32 v132, v132
	v_sub_f32_e32 v133, 1.0, v160
	v_add_f32_e32 v132, 1.0, v132
	v_div_scale_f32 v134, s[4:5], v132, v132, v133
	v_rcp_f32_e32 v135, v134
	v_div_scale_f32 v136, vcc, v133, v132, v133
	s_mov_b32 s4, 0x800000
	v_fma_f32 v137, -v134, v135, 1.0
	v_fmac_f32_e32 v135, v137, v135
	v_mul_f32_e32 v137, v136, v135
	v_fma_f32 v140, -v134, v137, v136
	v_fmac_f32_e32 v137, v140, v135
	v_fma_f32 v134, -v134, v137, v136
	v_div_fmas_f32 v134, v134, v135, v137
	v_div_fixup_f32 v132, v134, v132, v133
	v_add_f32_e32 v131, v160, v132
	v_cmp_gt_f32_e32 vcc, s4, v131
	s_mov_b32 s4, 0x3f317217
	s_nop 0
	v_cndmask_b32_e64 v132, 0, 32, vcc
	v_ldexp_f32 v131, v131, v132
	v_log_f32_e32 v131, v131
	s_nop 0
	v_mul_f32_e32 v132, 0x3f317217, v131
	v_fma_f32 v132, v131, s4, -v132
	v_fmac_f32_e32 v132, 0x3377d1cf, v131
	s_mov_b32 s4, 0x7f800000
	v_fmac_f32_e32 v132, 0x3f317217, v131
	v_cmp_lt_f32_e64 s[12:13], |v131|, s4
	s_nop 1
	v_cndmask_b32_e64 v131, v131, v132, s[12:13]
	v_cndmask_b32_e32 v132, 0, v227, vcc
	v_sub_f32_e32 v131, v131, v132
	v_cvt_pk_bf16_f32 v141, v131, s0
	global_store_short v139, v141, s[72:73]
	v_mul_f32_e32 v132, 0xbfb8aa3b, v111
	v_exp_f32_e32 v132, v132
	v_sub_f32_e32 v133, 1.0, v161
	v_add_f32_e32 v132, 1.0, v132
	v_div_scale_f32 v134, s[4:5], v132, v132, v133
	v_rcp_f32_e32 v135, v134
	v_div_scale_f32 v136, vcc, v133, v132, v133
	s_mov_b32 s4, 0x800000
	v_fma_f32 v137, -v134, v135, 1.0
	v_fmac_f32_e32 v135, v137, v135
	v_mul_f32_e32 v137, v136, v135
	v_fma_f32 v140, -v134, v137, v136
	v_fmac_f32_e32 v137, v140, v135
	v_fma_f32 v134, -v134, v137, v136
	v_div_fmas_f32 v134, v134, v135, v137
	v_div_fixup_f32 v132, v134, v132, v133
	v_add_f32_e32 v131, v161, v132
	v_cmp_gt_f32_e32 vcc, s4, v131
	s_mov_b32 s4, 0x3f317217
	s_nop 0
	v_cndmask_b32_e64 v132, 0, 32, vcc
	v_ldexp_f32 v131, v131, v132
	v_log_f32_e32 v131, v131
	s_nop 0
	v_mul_f32_e32 v132, 0x3f317217, v131
	v_fma_f32 v132, v131, s4, -v132
	v_fmac_f32_e32 v132, 0x3377d1cf, v131
	s_mov_b32 s4, 0x7f800000
	v_fmac_f32_e32 v132, 0x3f317217, v131
	v_cmp_lt_f32_e64 s[12:13], |v131|, s4
	s_nop 1
	v_cndmask_b32_e64 v131, v131, v132, s[12:13]
	v_cndmask_b32_e32 v132, 0, v227, vcc
	v_sub_f32_e32 v131, v131, v132
	v_cvt_pk_bf16_f32 v141, v131, s0
	global_store_short v139, v141, s[72:73] offset:32
	v_mul_f32_e32 v132, 0xbfb8aa3b, v115
	v_exp_f32_e32 v132, v132
	v_sub_f32_e32 v133, 1.0, v162
	v_add_f32_e32 v132, 1.0, v132
; DEV u16 f2bf(float f) { return (u16)(pack2(f, 0.f) & 0xffffu); }
; DEV void phase_win(const Params& P, int l, const u16* __restrict__ xb, const u16* __restrict__ Wt, u16* __restrict__ h, char* smem) {
;     ...
;       for (int ns = 0; ns < 4; ++ns)
; #pragma unroll
;         for (int j = 0; j < 4; ++j) {
;           int row = m0 + wm * 128 + ms * 16 + quad * 4 + j;
;           int col = cb + ns * 16 + l15;
;           float v = acc[ms][ns][j];
;           if (mode == 1) { float lbv = lbp[col - C_HF]; v = __logf(lbv + (1.f - lbv) / (1.f + __expf(-v))); }
;           else if (mode == 2) v = v / (1.f + __expf(-v));
;           h[(size_t)row * HS + col] = f2bf(v);
	v_div_scale_f32 v134, s[4:5], v132, v132, v133
	v_rcp_f32_e32 v135, v134
	v_div_scale_f32 v136, vcc, v133, v132, v133
	s_mov_b32 s4, 0x800000
	v_fma_f32 v137, -v134, v135, 1.0
	v_fmac_f32_e32 v135, v137, v135
	v_mul_f32_e32 v137, v136, v135
	v_fma_f32 v140, -v134, v137, v136
	v_fmac_f32_e32 v137, v140, v135
	v_fma_f32 v134, -v134, v137, v136
	v_div_fmas_f32 v134, v134, v135, v137
	v_div_fixup_f32 v132, v134, v132, v133
	v_add_f32_e32 v131, v162, v132
	v_cmp_gt_f32_e32 vcc, s4, v131
	s_mov_b32 s4, 0x3f317217
	s_nop 0
	v_cndmask_b32_e64 v132, 0, 32, vcc
	v_ldexp_f32 v131, v131, v132
	v_log_f32_e32 v131, v131
	s_nop 0
	v_mul_f32_e32 v132, 0x3f317217, v131
	v_fma_f32 v132, v131, s4, -v132
	v_fmac_f32_e32 v132, 0x3377d1cf, v131
	s_mov_b32 s4, 0x7f800000
	v_fmac_f32_e32 v132, 0x3f317217, v131
	v_cmp_lt_f32_e64 s[12:13], |v131|, s4
	s_nop 1
	v_cndmask_b32_e64 v131, v131, v132, s[12:13]
	v_cndmask_b32_e32 v132, 0, v227, vcc
	v_sub_f32_e32 v131, v131, v132
	v_cvt_pk_bf16_f32 v141, v131, s0
	global_store_short v139, v141, s[72:73] offset:64
	v_mul_f32_e32 v132, 0xbfb8aa3b, v107
	v_exp_f32_e32 v132, v132
	v_sub_f32_e32 v133, 1.0, v163
	v_add_f32_e32 v132, 1.0, v132
	v_div_scale_f32 v134, s[4:5], v132, v132, v133
	v_rcp_f32_e32 v135, v134
	v_div_scale_f32 v136, vcc, v133, v132, v133
	s_mov_b32 s4, 0x800000
	v_fma_f32 v137, -v134, v135, 1.0
	v_fmac_f32_e32 v135, v137, v135
	v_mul_f32_e32 v137, v136, v135
	v_fma_f32 v140, -v134, v137, v136
	v_fmac_f32_e32 v137, v140, v135
	v_fma_f32 v134, -v134, v137, v136
	v_div_fmas_f32 v134, v134, v135, v137
	v_div_fixup_f32 v132, v134, v132, v133
	v_add_f32_e32 v131, v163, v132
	v_cmp_gt_f32_e32 vcc, s4, v131
	s_mov_b32 s4, 0x3f317217
	s_nop 0
	v_cndmask_b32_e64 v132, 0, 32, vcc
	v_ldexp_f32 v131, v131, v132
	v_log_f32_e32 v131, v131
	s_nop 0
	v_mul_f32_e32 v132, 0x3f317217, v131
	v_fma_f32 v132, v131, s4, -v132
	v_fmac_f32_e32 v132, 0x3377d1cf, v131
	s_mov_b32 s4, 0x7f800000
	v_fmac_f32_e32 v132, 0x3f317217, v131
	v_cmp_lt_f32_e64 s[12:13], |v131|, s4
	s_nop 1
	v_cndmask_b32_e64 v131, v131, v132, s[12:13]
	v_cndmask_b32_e32 v132, 0, v227, vcc
	v_sub_f32_e32 v131, v131, v132
	v_cvt_pk_bf16_f32 v141, v131, s0
	global_store_short v139, v141, s[72:73] offset:96
	v_add_u32_e32 v139, 0x1e600, v138
	v_mul_f32_e32 v132, 0xbfb8aa3b, v28
	v_exp_f32_e32 v132, v132
	v_sub_f32_e32 v133, 1.0, v160
	v_add_f32_e32 v132, 1.0, v132
	v_div_scale_f32 v134, s[4:5], v132, v132, v133
	v_rcp_f32_e32 v135, v134
	v_div_scale_f32 v136, vcc, v133, v132, v133
	s_mov_b32 s4, 0x800000
	v_fma_f32 v137, -v134, v135, 1.0
	v_fmac_f32_e32 v135, v137, v135
	v_mul_f32_e32 v137, v136, v135
	v_fma_f32 v140, -v134, v137, v136
	v_fmac_f32_e32 v137, v140, v135
	v_fma_f32 v134, -v134, v137, v136
	v_div_fmas_f32 v134, v134, v135, v137
	v_div_fixup_f32 v132, v134, v132, v133
	v_add_f32_e32 v131, v160, v132
	v_cmp_gt_f32_e32 vcc, s4, v131
	s_mov_b32 s4, 0x3f317217
	s_nop 0
	v_cndmask_b32_e64 v132, 0, 32, vcc
	v_ldexp_f32 v131, v131, v132
	v_log_f32_e32 v131, v131
	s_nop 0
	v_mul_f32_e32 v132, 0x3f317217, v131
	v_fma_f32 v132, v131, s4, -v132
	v_fmac_f32_e32 v132, 0x3377d1cf, v131
	s_mov_b32 s4, 0x7f800000
	v_fmac_f32_e32 v132, 0x3f317217, v131
	v_cmp_lt_f32_e64 s[12:13], |v131|, s4
	s_nop 1
	v_cndmask_b32_e64 v131, v131, v132, s[12:13]
	v_cndmask_b32_e32 v132, 0, v227, vcc
	v_sub_f32_e32 v131, v131, v132
	v_cvt_pk_bf16_f32 v141, v131, s0
	global_store_short v139, v141, s[72:73]
	v_mul_f32_e32 v132, 0xbfb8aa3b, v112
	v_exp_f32_e32 v132, v132
	v_sub_f32_e32 v133, 1.0, v161
	v_add_f32_e32 v132, 1.0, v132
	v_div_scale_f32 v134, s[4:5], v132, v132, v133
	v_rcp_f32_e32 v135, v134
	v_div_scale_f32 v136, vcc, v133, v132, v133
	s_mov_b32 s4, 0x800000
	v_fma_f32 v137, -v134, v135, 1.0
	v_fmac_f32_e32 v135, v137, v135
	v_mul_f32_e32 v137, v136, v135
	v_fma_f32 v140, -v134, v137, v136
	v_fmac_f32_e32 v137, v140, v135
	v_fma_f32 v134, -v134, v137, v136
	v_div_fmas_f32 v134, v134, v135, v137
	v_div_fixup_f32 v132, v134, v132, v133
	v_add_f32_e32 v131, v161, v132
	v_cmp_gt_f32_e32 vcc, s4, v131
	s_mov_b32 s4, 0x3f317217
	s_nop 0
	v_cndmask_b32_e64 v132, 0, 32, vcc
	v_ldexp_f32 v131, v131, v132
	v_log_f32_e32 v131, v131
	s_nop 0
	v_mul_f32_e32 v132, 0x3f317217, v131
	v_fma_f32 v132, v131, s4, -v132
	v_fmac_f32_e32 v132, 0x3377d1cf, v131
	s_mov_b32 s4, 0x7f800000
	v_fmac_f32_e32 v132, 0x3f317217, v131
	v_cmp_lt_f32_e64 s[12:13], |v131|, s4
	s_nop 1
	v_cndmask_b32_e64 v131, v131, v132, s[12:13]
	v_cndmask_b32_e32 v132, 0, v227, vcc
	v_sub_f32_e32 v131, v131, v132
	v_cvt_pk_bf16_f32 v141, v131, s0
	global_store_short v139, v141, s[72:73] offset:32
	v_mul_f32_e32 v132, 0xbfb8aa3b, v116
	v_exp_f32_e32 v132, v132
	v_sub_f32_e32 v133, 1.0, v162
	v_add_f32_e32 v132, 1.0, v132
	v_div_scale_f32 v134, s[4:5], v132, v132, v133
	v_rcp_f32_e32 v135, v134
	v_div_scale_f32 v136, vcc, v133, v132, v133
	s_mov_b32 s4, 0x800000
	v_fma_f32 v137, -v134, v135, 1.0
	v_fmac_f32_e32 v135, v137, v135
	v_mul_f32_e32 v137, v136, v135
	v_fma_f32 v140, -v134, v137, v136
	v_fmac_f32_e32 v137, v140, v135
	v_fma_f32 v134, -v134, v137, v136
	v_div_fmas_f32 v134, v134, v135, v137
	v_div_fixup_f32 v132, v134, v132, v133
	v_add_f32_e32 v131, v162, v132
	v_cmp_gt_f32_e32 vcc, s4, v131
	s_mov_b32 s4, 0x3f317217
	s_nop 0
	v_cndmask_b32_e64 v132, 0, 32, vcc
	v_ldexp_f32 v131, v131, v132
	v_log_f32_e32 v131, v131
	s_nop 0
	v_mul_f32_e32 v132, 0x3f317217, v131
	v_fma_f32 v132, v131, s4, -v132
	v_fmac_f32_e32 v132, 0x3377d1cf, v131
	s_mov_b32 s4, 0x7f800000
	v_fmac_f32_e32 v132, 0x3f317217, v131
	v_cmp_lt_f32_e64 s[12:13], |v131|, s4
	s_nop 1
	v_cndmask_b32_e64 v131, v131, v132, s[12:13]
	v_cndmask_b32_e32 v132, 0, v227, vcc
; DEV u16 f2bf(float f) { return (u16)(pack2(f, 0.f) & 0xffffu); }
; DEV void phase_win(const Params& P, int l, const u16* __restrict__ xb, const u16* __restrict__ Wt, u16* __restrict__ h, char* smem) {
;     ...
;       for (int ns = 0; ns < 4; ++ns)
; #pragma unroll
;         for (int j = 0; j < 4; ++j) {
;           int row = m0 + wm * 128 + ms * 16 + quad * 4 + j;
;           int col = cb + ns * 16 + l15;
;           float v = acc[ms][ns][j];
;           if (mode == 1) { float lbv = lbp[col - C_HF]; v = __logf(lbv + (1.f - lbv) / (1.f + __expf(-v))); }
;           else if (mode == 2) v = v / (1.f + __expf(-v));
;           h[(size_t)row * HS + col] = f2bf(v);
	v_sub_f32_e32 v131, v131, v132
	v_cvt_pk_bf16_f32 v141, v131, s0
	global_store_short v139, v141, s[72:73] offset:64
	v_mul_f32_e32 v132, 0xbfb8aa3b, v108
	v_exp_f32_e32 v132, v132
	v_sub_f32_e32 v133, 1.0, v163
	v_add_f32_e32 v132, 1.0, v132
	v_div_scale_f32 v134, s[4:5], v132, v132, v133
	v_rcp_f32_e32 v135, v134
	v_div_scale_f32 v136, vcc, v133, v132, v133
	s_mov_b32 s4, 0x800000
	v_fma_f32 v137, -v134, v135, 1.0
	v_fmac_f32_e32 v135, v137, v135
	v_mul_f32_e32 v137, v136, v135
	v_fma_f32 v140, -v134, v137, v136
	v_fmac_f32_e32 v137, v140, v135
	v_fma_f32 v134, -v134, v137, v136
	v_div_fmas_f32 v134, v134, v135, v137
	v_div_fixup_f32 v132, v134, v132, v133
	v_add_f32_e32 v131, v163, v132
	v_cmp_gt_f32_e32 vcc, s4, v131
	s_mov_b32 s4, 0x3f317217
	s_nop 0
	v_cndmask_b32_e64 v132, 0, 32, vcc
	v_ldexp_f32 v131, v131, v132
	v_log_f32_e32 v131, v131
	s_nop 0
	v_mul_f32_e32 v132, 0x3f317217, v131
	v_fma_f32 v132, v131, s4, -v132
	v_fmac_f32_e32 v132, 0x3377d1cf, v131
	s_mov_b32 s4, 0x7f800000
	v_fmac_f32_e32 v132, 0x3f317217, v131
	v_cmp_lt_f32_e64 s[12:13], |v131|, s4
	s_nop 1
	v_cndmask_b32_e64 v131, v131, v132, s[12:13]
	v_cndmask_b32_e32 v132, 0, v227, vcc
	v_sub_f32_e32 v131, v131, v132
	v_cvt_pk_bf16_f32 v141, v131, s0
	global_store_short v139, v141, s[72:73] offset:96
	v_add_u32_e32 v139, 0x20100, v138
	v_mul_f32_e32 v132, 0xbfb8aa3b, v29
	v_exp_f32_e32 v132, v132
	v_sub_f32_e32 v133, 1.0, v160
	v_add_f32_e32 v132, 1.0, v132
	v_div_scale_f32 v134, s[4:5], v132, v132, v133
	v_rcp_f32_e32 v135, v134
	v_div_scale_f32 v136, vcc, v133, v132, v133
	s_mov_b32 s4, 0x800000
	v_fma_f32 v137, -v134, v135, 1.0
	v_fmac_f32_e32 v135, v137, v135
	v_mul_f32_e32 v137, v136, v135
	v_fma_f32 v140, -v134, v137, v136
	v_fmac_f32_e32 v137, v140, v135
	v_fma_f32 v134, -v134, v137, v136
	v_div_fmas_f32 v134, v134, v135, v137
	v_div_fixup_f32 v132, v134, v132, v133
	v_add_f32_e32 v131, v160, v132
	v_cmp_gt_f32_e32 vcc, s4, v131
	s_mov_b32 s4, 0x3f317217
	s_nop 0
	v_cndmask_b32_e64 v132, 0, 32, vcc
	v_ldexp_f32 v131, v131, v132
	v_log_f32_e32 v131, v131
	s_nop 0
	v_mul_f32_e32 v132, 0x3f317217, v131
	v_fma_f32 v132, v131, s4, -v132
	v_fmac_f32_e32 v132, 0x3377d1cf, v131
	s_mov_b32 s4, 0x7f800000
	v_fmac_f32_e32 v132, 0x3f317217, v131
	v_cmp_lt_f32_e64 s[12:13], |v131|, s4
	s_nop 1
	v_cndmask_b32_e64 v131, v131, v132, s[12:13]
	v_cndmask_b32_e32 v132, 0, v227, vcc
	v_sub_f32_e32 v131, v131, v132
	v_cvt_pk_bf16_f32 v141, v131, s0
	global_store_short v139, v141, s[72:73]
	v_mul_f32_e32 v132, 0xbfb8aa3b, v113
	v_exp_f32_e32 v132, v132
	v_sub_f32_e32 v133, 1.0, v161
	v_add_f32_e32 v132, 1.0, v132
	v_div_scale_f32 v134, s[4:5], v132, v132, v133
	v_rcp_f32_e32 v135, v134
	v_div_scale_f32 v136, vcc, v133, v132, v133
	s_mov_b32 s4, 0x800000
	v_fma_f32 v137, -v134, v135, 1.0
	v_fmac_f32_e32 v135, v137, v135
	v_mul_f32_e32 v137, v136, v135
	v_fma_f32 v140, -v134, v137, v136
	v_fmac_f32_e32 v137, v140, v135
	v_fma_f32 v134, -v134, v137, v136
	v_div_fmas_f32 v134, v134, v135, v137
	v_div_fixup_f32 v132, v134, v132, v133
	v_add_f32_e32 v131, v161, v132
	v_cmp_gt_f32_e32 vcc, s4, v131
	s_mov_b32 s4, 0x3f317217
	s_nop 0
	v_cndmask_b32_e64 v132, 0, 32, vcc
	v_ldexp_f32 v131, v131, v132
	v_log_f32_e32 v131, v131
	s_nop 0
	v_mul_f32_e32 v132, 0x3f317217, v131
	v_fma_f32 v132, v131, s4, -v132
	v_fmac_f32_e32 v132, 0x3377d1cf, v131
	s_mov_b32 s4, 0x7f800000
	v_fmac_f32_e32 v132, 0x3f317217, v131
	v_cmp_lt_f32_e64 s[12:13], |v131|, s4
	s_nop 1
	v_cndmask_b32_e64 v131, v131, v132, s[12:13]
	v_cndmask_b32_e32 v132, 0, v227, vcc
	v_sub_f32_e32 v131, v131, v132
	v_cvt_pk_bf16_f32 v141, v131, s0
	global_store_short v139, v141, s[72:73] offset:32
	v_mul_f32_e32 v132, 0xbfb8aa3b, v117
	v_exp_f32_e32 v132, v132
	v_sub_f32_e32 v133, 1.0, v162
	v_add_f32_e32 v132, 1.0, v132
	v_div_scale_f32 v134, s[4:5], v132, v132, v133
	v_rcp_f32_e32 v135, v134
	v_div_scale_f32 v136, vcc, v133, v132, v133
	s_mov_b32 s4, 0x800000
	v_fma_f32 v137, -v134, v135, 1.0
	v_fmac_f32_e32 v135, v137, v135
	v_mul_f32_e32 v137, v136, v135
	v_fma_f32 v140, -v134, v137, v136
	v_fmac_f32_e32 v137, v140, v135
	v_fma_f32 v134, -v134, v137, v136
	v_div_fmas_f32 v134, v134, v135, v137
	v_div_fixup_f32 v132, v134, v132, v133
	v_add_f32_e32 v131, v162, v132
	v_cmp_gt_f32_e32 vcc, s4, v131
	s_mov_b32 s4, 0x3f317217
	s_nop 0
	v_cndmask_b32_e64 v132, 0, 32, vcc
	v_ldexp_f32 v131, v131, v132
	v_log_f32_e32 v131, v131
	s_nop 0
	v_mul_f32_e32 v132, 0x3f317217, v131
	v_fma_f32 v132, v131, s4, -v132
	v_fmac_f32_e32 v132, 0x3377d1cf, v131
	s_mov_b32 s4, 0x7f800000
	v_fmac_f32_e32 v132, 0x3f317217, v131
	v_cmp_lt_f32_e64 s[12:13], |v131|, s4
	s_nop 1
	v_cndmask_b32_e64 v131, v131, v132, s[12:13]
	v_cndmask_b32_e32 v132, 0, v227, vcc
	v_sub_f32_e32 v131, v131, v132
	v_cvt_pk_bf16_f32 v141, v131, s0
	global_store_short v139, v141, s[72:73] offset:64
	v_mul_f32_e32 v132, 0xbfb8aa3b, v109
	v_exp_f32_e32 v132, v132
	v_sub_f32_e32 v133, 1.0, v163
	v_add_f32_e32 v132, 1.0, v132
	v_div_scale_f32 v134, s[4:5], v132, v132, v133
	v_rcp_f32_e32 v135, v134
	v_div_scale_f32 v136, vcc, v133, v132, v133
	s_mov_b32 s4, 0x800000
	v_fma_f32 v137, -v134, v135, 1.0
	v_fmac_f32_e32 v135, v137, v135
	v_mul_f32_e32 v137, v136, v135
	v_fma_f32 v140, -v134, v137, v136
	v_fmac_f32_e32 v137, v140, v135
	v_fma_f32 v134, -v134, v137, v136
	v_div_fmas_f32 v134, v134, v135, v137
	v_div_fixup_f32 v132, v134, v132, v133
	v_add_f32_e32 v131, v163, v132
	v_cmp_gt_f32_e32 vcc, s4, v131
	s_mov_b32 s4, 0x3f317217
	s_nop 0
	v_cndmask_b32_e64 v132, 0, 32, vcc
	v_ldexp_f32 v131, v131, v132
	v_log_f32_e32 v131, v131
	s_nop 0
	v_mul_f32_e32 v132, 0x3f317217, v131
; DEV u16 f2bf(float f) { return (u16)(pack2(f, 0.f) & 0xffffu); }
; DEV void phase_win(const Params& P, int l, const u16* __restrict__ xb, const u16* __restrict__ Wt, u16* __restrict__ h, char* smem) {
;     ...
;       for (int ns = 0; ns < 4; ++ns)
; #pragma unroll
;         for (int j = 0; j < 4; ++j) {
;           int row = m0 + wm * 128 + ms * 16 + quad * 4 + j;
;           int col = cb + ns * 16 + l15;
;           float v = acc[ms][ns][j];
;           if (mode == 1) { float lbv = lbp[col - C_HF]; v = __logf(lbv + (1.f - lbv) / (1.f + __expf(-v))); }
;           else if (mode == 2) v = v / (1.f + __expf(-v));
;           h[(size_t)row * HS + col] = f2bf(v);
	v_fma_f32 v132, v131, s4, -v132
	v_fmac_f32_e32 v132, 0x3377d1cf, v131
	s_mov_b32 s4, 0x7f800000
	v_fmac_f32_e32 v132, 0x3f317217, v131
	v_cmp_lt_f32_e64 s[12:13], |v131|, s4
	s_nop 1
	v_cndmask_b32_e64 v131, v131, v132, s[12:13]
	v_cndmask_b32_e32 v132, 0, v227, vcc
	v_sub_f32_e32 v131, v131, v132
	v_cvt_pk_bf16_f32 v141, v131, s0
	global_store_short v139, v141, s[72:73] offset:96
	v_add_u32_e32 v139, 0x36000, v138
	v_mul_f32_e32 v132, 0xbfb8aa3b, v22
	v_exp_f32_e32 v132, v132
	v_sub_f32_e32 v133, 1.0, v160
	v_add_f32_e32 v132, 1.0, v132
	v_div_scale_f32 v134, s[4:5], v132, v132, v133
	v_rcp_f32_e32 v135, v134
	v_div_scale_f32 v136, vcc, v133, v132, v133
	s_mov_b32 s4, 0x800000
	v_fma_f32 v137, -v134, v135, 1.0
	v_fmac_f32_e32 v135, v137, v135
	v_mul_f32_e32 v137, v136, v135
	v_fma_f32 v140, -v134, v137, v136
	v_fmac_f32_e32 v137, v140, v135
	v_fma_f32 v134, -v134, v137, v136
	v_div_fmas_f32 v134, v134, v135, v137
	v_div_fixup_f32 v132, v134, v132, v133
	v_add_f32_e32 v131, v160, v132
	v_cmp_gt_f32_e32 vcc, s4, v131
	s_mov_b32 s4, 0x3f317217
	s_nop 0
	v_cndmask_b32_e64 v132, 0, 32, vcc
	v_ldexp_f32 v131, v131, v132
	v_log_f32_e32 v131, v131
	s_nop 0
	v_mul_f32_e32 v132, 0x3f317217, v131
	v_fma_f32 v132, v131, s4, -v132
	v_fmac_f32_e32 v132, 0x3377d1cf, v131
	s_mov_b32 s4, 0x7f800000
	v_fmac_f32_e32 v132, 0x3f317217, v131
	v_cmp_lt_f32_e64 s[12:13], |v131|, s4
	s_nop 1
	v_cndmask_b32_e64 v131, v131, v132, s[12:13]
	v_cndmask_b32_e32 v132, 0, v227, vcc
	v_sub_f32_e32 v131, v131, v132
	v_cvt_pk_bf16_f32 v141, v131, s0
	global_store_short v139, v141, s[72:73]
	v_mul_f32_e32 v132, 0xbfb8aa3b, v98
	v_exp_f32_e32 v132, v132
	v_sub_f32_e32 v133, 1.0, v161
	v_add_f32_e32 v132, 1.0, v132
	v_div_scale_f32 v134, s[4:5], v132, v132, v133
	v_rcp_f32_e32 v135, v134
	v_div_scale_f32 v136, vcc, v133, v132, v133
	s_mov_b32 s4, 0x800000
	v_fma_f32 v137, -v134, v135, 1.0
	v_fmac_f32_e32 v135, v137, v135
	v_mul_f32_e32 v137, v136, v135
	v_fma_f32 v140, -v134, v137, v136
	v_fmac_f32_e32 v137, v140, v135
	v_fma_f32 v134, -v134, v137, v136
	v_div_fmas_f32 v134, v134, v135, v137
	v_div_fixup_f32 v132, v134, v132, v133
	v_add_f32_e32 v131, v161, v132
	v_cmp_gt_f32_e32 vcc, s4, v131
	s_mov_b32 s4, 0x3f317217
	s_nop 0
	v_cndmask_b32_e64 v132, 0, 32, vcc
	v_ldexp_f32 v131, v131, v132
	v_log_f32_e32 v131, v131
	s_nop 0
	v_mul_f32_e32 v132, 0x3f317217, v131
	v_fma_f32 v132, v131, s4, -v132
	v_fmac_f32_e32 v132, 0x3377d1cf, v131
	s_mov_b32 s4, 0x7f800000
	v_fmac_f32_e32 v132, 0x3f317217, v131
	v_cmp_lt_f32_e64 s[12:13], |v131|, s4
	s_nop 1
	v_cndmask_b32_e64 v131, v131, v132, s[12:13]
	v_cndmask_b32_e32 v132, 0, v227, vcc
	v_sub_f32_e32 v131, v131, v132
	v_cvt_pk_bf16_f32 v141, v131, s0
	global_store_short v139, v141, s[72:73] offset:32
	v_mul_f32_e32 v132, 0xbfb8aa3b, v102
	v_exp_f32_e32 v132, v132
	v_sub_f32_e32 v133, 1.0, v162
	v_add_f32_e32 v132, 1.0, v132
	v_div_scale_f32 v134, s[4:5], v132, v132, v133
	v_rcp_f32_e32 v135, v134
	v_div_scale_f32 v136, vcc, v133, v132, v133
	s_mov_b32 s4, 0x800000
	v_fma_f32 v137, -v134, v135, 1.0
	v_fmac_f32_e32 v135, v137, v135
	v_mul_f32_e32 v137, v136, v135
	v_fma_f32 v140, -v134, v137, v136
	v_fmac_f32_e32 v137, v140, v135
	v_fma_f32 v134, -v134, v137, v136
	v_div_fmas_f32 v134, v134, v135, v137
	v_div_fixup_f32 v132, v134, v132, v133
	v_add_f32_e32 v131, v162, v132
	v_cmp_gt_f32_e32 vcc, s4, v131
	s_mov_b32 s4, 0x3f317217
	s_nop 0
	v_cndmask_b32_e64 v132, 0, 32, vcc
	v_ldexp_f32 v131, v131, v132
	v_log_f32_e32 v131, v131
	s_nop 0
	v_mul_f32_e32 v132, 0x3f317217, v131
	v_fma_f32 v132, v131, s4, -v132
	v_fmac_f32_e32 v132, 0x3377d1cf, v131
	s_mov_b32 s4, 0x7f800000
	v_fmac_f32_e32 v132, 0x3f317217, v131
	v_cmp_lt_f32_e64 s[12:13], |v131|, s4
	s_nop 1
	v_cndmask_b32_e64 v131, v131, v132, s[12:13]
	v_cndmask_b32_e32 v132, 0, v227, vcc
	v_sub_f32_e32 v131, v131, v132
	v_cvt_pk_bf16_f32 v141, v131, s0
	global_store_short v139, v141, s[72:73] offset:64
	v_mul_f32_e32 v132, 0xbfb8aa3b, v94
	v_exp_f32_e32 v132, v132
	v_sub_f32_e32 v133, 1.0, v163
	v_add_f32_e32 v132, 1.0, v132
	v_div_scale_f32 v134, s[4:5], v132, v132, v133
	v_rcp_f32_e32 v135, v134
	v_div_scale_f32 v136, vcc, v133, v132, v133
	s_mov_b32 s4, 0x800000
	v_fma_f32 v137, -v134, v135, 1.0
	v_fmac_f32_e32 v135, v137, v135
	v_mul_f32_e32 v137, v136, v135
	v_fma_f32 v140, -v134, v137, v136
	v_fmac_f32_e32 v137, v140, v135
	v_fma_f32 v134, -v134, v137, v136
	v_div_fmas_f32 v134, v134, v135, v137
	v_div_fixup_f32 v132, v134, v132, v133
	v_add_f32_e32 v131, v163, v132
	v_cmp_gt_f32_e32 vcc, s4, v131
	s_mov_b32 s4, 0x3f317217
	s_nop 0
	v_cndmask_b32_e64 v132, 0, 32, vcc
	v_ldexp_f32 v131, v131, v132
	v_log_f32_e32 v131, v131
	s_nop 0
	v_mul_f32_e32 v132, 0x3f317217, v131
	v_fma_f32 v132, v131, s4, -v132
	v_fmac_f32_e32 v132, 0x3377d1cf, v131
	s_mov_b32 s4, 0x7f800000
	v_fmac_f32_e32 v132, 0x3f317217, v131
	v_cmp_lt_f32_e64 s[12:13], |v131|, s4
	s_nop 1
	v_cndmask_b32_e64 v131, v131, v132, s[12:13]
	v_cndmask_b32_e32 v132, 0, v227, vcc
	v_sub_f32_e32 v131, v131, v132
	v_cvt_pk_bf16_f32 v141, v131, s0
	global_store_short v139, v141, s[72:73] offset:96
	v_add_u32_e32 v139, 0x37b00, v138
	v_mul_f32_e32 v132, 0xbfb8aa3b, v23
	v_exp_f32_e32 v132, v132
	v_sub_f32_e32 v133, 1.0, v160
	v_add_f32_e32 v132, 1.0, v132
	v_div_scale_f32 v134, s[4:5], v132, v132, v133
	v_rcp_f32_e32 v135, v134
	v_div_scale_f32 v136, vcc, v133, v132, v133
	s_mov_b32 s4, 0x800000
	v_fma_f32 v137, -v134, v135, 1.0
	v_fmac_f32_e32 v135, v137, v135
	v_mul_f32_e32 v137, v136, v135
	v_fma_f32 v140, -v134, v137, v136
	v_fmac_f32_e32 v137, v140, v135
	v_fma_f32 v134, -v134, v137, v136
	v_div_fmas_f32 v134, v134, v135, v137
; DEV u16 f2bf(float f) { return (u16)(pack2(f, 0.f) & 0xffffu); }
; DEV void phase_win(const Params& P, int l, const u16* __restrict__ xb, const u16* __restrict__ Wt, u16* __restrict__ h, char* smem) {
;     ...
;       for (int ns = 0; ns < 4; ++ns)
; #pragma unroll
;         for (int j = 0; j < 4; ++j) {
;           int row = m0 + wm * 128 + ms * 16 + quad * 4 + j;
;           int col = cb + ns * 16 + l15;
;           float v = acc[ms][ns][j];
;           if (mode == 1) { float lbv = lbp[col - C_HF]; v = __logf(lbv + (1.f - lbv) / (1.f + __expf(-v))); }
;           else if (mode == 2) v = v / (1.f + __expf(-v));
;           h[(size_t)row * HS + col] = f2bf(v);
	v_div_fixup_f32 v132, v134, v132, v133
	v_add_f32_e32 v131, v160, v132
	v_cmp_gt_f32_e32 vcc, s4, v131
	s_mov_b32 s4, 0x3f317217
	s_nop 0
	v_cndmask_b32_e64 v132, 0, 32, vcc
	v_ldexp_f32 v131, v131, v132
	v_log_f32_e32 v131, v131
	s_nop 0
	v_mul_f32_e32 v132, 0x3f317217, v131
	v_fma_f32 v132, v131, s4, -v132
	v_fmac_f32_e32 v132, 0x3377d1cf, v131
	s_mov_b32 s4, 0x7f800000
	v_fmac_f32_e32 v132, 0x3f317217, v131
	v_cmp_lt_f32_e64 s[12:13], |v131|, s4
	s_nop 1
	v_cndmask_b32_e64 v131, v131, v132, s[12:13]
	v_cndmask_b32_e32 v132, 0, v227, vcc
	v_sub_f32_e32 v131, v131, v132
	v_cvt_pk_bf16_f32 v141, v131, s0
	global_store_short v139, v141, s[72:73]
	v_mul_f32_e32 v132, 0xbfb8aa3b, v99
	v_exp_f32_e32 v132, v132
	v_sub_f32_e32 v133, 1.0, v161
	v_add_f32_e32 v132, 1.0, v132
	v_div_scale_f32 v134, s[4:5], v132, v132, v133
	v_rcp_f32_e32 v135, v134
	v_div_scale_f32 v136, vcc, v133, v132, v133
	s_mov_b32 s4, 0x800000
	v_fma_f32 v137, -v134, v135, 1.0
	v_fmac_f32_e32 v135, v137, v135
	v_mul_f32_e32 v137, v136, v135
	v_fma_f32 v140, -v134, v137, v136
	v_fmac_f32_e32 v137, v140, v135
	v_fma_f32 v134, -v134, v137, v136
	v_div_fmas_f32 v134, v134, v135, v137
	v_div_fixup_f32 v132, v134, v132, v133
	v_add_f32_e32 v131, v161, v132
	v_cmp_gt_f32_e32 vcc, s4, v131
	s_mov_b32 s4, 0x3f317217
	s_nop 0
	v_cndmask_b32_e64 v132, 0, 32, vcc
	v_ldexp_f32 v131, v131, v132
	v_log_f32_e32 v131, v131
	s_nop 0
	v_mul_f32_e32 v132, 0x3f317217, v131
	v_fma_f32 v132, v131, s4, -v132
	v_fmac_f32_e32 v132, 0x3377d1cf, v131
	s_mov_b32 s4, 0x7f800000
	v_fmac_f32_e32 v132, 0x3f317217, v131
	v_cmp_lt_f32_e64 s[12:13], |v131|, s4
	s_nop 1
	v_cndmask_b32_e64 v131, v131, v132, s[12:13]
	v_cndmask_b32_e32 v132, 0, v227, vcc
	v_sub_f32_e32 v131, v131, v132
	v_cvt_pk_bf16_f32 v141, v131, s0
	global_store_short v139, v141, s[72:73] offset:32
	v_mul_f32_e32 v132, 0xbfb8aa3b, v103
	v_exp_f32_e32 v132, v132
	v_sub_f32_e32 v133, 1.0, v162
	v_add_f32_e32 v132, 1.0, v132
	v_div_scale_f32 v134, s[4:5], v132, v132, v133
	v_rcp_f32_e32 v135, v134
	v_div_scale_f32 v136, vcc, v133, v132, v133
	s_mov_b32 s4, 0x800000
	v_fma_f32 v137, -v134, v135, 1.0
	v_fmac_f32_e32 v135, v137, v135
	v_mul_f32_e32 v137, v136, v135
	v_fma_f32 v140, -v134, v137, v136
	v_fmac_f32_e32 v137, v140, v135
	v_fma_f32 v134, -v134, v137, v136
	v_div_fmas_f32 v134, v134, v135, v137
	v_div_fixup_f32 v132, v134, v132, v133
	v_add_f32_e32 v131, v162, v132
	v_cmp_gt_f32_e32 vcc, s4, v131
	s_mov_b32 s4, 0x3f317217
	s_nop 0
	v_cndmask_b32_e64 v132, 0, 32, vcc
	v_ldexp_f32 v131, v131, v132
	v_log_f32_e32 v131, v131
	s_nop 0
	v_mul_f32_e32 v132, 0x3f317217, v131
	v_fma_f32 v132, v131, s4, -v132
	v_fmac_f32_e32 v132, 0x3377d1cf, v131
	s_mov_b32 s4, 0x7f800000
	v_fmac_f32_e32 v132, 0x3f317217, v131
	v_cmp_lt_f32_e64 s[12:13], |v131|, s4
	s_nop 1
	v_cndmask_b32_e64 v131, v131, v132, s[12:13]
	v_cndmask_b32_e32 v132, 0, v227, vcc
	v_sub_f32_e32 v131, v131, v132
	v_cvt_pk_bf16_f32 v141, v131, s0
	global_store_short v139, v141, s[72:73] offset:64
	v_mul_f32_e32 v132, 0xbfb8aa3b, v95
	v_exp_f32_e32 v132, v132
	v_sub_f32_e32 v133, 1.0, v163
	v_add_f32_e32 v132, 1.0, v132
	v_div_scale_f32 v134, s[4:5], v132, v132, v133
	v_rcp_f32_e32 v135, v134
	v_div_scale_f32 v136, vcc, v133, v132, v133
	s_mov_b32 s4, 0x800000
	v_fma_f32 v137, -v134, v135, 1.0
	v_fmac_f32_e32 v135, v137, v135
	v_mul_f32_e32 v137, v136, v135
	v_fma_f32 v140, -v134, v137, v136
	v_fmac_f32_e32 v137, v140, v135
	v_fma_f32 v134, -v134, v137, v136
	v_div_fmas_f32 v134, v134, v135, v137
	v_div_fixup_f32 v132, v134, v132, v133
	v_add_f32_e32 v131, v163, v132
	v_cmp_gt_f32_e32 vcc, s4, v131
	s_mov_b32 s4, 0x3f317217
	s_nop 0
	v_cndmask_b32_e64 v132, 0, 32, vcc
	v_ldexp_f32 v131, v131, v132
	v_log_f32_e32 v131, v131
	s_nop 0
	v_mul_f32_e32 v132, 0x3f317217, v131
	v_fma_f32 v132, v131, s4, -v132
	v_fmac_f32_e32 v132, 0x3377d1cf, v131
	s_mov_b32 s4, 0x7f800000
	v_fmac_f32_e32 v132, 0x3f317217, v131
	v_cmp_lt_f32_e64 s[12:13], |v131|, s4
	s_nop 1
	v_cndmask_b32_e64 v131, v131, v132, s[12:13]
	v_cndmask_b32_e32 v132, 0, v227, vcc
	v_sub_f32_e32 v131, v131, v132
	v_cvt_pk_bf16_f32 v141, v131, s0
	global_store_short v139, v141, s[72:73] offset:96
	v_add_u32_e32 v139, 0x39600, v138
	v_mul_f32_e32 v132, 0xbfb8aa3b, v24
	v_exp_f32_e32 v132, v132
	v_sub_f32_e32 v133, 1.0, v160
	v_add_f32_e32 v132, 1.0, v132
	v_div_scale_f32 v134, s[4:5], v132, v132, v133
	v_rcp_f32_e32 v135, v134
	v_div_scale_f32 v136, vcc, v133, v132, v133
	s_mov_b32 s4, 0x800000
	v_fma_f32 v137, -v134, v135, 1.0
	v_fmac_f32_e32 v135, v137, v135
	v_mul_f32_e32 v137, v136, v135
	v_fma_f32 v140, -v134, v137, v136
	v_fmac_f32_e32 v137, v140, v135
	v_fma_f32 v134, -v134, v137, v136
	v_div_fmas_f32 v134, v134, v135, v137
	v_div_fixup_f32 v132, v134, v132, v133
	v_add_f32_e32 v131, v160, v132
	v_cmp_gt_f32_e32 vcc, s4, v131
	s_mov_b32 s4, 0x3f317217
	s_nop 0
	v_cndmask_b32_e64 v132, 0, 32, vcc
	v_ldexp_f32 v131, v131, v132
	v_log_f32_e32 v131, v131
	s_nop 0
	v_mul_f32_e32 v132, 0x3f317217, v131
	v_fma_f32 v132, v131, s4, -v132
	v_fmac_f32_e32 v132, 0x3377d1cf, v131
	s_mov_b32 s4, 0x7f800000
	v_fmac_f32_e32 v132, 0x3f317217, v131
	v_cmp_lt_f32_e64 s[12:13], |v131|, s4
	s_nop 1
	v_cndmask_b32_e64 v131, v131, v132, s[12:13]
	v_cndmask_b32_e32 v132, 0, v227, vcc
	v_sub_f32_e32 v131, v131, v132
	v_cvt_pk_bf16_f32 v141, v131, s0
	global_store_short v139, v141, s[72:73]
	v_mul_f32_e32 v132, 0xbfb8aa3b, v100
	v_exp_f32_e32 v132, v132
	v_sub_f32_e32 v133, 1.0, v161
	v_add_f32_e32 v132, 1.0, v132
	v_div_scale_f32 v134, s[4:5], v132, v132, v133
	v_rcp_f32_e32 v135, v134
	v_div_scale_f32 v136, vcc, v133, v132, v133
	s_mov_b32 s4, 0x800000
; DEV u16 f2bf(float f) { return (u16)(pack2(f, 0.f) & 0xffffu); }
; DEV void phase_win(const Params& P, int l, const u16* __restrict__ xb, const u16* __restrict__ Wt, u16* __restrict__ h, char* smem) {
;     ...
;       for (int ns = 0; ns < 4; ++ns)
; #pragma unroll
;         for (int j = 0; j < 4; ++j) {
;           int row = m0 + wm * 128 + ms * 16 + quad * 4 + j;
;           int col = cb + ns * 16 + l15;
;           float v = acc[ms][ns][j];
;           if (mode == 1) { float lbv = lbp[col - C_HF]; v = __logf(lbv + (1.f - lbv) / (1.f + __expf(-v))); }
;           else if (mode == 2) v = v / (1.f + __expf(-v));
;           h[(size_t)row * HS + col] = f2bf(v);
	v_fma_f32 v137, -v134, v135, 1.0
	v_fmac_f32_e32 v135, v137, v135
	v_mul_f32_e32 v137, v136, v135
	v_fma_f32 v140, -v134, v137, v136
	v_fmac_f32_e32 v137, v140, v135
	v_fma_f32 v134, -v134, v137, v136
	v_div_fmas_f32 v134, v134, v135, v137
	v_div_fixup_f32 v132, v134, v132, v133
	v_add_f32_e32 v131, v161, v132
	v_cmp_gt_f32_e32 vcc, s4, v131
	s_mov_b32 s4, 0x3f317217
	s_nop 0
	v_cndmask_b32_e64 v132, 0, 32, vcc
	v_ldexp_f32 v131, v131, v132
	v_log_f32_e32 v131, v131
	s_nop 0
	v_mul_f32_e32 v132, 0x3f317217, v131
	v_fma_f32 v132, v131, s4, -v132
	v_fmac_f32_e32 v132, 0x3377d1cf, v131
	s_mov_b32 s4, 0x7f800000
	v_fmac_f32_e32 v132, 0x3f317217, v131
	v_cmp_lt_f32_e64 s[12:13], |v131|, s4
	s_nop 1
	v_cndmask_b32_e64 v131, v131, v132, s[12:13]
	v_cndmask_b32_e32 v132, 0, v227, vcc
	v_sub_f32_e32 v131, v131, v132
	v_cvt_pk_bf16_f32 v141, v131, s0
	global_store_short v139, v141, s[72:73] offset:32
	v_mul_f32_e32 v132, 0xbfb8aa3b, v104
	v_exp_f32_e32 v132, v132
	v_sub_f32_e32 v133, 1.0, v162
	v_add_f32_e32 v132, 1.0, v132
	v_div_scale_f32 v134, s[4:5], v132, v132, v133
	v_rcp_f32_e32 v135, v134
	v_div_scale_f32 v136, vcc, v133, v132, v133
	s_mov_b32 s4, 0x800000
	v_fma_f32 v137, -v134, v135, 1.0
	v_fmac_f32_e32 v135, v137, v135
	v_mul_f32_e32 v137, v136, v135
	v_fma_f32 v140, -v134, v137, v136
	v_fmac_f32_e32 v137, v140, v135
	v_fma_f32 v134, -v134, v137, v136
	v_div_fmas_f32 v134, v134, v135, v137
	v_div_fixup_f32 v132, v134, v132, v133
	v_add_f32_e32 v131, v162, v132
	v_cmp_gt_f32_e32 vcc, s4, v131
	s_mov_b32 s4, 0x3f317217
	s_nop 0
	v_cndmask_b32_e64 v132, 0, 32, vcc
	v_ldexp_f32 v131, v131, v132
	v_log_f32_e32 v131, v131
	s_nop 0
	v_mul_f32_e32 v132, 0x3f317217, v131
	v_fma_f32 v132, v131, s4, -v132
	v_fmac_f32_e32 v132, 0x3377d1cf, v131
	s_mov_b32 s4, 0x7f800000
	v_fmac_f32_e32 v132, 0x3f317217, v131
	v_cmp_lt_f32_e64 s[12:13], |v131|, s4
	s_nop 1
	v_cndmask_b32_e64 v131, v131, v132, s[12:13]
	v_cndmask_b32_e32 v132, 0, v227, vcc
	v_sub_f32_e32 v131, v131, v132
	v_cvt_pk_bf16_f32 v141, v131, s0
	global_store_short v139, v141, s[72:73] offset:64
	v_mul_f32_e32 v132, 0xbfb8aa3b, v96
	v_exp_f32_e32 v132, v132
	v_sub_f32_e32 v133, 1.0, v163
	v_add_f32_e32 v132, 1.0, v132
	v_div_scale_f32 v134, s[4:5], v132, v132, v133
	v_rcp_f32_e32 v135, v134
	v_div_scale_f32 v136, vcc, v133, v132, v133
	s_mov_b32 s4, 0x800000
	v_fma_f32 v137, -v134, v135, 1.0
	v_fmac_f32_e32 v135, v137, v135
	v_mul_f32_e32 v137, v136, v135
	v_fma_f32 v140, -v134, v137, v136
	v_fmac_f32_e32 v137, v140, v135
	v_fma_f32 v134, -v134, v137, v136
	v_div_fmas_f32 v134, v134, v135, v137
	v_div_fixup_f32 v132, v134, v132, v133
	v_add_f32_e32 v131, v163, v132
	v_cmp_gt_f32_e32 vcc, s4, v131
	s_mov_b32 s4, 0x3f317217
	s_nop 0
	v_cndmask_b32_e64 v132, 0, 32, vcc
	v_ldexp_f32 v131, v131, v132
	v_log_f32_e32 v131, v131
	s_nop 0
	v_mul_f32_e32 v132, 0x3f317217, v131
	v_fma_f32 v132, v131, s4, -v132
	v_fmac_f32_e32 v132, 0x3377d1cf, v131
	s_mov_b32 s4, 0x7f800000
	v_fmac_f32_e32 v132, 0x3f317217, v131
	v_cmp_lt_f32_e64 s[12:13], |v131|, s4
	s_nop 1
	v_cndmask_b32_e64 v131, v131, v132, s[12:13]
	v_cndmask_b32_e32 v132, 0, v227, vcc
	v_sub_f32_e32 v131, v131, v132
	v_cvt_pk_bf16_f32 v141, v131, s0
	global_store_short v139, v141, s[72:73] offset:96
	v_add_u32_e32 v139, 0x3b100, v138
	v_mul_f32_e32 v132, 0xbfb8aa3b, v25
	v_exp_f32_e32 v132, v132
	v_sub_f32_e32 v133, 1.0, v160
	v_add_f32_e32 v132, 1.0, v132
	v_div_scale_f32 v134, s[4:5], v132, v132, v133
	v_rcp_f32_e32 v135, v134
	v_div_scale_f32 v136, vcc, v133, v132, v133
	s_mov_b32 s4, 0x800000
	v_fma_f32 v137, -v134, v135, 1.0
	v_fmac_f32_e32 v135, v137, v135
	v_mul_f32_e32 v137, v136, v135
	v_fma_f32 v140, -v134, v137, v136
	v_fmac_f32_e32 v137, v140, v135
	v_fma_f32 v134, -v134, v137, v136
	v_div_fmas_f32 v134, v134, v135, v137
	v_div_fixup_f32 v132, v134, v132, v133
	v_add_f32_e32 v131, v160, v132
	v_cmp_gt_f32_e32 vcc, s4, v131
	s_mov_b32 s4, 0x3f317217
	s_nop 0
	v_cndmask_b32_e64 v132, 0, 32, vcc
	v_ldexp_f32 v131, v131, v132
	v_log_f32_e32 v131, v131
	s_nop 0
	v_mul_f32_e32 v132, 0x3f317217, v131
	v_fma_f32 v132, v131, s4, -v132
	v_fmac_f32_e32 v132, 0x3377d1cf, v131
	s_mov_b32 s4, 0x7f800000
	v_fmac_f32_e32 v132, 0x3f317217, v131
	v_cmp_lt_f32_e64 s[12:13], |v131|, s4
	s_nop 1
	v_cndmask_b32_e64 v131, v131, v132, s[12:13]
	v_cndmask_b32_e32 v132, 0, v227, vcc
	v_sub_f32_e32 v131, v131, v132
	v_cvt_pk_bf16_f32 v141, v131, s0
	global_store_short v139, v141, s[72:73]
	v_mul_f32_e32 v132, 0xbfb8aa3b, v101
	v_exp_f32_e32 v132, v132
	v_sub_f32_e32 v133, 1.0, v161
	v_add_f32_e32 v132, 1.0, v132
	v_div_scale_f32 v134, s[4:5], v132, v132, v133
	v_rcp_f32_e32 v135, v134
	v_div_scale_f32 v136, vcc, v133, v132, v133
	s_mov_b32 s4, 0x800000
	v_fma_f32 v137, -v134, v135, 1.0
	v_fmac_f32_e32 v135, v137, v135
	v_mul_f32_e32 v137, v136, v135
	v_fma_f32 v140, -v134, v137, v136
	v_fmac_f32_e32 v137, v140, v135
	v_fma_f32 v134, -v134, v137, v136
	v_div_fmas_f32 v134, v134, v135, v137
	v_div_fixup_f32 v132, v134, v132, v133
	v_add_f32_e32 v131, v161, v132
	v_cmp_gt_f32_e32 vcc, s4, v131
	s_mov_b32 s4, 0x3f317217
	s_nop 0
	v_cndmask_b32_e64 v132, 0, 32, vcc
	v_ldexp_f32 v131, v131, v132
	v_log_f32_e32 v131, v131
	s_nop 0
	v_mul_f32_e32 v132, 0x3f317217, v131
	v_fma_f32 v132, v131, s4, -v132
	v_fmac_f32_e32 v132, 0x3377d1cf, v131
	s_mov_b32 s4, 0x7f800000
	v_fmac_f32_e32 v132, 0x3f317217, v131
	v_cmp_lt_f32_e64 s[12:13], |v131|, s4
	s_nop 1
	v_cndmask_b32_e64 v131, v131, v132, s[12:13]
	v_cndmask_b32_e32 v132, 0, v227, vcc
	v_sub_f32_e32 v131, v131, v132
	v_cvt_pk_bf16_f32 v141, v131, s0
	global_store_short v139, v141, s[72:73] offset:32
; DEV u16 f2bf(float f) { return (u16)(pack2(f, 0.f) & 0xffffu); }
; DEV void phase_win(const Params& P, int l, const u16* __restrict__ xb, const u16* __restrict__ Wt, u16* __restrict__ h, char* smem) {
;     ...
;       for (int ns = 0; ns < 4; ++ns)
; #pragma unroll
;         for (int j = 0; j < 4; ++j) {
;           int row = m0 + wm * 128 + ms * 16 + quad * 4 + j;
;           int col = cb + ns * 16 + l15;
;           float v = acc[ms][ns][j];
;           if (mode == 1) { float lbv = lbp[col - C_HF]; v = __logf(lbv + (1.f - lbv) / (1.f + __expf(-v))); }
;           else if (mode == 2) v = v / (1.f + __expf(-v));
;           h[(size_t)row * HS + col] = f2bf(v);
	v_mul_f32_e32 v132, 0xbfb8aa3b, v105
	v_exp_f32_e32 v132, v132
	v_sub_f32_e32 v133, 1.0, v162
	v_add_f32_e32 v132, 1.0, v132
	v_div_scale_f32 v134, s[4:5], v132, v132, v133
	v_rcp_f32_e32 v135, v134
	v_div_scale_f32 v136, vcc, v133, v132, v133
	s_mov_b32 s4, 0x800000
	v_fma_f32 v137, -v134, v135, 1.0
	v_fmac_f32_e32 v135, v137, v135
	v_mul_f32_e32 v137, v136, v135
	v_fma_f32 v140, -v134, v137, v136
	v_fmac_f32_e32 v137, v140, v135
	v_fma_f32 v134, -v134, v137, v136
	v_div_fmas_f32 v134, v134, v135, v137
	v_div_fixup_f32 v132, v134, v132, v133
	v_add_f32_e32 v131, v162, v132
	v_cmp_gt_f32_e32 vcc, s4, v131
	s_mov_b32 s4, 0x3f317217
	s_nop 0
	v_cndmask_b32_e64 v132, 0, 32, vcc
	v_ldexp_f32 v131, v131, v132
	v_log_f32_e32 v131, v131
	s_nop 0
	v_mul_f32_e32 v132, 0x3f317217, v131
	v_fma_f32 v132, v131, s4, -v132
	v_fmac_f32_e32 v132, 0x3377d1cf, v131
	s_mov_b32 s4, 0x7f800000
	v_fmac_f32_e32 v132, 0x3f317217, v131
	v_cmp_lt_f32_e64 s[12:13], |v131|, s4
	s_nop 1
	v_cndmask_b32_e64 v131, v131, v132, s[12:13]
	v_cndmask_b32_e32 v132, 0, v227, vcc
	v_sub_f32_e32 v131, v131, v132
	v_cvt_pk_bf16_f32 v141, v131, s0
	global_store_short v139, v141, s[72:73] offset:64
	v_mul_f32_e32 v132, 0xbfb8aa3b, v97
	v_exp_f32_e32 v132, v132
	v_sub_f32_e32 v133, 1.0, v163
	v_add_f32_e32 v132, 1.0, v132
	v_div_scale_f32 v134, s[4:5], v132, v132, v133
	v_rcp_f32_e32 v135, v134
	v_div_scale_f32 v136, vcc, v133, v132, v133
	s_mov_b32 s4, 0x800000
	v_fma_f32 v137, -v134, v135, 1.0
	v_fmac_f32_e32 v135, v137, v135
	v_mul_f32_e32 v137, v136, v135
	v_fma_f32 v140, -v134, v137, v136
	v_fmac_f32_e32 v137, v140, v135
	v_fma_f32 v134, -v134, v137, v136
	v_div_fmas_f32 v134, v134, v135, v137
	v_div_fixup_f32 v132, v134, v132, v133
	v_add_f32_e32 v131, v163, v132
	v_cmp_gt_f32_e32 vcc, s4, v131
	s_mov_b32 s4, 0x3f317217
	s_nop 0
	v_cndmask_b32_e64 v132, 0, 32, vcc
	v_ldexp_f32 v131, v131, v132
	v_log_f32_e32 v131, v131
	s_nop 0
	v_mul_f32_e32 v132, 0x3f317217, v131
	v_fma_f32 v132, v131, s4, -v132
	v_fmac_f32_e32 v132, 0x3377d1cf, v131
	s_mov_b32 s4, 0x7f800000
	v_fmac_f32_e32 v132, 0x3f317217, v131
	v_cmp_lt_f32_e64 s[12:13], |v131|, s4
	s_nop 1
	v_cndmask_b32_e64 v131, v131, v132, s[12:13]
	v_cndmask_b32_e32 v132, 0, v227, vcc
	v_sub_f32_e32 v131, v131, v132
	v_cvt_pk_bf16_f32 v141, v131, s0
	global_store_short v139, v141, s[72:73] offset:96
	v_add_u32_e32 v139, 0x51000, v138
	v_mul_f32_e32 v132, 0xbfb8aa3b, v18
	v_exp_f32_e32 v132, v132
	v_sub_f32_e32 v133, 1.0, v160
	v_add_f32_e32 v132, 1.0, v132
	v_div_scale_f32 v134, s[4:5], v132, v132, v133
	v_rcp_f32_e32 v135, v134
	v_div_scale_f32 v136, vcc, v133, v132, v133
	s_mov_b32 s4, 0x800000
	v_fma_f32 v137, -v134, v135, 1.0
	v_fmac_f32_e32 v135, v137, v135
	v_mul_f32_e32 v137, v136, v135
	v_fma_f32 v140, -v134, v137, v136
	v_fmac_f32_e32 v137, v140, v135
	v_fma_f32 v134, -v134, v137, v136
	v_div_fmas_f32 v134, v134, v135, v137
	v_div_fixup_f32 v132, v134, v132, v133
	v_add_f32_e32 v131, v160, v132
	v_cmp_gt_f32_e32 vcc, s4, v131
	s_mov_b32 s4, 0x3f317217
	s_nop 0
	v_cndmask_b32_e64 v132, 0, 32, vcc
	v_ldexp_f32 v131, v131, v132
	v_log_f32_e32 v131, v131
	s_nop 0
	v_mul_f32_e32 v132, 0x3f317217, v131
	v_fma_f32 v132, v131, s4, -v132
	v_fmac_f32_e32 v132, 0x3377d1cf, v131
	s_mov_b32 s4, 0x7f800000
	v_fmac_f32_e32 v132, 0x3f317217, v131
	v_cmp_lt_f32_e64 s[12:13], |v131|, s4
	s_nop 1
	v_cndmask_b32_e64 v131, v131, v132, s[12:13]
	v_cndmask_b32_e32 v132, 0, v227, vcc
	v_sub_f32_e32 v131, v131, v132
	v_cvt_pk_bf16_f32 v141, v131, s0
	global_store_short v139, v141, s[72:73]
	v_mul_f32_e32 v132, 0xbfb8aa3b, v86
	v_exp_f32_e32 v132, v132
	v_sub_f32_e32 v133, 1.0, v161
	v_add_f32_e32 v132, 1.0, v132
	v_div_scale_f32 v134, s[4:5], v132, v132, v133
	v_rcp_f32_e32 v135, v134
	v_div_scale_f32 v136, vcc, v133, v132, v133
	s_mov_b32 s4, 0x800000
	v_fma_f32 v137, -v134, v135, 1.0
	v_fmac_f32_e32 v135, v137, v135
	v_mul_f32_e32 v137, v136, v135
	v_fma_f32 v140, -v134, v137, v136
	v_fmac_f32_e32 v137, v140, v135
	v_fma_f32 v134, -v134, v137, v136
	v_div_fmas_f32 v134, v134, v135, v137
	v_div_fixup_f32 v132, v134, v132, v133
	v_add_f32_e32 v131, v161, v132
	v_cmp_gt_f32_e32 vcc, s4, v131
	s_mov_b32 s4, 0x3f317217
	s_nop 0
	v_cndmask_b32_e64 v132, 0, 32, vcc
	v_ldexp_f32 v131, v131, v132
	v_log_f32_e32 v131, v131
	s_nop 0
	v_mul_f32_e32 v132, 0x3f317217, v131
	v_fma_f32 v132, v131, s4, -v132
	v_fmac_f32_e32 v132, 0x3377d1cf, v131
	s_mov_b32 s4, 0x7f800000
	v_fmac_f32_e32 v132, 0x3f317217, v131
	v_cmp_lt_f32_e64 s[12:13], |v131|, s4
	s_nop 1
	v_cndmask_b32_e64 v131, v131, v132, s[12:13]
	v_cndmask_b32_e32 v132, 0, v227, vcc
	v_sub_f32_e32 v131, v131, v132
	v_cvt_pk_bf16_f32 v141, v131, s0
	global_store_short v139, v141, s[72:73] offset:32
	v_mul_f32_e32 v132, 0xbfb8aa3b, v90
	v_exp_f32_e32 v132, v132
	v_sub_f32_e32 v133, 1.0, v162
	v_add_f32_e32 v132, 1.0, v132
	v_div_scale_f32 v134, s[4:5], v132, v132, v133
	v_rcp_f32_e32 v135, v134
	v_div_scale_f32 v136, vcc, v133, v132, v133
	s_mov_b32 s4, 0x800000
	v_fma_f32 v137, -v134, v135, 1.0
	v_fmac_f32_e32 v135, v137, v135
	v_mul_f32_e32 v137, v136, v135
	v_fma_f32 v140, -v134, v137, v136
	v_fmac_f32_e32 v137, v140, v135
	v_fma_f32 v134, -v134, v137, v136
	v_div_fmas_f32 v134, v134, v135, v137
	v_div_fixup_f32 v132, v134, v132, v133
	v_add_f32_e32 v131, v162, v132
	v_cmp_gt_f32_e32 vcc, s4, v131
	s_mov_b32 s4, 0x3f317217
	s_nop 0
	v_cndmask_b32_e64 v132, 0, 32, vcc
	v_ldexp_f32 v131, v131, v132
	v_log_f32_e32 v131, v131
	s_nop 0
	v_mul_f32_e32 v132, 0x3f317217, v131
	v_fma_f32 v132, v131, s4, -v132
	v_fmac_f32_e32 v132, 0x3377d1cf, v131
	s_mov_b32 s4, 0x7f800000
	v_fmac_f32_e32 v132, 0x3f317217, v131
; DEV u16 f2bf(float f) { return (u16)(pack2(f, 0.f) & 0xffffu); }
; DEV void phase_win(const Params& P, int l, const u16* __restrict__ xb, const u16* __restrict__ Wt, u16* __restrict__ h, char* smem) {
;     ...
;       for (int ns = 0; ns < 4; ++ns)
; #pragma unroll
;         for (int j = 0; j < 4; ++j) {
;           int row = m0 + wm * 128 + ms * 16 + quad * 4 + j;
;           int col = cb + ns * 16 + l15;
;           float v = acc[ms][ns][j];
;           if (mode == 1) { float lbv = lbp[col - C_HF]; v = __logf(lbv + (1.f - lbv) / (1.f + __expf(-v))); }
;           else if (mode == 2) v = v / (1.f + __expf(-v));
;           h[(size_t)row * HS + col] = f2bf(v);
	v_cmp_lt_f32_e64 s[12:13], |v131|, s4
	s_nop 1
	v_cndmask_b32_e64 v131, v131, v132, s[12:13]
	v_cndmask_b32_e32 v132, 0, v227, vcc
	v_sub_f32_e32 v131, v131, v132
	v_cvt_pk_bf16_f32 v141, v131, s0
	global_store_short v139, v141, s[72:73] offset:64
	v_mul_f32_e32 v132, 0xbfb8aa3b, v82
	v_exp_f32_e32 v132, v132
	v_sub_f32_e32 v133, 1.0, v163
	v_add_f32_e32 v132, 1.0, v132
	v_div_scale_f32 v134, s[4:5], v132, v132, v133
	v_rcp_f32_e32 v135, v134
	v_div_scale_f32 v136, vcc, v133, v132, v133
	s_mov_b32 s4, 0x800000
	v_fma_f32 v137, -v134, v135, 1.0
	v_fmac_f32_e32 v135, v137, v135
	v_mul_f32_e32 v137, v136, v135
	v_fma_f32 v140, -v134, v137, v136
	v_fmac_f32_e32 v137, v140, v135
	v_fma_f32 v134, -v134, v137, v136
	v_div_fmas_f32 v134, v134, v135, v137
	v_div_fixup_f32 v132, v134, v132, v133
	v_add_f32_e32 v131, v163, v132
	v_cmp_gt_f32_e32 vcc, s4, v131
	s_mov_b32 s4, 0x3f317217
	s_nop 0
	v_cndmask_b32_e64 v132, 0, 32, vcc
	v_ldexp_f32 v131, v131, v132
	v_log_f32_e32 v131, v131
	s_nop 0
	v_mul_f32_e32 v132, 0x3f317217, v131
	v_fma_f32 v132, v131, s4, -v132
	v_fmac_f32_e32 v132, 0x3377d1cf, v131
	s_mov_b32 s4, 0x7f800000
	v_fmac_f32_e32 v132, 0x3f317217, v131
	v_cmp_lt_f32_e64 s[12:13], |v131|, s4
	s_nop 1
	v_cndmask_b32_e64 v131, v131, v132, s[12:13]
	v_cndmask_b32_e32 v132, 0, v227, vcc
	v_sub_f32_e32 v131, v131, v132
	v_cvt_pk_bf16_f32 v141, v131, s0
	global_store_short v139, v141, s[72:73] offset:96
	v_add_u32_e32 v139, 0x52b00, v138
	v_mul_f32_e32 v132, 0xbfb8aa3b, v19
	v_exp_f32_e32 v132, v132
	v_sub_f32_e32 v133, 1.0, v160
	v_add_f32_e32 v132, 1.0, v132
	v_div_scale_f32 v134, s[4:5], v132, v132, v133
	v_rcp_f32_e32 v135, v134
	v_div_scale_f32 v136, vcc, v133, v132, v133
	s_mov_b32 s4, 0x800000
	v_fma_f32 v137, -v134, v135, 1.0
	v_fmac_f32_e32 v135, v137, v135
	v_mul_f32_e32 v137, v136, v135
	v_fma_f32 v140, -v134, v137, v136
	v_fmac_f32_e32 v137, v140, v135
	v_fma_f32 v134, -v134, v137, v136
	v_div_fmas_f32 v134, v134, v135, v137
	v_div_fixup_f32 v132, v134, v132, v133
	v_add_f32_e32 v131, v160, v132
	v_cmp_gt_f32_e32 vcc, s4, v131
	s_mov_b32 s4, 0x3f317217
	s_nop 0
	v_cndmask_b32_e64 v132, 0, 32, vcc
	v_ldexp_f32 v131, v131, v132
	v_log_f32_e32 v131, v131
	s_nop 0
	v_mul_f32_e32 v132, 0x3f317217, v131
	v_fma_f32 v132, v131, s4, -v132
	v_fmac_f32_e32 v132, 0x3377d1cf, v131
	s_mov_b32 s4, 0x7f800000
	v_fmac_f32_e32 v132, 0x3f317217, v131
	v_cmp_lt_f32_e64 s[12:13], |v131|, s4
	s_nop 1
	v_cndmask_b32_e64 v131, v131, v132, s[12:13]
	v_cndmask_b32_e32 v132, 0, v227, vcc
	v_sub_f32_e32 v131, v131, v132
	v_cvt_pk_bf16_f32 v141, v131, s0
	global_store_short v139, v141, s[72:73]
	v_mul_f32_e32 v132, 0xbfb8aa3b, v87
	v_exp_f32_e32 v132, v132
	v_sub_f32_e32 v133, 1.0, v161
	v_add_f32_e32 v132, 1.0, v132
	v_div_scale_f32 v134, s[4:5], v132, v132, v133
	v_rcp_f32_e32 v135, v134
	v_div_scale_f32 v136, vcc, v133, v132, v133
	s_mov_b32 s4, 0x800000
	v_fma_f32 v137, -v134, v135, 1.0
	v_fmac_f32_e32 v135, v137, v135
	v_mul_f32_e32 v137, v136, v135
	v_fma_f32 v140, -v134, v137, v136
	v_fmac_f32_e32 v137, v140, v135
	v_fma_f32 v134, -v134, v137, v136
	v_div_fmas_f32 v134, v134, v135, v137
	v_div_fixup_f32 v132, v134, v132, v133
	v_add_f32_e32 v131, v161, v132
	v_cmp_gt_f32_e32 vcc, s4, v131
	s_mov_b32 s4, 0x3f317217
	s_nop 0
	v_cndmask_b32_e64 v132, 0, 32, vcc
	v_ldexp_f32 v131, v131, v132
	v_log_f32_e32 v131, v131
	s_nop 0
	v_mul_f32_e32 v132, 0x3f317217, v131
	v_fma_f32 v132, v131, s4, -v132
	v_fmac_f32_e32 v132, 0x3377d1cf, v131
	s_mov_b32 s4, 0x7f800000
	v_fmac_f32_e32 v132, 0x3f317217, v131
	v_cmp_lt_f32_e64 s[12:13], |v131|, s4
	s_nop 1
	v_cndmask_b32_e64 v131, v131, v132, s[12:13]
	v_cndmask_b32_e32 v132, 0, v227, vcc
	v_sub_f32_e32 v131, v131, v132
	v_cvt_pk_bf16_f32 v141, v131, s0
	global_store_short v139, v141, s[72:73] offset:32
	v_mul_f32_e32 v132, 0xbfb8aa3b, v91
	v_exp_f32_e32 v132, v132
	v_sub_f32_e32 v133, 1.0, v162
	v_add_f32_e32 v132, 1.0, v132
	v_div_scale_f32 v134, s[4:5], v132, v132, v133
	v_rcp_f32_e32 v135, v134
	v_div_scale_f32 v136, vcc, v133, v132, v133
	s_mov_b32 s4, 0x800000
	v_fma_f32 v137, -v134, v135, 1.0
	v_fmac_f32_e32 v135, v137, v135
	v_mul_f32_e32 v137, v136, v135
	v_fma_f32 v140, -v134, v137, v136
	v_fmac_f32_e32 v137, v140, v135
	v_fma_f32 v134, -v134, v137, v136
	v_div_fmas_f32 v134, v134, v135, v137
	v_div_fixup_f32 v132, v134, v132, v133
	v_add_f32_e32 v131, v162, v132
	v_cmp_gt_f32_e32 vcc, s4, v131
	s_mov_b32 s4, 0x3f317217
	s_nop 0
	v_cndmask_b32_e64 v132, 0, 32, vcc
	v_ldexp_f32 v131, v131, v132
	v_log_f32_e32 v131, v131
	s_nop 0
	v_mul_f32_e32 v132, 0x3f317217, v131
	v_fma_f32 v132, v131, s4, -v132
	v_fmac_f32_e32 v132, 0x3377d1cf, v131
	s_mov_b32 s4, 0x7f800000
	v_fmac_f32_e32 v132, 0x3f317217, v131
	v_cmp_lt_f32_e64 s[12:13], |v131|, s4
	s_nop 1
	v_cndmask_b32_e64 v131, v131, v132, s[12:13]
	v_cndmask_b32_e32 v132, 0, v227, vcc
	v_sub_f32_e32 v131, v131, v132
	v_cvt_pk_bf16_f32 v141, v131, s0
	global_store_short v139, v141, s[72:73] offset:64
	v_mul_f32_e32 v132, 0xbfb8aa3b, v83
	v_exp_f32_e32 v132, v132
	v_sub_f32_e32 v133, 1.0, v163
	v_add_f32_e32 v132, 1.0, v132
	v_div_scale_f32 v134, s[4:5], v132, v132, v133
	v_rcp_f32_e32 v135, v134
	v_div_scale_f32 v136, vcc, v133, v132, v133
	s_mov_b32 s4, 0x800000
	v_fma_f32 v137, -v134, v135, 1.0
	v_fmac_f32_e32 v135, v137, v135
	v_mul_f32_e32 v137, v136, v135
	v_fma_f32 v140, -v134, v137, v136
	v_fmac_f32_e32 v137, v140, v135
	v_fma_f32 v134, -v134, v137, v136
	v_div_fmas_f32 v134, v134, v135, v137
	v_div_fixup_f32 v132, v134, v132, v133
	v_add_f32_e32 v131, v163, v132
	v_cmp_gt_f32_e32 vcc, s4, v131
	s_mov_b32 s4, 0x3f317217
	s_nop 0
	v_cndmask_b32_e64 v132, 0, 32, vcc
; DEV u16 f2bf(float f) { return (u16)(pack2(f, 0.f) & 0xffffu); }
; DEV void phase_win(const Params& P, int l, const u16* __restrict__ xb, const u16* __restrict__ Wt, u16* __restrict__ h, char* smem) {
;     ...
;       for (int ns = 0; ns < 4; ++ns)
; #pragma unroll
;         for (int j = 0; j < 4; ++j) {
;           int row = m0 + wm * 128 + ms * 16 + quad * 4 + j;
;           int col = cb + ns * 16 + l15;
;           float v = acc[ms][ns][j];
;           if (mode == 1) { float lbv = lbp[col - C_HF]; v = __logf(lbv + (1.f - lbv) / (1.f + __expf(-v))); }
;           else if (mode == 2) v = v / (1.f + __expf(-v));
;           h[(size_t)row * HS + col] = f2bf(v);
	v_ldexp_f32 v131, v131, v132
	v_log_f32_e32 v131, v131
	s_nop 0
	v_mul_f32_e32 v132, 0x3f317217, v131
	v_fma_f32 v132, v131, s4, -v132
	v_fmac_f32_e32 v132, 0x3377d1cf, v131
	s_mov_b32 s4, 0x7f800000
	v_fmac_f32_e32 v132, 0x3f317217, v131
	v_cmp_lt_f32_e64 s[12:13], |v131|, s4
	s_nop 1
	v_cndmask_b32_e64 v131, v131, v132, s[12:13]
	v_cndmask_b32_e32 v132, 0, v227, vcc
	v_sub_f32_e32 v131, v131, v132
	v_cvt_pk_bf16_f32 v141, v131, s0
	global_store_short v139, v141, s[72:73] offset:96
	v_add_u32_e32 v139, 0x54600, v138
	v_mul_f32_e32 v132, 0xbfb8aa3b, v20
	v_exp_f32_e32 v132, v132
	v_sub_f32_e32 v133, 1.0, v160
	v_add_f32_e32 v132, 1.0, v132
	v_div_scale_f32 v134, s[4:5], v132, v132, v133
	v_rcp_f32_e32 v135, v134
	v_div_scale_f32 v136, vcc, v133, v132, v133
	s_mov_b32 s4, 0x800000
	v_fma_f32 v137, -v134, v135, 1.0
	v_fmac_f32_e32 v135, v137, v135
	v_mul_f32_e32 v137, v136, v135
	v_fma_f32 v140, -v134, v137, v136
	v_fmac_f32_e32 v137, v140, v135
	v_fma_f32 v134, -v134, v137, v136
	v_div_fmas_f32 v134, v134, v135, v137
	v_div_fixup_f32 v132, v134, v132, v133
	v_add_f32_e32 v131, v160, v132
	v_cmp_gt_f32_e32 vcc, s4, v131
	s_mov_b32 s4, 0x3f317217
	s_nop 0
	v_cndmask_b32_e64 v132, 0, 32, vcc
	v_ldexp_f32 v131, v131, v132
	v_log_f32_e32 v131, v131
	s_nop 0
	v_mul_f32_e32 v132, 0x3f317217, v131
	v_fma_f32 v132, v131, s4, -v132
	v_fmac_f32_e32 v132, 0x3377d1cf, v131
	s_mov_b32 s4, 0x7f800000
	v_fmac_f32_e32 v132, 0x3f317217, v131
	v_cmp_lt_f32_e64 s[12:13], |v131|, s4
	s_nop 1
	v_cndmask_b32_e64 v131, v131, v132, s[12:13]
	v_cndmask_b32_e32 v132, 0, v227, vcc
	v_sub_f32_e32 v131, v131, v132
	v_cvt_pk_bf16_f32 v141, v131, s0
	global_store_short v139, v141, s[72:73]
	v_mul_f32_e32 v132, 0xbfb8aa3b, v88
	v_exp_f32_e32 v132, v132
	v_sub_f32_e32 v133, 1.0, v161
	v_add_f32_e32 v132, 1.0, v132
	v_div_scale_f32 v134, s[4:5], v132, v132, v133
	v_rcp_f32_e32 v135, v134
	v_div_scale_f32 v136, vcc, v133, v132, v133
	s_mov_b32 s4, 0x800000
	v_fma_f32 v137, -v134, v135, 1.0
	v_fmac_f32_e32 v135, v137, v135
	v_mul_f32_e32 v137, v136, v135
	v_fma_f32 v140, -v134, v137, v136
	v_fmac_f32_e32 v137, v140, v135
	v_fma_f32 v134, -v134, v137, v136
	v_div_fmas_f32 v134, v134, v135, v137
	v_div_fixup_f32 v132, v134, v132, v133
	v_add_f32_e32 v131, v161, v132
	v_cmp_gt_f32_e32 vcc, s4, v131
	s_mov_b32 s4, 0x3f317217
	s_nop 0
	v_cndmask_b32_e64 v132, 0, 32, vcc
	v_ldexp_f32 v131, v131, v132
	v_log_f32_e32 v131, v131
	s_nop 0
	v_mul_f32_e32 v132, 0x3f317217, v131
	v_fma_f32 v132, v131, s4, -v132
	v_fmac_f32_e32 v132, 0x3377d1cf, v131
	s_mov_b32 s4, 0x7f800000
	v_fmac_f32_e32 v132, 0x3f317217, v131
	v_cmp_lt_f32_e64 s[12:13], |v131|, s4
	s_nop 1
	v_cndmask_b32_e64 v131, v131, v132, s[12:13]
	v_cndmask_b32_e32 v132, 0, v227, vcc
	v_sub_f32_e32 v131, v131, v132
	v_cvt_pk_bf16_f32 v141, v131, s0
	global_store_short v139, v141, s[72:73] offset:32
	v_mul_f32_e32 v132, 0xbfb8aa3b, v92
	v_exp_f32_e32 v132, v132
	v_sub_f32_e32 v133, 1.0, v162
	v_add_f32_e32 v132, 1.0, v132
	v_div_scale_f32 v134, s[4:5], v132, v132, v133
	v_rcp_f32_e32 v135, v134
	v_div_scale_f32 v136, vcc, v133, v132, v133
	s_mov_b32 s4, 0x800000
	v_fma_f32 v137, -v134, v135, 1.0
	v_fmac_f32_e32 v135, v137, v135
	v_mul_f32_e32 v137, v136, v135
	v_fma_f32 v140, -v134, v137, v136
	v_fmac_f32_e32 v137, v140, v135
	v_fma_f32 v134, -v134, v137, v136
	v_div_fmas_f32 v134, v134, v135, v137
	v_div_fixup_f32 v132, v134, v132, v133
	v_add_f32_e32 v131, v162, v132
	v_cmp_gt_f32_e32 vcc, s4, v131
	s_mov_b32 s4, 0x3f317217
	s_nop 0
	v_cndmask_b32_e64 v132, 0, 32, vcc
	v_ldexp_f32 v131, v131, v132
	v_log_f32_e32 v131, v131
	s_nop 0
	v_mul_f32_e32 v132, 0x3f317217, v131
	v_fma_f32 v132, v131, s4, -v132
	v_fmac_f32_e32 v132, 0x3377d1cf, v131
	s_mov_b32 s4, 0x7f800000
	v_fmac_f32_e32 v132, 0x3f317217, v131
	v_cmp_lt_f32_e64 s[12:13], |v131|, s4
	s_nop 1
	v_cndmask_b32_e64 v131, v131, v132, s[12:13]
	v_cndmask_b32_e32 v132, 0, v227, vcc
	v_sub_f32_e32 v131, v131, v132
	v_cvt_pk_bf16_f32 v141, v131, s0
	global_store_short v139, v141, s[72:73] offset:64
	v_mul_f32_e32 v132, 0xbfb8aa3b, v84
	v_exp_f32_e32 v132, v132
	v_sub_f32_e32 v133, 1.0, v163
	v_add_f32_e32 v132, 1.0, v132
	v_div_scale_f32 v134, s[4:5], v132, v132, v133
	v_rcp_f32_e32 v135, v134
	v_div_scale_f32 v136, vcc, v133, v132, v133
	s_mov_b32 s4, 0x800000
	v_fma_f32 v137, -v134, v135, 1.0
	v_fmac_f32_e32 v135, v137, v135
	v_mul_f32_e32 v137, v136, v135
	v_fma_f32 v140, -v134, v137, v136
	v_fmac_f32_e32 v137, v140, v135
	v_fma_f32 v134, -v134, v137, v136
	v_div_fmas_f32 v134, v134, v135, v137
	v_div_fixup_f32 v132, v134, v132, v133
	v_add_f32_e32 v131, v163, v132
	v_cmp_gt_f32_e32 vcc, s4, v131
	s_mov_b32 s4, 0x3f317217
	s_nop 0
	v_cndmask_b32_e64 v132, 0, 32, vcc
	v_ldexp_f32 v131, v131, v132
	v_log_f32_e32 v131, v131
	s_nop 0
	v_mul_f32_e32 v132, 0x3f317217, v131
	v_fma_f32 v132, v131, s4, -v132
	v_fmac_f32_e32 v132, 0x3377d1cf, v131
	s_mov_b32 s4, 0x7f800000
	v_fmac_f32_e32 v132, 0x3f317217, v131
	v_cmp_lt_f32_e64 s[12:13], |v131|, s4
	s_nop 1
	v_cndmask_b32_e64 v131, v131, v132, s[12:13]
	v_cndmask_b32_e32 v132, 0, v227, vcc
	v_sub_f32_e32 v131, v131, v132
	v_cvt_pk_bf16_f32 v141, v131, s0
	global_store_short v139, v141, s[72:73] offset:96
	v_add_u32_e32 v139, 0x56100, v138
	v_mul_f32_e32 v132, 0xbfb8aa3b, v21
	v_exp_f32_e32 v132, v132
	v_sub_f32_e32 v133, 1.0, v160
	v_add_f32_e32 v132, 1.0, v132
	v_div_scale_f32 v134, s[4:5], v132, v132, v133
	v_rcp_f32_e32 v135, v134
	v_div_scale_f32 v136, vcc, v133, v132, v133
	s_mov_b32 s4, 0x800000
	v_fma_f32 v137, -v134, v135, 1.0
	v_fmac_f32_e32 v135, v137, v135
	v_mul_f32_e32 v137, v136, v135
	v_fma_f32 v140, -v134, v137, v136
; DEV u16 f2bf(float f) { return (u16)(pack2(f, 0.f) & 0xffffu); }
; DEV void phase_win(const Params& P, int l, const u16* __restrict__ xb, const u16* __restrict__ Wt, u16* __restrict__ h, char* smem) {
;     ...
;     const int mode = (cb >= C_HF && cb < C_HI) ? 1 : ((cb >= C_HG) ? 2 : 0);
; #pragma unroll
;     for (int ms = 0; ms < 8; ++ms) {
;       asm volatile("" ::: "memory");
; #pragma unroll
;       for (int ns = 0; ns < 4; ++ns)
; #pragma unroll
;         for (int j = 0; j < 4; ++j) {
;           int row = m0 + wm * 128 + ms * 16 + quad * 4 + j;
;           int col = cb + ns * 16 + l15;
;           float v = acc[ms][ns][j];
;           if (mode == 1) { float lbv = lbp[col - C_HF]; v = __logf(lbv + (1.f - lbv) / (1.f + __expf(-v))); }
;           else if (mode == 2) v = v / (1.f + __expf(-v));
;           h[(size_t)row * HS + col] = f2bf(v);
;         }
	v_fmac_f32_e32 v137, v140, v135
	v_fma_f32 v134, -v134, v137, v136
	v_div_fmas_f32 v134, v134, v135, v137
	v_div_fixup_f32 v132, v134, v132, v133
	v_add_f32_e32 v131, v160, v132
	v_cmp_gt_f32_e32 vcc, s4, v131
	s_mov_b32 s4, 0x3f317217
	s_nop 0
	v_cndmask_b32_e64 v132, 0, 32, vcc
	v_ldexp_f32 v131, v131, v132
	v_log_f32_e32 v131, v131
	s_nop 0
	v_mul_f32_e32 v132, 0x3f317217, v131
	v_fma_f32 v132, v131, s4, -v132
	v_fmac_f32_e32 v132, 0x3377d1cf, v131
	s_mov_b32 s4, 0x7f800000
	v_fmac_f32_e32 v132, 0x3f317217, v131
	v_cmp_lt_f32_e64 s[12:13], |v131|, s4
	s_nop 1
	v_cndmask_b32_e64 v131, v131, v132, s[12:13]
	v_cndmask_b32_e32 v132, 0, v227, vcc
	v_sub_f32_e32 v131, v131, v132
	v_cvt_pk_bf16_f32 v141, v131, s0
	global_store_short v139, v141, s[72:73]
	v_mul_f32_e32 v132, 0xbfb8aa3b, v89
	v_exp_f32_e32 v132, v132
	v_sub_f32_e32 v133, 1.0, v161
	v_add_f32_e32 v132, 1.0, v132
	v_div_scale_f32 v134, s[4:5], v132, v132, v133
	v_rcp_f32_e32 v135, v134
	v_div_scale_f32 v136, vcc, v133, v132, v133
	s_mov_b32 s4, 0x800000
	v_fma_f32 v137, -v134, v135, 1.0
	v_fmac_f32_e32 v135, v137, v135
	v_mul_f32_e32 v137, v136, v135
	v_fma_f32 v140, -v134, v137, v136
	v_fmac_f32_e32 v137, v140, v135
	v_fma_f32 v134, -v134, v137, v136
	v_div_fmas_f32 v134, v134, v135, v137
	v_div_fixup_f32 v132, v134, v132, v133
	v_add_f32_e32 v131, v161, v132
	v_cmp_gt_f32_e32 vcc, s4, v131
	s_mov_b32 s4, 0x3f317217
	s_nop 0
	v_cndmask_b32_e64 v132, 0, 32, vcc
	v_ldexp_f32 v131, v131, v132
	v_log_f32_e32 v131, v131
	s_nop 0
	v_mul_f32_e32 v132, 0x3f317217, v131
	v_fma_f32 v132, v131, s4, -v132
	v_fmac_f32_e32 v132, 0x3377d1cf, v131
	s_mov_b32 s4, 0x7f800000
	v_fmac_f32_e32 v132, 0x3f317217, v131
	v_cmp_lt_f32_e64 s[12:13], |v131|, s4
	s_nop 1
	v_cndmask_b32_e64 v131, v131, v132, s[12:13]
	v_cndmask_b32_e32 v132, 0, v227, vcc
	v_sub_f32_e32 v131, v131, v132
	v_cvt_pk_bf16_f32 v141, v131, s0
	global_store_short v139, v141, s[72:73] offset:32
	v_mul_f32_e32 v132, 0xbfb8aa3b, v93
	v_exp_f32_e32 v132, v132
	v_sub_f32_e32 v133, 1.0, v162
	v_add_f32_e32 v132, 1.0, v132
	v_div_scale_f32 v134, s[4:5], v132, v132, v133
	v_rcp_f32_e32 v135, v134
	v_div_scale_f32 v136, vcc, v133, v132, v133
	s_mov_b32 s4, 0x800000
	v_fma_f32 v137, -v134, v135, 1.0
	v_fmac_f32_e32 v135, v137, v135
	v_mul_f32_e32 v137, v136, v135
	v_fma_f32 v140, -v134, v137, v136
	v_fmac_f32_e32 v137, v140, v135
	v_fma_f32 v134, -v134, v137, v136
	v_div_fmas_f32 v134, v134, v135, v137
	v_div_fixup_f32 v132, v134, v132, v133
	v_add_f32_e32 v131, v162, v132
	v_cmp_gt_f32_e32 vcc, s4, v131
	s_mov_b32 s4, 0x3f317217
	s_nop 0
	v_cndmask_b32_e64 v132, 0, 32, vcc
	v_ldexp_f32 v131, v131, v132
	v_log_f32_e32 v131, v131
	s_nop 0
	v_mul_f32_e32 v132, 0x3f317217, v131
	v_fma_f32 v132, v131, s4, -v132
	v_fmac_f32_e32 v132, 0x3377d1cf, v131
	s_mov_b32 s4, 0x7f800000
	v_fmac_f32_e32 v132, 0x3f317217, v131
	v_cmp_lt_f32_e64 s[12:13], |v131|, s4
	s_nop 1
	v_cndmask_b32_e64 v131, v131, v132, s[12:13]
	v_cndmask_b32_e32 v132, 0, v227, vcc
	v_sub_f32_e32 v131, v131, v132
	v_cvt_pk_bf16_f32 v141, v131, s0
	global_store_short v139, v141, s[72:73] offset:64
	v_mul_f32_e32 v132, 0xbfb8aa3b, v85
	v_exp_f32_e32 v132, v132
	v_sub_f32_e32 v133, 1.0, v163
	v_add_f32_e32 v132, 1.0, v132
	v_div_scale_f32 v134, s[4:5], v132, v132, v133
	v_rcp_f32_e32 v135, v134
	v_div_scale_f32 v136, vcc, v133, v132, v133
	s_mov_b32 s4, 0x800000
	v_fma_f32 v137, -v134, v135, 1.0
	v_fmac_f32_e32 v135, v137, v135
	v_mul_f32_e32 v137, v136, v135
	v_fma_f32 v140, -v134, v137, v136
	v_fmac_f32_e32 v137, v140, v135
	v_fma_f32 v134, -v134, v137, v136
	v_div_fmas_f32 v134, v134, v135, v137
	v_div_fixup_f32 v132, v134, v132, v133
	v_add_f32_e32 v131, v163, v132
	v_cmp_gt_f32_e32 vcc, s4, v131
	s_mov_b32 s4, 0x3f317217
	s_nop 0
	v_cndmask_b32_e64 v132, 0, 32, vcc
	v_ldexp_f32 v131, v131, v132
	v_log_f32_e32 v131, v131
	s_nop 0
	v_mul_f32_e32 v132, 0x3f317217, v131
	v_fma_f32 v132, v131, s4, -v132
	v_fmac_f32_e32 v132, 0x3377d1cf, v131
	s_mov_b32 s4, 0x7f800000
	v_fmac_f32_e32 v132, 0x3f317217, v131
	v_cmp_lt_f32_e64 s[12:13], |v131|, s4
	s_nop 1
	v_cndmask_b32_e64 v131, v131, v132, s[12:13]
	v_cndmask_b32_e32 v132, 0, v227, vcc
	v_sub_f32_e32 v131, v131, v132
	v_cvt_pk_bf16_f32 v141, v131, s0
	global_store_short v139, v141, s[72:73] offset:96
	v_add_u32_e32 v139, 0x6c000, v138
	v_mul_f32_e32 v132, 0xbfb8aa3b, v14
	v_exp_f32_e32 v132, v132
	v_sub_f32_e32 v133, 1.0, v160
	v_add_f32_e32 v132, 1.0, v132
	v_div_scale_f32 v134, s[4:5], v132, v132, v133
	v_rcp_f32_e32 v135, v134
	v_div_scale_f32 v136, vcc, v133, v132, v133
	s_mov_b32 s4, 0x800000
	v_fma_f32 v137, -v134, v135, 1.0
	v_fmac_f32_e32 v135, v137, v135
	v_mul_f32_e32 v137, v136, v135
	v_fma_f32 v140, -v134, v137, v136
	v_fmac_f32_e32 v137, v140, v135
	v_fma_f32 v134, -v134, v137, v136
	v_div_fmas_f32 v134, v134, v135, v137
	v_div_fixup_f32 v132, v134, v132, v133
	v_add_f32_e32 v131, v160, v132
	v_cmp_gt_f32_e32 vcc, s4, v131
	s_mov_b32 s4, 0x3f317217
	s_nop 0
	v_cndmask_b32_e64 v132, 0, 32, vcc
	v_ldexp_f32 v131, v131, v132
	v_log_f32_e32 v131, v131
	s_nop 0
	v_mul_f32_e32 v132, 0x3f317217, v131
	v_fma_f32 v132, v131, s4, -v132
	v_fmac_f32_e32 v132, 0x3377d1cf, v131
	s_mov_b32 s4, 0x7f800000
	v_fmac_f32_e32 v132, 0x3f317217, v131
	v_cmp_lt_f32_e64 s[12:13], |v131|, s4
	s_nop 1
	v_cndmask_b32_e64 v131, v131, v132, s[12:13]
	v_cndmask_b32_e32 v132, 0, v227, vcc
	v_sub_f32_e32 v131, v131, v132
	v_cvt_pk_bf16_f32 v141, v131, s0
	global_store_short v139, v141, s[72:73]
	v_mul_f32_e32 v132, 0xbfb8aa3b, v74
	v_exp_f32_e32 v132, v132
	v_sub_f32_e32 v133, 1.0, v161
	v_add_f32_e32 v132, 1.0, v132
	v_div_scale_f32 v134, s[4:5], v132, v132, v133
; DEV u16 f2bf(float f) { return (u16)(pack2(f, 0.f) & 0xffffu); }
; DEV void phase_win(const Params& P, int l, const u16* __restrict__ xb, const u16* __restrict__ Wt, u16* __restrict__ h, char* smem) {
;     ...
;     const int mode = (cb >= C_HF && cb < C_HI) ? 1 : ((cb >= C_HG) ? 2 : 0);
; #pragma unroll
;     for (int ms = 0; ms < 8; ++ms) {
;       asm volatile("" ::: "memory");
; #pragma unroll
;       for (int ns = 0; ns < 4; ++ns)
; #pragma unroll
;         for (int j = 0; j < 4; ++j) {
;           int row = m0 + wm * 128 + ms * 16 + quad * 4 + j;
;           int col = cb + ns * 16 + l15;
;           float v = acc[ms][ns][j];
;           if (mode == 1) { float lbv = lbp[col - C_HF]; v = __logf(lbv + (1.f - lbv) / (1.f + __expf(-v))); }
;           else if (mode == 2) v = v / (1.f + __expf(-v));
;           h[(size_t)row * HS + col] = f2bf(v);
;         }
	v_rcp_f32_e32 v135, v134
	v_div_scale_f32 v136, vcc, v133, v132, v133
	s_mov_b32 s4, 0x800000
	v_fma_f32 v137, -v134, v135, 1.0
	v_fmac_f32_e32 v135, v137, v135
	v_mul_f32_e32 v137, v136, v135
	v_fma_f32 v140, -v134, v137, v136
	v_fmac_f32_e32 v137, v140, v135
	v_fma_f32 v134, -v134, v137, v136
	v_div_fmas_f32 v134, v134, v135, v137
	v_div_fixup_f32 v132, v134, v132, v133
	v_add_f32_e32 v131, v161, v132
	v_cmp_gt_f32_e32 vcc, s4, v131
	s_mov_b32 s4, 0x3f317217
	s_nop 0
	v_cndmask_b32_e64 v132, 0, 32, vcc
	v_ldexp_f32 v131, v131, v132
	v_log_f32_e32 v131, v131
	s_nop 0
	v_mul_f32_e32 v132, 0x3f317217, v131
	v_fma_f32 v132, v131, s4, -v132
	v_fmac_f32_e32 v132, 0x3377d1cf, v131
	s_mov_b32 s4, 0x7f800000
	v_fmac_f32_e32 v132, 0x3f317217, v131
	v_cmp_lt_f32_e64 s[12:13], |v131|, s4
	s_nop 1
	v_cndmask_b32_e64 v131, v131, v132, s[12:13]
	v_cndmask_b32_e32 v132, 0, v227, vcc
	v_sub_f32_e32 v131, v131, v132
	v_cvt_pk_bf16_f32 v141, v131, s0
	global_store_short v139, v141, s[72:73] offset:32
	v_mul_f32_e32 v132, 0xbfb8aa3b, v78
	v_exp_f32_e32 v132, v132
	v_sub_f32_e32 v133, 1.0, v162
	v_add_f32_e32 v132, 1.0, v132
	v_div_scale_f32 v134, s[4:5], v132, v132, v133
	v_rcp_f32_e32 v135, v134
	v_div_scale_f32 v136, vcc, v133, v132, v133
	s_mov_b32 s4, 0x800000
	v_fma_f32 v137, -v134, v135, 1.0
	v_fmac_f32_e32 v135, v137, v135
	v_mul_f32_e32 v137, v136, v135
	v_fma_f32 v140, -v134, v137, v136
	v_fmac_f32_e32 v137, v140, v135
	v_fma_f32 v134, -v134, v137, v136
	v_div_fmas_f32 v134, v134, v135, v137
	v_div_fixup_f32 v132, v134, v132, v133
	v_add_f32_e32 v131, v162, v132
	v_cmp_gt_f32_e32 vcc, s4, v131
	s_mov_b32 s4, 0x3f317217
	s_nop 0
	v_cndmask_b32_e64 v132, 0, 32, vcc
	v_ldexp_f32 v131, v131, v132
	v_log_f32_e32 v131, v131
	s_nop 0
	v_mul_f32_e32 v132, 0x3f317217, v131
	v_fma_f32 v132, v131, s4, -v132
	v_fmac_f32_e32 v132, 0x3377d1cf, v131
	s_mov_b32 s4, 0x7f800000
	v_fmac_f32_e32 v132, 0x3f317217, v131
	v_cmp_lt_f32_e64 s[12:13], |v131|, s4
	s_nop 1
	v_cndmask_b32_e64 v131, v131, v132, s[12:13]
	v_cndmask_b32_e32 v132, 0, v227, vcc
	v_sub_f32_e32 v131, v131, v132
	v_cvt_pk_bf16_f32 v141, v131, s0
	global_store_short v139, v141, s[72:73] offset:64
	v_mul_f32_e32 v132, 0xbfb8aa3b, v70
	v_exp_f32_e32 v132, v132
	v_sub_f32_e32 v133, 1.0, v163
	v_add_f32_e32 v132, 1.0, v132
	v_div_scale_f32 v134, s[4:5], v132, v132, v133
	v_rcp_f32_e32 v135, v134
	v_div_scale_f32 v136, vcc, v133, v132, v133
	s_mov_b32 s4, 0x800000
	v_fma_f32 v137, -v134, v135, 1.0
	v_fmac_f32_e32 v135, v137, v135
	v_mul_f32_e32 v137, v136, v135
	v_fma_f32 v140, -v134, v137, v136
	v_fmac_f32_e32 v137, v140, v135
	v_fma_f32 v134, -v134, v137, v136
	v_div_fmas_f32 v134, v134, v135, v137
	v_div_fixup_f32 v132, v134, v132, v133
	v_add_f32_e32 v131, v163, v132
	v_cmp_gt_f32_e32 vcc, s4, v131
	s_mov_b32 s4, 0x3f317217
	s_nop 0
	v_cndmask_b32_e64 v132, 0, 32, vcc
	v_ldexp_f32 v131, v131, v132
	v_log_f32_e32 v131, v131
	s_nop 0
	v_mul_f32_e32 v132, 0x3f317217, v131
	v_fma_f32 v132, v131, s4, -v132
	v_fmac_f32_e32 v132, 0x3377d1cf, v131
	s_mov_b32 s4, 0x7f800000
	v_fmac_f32_e32 v132, 0x3f317217, v131
	v_cmp_lt_f32_e64 s[12:13], |v131|, s4
	s_nop 1
	v_cndmask_b32_e64 v131, v131, v132, s[12:13]
	v_cndmask_b32_e32 v132, 0, v227, vcc
	v_sub_f32_e32 v131, v131, v132
	v_cvt_pk_bf16_f32 v141, v131, s0
	global_store_short v139, v141, s[72:73] offset:96
	v_add_u32_e32 v139, 0x6db00, v138
	v_mul_f32_e32 v132, 0xbfb8aa3b, v15
	v_exp_f32_e32 v132, v132
	v_sub_f32_e32 v133, 1.0, v160
	v_add_f32_e32 v132, 1.0, v132
	v_div_scale_f32 v134, s[4:5], v132, v132, v133
	v_rcp_f32_e32 v135, v134
	v_div_scale_f32 v136, vcc, v133, v132, v133
	s_mov_b32 s4, 0x800000
	v_fma_f32 v137, -v134, v135, 1.0
	v_fmac_f32_e32 v135, v137, v135
	v_mul_f32_e32 v137, v136, v135
	v_fma_f32 v140, -v134, v137, v136
	v_fmac_f32_e32 v137, v140, v135
	v_fma_f32 v134, -v134, v137, v136
	v_div_fmas_f32 v134, v134, v135, v137
	v_div_fixup_f32 v132, v134, v132, v133
	v_add_f32_e32 v131, v160, v132
	v_cmp_gt_f32_e32 vcc, s4, v131
	s_mov_b32 s4, 0x3f317217
	s_nop 0
	v_cndmask_b32_e64 v132, 0, 32, vcc
	v_ldexp_f32 v131, v131, v132
	v_log_f32_e32 v131, v131
	s_nop 0
	v_mul_f32_e32 v132, 0x3f317217, v131
	v_fma_f32 v132, v131, s4, -v132
	v_fmac_f32_e32 v132, 0x3377d1cf, v131
	s_mov_b32 s4, 0x7f800000
	v_fmac_f32_e32 v132, 0x3f317217, v131
	v_cmp_lt_f32_e64 s[12:13], |v131|, s4
	s_nop 1
	v_cndmask_b32_e64 v131, v131, v132, s[12:13]
	v_cndmask_b32_e32 v132, 0, v227, vcc
	v_sub_f32_e32 v131, v131, v132
	v_cvt_pk_bf16_f32 v141, v131, s0
	global_store_short v139, v141, s[72:73]
	v_mul_f32_e32 v132, 0xbfb8aa3b, v75
	v_exp_f32_e32 v132, v132
	v_sub_f32_e32 v133, 1.0, v161
	v_add_f32_e32 v132, 1.0, v132
	v_div_scale_f32 v134, s[4:5], v132, v132, v133
	v_rcp_f32_e32 v135, v134
	v_div_scale_f32 v136, vcc, v133, v132, v133
	s_mov_b32 s4, 0x800000
	v_fma_f32 v137, -v134, v135, 1.0
	v_fmac_f32_e32 v135, v137, v135
	v_mul_f32_e32 v137, v136, v135
	v_fma_f32 v140, -v134, v137, v136
	v_fmac_f32_e32 v137, v140, v135
	v_fma_f32 v134, -v134, v137, v136
	v_div_fmas_f32 v134, v134, v135, v137
	v_div_fixup_f32 v132, v134, v132, v133
	v_add_f32_e32 v131, v161, v132
	v_cmp_gt_f32_e32 vcc, s4, v131
	s_mov_b32 s4, 0x3f317217
	s_nop 0
	v_cndmask_b32_e64 v132, 0, 32, vcc
	v_ldexp_f32 v131, v131, v132
	v_log_f32_e32 v131, v131
	s_nop 0
	v_mul_f32_e32 v132, 0x3f317217, v131
	v_fma_f32 v132, v131, s4, -v132
	v_fmac_f32_e32 v132, 0x3377d1cf, v131
	s_mov_b32 s4, 0x7f800000
	v_fmac_f32_e32 v132, 0x3f317217, v131
	v_cmp_lt_f32_e64 s[12:13], |v131|, s4
	s_nop 1
	v_cndmask_b32_e64 v131, v131, v132, s[12:13]
	v_cndmask_b32_e32 v132, 0, v227, vcc
	v_sub_f32_e32 v131, v131, v132
; DEV u16 f2bf(float f) { return (u16)(pack2(f, 0.f) & 0xffffu); }
; DEV void phase_win(const Params& P, int l, const u16* __restrict__ xb, const u16* __restrict__ Wt, u16* __restrict__ h, char* smem) {
;     ...
;     const int mode = (cb >= C_HF && cb < C_HI) ? 1 : ((cb >= C_HG) ? 2 : 0);
; #pragma unroll
;     for (int ms = 0; ms < 8; ++ms) {
;       asm volatile("" ::: "memory");
; #pragma unroll
;       for (int ns = 0; ns < 4; ++ns)
; #pragma unroll
;         for (int j = 0; j < 4; ++j) {
;           int row = m0 + wm * 128 + ms * 16 + quad * 4 + j;
;           int col = cb + ns * 16 + l15;
;           float v = acc[ms][ns][j];
;           if (mode == 1) { float lbv = lbp[col - C_HF]; v = __logf(lbv + (1.f - lbv) / (1.f + __expf(-v))); }
;           else if (mode == 2) v = v / (1.f + __expf(-v));
;           h[(size_t)row * HS + col] = f2bf(v);
;         }
	v_cvt_pk_bf16_f32 v141, v131, s0
	global_store_short v139, v141, s[72:73] offset:32
	v_mul_f32_e32 v132, 0xbfb8aa3b, v79
	v_exp_f32_e32 v132, v132
	v_sub_f32_e32 v133, 1.0, v162
	v_add_f32_e32 v132, 1.0, v132
	v_div_scale_f32 v134, s[4:5], v132, v132, v133
	v_rcp_f32_e32 v135, v134
	v_div_scale_f32 v136, vcc, v133, v132, v133
	s_mov_b32 s4, 0x800000
	v_fma_f32 v137, -v134, v135, 1.0
	v_fmac_f32_e32 v135, v137, v135
	v_mul_f32_e32 v137, v136, v135
	v_fma_f32 v140, -v134, v137, v136
	v_fmac_f32_e32 v137, v140, v135
	v_fma_f32 v134, -v134, v137, v136
	v_div_fmas_f32 v134, v134, v135, v137
	v_div_fixup_f32 v132, v134, v132, v133
	v_add_f32_e32 v131, v162, v132
	v_cmp_gt_f32_e32 vcc, s4, v131
	s_mov_b32 s4, 0x3f317217
	s_nop 0
	v_cndmask_b32_e64 v132, 0, 32, vcc
	v_ldexp_f32 v131, v131, v132
	v_log_f32_e32 v131, v131
	s_nop 0
	v_mul_f32_e32 v132, 0x3f317217, v131
	v_fma_f32 v132, v131, s4, -v132
	v_fmac_f32_e32 v132, 0x3377d1cf, v131
	s_mov_b32 s4, 0x7f800000
	v_fmac_f32_e32 v132, 0x3f317217, v131
	v_cmp_lt_f32_e64 s[12:13], |v131|, s4
	s_nop 1
	v_cndmask_b32_e64 v131, v131, v132, s[12:13]
	v_cndmask_b32_e32 v132, 0, v227, vcc
	v_sub_f32_e32 v131, v131, v132
	v_cvt_pk_bf16_f32 v141, v131, s0
	global_store_short v139, v141, s[72:73] offset:64
	v_mul_f32_e32 v132, 0xbfb8aa3b, v71
	v_exp_f32_e32 v132, v132
	v_sub_f32_e32 v133, 1.0, v163
	v_add_f32_e32 v132, 1.0, v132
	v_div_scale_f32 v134, s[4:5], v132, v132, v133
	v_rcp_f32_e32 v135, v134
	v_div_scale_f32 v136, vcc, v133, v132, v133
	s_mov_b32 s4, 0x800000
	v_fma_f32 v137, -v134, v135, 1.0
	v_fmac_f32_e32 v135, v137, v135
	v_mul_f32_e32 v137, v136, v135
	v_fma_f32 v140, -v134, v137, v136
	v_fmac_f32_e32 v137, v140, v135
	v_fma_f32 v134, -v134, v137, v136
	v_div_fmas_f32 v134, v134, v135, v137
	v_div_fixup_f32 v132, v134, v132, v133
	v_add_f32_e32 v131, v163, v132
	v_cmp_gt_f32_e32 vcc, s4, v131
	s_mov_b32 s4, 0x3f317217
	s_nop 0
	v_cndmask_b32_e64 v132, 0, 32, vcc
	v_ldexp_f32 v131, v131, v132
	v_log_f32_e32 v131, v131
	s_nop 0
	v_mul_f32_e32 v132, 0x3f317217, v131
	v_fma_f32 v132, v131, s4, -v132
	v_fmac_f32_e32 v132, 0x3377d1cf, v131
	s_mov_b32 s4, 0x7f800000
	v_fmac_f32_e32 v132, 0x3f317217, v131
	v_cmp_lt_f32_e64 s[12:13], |v131|, s4
	s_nop 1
	v_cndmask_b32_e64 v131, v131, v132, s[12:13]
	v_cndmask_b32_e32 v132, 0, v227, vcc
	v_sub_f32_e32 v131, v131, v132
	v_cvt_pk_bf16_f32 v141, v131, s0
	global_store_short v139, v141, s[72:73] offset:96
	v_add_u32_e32 v139, 0x6f600, v138
	v_mul_f32_e32 v132, 0xbfb8aa3b, v16
	v_exp_f32_e32 v132, v132
	v_sub_f32_e32 v133, 1.0, v160
	v_add_f32_e32 v132, 1.0, v132
	v_div_scale_f32 v134, s[4:5], v132, v132, v133
	v_rcp_f32_e32 v135, v134
	v_div_scale_f32 v136, vcc, v133, v132, v133
	s_mov_b32 s4, 0x800000
	v_fma_f32 v137, -v134, v135, 1.0
	v_fmac_f32_e32 v135, v137, v135
	v_mul_f32_e32 v137, v136, v135
	v_fma_f32 v140, -v134, v137, v136
	v_fmac_f32_e32 v137, v140, v135
	v_fma_f32 v134, -v134, v137, v136
	v_div_fmas_f32 v134, v134, v135, v137
	v_div_fixup_f32 v132, v134, v132, v133
	v_add_f32_e32 v131, v160, v132
	v_cmp_gt_f32_e32 vcc, s4, v131
	s_mov_b32 s4, 0x3f317217
	s_nop 0
	v_cndmask_b32_e64 v132, 0, 32, vcc
	v_ldexp_f32 v131, v131, v132
	v_log_f32_e32 v131, v131
	s_nop 0
	v_mul_f32_e32 v132, 0x3f317217, v131
	v_fma_f32 v132, v131, s4, -v132
	v_fmac_f32_e32 v132, 0x3377d1cf, v131
	s_mov_b32 s4, 0x7f800000
	v_fmac_f32_e32 v132, 0x3f317217, v131
	v_cmp_lt_f32_e64 s[12:13], |v131|, s4
	s_nop 1
	v_cndmask_b32_e64 v131, v131, v132, s[12:13]
	v_cndmask_b32_e32 v132, 0, v227, vcc
	v_sub_f32_e32 v131, v131, v132
	v_cvt_pk_bf16_f32 v141, v131, s0
	global_store_short v139, v141, s[72:73]
	v_mul_f32_e32 v132, 0xbfb8aa3b, v76
	v_exp_f32_e32 v132, v132
	v_sub_f32_e32 v133, 1.0, v161
	v_add_f32_e32 v132, 1.0, v132
	v_div_scale_f32 v134, s[4:5], v132, v132, v133
	v_rcp_f32_e32 v135, v134
	v_div_scale_f32 v136, vcc, v133, v132, v133
	s_mov_b32 s4, 0x800000
	v_fma_f32 v137, -v134, v135, 1.0
	v_fmac_f32_e32 v135, v137, v135
	v_mul_f32_e32 v137, v136, v135
	v_fma_f32 v140, -v134, v137, v136
	v_fmac_f32_e32 v137, v140, v135
	v_fma_f32 v134, -v134, v137, v136
	v_div_fmas_f32 v134, v134, v135, v137
	v_div_fixup_f32 v132, v134, v132, v133
	v_add_f32_e32 v131, v161, v132
	v_cmp_gt_f32_e32 vcc, s4, v131
	s_mov_b32 s4, 0x3f317217
	s_nop 0
	v_cndmask_b32_e64 v132, 0, 32, vcc
	v_ldexp_f32 v131, v131, v132
	v_log_f32_e32 v131, v131
	s_nop 0
	v_mul_f32_e32 v132, 0x3f317217, v131
	v_fma_f32 v132, v131, s4, -v132
	v_fmac_f32_e32 v132, 0x3377d1cf, v131
	s_mov_b32 s4, 0x7f800000
	v_fmac_f32_e32 v132, 0x3f317217, v131
	v_cmp_lt_f32_e64 s[12:13], |v131|, s4
	s_nop 1
	v_cndmask_b32_e64 v131, v131, v132, s[12:13]
	v_cndmask_b32_e32 v132, 0, v227, vcc
	v_sub_f32_e32 v131, v131, v132
	v_cvt_pk_bf16_f32 v141, v131, s0
	global_store_short v139, v141, s[72:73] offset:32
	v_mul_f32_e32 v132, 0xbfb8aa3b, v80
	v_exp_f32_e32 v132, v132
	v_sub_f32_e32 v133, 1.0, v162
	v_add_f32_e32 v132, 1.0, v132
	v_div_scale_f32 v134, s[4:5], v132, v132, v133
	v_rcp_f32_e32 v135, v134
	v_div_scale_f32 v136, vcc, v133, v132, v133
	s_mov_b32 s4, 0x800000
	v_fma_f32 v137, -v134, v135, 1.0
	v_fmac_f32_e32 v135, v137, v135
	v_mul_f32_e32 v137, v136, v135
	v_fma_f32 v140, -v134, v137, v136
	v_fmac_f32_e32 v137, v140, v135
	v_fma_f32 v134, -v134, v137, v136
	v_div_fmas_f32 v134, v134, v135, v137
	v_div_fixup_f32 v132, v134, v132, v133
	v_add_f32_e32 v131, v162, v132
	v_cmp_gt_f32_e32 vcc, s4, v131
	s_mov_b32 s4, 0x3f317217
	s_nop 0
	v_cndmask_b32_e64 v132, 0, 32, vcc
	v_ldexp_f32 v131, v131, v132
	v_log_f32_e32 v131, v131
	s_nop 0
	v_mul_f32_e32 v132, 0x3f317217, v131
	v_fma_f32 v132, v131, s4, -v132
; DEV u16 f2bf(float f) { return (u16)(pack2(f, 0.f) & 0xffffu); }
; DEV void phase_win(const Params& P, int l, const u16* __restrict__ xb, const u16* __restrict__ Wt, u16* __restrict__ h, char* smem) {
;     ...
;     const int mode = (cb >= C_HF && cb < C_HI) ? 1 : ((cb >= C_HG) ? 2 : 0);
; #pragma unroll
;     for (int ms = 0; ms < 8; ++ms) {
;       asm volatile("" ::: "memory");
; #pragma unroll
;       for (int ns = 0; ns < 4; ++ns)
; #pragma unroll
;         for (int j = 0; j < 4; ++j) {
;           int row = m0 + wm * 128 + ms * 16 + quad * 4 + j;
;           int col = cb + ns * 16 + l15;
;           float v = acc[ms][ns][j];
;           if (mode == 1) { float lbv = lbp[col - C_HF]; v = __logf(lbv + (1.f - lbv) / (1.f + __expf(-v))); }
;           else if (mode == 2) v = v / (1.f + __expf(-v));
;           h[(size_t)row * HS + col] = f2bf(v);
;         }
	v_fmac_f32_e32 v132, 0x3377d1cf, v131
	s_mov_b32 s4, 0x7f800000
	v_fmac_f32_e32 v132, 0x3f317217, v131
	v_cmp_lt_f32_e64 s[12:13], |v131|, s4
	s_nop 1
	v_cndmask_b32_e64 v131, v131, v132, s[12:13]
	v_cndmask_b32_e32 v132, 0, v227, vcc
	v_sub_f32_e32 v131, v131, v132
	v_cvt_pk_bf16_f32 v141, v131, s0
	global_store_short v139, v141, s[72:73] offset:64
	v_mul_f32_e32 v132, 0xbfb8aa3b, v72
	v_exp_f32_e32 v132, v132
	v_sub_f32_e32 v133, 1.0, v163
	v_add_f32_e32 v132, 1.0, v132
	v_div_scale_f32 v134, s[4:5], v132, v132, v133
	v_rcp_f32_e32 v135, v134
	v_div_scale_f32 v136, vcc, v133, v132, v133
	s_mov_b32 s4, 0x800000
	v_fma_f32 v137, -v134, v135, 1.0
	v_fmac_f32_e32 v135, v137, v135
	v_mul_f32_e32 v137, v136, v135
	v_fma_f32 v140, -v134, v137, v136
	v_fmac_f32_e32 v137, v140, v135
	v_fma_f32 v134, -v134, v137, v136
	v_div_fmas_f32 v134, v134, v135, v137
	v_div_fixup_f32 v132, v134, v132, v133
	v_add_f32_e32 v131, v163, v132
	v_cmp_gt_f32_e32 vcc, s4, v131
	s_mov_b32 s4, 0x3f317217
	s_nop 0
	v_cndmask_b32_e64 v132, 0, 32, vcc
	v_ldexp_f32 v131, v131, v132
	v_log_f32_e32 v131, v131
	s_nop 0
	v_mul_f32_e32 v132, 0x3f317217, v131
	v_fma_f32 v132, v131, s4, -v132
	v_fmac_f32_e32 v132, 0x3377d1cf, v131
	s_mov_b32 s4, 0x7f800000
	v_fmac_f32_e32 v132, 0x3f317217, v131
	v_cmp_lt_f32_e64 s[12:13], |v131|, s4
	s_nop 1
	v_cndmask_b32_e64 v131, v131, v132, s[12:13]
	v_cndmask_b32_e32 v132, 0, v227, vcc
	v_sub_f32_e32 v131, v131, v132
	v_cvt_pk_bf16_f32 v141, v131, s0
	global_store_short v139, v141, s[72:73] offset:96
	v_add_u32_e32 v139, 0x71100, v138
	v_mul_f32_e32 v132, 0xbfb8aa3b, v17
	v_exp_f32_e32 v132, v132
	v_sub_f32_e32 v133, 1.0, v160
	v_add_f32_e32 v132, 1.0, v132
	v_div_scale_f32 v134, s[4:5], v132, v132, v133
	v_rcp_f32_e32 v135, v134
	v_div_scale_f32 v136, vcc, v133, v132, v133
	s_mov_b32 s4, 0x800000
	v_fma_f32 v137, -v134, v135, 1.0
	v_fmac_f32_e32 v135, v137, v135
	v_mul_f32_e32 v137, v136, v135
	v_fma_f32 v140, -v134, v137, v136
	v_fmac_f32_e32 v137, v140, v135
	v_fma_f32 v134, -v134, v137, v136
	v_div_fmas_f32 v134, v134, v135, v137
	v_div_fixup_f32 v132, v134, v132, v133
	v_add_f32_e32 v131, v160, v132
	v_cmp_gt_f32_e32 vcc, s4, v131
	s_mov_b32 s4, 0x3f317217
	s_nop 0
	v_cndmask_b32_e64 v132, 0, 32, vcc
	v_ldexp_f32 v131, v131, v132
	v_log_f32_e32 v131, v131
	s_nop 0
	v_mul_f32_e32 v132, 0x3f317217, v131
	v_fma_f32 v132, v131, s4, -v132
	v_fmac_f32_e32 v132, 0x3377d1cf, v131
	s_mov_b32 s4, 0x7f800000
	v_fmac_f32_e32 v132, 0x3f317217, v131
	v_cmp_lt_f32_e64 s[12:13], |v131|, s4
	s_nop 1
	v_cndmask_b32_e64 v131, v131, v132, s[12:13]
	v_cndmask_b32_e32 v132, 0, v227, vcc
	v_sub_f32_e32 v131, v131, v132
	v_cvt_pk_bf16_f32 v141, v131, s0
	global_store_short v139, v141, s[72:73]
	v_mul_f32_e32 v132, 0xbfb8aa3b, v77
	v_exp_f32_e32 v132, v132
	v_sub_f32_e32 v133, 1.0, v161
	v_add_f32_e32 v132, 1.0, v132
	v_div_scale_f32 v134, s[4:5], v132, v132, v133
	v_rcp_f32_e32 v135, v134
	v_div_scale_f32 v136, vcc, v133, v132, v133
	s_mov_b32 s4, 0x800000
	v_fma_f32 v137, -v134, v135, 1.0
	v_fmac_f32_e32 v135, v137, v135
	v_mul_f32_e32 v137, v136, v135
	v_fma_f32 v140, -v134, v137, v136
	v_fmac_f32_e32 v137, v140, v135
	v_fma_f32 v134, -v134, v137, v136
	v_div_fmas_f32 v134, v134, v135, v137
	v_div_fixup_f32 v132, v134, v132, v133
	v_add_f32_e32 v131, v161, v132
	v_cmp_gt_f32_e32 vcc, s4, v131
	s_mov_b32 s4, 0x3f317217
	s_nop 0
	v_cndmask_b32_e64 v132, 0, 32, vcc
	v_ldexp_f32 v131, v131, v132
	v_log_f32_e32 v131, v131
	s_nop 0
	v_mul_f32_e32 v132, 0x3f317217, v131
	v_fma_f32 v132, v131, s4, -v132
	v_fmac_f32_e32 v132, 0x3377d1cf, v131
	s_mov_b32 s4, 0x7f800000
	v_fmac_f32_e32 v132, 0x3f317217, v131
	v_cmp_lt_f32_e64 s[12:13], |v131|, s4
	s_nop 1
	v_cndmask_b32_e64 v131, v131, v132, s[12:13]
	v_cndmask_b32_e32 v132, 0, v227, vcc
	v_sub_f32_e32 v131, v131, v132
	v_cvt_pk_bf16_f32 v141, v131, s0
	global_store_short v139, v141, s[72:73] offset:32
	v_mul_f32_e32 v132, 0xbfb8aa3b, v81
	v_exp_f32_e32 v132, v132
	v_sub_f32_e32 v133, 1.0, v162
	v_add_f32_e32 v132, 1.0, v132
	v_div_scale_f32 v134, s[4:5], v132, v132, v133
	v_rcp_f32_e32 v135, v134
	v_div_scale_f32 v136, vcc, v133, v132, v133
	s_mov_b32 s4, 0x800000
	v_fma_f32 v137, -v134, v135, 1.0
	v_fmac_f32_e32 v135, v137, v135
	v_mul_f32_e32 v137, v136, v135
	v_fma_f32 v140, -v134, v137, v136
	v_fmac_f32_e32 v137, v140, v135
	v_fma_f32 v134, -v134, v137, v136
	v_div_fmas_f32 v134, v134, v135, v137
	v_div_fixup_f32 v132, v134, v132, v133
	v_add_f32_e32 v131, v162, v132
	v_cmp_gt_f32_e32 vcc, s4, v131
	s_mov_b32 s4, 0x3f317217
	s_nop 0
	v_cndmask_b32_e64 v132, 0, 32, vcc
	v_ldexp_f32 v131, v131, v132
	v_log_f32_e32 v131, v131
	s_nop 0
	v_mul_f32_e32 v132, 0x3f317217, v131
	v_fma_f32 v132, v131, s4, -v132
	v_fmac_f32_e32 v132, 0x3377d1cf, v131
	s_mov_b32 s4, 0x7f800000
	v_fmac_f32_e32 v132, 0x3f317217, v131
	v_cmp_lt_f32_e64 s[12:13], |v131|, s4
	s_nop 1
	v_cndmask_b32_e64 v131, v131, v132, s[12:13]
	v_cndmask_b32_e32 v132, 0, v227, vcc
	v_sub_f32_e32 v131, v131, v132
	v_cvt_pk_bf16_f32 v141, v131, s0
	global_store_short v139, v141, s[72:73] offset:64
	v_mul_f32_e32 v132, 0xbfb8aa3b, v73
	v_exp_f32_e32 v132, v132
	v_sub_f32_e32 v133, 1.0, v163
	v_add_f32_e32 v132, 1.0, v132
	v_div_scale_f32 v134, s[4:5], v132, v132, v133
	v_rcp_f32_e32 v135, v134
	v_div_scale_f32 v136, vcc, v133, v132, v133
	s_mov_b32 s4, 0x800000
	v_fma_f32 v137, -v134, v135, 1.0
	v_fmac_f32_e32 v135, v137, v135
	v_mul_f32_e32 v137, v136, v135
	v_fma_f32 v140, -v134, v137, v136
	v_fmac_f32_e32 v137, v140, v135
	v_fma_f32 v134, -v134, v137, v136
	v_div_fmas_f32 v134, v134, v135, v137
	v_div_fixup_f32 v132, v134, v132, v133
	v_add_f32_e32 v131, v163, v132
; DEV u16 f2bf(float f) { return (u16)(pack2(f, 0.f) & 0xffffu); }
; DEV void phase_win(const Params& P, int l, const u16* __restrict__ xb, const u16* __restrict__ Wt, u16* __restrict__ h, char* smem) {
;     ...
;     const int mode = (cb >= C_HF && cb < C_HI) ? 1 : ((cb >= C_HG) ? 2 : 0);
; #pragma unroll
;     for (int ms = 0; ms < 8; ++ms) {
;       asm volatile("" ::: "memory");
; #pragma unroll
;       for (int ns = 0; ns < 4; ++ns)
; #pragma unroll
;         for (int j = 0; j < 4; ++j) {
;           int row = m0 + wm * 128 + ms * 16 + quad * 4 + j;
;           int col = cb + ns * 16 + l15;
;           float v = acc[ms][ns][j];
;           if (mode == 1) { float lbv = lbp[col - C_HF]; v = __logf(lbv + (1.f - lbv) / (1.f + __expf(-v))); }
;           else if (mode == 2) v = v / (1.f + __expf(-v));
;           h[(size_t)row * HS + col] = f2bf(v);
;         }
	v_cmp_gt_f32_e32 vcc, s4, v131
	s_mov_b32 s4, 0x3f317217
	s_nop 0
	v_cndmask_b32_e64 v132, 0, 32, vcc
	v_ldexp_f32 v131, v131, v132
	v_log_f32_e32 v131, v131
	s_nop 0
	v_mul_f32_e32 v132, 0x3f317217, v131
	v_fma_f32 v132, v131, s4, -v132
	v_fmac_f32_e32 v132, 0x3377d1cf, v131
	s_mov_b32 s4, 0x7f800000
	v_fmac_f32_e32 v132, 0x3f317217, v131
	v_cmp_lt_f32_e64 s[12:13], |v131|, s4
	s_nop 1
	v_cndmask_b32_e64 v131, v131, v132, s[12:13]
	v_cndmask_b32_e32 v132, 0, v227, vcc
	v_sub_f32_e32 v131, v131, v132
	v_cvt_pk_bf16_f32 v141, v131, s0
	global_store_short v139, v141, s[72:73] offset:96
	v_add_u32_e32 v139, 0x87000, v138
	v_mul_f32_e32 v132, 0xbfb8aa3b, v10
	v_exp_f32_e32 v132, v132
	v_sub_f32_e32 v133, 1.0, v160
	v_add_f32_e32 v132, 1.0, v132
	v_div_scale_f32 v134, s[4:5], v132, v132, v133
	v_rcp_f32_e32 v135, v134
	v_div_scale_f32 v136, vcc, v133, v132, v133
	s_mov_b32 s4, 0x800000
	v_fma_f32 v137, -v134, v135, 1.0
	v_fmac_f32_e32 v135, v137, v135
	v_mul_f32_e32 v137, v136, v135
	v_fma_f32 v140, -v134, v137, v136
	v_fmac_f32_e32 v137, v140, v135
	v_fma_f32 v134, -v134, v137, v136
	v_div_fmas_f32 v134, v134, v135, v137
	v_div_fixup_f32 v132, v134, v132, v133
	v_add_f32_e32 v131, v160, v132
	v_cmp_gt_f32_e32 vcc, s4, v131
	s_mov_b32 s4, 0x3f317217
	s_nop 0
	v_cndmask_b32_e64 v132, 0, 32, vcc
	v_ldexp_f32 v131, v131, v132
	v_log_f32_e32 v131, v131
	s_nop 0
	v_mul_f32_e32 v132, 0x3f317217, v131
	v_fma_f32 v132, v131, s4, -v132
	v_fmac_f32_e32 v132, 0x3377d1cf, v131
	s_mov_b32 s4, 0x7f800000
	v_fmac_f32_e32 v132, 0x3f317217, v131
	v_cmp_lt_f32_e64 s[12:13], |v131|, s4
	s_nop 1
	v_cndmask_b32_e64 v131, v131, v132, s[12:13]
	v_cndmask_b32_e32 v132, 0, v227, vcc
	v_sub_f32_e32 v131, v131, v132
	v_cvt_pk_bf16_f32 v141, v131, s0
	global_store_short v139, v141, s[72:73]
	v_mul_f32_e32 v132, 0xbfb8aa3b, v62
	v_exp_f32_e32 v132, v132
	v_sub_f32_e32 v133, 1.0, v161
	v_add_f32_e32 v132, 1.0, v132
	v_div_scale_f32 v134, s[4:5], v132, v132, v133
	v_rcp_f32_e32 v135, v134
	v_div_scale_f32 v136, vcc, v133, v132, v133
	s_mov_b32 s4, 0x800000
	v_fma_f32 v137, -v134, v135, 1.0
	v_fmac_f32_e32 v135, v137, v135
	v_mul_f32_e32 v137, v136, v135
	v_fma_f32 v140, -v134, v137, v136
	v_fmac_f32_e32 v137, v140, v135
	v_fma_f32 v134, -v134, v137, v136
	v_div_fmas_f32 v134, v134, v135, v137
	v_div_fixup_f32 v132, v134, v132, v133
	v_add_f32_e32 v131, v161, v132
	v_cmp_gt_f32_e32 vcc, s4, v131
	s_mov_b32 s4, 0x3f317217
	s_nop 0
	v_cndmask_b32_e64 v132, 0, 32, vcc
	v_ldexp_f32 v131, v131, v132
	v_log_f32_e32 v131, v131
	s_nop 0
	v_mul_f32_e32 v132, 0x3f317217, v131
	v_fma_f32 v132, v131, s4, -v132
	v_fmac_f32_e32 v132, 0x3377d1cf, v131
	s_mov_b32 s4, 0x7f800000
	v_fmac_f32_e32 v132, 0x3f317217, v131
	v_cmp_lt_f32_e64 s[12:13], |v131|, s4
	s_nop 1
	v_cndmask_b32_e64 v131, v131, v132, s[12:13]
	v_cndmask_b32_e32 v132, 0, v227, vcc
	v_sub_f32_e32 v131, v131, v132
	v_cvt_pk_bf16_f32 v141, v131, s0
	global_store_short v139, v141, s[72:73] offset:32
	v_mul_f32_e32 v132, 0xbfb8aa3b, v66
	v_exp_f32_e32 v132, v132
	v_sub_f32_e32 v133, 1.0, v162
	v_add_f32_e32 v132, 1.0, v132
	v_div_scale_f32 v134, s[4:5], v132, v132, v133
	v_rcp_f32_e32 v135, v134
	v_div_scale_f32 v136, vcc, v133, v132, v133
	s_mov_b32 s4, 0x800000
	v_fma_f32 v137, -v134, v135, 1.0
	v_fmac_f32_e32 v135, v137, v135
	v_mul_f32_e32 v137, v136, v135
	v_fma_f32 v140, -v134, v137, v136
	v_fmac_f32_e32 v137, v140, v135
	v_fma_f32 v134, -v134, v137, v136
	v_div_fmas_f32 v134, v134, v135, v137
	v_div_fixup_f32 v132, v134, v132, v133
	v_add_f32_e32 v131, v162, v132
	v_cmp_gt_f32_e32 vcc, s4, v131
	s_mov_b32 s4, 0x3f317217
	s_nop 0
	v_cndmask_b32_e64 v132, 0, 32, vcc
	v_ldexp_f32 v131, v131, v132
	v_log_f32_e32 v131, v131
	s_nop 0
	v_mul_f32_e32 v132, 0x3f317217, v131
	v_fma_f32 v132, v131, s4, -v132
	v_fmac_f32_e32 v132, 0x3377d1cf, v131
	s_mov_b32 s4, 0x7f800000
	v_fmac_f32_e32 v132, 0x3f317217, v131
	v_cmp_lt_f32_e64 s[12:13], |v131|, s4
	s_nop 1
	v_cndmask_b32_e64 v131, v131, v132, s[12:13]
	v_cndmask_b32_e32 v132, 0, v227, vcc
	v_sub_f32_e32 v131, v131, v132
	v_cvt_pk_bf16_f32 v141, v131, s0
	global_store_short v139, v141, s[72:73] offset:64
	v_mul_f32_e32 v132, 0xbfb8aa3b, v58
	v_exp_f32_e32 v132, v132
	v_sub_f32_e32 v133, 1.0, v163
	v_add_f32_e32 v132, 1.0, v132
	v_div_scale_f32 v134, s[4:5], v132, v132, v133
	v_rcp_f32_e32 v135, v134
	v_div_scale_f32 v136, vcc, v133, v132, v133
	s_mov_b32 s4, 0x800000
	v_fma_f32 v137, -v134, v135, 1.0
	v_fmac_f32_e32 v135, v137, v135
	v_mul_f32_e32 v137, v136, v135
	v_fma_f32 v140, -v134, v137, v136
	v_fmac_f32_e32 v137, v140, v135
	v_fma_f32 v134, -v134, v137, v136
	v_div_fmas_f32 v134, v134, v135, v137
	v_div_fixup_f32 v132, v134, v132, v133
	v_add_f32_e32 v131, v163, v132
	v_cmp_gt_f32_e32 vcc, s4, v131
	s_mov_b32 s4, 0x3f317217
	s_nop 0
	v_cndmask_b32_e64 v132, 0, 32, vcc
	v_ldexp_f32 v131, v131, v132
	v_log_f32_e32 v131, v131
	s_nop 0
	v_mul_f32_e32 v132, 0x3f317217, v131
	v_fma_f32 v132, v131, s4, -v132
	v_fmac_f32_e32 v132, 0x3377d1cf, v131
	s_mov_b32 s4, 0x7f800000
	v_fmac_f32_e32 v132, 0x3f317217, v131
	v_cmp_lt_f32_e64 s[12:13], |v131|, s4
	s_nop 1
	v_cndmask_b32_e64 v131, v131, v132, s[12:13]
	v_cndmask_b32_e32 v132, 0, v227, vcc
	v_sub_f32_e32 v131, v131, v132
	v_cvt_pk_bf16_f32 v141, v131, s0
	global_store_short v139, v141, s[72:73] offset:96
	v_add_u32_e32 v139, 0x88b00, v138
	v_mul_f32_e32 v132, 0xbfb8aa3b, v11
	v_exp_f32_e32 v132, v132
	v_sub_f32_e32 v133, 1.0, v160
	v_add_f32_e32 v132, 1.0, v132
	v_div_scale_f32 v134, s[4:5], v132, v132, v133
	v_rcp_f32_e32 v135, v134
	v_div_scale_f32 v136, vcc, v133, v132, v133
	s_mov_b32 s4, 0x800000
	v_fma_f32 v137, -v134, v135, 1.0
; DEV u16 f2bf(float f) { return (u16)(pack2(f, 0.f) & 0xffffu); }
; DEV void phase_win(const Params& P, int l, const u16* __restrict__ xb, const u16* __restrict__ Wt, u16* __restrict__ h, char* smem) {
;     ...
;     const int mode = (cb >= C_HF && cb < C_HI) ? 1 : ((cb >= C_HG) ? 2 : 0);
; #pragma unroll
;     for (int ms = 0; ms < 8; ++ms) {
;       asm volatile("" ::: "memory");
; #pragma unroll
;       for (int ns = 0; ns < 4; ++ns)
; #pragma unroll
;         for (int j = 0; j < 4; ++j) {
;           int row = m0 + wm * 128 + ms * 16 + quad * 4 + j;
;           int col = cb + ns * 16 + l15;
;           float v = acc[ms][ns][j];
;           if (mode == 1) { float lbv = lbp[col - C_HF]; v = __logf(lbv + (1.f - lbv) / (1.f + __expf(-v))); }
;           else if (mode == 2) v = v / (1.f + __expf(-v));
;           h[(size_t)row * HS + col] = f2bf(v);
;         }
	v_fmac_f32_e32 v135, v137, v135
	v_mul_f32_e32 v137, v136, v135
	v_fma_f32 v140, -v134, v137, v136
	v_fmac_f32_e32 v137, v140, v135
	v_fma_f32 v134, -v134, v137, v136
	v_div_fmas_f32 v134, v134, v135, v137
	v_div_fixup_f32 v132, v134, v132, v133
	v_add_f32_e32 v131, v160, v132
	v_cmp_gt_f32_e32 vcc, s4, v131
	s_mov_b32 s4, 0x3f317217
	s_nop 0
	v_cndmask_b32_e64 v132, 0, 32, vcc
	v_ldexp_f32 v131, v131, v132
	v_log_f32_e32 v131, v131
	s_nop 0
	v_mul_f32_e32 v132, 0x3f317217, v131
	v_fma_f32 v132, v131, s4, -v132
	v_fmac_f32_e32 v132, 0x3377d1cf, v131
	s_mov_b32 s4, 0x7f800000
	v_fmac_f32_e32 v132, 0x3f317217, v131
	v_cmp_lt_f32_e64 s[12:13], |v131|, s4
	s_nop 1
	v_cndmask_b32_e64 v131, v131, v132, s[12:13]
	v_cndmask_b32_e32 v132, 0, v227, vcc
	v_sub_f32_e32 v131, v131, v132
	v_cvt_pk_bf16_f32 v141, v131, s0
	global_store_short v139, v141, s[72:73]
	v_mul_f32_e32 v132, 0xbfb8aa3b, v63
	v_exp_f32_e32 v132, v132
	v_sub_f32_e32 v133, 1.0, v161
	v_add_f32_e32 v132, 1.0, v132
	v_div_scale_f32 v134, s[4:5], v132, v132, v133
	v_rcp_f32_e32 v135, v134
	v_div_scale_f32 v136, vcc, v133, v132, v133
	s_mov_b32 s4, 0x800000
	v_fma_f32 v137, -v134, v135, 1.0
	v_fmac_f32_e32 v135, v137, v135
	v_mul_f32_e32 v137, v136, v135
	v_fma_f32 v140, -v134, v137, v136
	v_fmac_f32_e32 v137, v140, v135
	v_fma_f32 v134, -v134, v137, v136
	v_div_fmas_f32 v134, v134, v135, v137
	v_div_fixup_f32 v132, v134, v132, v133
	v_add_f32_e32 v131, v161, v132
	v_cmp_gt_f32_e32 vcc, s4, v131
	s_mov_b32 s4, 0x3f317217
	s_nop 0
	v_cndmask_b32_e64 v132, 0, 32, vcc
	v_ldexp_f32 v131, v131, v132
	v_log_f32_e32 v131, v131
	s_nop 0
	v_mul_f32_e32 v132, 0x3f317217, v131
	v_fma_f32 v132, v131, s4, -v132
	v_fmac_f32_e32 v132, 0x3377d1cf, v131
	s_mov_b32 s4, 0x7f800000
	v_fmac_f32_e32 v132, 0x3f317217, v131
	v_cmp_lt_f32_e64 s[12:13], |v131|, s4
	s_nop 1
	v_cndmask_b32_e64 v131, v131, v132, s[12:13]
	v_cndmask_b32_e32 v132, 0, v227, vcc
	v_sub_f32_e32 v131, v131, v132
	v_cvt_pk_bf16_f32 v141, v131, s0
	global_store_short v139, v141, s[72:73] offset:32
	v_mul_f32_e32 v132, 0xbfb8aa3b, v67
	v_exp_f32_e32 v132, v132
	v_sub_f32_e32 v133, 1.0, v162
	v_add_f32_e32 v132, 1.0, v132
	v_div_scale_f32 v134, s[4:5], v132, v132, v133
	v_rcp_f32_e32 v135, v134
	v_div_scale_f32 v136, vcc, v133, v132, v133
	s_mov_b32 s4, 0x800000
	v_fma_f32 v137, -v134, v135, 1.0
	v_fmac_f32_e32 v135, v137, v135
	v_mul_f32_e32 v137, v136, v135
	v_fma_f32 v140, -v134, v137, v136
	v_fmac_f32_e32 v137, v140, v135
	v_fma_f32 v134, -v134, v137, v136
	v_div_fmas_f32 v134, v134, v135, v137
	v_div_fixup_f32 v132, v134, v132, v133
	v_add_f32_e32 v131, v162, v132
	v_cmp_gt_f32_e32 vcc, s4, v131
	s_mov_b32 s4, 0x3f317217
	s_nop 0
	v_cndmask_b32_e64 v132, 0, 32, vcc
	v_ldexp_f32 v131, v131, v132
	v_log_f32_e32 v131, v131
	s_nop 0
	v_mul_f32_e32 v132, 0x3f317217, v131
	v_fma_f32 v132, v131, s4, -v132
	v_fmac_f32_e32 v132, 0x3377d1cf, v131
	s_mov_b32 s4, 0x7f800000
	v_fmac_f32_e32 v132, 0x3f317217, v131
	v_cmp_lt_f32_e64 s[12:13], |v131|, s4
	s_nop 1
	v_cndmask_b32_e64 v131, v131, v132, s[12:13]
	v_cndmask_b32_e32 v132, 0, v227, vcc
	v_sub_f32_e32 v131, v131, v132
	v_cvt_pk_bf16_f32 v141, v131, s0
	global_store_short v139, v141, s[72:73] offset:64
	v_mul_f32_e32 v132, 0xbfb8aa3b, v59
	v_exp_f32_e32 v132, v132
	v_sub_f32_e32 v133, 1.0, v163
	v_add_f32_e32 v132, 1.0, v132
	v_div_scale_f32 v134, s[4:5], v132, v132, v133
	v_rcp_f32_e32 v135, v134
	v_div_scale_f32 v136, vcc, v133, v132, v133
	s_mov_b32 s4, 0x800000
	v_fma_f32 v137, -v134, v135, 1.0
	v_fmac_f32_e32 v135, v137, v135
	v_mul_f32_e32 v137, v136, v135
	v_fma_f32 v140, -v134, v137, v136
	v_fmac_f32_e32 v137, v140, v135
	v_fma_f32 v134, -v134, v137, v136
	v_div_fmas_f32 v134, v134, v135, v137
	v_div_fixup_f32 v132, v134, v132, v133
	v_add_f32_e32 v131, v163, v132
	v_cmp_gt_f32_e32 vcc, s4, v131
	s_mov_b32 s4, 0x3f317217
	s_nop 0
	v_cndmask_b32_e64 v132, 0, 32, vcc
	v_ldexp_f32 v131, v131, v132
	v_log_f32_e32 v131, v131
	s_nop 0
	v_mul_f32_e32 v132, 0x3f317217, v131
	v_fma_f32 v132, v131, s4, -v132
	v_fmac_f32_e32 v132, 0x3377d1cf, v131
	s_mov_b32 s4, 0x7f800000
	v_fmac_f32_e32 v132, 0x3f317217, v131
	v_cmp_lt_f32_e64 s[12:13], |v131|, s4
	s_nop 1
	v_cndmask_b32_e64 v131, v131, v132, s[12:13]
	v_cndmask_b32_e32 v132, 0, v227, vcc
	v_sub_f32_e32 v131, v131, v132
	v_cvt_pk_bf16_f32 v141, v131, s0
	global_store_short v139, v141, s[72:73] offset:96
	v_add_u32_e32 v139, 0x8a600, v138
	v_mul_f32_e32 v132, 0xbfb8aa3b, v12
	v_exp_f32_e32 v132, v132
	v_sub_f32_e32 v133, 1.0, v160
	v_add_f32_e32 v132, 1.0, v132
	v_div_scale_f32 v134, s[4:5], v132, v132, v133
	v_rcp_f32_e32 v135, v134
	v_div_scale_f32 v136, vcc, v133, v132, v133
	s_mov_b32 s4, 0x800000
	v_fma_f32 v137, -v134, v135, 1.0
	v_fmac_f32_e32 v135, v137, v135
	v_mul_f32_e32 v137, v136, v135
	v_fma_f32 v140, -v134, v137, v136
	v_fmac_f32_e32 v137, v140, v135
	v_fma_f32 v134, -v134, v137, v136
	v_div_fmas_f32 v134, v134, v135, v137
	v_div_fixup_f32 v132, v134, v132, v133
	v_add_f32_e32 v131, v160, v132
	v_cmp_gt_f32_e32 vcc, s4, v131
	s_mov_b32 s4, 0x3f317217
	s_nop 0
	v_cndmask_b32_e64 v132, 0, 32, vcc
	v_ldexp_f32 v131, v131, v132
	v_log_f32_e32 v131, v131
	s_nop 0
	v_mul_f32_e32 v132, 0x3f317217, v131
	v_fma_f32 v132, v131, s4, -v132
	v_fmac_f32_e32 v132, 0x3377d1cf, v131
	s_mov_b32 s4, 0x7f800000
	v_fmac_f32_e32 v132, 0x3f317217, v131
	v_cmp_lt_f32_e64 s[12:13], |v131|, s4
	s_nop 1
	v_cndmask_b32_e64 v131, v131, v132, s[12:13]
	v_cndmask_b32_e32 v132, 0, v227, vcc
	v_sub_f32_e32 v131, v131, v132
	v_cvt_pk_bf16_f32 v141, v131, s0
	global_store_short v139, v141, s[72:73]
	v_mul_f32_e32 v132, 0xbfb8aa3b, v64
	v_exp_f32_e32 v132, v132
; DEV u16 f2bf(float f) { return (u16)(pack2(f, 0.f) & 0xffffu); }
; DEV void phase_win(const Params& P, int l, const u16* __restrict__ xb, const u16* __restrict__ Wt, u16* __restrict__ h, char* smem) {
;     ...
;     const int mode = (cb >= C_HF && cb < C_HI) ? 1 : ((cb >= C_HG) ? 2 : 0);
; #pragma unroll
;     for (int ms = 0; ms < 8; ++ms) {
;       asm volatile("" ::: "memory");
; #pragma unroll
;       for (int ns = 0; ns < 4; ++ns)
; #pragma unroll
;         for (int j = 0; j < 4; ++j) {
;           int row = m0 + wm * 128 + ms * 16 + quad * 4 + j;
;           int col = cb + ns * 16 + l15;
;           float v = acc[ms][ns][j];
;           if (mode == 1) { float lbv = lbp[col - C_HF]; v = __logf(lbv + (1.f - lbv) / (1.f + __expf(-v))); }
;           else if (mode == 2) v = v / (1.f + __expf(-v));
;           h[(size_t)row * HS + col] = f2bf(v);
;         }
	v_sub_f32_e32 v133, 1.0, v161
	v_add_f32_e32 v132, 1.0, v132
	v_div_scale_f32 v134, s[4:5], v132, v132, v133
	v_rcp_f32_e32 v135, v134
	v_div_scale_f32 v136, vcc, v133, v132, v133
	s_mov_b32 s4, 0x800000
	v_fma_f32 v137, -v134, v135, 1.0
	v_fmac_f32_e32 v135, v137, v135
	v_mul_f32_e32 v137, v136, v135
	v_fma_f32 v140, -v134, v137, v136
	v_fmac_f32_e32 v137, v140, v135
	v_fma_f32 v134, -v134, v137, v136
	v_div_fmas_f32 v134, v134, v135, v137
	v_div_fixup_f32 v132, v134, v132, v133
	v_add_f32_e32 v131, v161, v132
	v_cmp_gt_f32_e32 vcc, s4, v131
	s_mov_b32 s4, 0x3f317217
	s_nop 0
	v_cndmask_b32_e64 v132, 0, 32, vcc
	v_ldexp_f32 v131, v131, v132
	v_log_f32_e32 v131, v131
	s_nop 0
	v_mul_f32_e32 v132, 0x3f317217, v131
	v_fma_f32 v132, v131, s4, -v132
	v_fmac_f32_e32 v132, 0x3377d1cf, v131
	s_mov_b32 s4, 0x7f800000
	v_fmac_f32_e32 v132, 0x3f317217, v131
	v_cmp_lt_f32_e64 s[12:13], |v131|, s4
	s_nop 1
	v_cndmask_b32_e64 v131, v131, v132, s[12:13]
	v_cndmask_b32_e32 v132, 0, v227, vcc
	v_sub_f32_e32 v131, v131, v132
	v_cvt_pk_bf16_f32 v141, v131, s0
	global_store_short v139, v141, s[72:73] offset:32
	v_mul_f32_e32 v132, 0xbfb8aa3b, v68
	v_exp_f32_e32 v132, v132
	v_sub_f32_e32 v133, 1.0, v162
	v_add_f32_e32 v132, 1.0, v132
	v_div_scale_f32 v134, s[4:5], v132, v132, v133
	v_rcp_f32_e32 v135, v134
	v_div_scale_f32 v136, vcc, v133, v132, v133
	s_mov_b32 s4, 0x800000
	v_fma_f32 v137, -v134, v135, 1.0
	v_fmac_f32_e32 v135, v137, v135
	v_mul_f32_e32 v137, v136, v135
	v_fma_f32 v140, -v134, v137, v136
	v_fmac_f32_e32 v137, v140, v135
	v_fma_f32 v134, -v134, v137, v136
	v_div_fmas_f32 v134, v134, v135, v137
	v_div_fixup_f32 v132, v134, v132, v133
	v_add_f32_e32 v131, v162, v132
	v_cmp_gt_f32_e32 vcc, s4, v131
	s_mov_b32 s4, 0x3f317217
	s_nop 0
	v_cndmask_b32_e64 v132, 0, 32, vcc
	v_ldexp_f32 v131, v131, v132
	v_log_f32_e32 v131, v131
	s_nop 0
	v_mul_f32_e32 v132, 0x3f317217, v131
	v_fma_f32 v132, v131, s4, -v132
	v_fmac_f32_e32 v132, 0x3377d1cf, v131
	s_mov_b32 s4, 0x7f800000
	v_fmac_f32_e32 v132, 0x3f317217, v131
	v_cmp_lt_f32_e64 s[12:13], |v131|, s4
	s_nop 1
	v_cndmask_b32_e64 v131, v131, v132, s[12:13]
	v_cndmask_b32_e32 v132, 0, v227, vcc
	v_sub_f32_e32 v131, v131, v132
	v_cvt_pk_bf16_f32 v141, v131, s0
	global_store_short v139, v141, s[72:73] offset:64
	v_mul_f32_e32 v132, 0xbfb8aa3b, v60
	v_exp_f32_e32 v132, v132
	v_sub_f32_e32 v133, 1.0, v163
	v_add_f32_e32 v132, 1.0, v132
	v_div_scale_f32 v134, s[4:5], v132, v132, v133
	v_rcp_f32_e32 v135, v134
	v_div_scale_f32 v136, vcc, v133, v132, v133
	s_mov_b32 s4, 0x800000
	v_fma_f32 v137, -v134, v135, 1.0
	v_fmac_f32_e32 v135, v137, v135
	v_mul_f32_e32 v137, v136, v135
	v_fma_f32 v140, -v134, v137, v136
	v_fmac_f32_e32 v137, v140, v135
	v_fma_f32 v134, -v134, v137, v136
	v_div_fmas_f32 v134, v134, v135, v137
	v_div_fixup_f32 v132, v134, v132, v133
	v_add_f32_e32 v131, v163, v132
	v_cmp_gt_f32_e32 vcc, s4, v131
	s_mov_b32 s4, 0x3f317217
	s_nop 0
	v_cndmask_b32_e64 v132, 0, 32, vcc
	v_ldexp_f32 v131, v131, v132
	v_log_f32_e32 v131, v131
	s_nop 0
	v_mul_f32_e32 v132, 0x3f317217, v131
	v_fma_f32 v132, v131, s4, -v132
	v_fmac_f32_e32 v132, 0x3377d1cf, v131
	s_mov_b32 s4, 0x7f800000
	v_fmac_f32_e32 v132, 0x3f317217, v131
	v_cmp_lt_f32_e64 s[12:13], |v131|, s4
	s_nop 1
	v_cndmask_b32_e64 v131, v131, v132, s[12:13]
	v_cndmask_b32_e32 v132, 0, v227, vcc
	v_sub_f32_e32 v131, v131, v132
	v_cvt_pk_bf16_f32 v141, v131, s0
	global_store_short v139, v141, s[72:73] offset:96
	v_add_u32_e32 v139, 0x8c100, v138
	v_mul_f32_e32 v132, 0xbfb8aa3b, v13
	v_exp_f32_e32 v132, v132
	v_sub_f32_e32 v133, 1.0, v160
	v_add_f32_e32 v132, 1.0, v132
	v_div_scale_f32 v134, s[4:5], v132, v132, v133
	v_rcp_f32_e32 v135, v134
	v_div_scale_f32 v136, vcc, v133, v132, v133
	s_mov_b32 s4, 0x800000
	v_fma_f32 v137, -v134, v135, 1.0
	v_fmac_f32_e32 v135, v137, v135
	v_mul_f32_e32 v137, v136, v135
	v_fma_f32 v140, -v134, v137, v136
	v_fmac_f32_e32 v137, v140, v135
	v_fma_f32 v134, -v134, v137, v136
	v_div_fmas_f32 v134, v134, v135, v137
	v_div_fixup_f32 v132, v134, v132, v133
	v_add_f32_e32 v131, v160, v132
	v_cmp_gt_f32_e32 vcc, s4, v131
	s_mov_b32 s4, 0x3f317217
	s_nop 0
	v_cndmask_b32_e64 v132, 0, 32, vcc
	v_ldexp_f32 v131, v131, v132
	v_log_f32_e32 v131, v131
	s_nop 0
	v_mul_f32_e32 v132, 0x3f317217, v131
	v_fma_f32 v132, v131, s4, -v132
	v_fmac_f32_e32 v132, 0x3377d1cf, v131
	s_mov_b32 s4, 0x7f800000
	v_fmac_f32_e32 v132, 0x3f317217, v131
	v_cmp_lt_f32_e64 s[12:13], |v131|, s4
	s_nop 1
	v_cndmask_b32_e64 v131, v131, v132, s[12:13]
	v_cndmask_b32_e32 v132, 0, v227, vcc
	v_sub_f32_e32 v131, v131, v132
	v_cvt_pk_bf16_f32 v141, v131, s0
	global_store_short v139, v141, s[72:73]
	v_mul_f32_e32 v132, 0xbfb8aa3b, v65
	v_exp_f32_e32 v132, v132
	v_sub_f32_e32 v133, 1.0, v161
	v_add_f32_e32 v132, 1.0, v132
	v_div_scale_f32 v134, s[4:5], v132, v132, v133
	v_rcp_f32_e32 v135, v134
	v_div_scale_f32 v136, vcc, v133, v132, v133
	s_mov_b32 s4, 0x800000
	v_fma_f32 v137, -v134, v135, 1.0
	v_fmac_f32_e32 v135, v137, v135
	v_mul_f32_e32 v137, v136, v135
	v_fma_f32 v140, -v134, v137, v136
	v_fmac_f32_e32 v137, v140, v135
	v_fma_f32 v134, -v134, v137, v136
	v_div_fmas_f32 v134, v134, v135, v137
	v_div_fixup_f32 v132, v134, v132, v133
	v_add_f32_e32 v131, v161, v132
	v_cmp_gt_f32_e32 vcc, s4, v131
	s_mov_b32 s4, 0x3f317217
	s_nop 0
	v_cndmask_b32_e64 v132, 0, 32, vcc
	v_ldexp_f32 v131, v131, v132
	v_log_f32_e32 v131, v131
	s_nop 0
	v_mul_f32_e32 v132, 0x3f317217, v131
	v_fma_f32 v132, v131, s4, -v132
	v_fmac_f32_e32 v132, 0x3377d1cf, v131
	s_mov_b32 s4, 0x7f800000
	v_fmac_f32_e32 v132, 0x3f317217, v131
	v_cmp_lt_f32_e64 s[12:13], |v131|, s4
	s_nop 1
; DEV u16 f2bf(float f) { return (u16)(pack2(f, 0.f) & 0xffffu); }
; DEV void phase_win(const Params& P, int l, const u16* __restrict__ xb, const u16* __restrict__ Wt, u16* __restrict__ h, char* smem) {
;     ...
;     const int mode = (cb >= C_HF && cb < C_HI) ? 1 : ((cb >= C_HG) ? 2 : 0);
; #pragma unroll
;     for (int ms = 0; ms < 8; ++ms) {
;       asm volatile("" ::: "memory");
; #pragma unroll
;       for (int ns = 0; ns < 4; ++ns)
; #pragma unroll
;         for (int j = 0; j < 4; ++j) {
;           int row = m0 + wm * 128 + ms * 16 + quad * 4 + j;
;           int col = cb + ns * 16 + l15;
;           float v = acc[ms][ns][j];
;           if (mode == 1) { float lbv = lbp[col - C_HF]; v = __logf(lbv + (1.f - lbv) / (1.f + __expf(-v))); }
;           else if (mode == 2) v = v / (1.f + __expf(-v));
;           h[(size_t)row * HS + col] = f2bf(v);
;         }
	v_cndmask_b32_e64 v131, v131, v132, s[12:13]
	v_cndmask_b32_e32 v132, 0, v227, vcc
	v_sub_f32_e32 v131, v131, v132
	v_cvt_pk_bf16_f32 v141, v131, s0
	global_store_short v139, v141, s[72:73] offset:32
	v_mul_f32_e32 v132, 0xbfb8aa3b, v69
	v_exp_f32_e32 v132, v132
	v_sub_f32_e32 v133, 1.0, v162
	v_add_f32_e32 v132, 1.0, v132
	v_div_scale_f32 v134, s[4:5], v132, v132, v133
	v_rcp_f32_e32 v135, v134
	v_div_scale_f32 v136, vcc, v133, v132, v133
	s_mov_b32 s4, 0x800000
	v_fma_f32 v137, -v134, v135, 1.0
	v_fmac_f32_e32 v135, v137, v135
	v_mul_f32_e32 v137, v136, v135
	v_fma_f32 v140, -v134, v137, v136
	v_fmac_f32_e32 v137, v140, v135
	v_fma_f32 v134, -v134, v137, v136
	v_div_fmas_f32 v134, v134, v135, v137
	v_div_fixup_f32 v132, v134, v132, v133
	v_add_f32_e32 v131, v162, v132
	v_cmp_gt_f32_e32 vcc, s4, v131
	s_mov_b32 s4, 0x3f317217
	s_nop 0
	v_cndmask_b32_e64 v132, 0, 32, vcc
	v_ldexp_f32 v131, v131, v132
	v_log_f32_e32 v131, v131
	s_nop 0
	v_mul_f32_e32 v132, 0x3f317217, v131
	v_fma_f32 v132, v131, s4, -v132
	v_fmac_f32_e32 v132, 0x3377d1cf, v131
	s_mov_b32 s4, 0x7f800000
	v_fmac_f32_e32 v132, 0x3f317217, v131
	v_cmp_lt_f32_e64 s[12:13], |v131|, s4
	s_nop 1
	v_cndmask_b32_e64 v131, v131, v132, s[12:13]
	v_cndmask_b32_e32 v132, 0, v227, vcc
	v_sub_f32_e32 v131, v131, v132
	v_cvt_pk_bf16_f32 v141, v131, s0
	global_store_short v139, v141, s[72:73] offset:64
	v_mul_f32_e32 v132, 0xbfb8aa3b, v61
	v_exp_f32_e32 v132, v132
	v_sub_f32_e32 v133, 1.0, v163
	v_add_f32_e32 v132, 1.0, v132
	v_div_scale_f32 v134, s[4:5], v132, v132, v133
	v_rcp_f32_e32 v135, v134
	v_div_scale_f32 v136, vcc, v133, v132, v133
	s_mov_b32 s4, 0x800000
	v_fma_f32 v137, -v134, v135, 1.0
	v_fmac_f32_e32 v135, v137, v135
	v_mul_f32_e32 v137, v136, v135
	v_fma_f32 v140, -v134, v137, v136
	v_fmac_f32_e32 v137, v140, v135
	v_fma_f32 v134, -v134, v137, v136
	v_div_fmas_f32 v134, v134, v135, v137
	v_div_fixup_f32 v132, v134, v132, v133
	v_add_f32_e32 v131, v163, v132
	v_cmp_gt_f32_e32 vcc, s4, v131
	s_mov_b32 s4, 0x3f317217
	s_nop 0
	v_cndmask_b32_e64 v132, 0, 32, vcc
	v_ldexp_f32 v131, v131, v132
	v_log_f32_e32 v131, v131
	s_nop 0
	v_mul_f32_e32 v132, 0x3f317217, v131
	v_fma_f32 v132, v131, s4, -v132
	v_fmac_f32_e32 v132, 0x3377d1cf, v131
	s_mov_b32 s4, 0x7f800000
	v_fmac_f32_e32 v132, 0x3f317217, v131
	v_cmp_lt_f32_e64 s[12:13], |v131|, s4
	s_nop 1
	v_cndmask_b32_e64 v131, v131, v132, s[12:13]
	v_cndmask_b32_e32 v132, 0, v227, vcc
	v_sub_f32_e32 v131, v131, v132
	v_cvt_pk_bf16_f32 v141, v131, s0
	global_store_short v139, v141, s[72:73] offset:96
	v_add_u32_e32 v139, 0xa2000, v138
	v_mul_f32_e32 v132, 0xbfb8aa3b, v6
	v_exp_f32_e32 v132, v132
	v_sub_f32_e32 v133, 1.0, v160
	v_add_f32_e32 v132, 1.0, v132
	v_div_scale_f32 v134, s[4:5], v132, v132, v133
	v_rcp_f32_e32 v135, v134
	v_div_scale_f32 v136, vcc, v133, v132, v133
	s_mov_b32 s4, 0x800000
	v_fma_f32 v137, -v134, v135, 1.0
	v_fmac_f32_e32 v135, v137, v135
	v_mul_f32_e32 v137, v136, v135
	v_fma_f32 v140, -v134, v137, v136
	v_fmac_f32_e32 v137, v140, v135
	v_fma_f32 v134, -v134, v137, v136
	v_div_fmas_f32 v134, v134, v135, v137
	v_div_fixup_f32 v132, v134, v132, v133
	v_add_f32_e32 v131, v160, v132
	v_cmp_gt_f32_e32 vcc, s4, v131
	s_mov_b32 s4, 0x3f317217
	s_nop 0
	v_cndmask_b32_e64 v132, 0, 32, vcc
	v_ldexp_f32 v131, v131, v132
	v_log_f32_e32 v131, v131
	s_nop 0
	v_mul_f32_e32 v132, 0x3f317217, v131
	v_fma_f32 v132, v131, s4, -v132
	v_fmac_f32_e32 v132, 0x3377d1cf, v131
	s_mov_b32 s4, 0x7f800000
	v_fmac_f32_e32 v132, 0x3f317217, v131
	v_cmp_lt_f32_e64 s[12:13], |v131|, s4
	s_nop 1
	v_cndmask_b32_e64 v131, v131, v132, s[12:13]
	v_cndmask_b32_e32 v132, 0, v227, vcc
	v_sub_f32_e32 v131, v131, v132
	v_cvt_pk_bf16_f32 v141, v131, s0
	global_store_short v139, v141, s[72:73]
	v_mul_f32_e32 v132, 0xbfb8aa3b, v50
	v_exp_f32_e32 v132, v132
	v_sub_f32_e32 v133, 1.0, v161
	v_add_f32_e32 v132, 1.0, v132
	v_div_scale_f32 v134, s[4:5], v132, v132, v133
	v_rcp_f32_e32 v135, v134
	v_div_scale_f32 v136, vcc, v133, v132, v133
	s_mov_b32 s4, 0x800000
	v_fma_f32 v137, -v134, v135, 1.0
	v_fmac_f32_e32 v135, v137, v135
	v_mul_f32_e32 v137, v136, v135
	v_fma_f32 v140, -v134, v137, v136
	v_fmac_f32_e32 v137, v140, v135
	v_fma_f32 v134, -v134, v137, v136
	v_div_fmas_f32 v134, v134, v135, v137
	v_div_fixup_f32 v132, v134, v132, v133
	v_add_f32_e32 v131, v161, v132
	v_cmp_gt_f32_e32 vcc, s4, v131
	s_mov_b32 s4, 0x3f317217
	s_nop 0
	v_cndmask_b32_e64 v132, 0, 32, vcc
	v_ldexp_f32 v131, v131, v132
	v_log_f32_e32 v131, v131
	s_nop 0
	v_mul_f32_e32 v132, 0x3f317217, v131
	v_fma_f32 v132, v131, s4, -v132
	v_fmac_f32_e32 v132, 0x3377d1cf, v131
	s_mov_b32 s4, 0x7f800000
	v_fmac_f32_e32 v132, 0x3f317217, v131
	v_cmp_lt_f32_e64 s[12:13], |v131|, s4
	s_nop 1
	v_cndmask_b32_e64 v131, v131, v132, s[12:13]
	v_cndmask_b32_e32 v132, 0, v227, vcc
	v_sub_f32_e32 v131, v131, v132
	v_cvt_pk_bf16_f32 v141, v131, s0
	global_store_short v139, v141, s[72:73] offset:32
	v_mul_f32_e32 v132, 0xbfb8aa3b, v54
	v_exp_f32_e32 v132, v132
	v_sub_f32_e32 v133, 1.0, v162
	v_add_f32_e32 v132, 1.0, v132
	v_div_scale_f32 v134, s[4:5], v132, v132, v133
	v_rcp_f32_e32 v135, v134
	v_div_scale_f32 v136, vcc, v133, v132, v133
	s_mov_b32 s4, 0x800000
	v_fma_f32 v137, -v134, v135, 1.0
	v_fmac_f32_e32 v135, v137, v135
	v_mul_f32_e32 v137, v136, v135
	v_fma_f32 v140, -v134, v137, v136
	v_fmac_f32_e32 v137, v140, v135
	v_fma_f32 v134, -v134, v137, v136
	v_div_fmas_f32 v134, v134, v135, v137
	v_div_fixup_f32 v132, v134, v132, v133
	v_add_f32_e32 v131, v162, v132
	v_cmp_gt_f32_e32 vcc, s4, v131
	s_mov_b32 s4, 0x3f317217
	s_nop 0
	v_cndmask_b32_e64 v132, 0, 32, vcc
	v_ldexp_f32 v131, v131, v132
; DEV u16 f2bf(float f) { return (u16)(pack2(f, 0.f) & 0xffffu); }
; DEV void phase_win(const Params& P, int l, const u16* __restrict__ xb, const u16* __restrict__ Wt, u16* __restrict__ h, char* smem) {
;     ...
;     const int mode = (cb >= C_HF && cb < C_HI) ? 1 : ((cb >= C_HG) ? 2 : 0);
; #pragma unroll
;     for (int ms = 0; ms < 8; ++ms) {
;       asm volatile("" ::: "memory");
; #pragma unroll
;       for (int ns = 0; ns < 4; ++ns)
; #pragma unroll
;         for (int j = 0; j < 4; ++j) {
;           int row = m0 + wm * 128 + ms * 16 + quad * 4 + j;
;           int col = cb + ns * 16 + l15;
;           float v = acc[ms][ns][j];
;           if (mode == 1) { float lbv = lbp[col - C_HF]; v = __logf(lbv + (1.f - lbv) / (1.f + __expf(-v))); }
;           else if (mode == 2) v = v / (1.f + __expf(-v));
;           h[(size_t)row * HS + col] = f2bf(v);
;         }
	v_log_f32_e32 v131, v131
	s_nop 0
	v_mul_f32_e32 v132, 0x3f317217, v131
	v_fma_f32 v132, v131, s4, -v132
	v_fmac_f32_e32 v132, 0x3377d1cf, v131
	s_mov_b32 s4, 0x7f800000
	v_fmac_f32_e32 v132, 0x3f317217, v131
	v_cmp_lt_f32_e64 s[12:13], |v131|, s4
	s_nop 1
	v_cndmask_b32_e64 v131, v131, v132, s[12:13]
	v_cndmask_b32_e32 v132, 0, v227, vcc
	v_sub_f32_e32 v131, v131, v132
	v_cvt_pk_bf16_f32 v141, v131, s0
	global_store_short v139, v141, s[72:73] offset:64
	v_mul_f32_e32 v132, 0xbfb8aa3b, v46
	v_exp_f32_e32 v132, v132
	v_sub_f32_e32 v133, 1.0, v163
	v_add_f32_e32 v132, 1.0, v132
	v_div_scale_f32 v134, s[4:5], v132, v132, v133
	v_rcp_f32_e32 v135, v134
	v_div_scale_f32 v136, vcc, v133, v132, v133
	s_mov_b32 s4, 0x800000
	v_fma_f32 v137, -v134, v135, 1.0
	v_fmac_f32_e32 v135, v137, v135
	v_mul_f32_e32 v137, v136, v135
	v_fma_f32 v140, -v134, v137, v136
	v_fmac_f32_e32 v137, v140, v135
	v_fma_f32 v134, -v134, v137, v136
	v_div_fmas_f32 v134, v134, v135, v137
	v_div_fixup_f32 v132, v134, v132, v133
	v_add_f32_e32 v131, v163, v132
	v_cmp_gt_f32_e32 vcc, s4, v131
	s_mov_b32 s4, 0x3f317217
	s_nop 0
	v_cndmask_b32_e64 v132, 0, 32, vcc
	v_ldexp_f32 v131, v131, v132
	v_log_f32_e32 v131, v131
	s_nop 0
	v_mul_f32_e32 v132, 0x3f317217, v131
	v_fma_f32 v132, v131, s4, -v132
	v_fmac_f32_e32 v132, 0x3377d1cf, v131
	s_mov_b32 s4, 0x7f800000
	v_fmac_f32_e32 v132, 0x3f317217, v131
	v_cmp_lt_f32_e64 s[12:13], |v131|, s4
	s_nop 1
	v_cndmask_b32_e64 v131, v131, v132, s[12:13]
	v_cndmask_b32_e32 v132, 0, v227, vcc
	v_sub_f32_e32 v131, v131, v132
	v_cvt_pk_bf16_f32 v141, v131, s0
	global_store_short v139, v141, s[72:73] offset:96
	v_add_u32_e32 v139, 0xa3b00, v138
	v_mul_f32_e32 v132, 0xbfb8aa3b, v7
	v_exp_f32_e32 v132, v132
	v_sub_f32_e32 v133, 1.0, v160
	v_add_f32_e32 v132, 1.0, v132
	v_div_scale_f32 v134, s[4:5], v132, v132, v133
	v_rcp_f32_e32 v135, v134
	v_div_scale_f32 v136, vcc, v133, v132, v133
	s_mov_b32 s4, 0x800000
	v_fma_f32 v137, -v134, v135, 1.0
	v_fmac_f32_e32 v135, v137, v135
	v_mul_f32_e32 v137, v136, v135
	v_fma_f32 v140, -v134, v137, v136
	v_fmac_f32_e32 v137, v140, v135
	v_fma_f32 v134, -v134, v137, v136
	v_div_fmas_f32 v134, v134, v135, v137
	v_div_fixup_f32 v132, v134, v132, v133
	v_add_f32_e32 v131, v160, v132
	v_cmp_gt_f32_e32 vcc, s4, v131
	s_mov_b32 s4, 0x3f317217
	s_nop 0
	v_cndmask_b32_e64 v132, 0, 32, vcc
	v_ldexp_f32 v131, v131, v132
	v_log_f32_e32 v131, v131
	s_nop 0
	v_mul_f32_e32 v132, 0x3f317217, v131
	v_fma_f32 v132, v131, s4, -v132
	v_fmac_f32_e32 v132, 0x3377d1cf, v131
	s_mov_b32 s4, 0x7f800000
	v_fmac_f32_e32 v132, 0x3f317217, v131
	v_cmp_lt_f32_e64 s[12:13], |v131|, s4
	s_nop 1
	v_cndmask_b32_e64 v131, v131, v132, s[12:13]
	v_cndmask_b32_e32 v132, 0, v227, vcc
	v_sub_f32_e32 v131, v131, v132
	v_cvt_pk_bf16_f32 v141, v131, s0
	global_store_short v139, v141, s[72:73]
	v_mul_f32_e32 v132, 0xbfb8aa3b, v51
	v_exp_f32_e32 v132, v132
	v_sub_f32_e32 v133, 1.0, v161
	v_add_f32_e32 v132, 1.0, v132
	v_div_scale_f32 v134, s[4:5], v132, v132, v133
	v_rcp_f32_e32 v135, v134
	v_div_scale_f32 v136, vcc, v133, v132, v133
	s_mov_b32 s4, 0x800000
	v_fma_f32 v137, -v134, v135, 1.0
	v_fmac_f32_e32 v135, v137, v135
	v_mul_f32_e32 v137, v136, v135
	v_fma_f32 v140, -v134, v137, v136
	v_fmac_f32_e32 v137, v140, v135
	v_fma_f32 v134, -v134, v137, v136
	v_div_fmas_f32 v134, v134, v135, v137
	v_div_fixup_f32 v132, v134, v132, v133
	v_add_f32_e32 v131, v161, v132
	v_cmp_gt_f32_e32 vcc, s4, v131
	s_mov_b32 s4, 0x3f317217
	s_nop 0
	v_cndmask_b32_e64 v132, 0, 32, vcc
	v_ldexp_f32 v131, v131, v132
	v_log_f32_e32 v131, v131
	s_nop 0
	v_mul_f32_e32 v132, 0x3f317217, v131
	v_fma_f32 v132, v131, s4, -v132
	v_fmac_f32_e32 v132, 0x3377d1cf, v131
	s_mov_b32 s4, 0x7f800000
	v_fmac_f32_e32 v132, 0x3f317217, v131
	v_cmp_lt_f32_e64 s[12:13], |v131|, s4
	s_nop 1
	v_cndmask_b32_e64 v131, v131, v132, s[12:13]
	v_cndmask_b32_e32 v132, 0, v227, vcc
	v_sub_f32_e32 v131, v131, v132
	v_cvt_pk_bf16_f32 v141, v131, s0
	global_store_short v139, v141, s[72:73] offset:32
	v_mul_f32_e32 v132, 0xbfb8aa3b, v55
	v_exp_f32_e32 v132, v132
	v_sub_f32_e32 v133, 1.0, v162
	v_add_f32_e32 v132, 1.0, v132
	v_div_scale_f32 v134, s[4:5], v132, v132, v133
	v_rcp_f32_e32 v135, v134
	v_div_scale_f32 v136, vcc, v133, v132, v133
	s_mov_b32 s4, 0x800000
	v_fma_f32 v137, -v134, v135, 1.0
	v_fmac_f32_e32 v135, v137, v135
	v_mul_f32_e32 v137, v136, v135
	v_fma_f32 v140, -v134, v137, v136
	v_fmac_f32_e32 v137, v140, v135
	v_fma_f32 v134, -v134, v137, v136
	v_div_fmas_f32 v134, v134, v135, v137
	v_div_fixup_f32 v132, v134, v132, v133
	v_add_f32_e32 v131, v162, v132
	v_cmp_gt_f32_e32 vcc, s4, v131
	s_mov_b32 s4, 0x3f317217
	s_nop 0
	v_cndmask_b32_e64 v132, 0, 32, vcc
	v_ldexp_f32 v131, v131, v132
	v_log_f32_e32 v131, v131
	s_nop 0
	v_mul_f32_e32 v132, 0x3f317217, v131
	v_fma_f32 v132, v131, s4, -v132
	v_fmac_f32_e32 v132, 0x3377d1cf, v131
	s_mov_b32 s4, 0x7f800000
	v_fmac_f32_e32 v132, 0x3f317217, v131
	v_cmp_lt_f32_e64 s[12:13], |v131|, s4
	s_nop 1
	v_cndmask_b32_e64 v131, v131, v132, s[12:13]
	v_cndmask_b32_e32 v132, 0, v227, vcc
	v_sub_f32_e32 v131, v131, v132
	v_cvt_pk_bf16_f32 v141, v131, s0
	global_store_short v139, v141, s[72:73] offset:64
	v_mul_f32_e32 v132, 0xbfb8aa3b, v47
	v_exp_f32_e32 v132, v132
	v_sub_f32_e32 v133, 1.0, v163
	v_add_f32_e32 v132, 1.0, v132
	v_div_scale_f32 v134, s[4:5], v132, v132, v133
	v_rcp_f32_e32 v135, v134
	v_div_scale_f32 v136, vcc, v133, v132, v133
	s_mov_b32 s4, 0x800000
	v_fma_f32 v137, -v134, v135, 1.0
	v_fmac_f32_e32 v135, v137, v135
	v_mul_f32_e32 v137, v136, v135
	v_fma_f32 v140, -v134, v137, v136
	v_fmac_f32_e32 v137, v140, v135
	v_fma_f32 v134, -v134, v137, v136
; DEV u16 f2bf(float f) { return (u16)(pack2(f, 0.f) & 0xffffu); }
; DEV void phase_win(const Params& P, int l, const u16* __restrict__ xb, const u16* __restrict__ Wt, u16* __restrict__ h, char* smem) {
;     ...
;     const int mode = (cb >= C_HF && cb < C_HI) ? 1 : ((cb >= C_HG) ? 2 : 0);
; #pragma unroll
;     for (int ms = 0; ms < 8; ++ms) {
;       asm volatile("" ::: "memory");
; #pragma unroll
;       for (int ns = 0; ns < 4; ++ns)
; #pragma unroll
;         for (int j = 0; j < 4; ++j) {
;           int row = m0 + wm * 128 + ms * 16 + quad * 4 + j;
;           int col = cb + ns * 16 + l15;
;           float v = acc[ms][ns][j];
;           if (mode == 1) { float lbv = lbp[col - C_HF]; v = __logf(lbv + (1.f - lbv) / (1.f + __expf(-v))); }
;           else if (mode == 2) v = v / (1.f + __expf(-v));
;           h[(size_t)row * HS + col] = f2bf(v);
;         }
	v_div_fmas_f32 v134, v134, v135, v137
	v_div_fixup_f32 v132, v134, v132, v133
	v_add_f32_e32 v131, v163, v132
	v_cmp_gt_f32_e32 vcc, s4, v131
	s_mov_b32 s4, 0x3f317217
	s_nop 0
	v_cndmask_b32_e64 v132, 0, 32, vcc
	v_ldexp_f32 v131, v131, v132
	v_log_f32_e32 v131, v131
	s_nop 0
	v_mul_f32_e32 v132, 0x3f317217, v131
	v_fma_f32 v132, v131, s4, -v132
	v_fmac_f32_e32 v132, 0x3377d1cf, v131
	s_mov_b32 s4, 0x7f800000
	v_fmac_f32_e32 v132, 0x3f317217, v131
	v_cmp_lt_f32_e64 s[12:13], |v131|, s4
	s_nop 1
	v_cndmask_b32_e64 v131, v131, v132, s[12:13]
	v_cndmask_b32_e32 v132, 0, v227, vcc
	v_sub_f32_e32 v131, v131, v132
	v_cvt_pk_bf16_f32 v141, v131, s0
	global_store_short v139, v141, s[72:73] offset:96
	v_add_u32_e32 v139, 0xa5600, v138
	v_mul_f32_e32 v132, 0xbfb8aa3b, v8
	v_exp_f32_e32 v132, v132
	v_sub_f32_e32 v133, 1.0, v160
	v_add_f32_e32 v132, 1.0, v132
	v_div_scale_f32 v134, s[4:5], v132, v132, v133
	v_rcp_f32_e32 v135, v134
	v_div_scale_f32 v136, vcc, v133, v132, v133
	s_mov_b32 s4, 0x800000
	v_fma_f32 v137, -v134, v135, 1.0
	v_fmac_f32_e32 v135, v137, v135
	v_mul_f32_e32 v137, v136, v135
	v_fma_f32 v140, -v134, v137, v136
	v_fmac_f32_e32 v137, v140, v135
	v_fma_f32 v134, -v134, v137, v136
	v_div_fmas_f32 v134, v134, v135, v137
	v_div_fixup_f32 v132, v134, v132, v133
	v_add_f32_e32 v131, v160, v132
	v_cmp_gt_f32_e32 vcc, s4, v131
	s_mov_b32 s4, 0x3f317217
	s_nop 0
	v_cndmask_b32_e64 v132, 0, 32, vcc
	v_ldexp_f32 v131, v131, v132
	v_log_f32_e32 v131, v131
	s_nop 0
	v_mul_f32_e32 v132, 0x3f317217, v131
	v_fma_f32 v132, v131, s4, -v132
	v_fmac_f32_e32 v132, 0x3377d1cf, v131
	s_mov_b32 s4, 0x7f800000
	v_fmac_f32_e32 v132, 0x3f317217, v131
	v_cmp_lt_f32_e64 s[12:13], |v131|, s4
	s_nop 1
	v_cndmask_b32_e64 v131, v131, v132, s[12:13]
	v_cndmask_b32_e32 v132, 0, v227, vcc
	v_sub_f32_e32 v131, v131, v132
	v_cvt_pk_bf16_f32 v141, v131, s0
	global_store_short v139, v141, s[72:73]
	v_mul_f32_e32 v132, 0xbfb8aa3b, v52
	v_exp_f32_e32 v132, v132
	v_sub_f32_e32 v133, 1.0, v161
	v_add_f32_e32 v132, 1.0, v132
	v_div_scale_f32 v134, s[4:5], v132, v132, v133
	v_rcp_f32_e32 v135, v134
	v_div_scale_f32 v136, vcc, v133, v132, v133
	s_mov_b32 s4, 0x800000
	v_fma_f32 v137, -v134, v135, 1.0
	v_fmac_f32_e32 v135, v137, v135
	v_mul_f32_e32 v137, v136, v135
	v_fma_f32 v140, -v134, v137, v136
	v_fmac_f32_e32 v137, v140, v135
	v_fma_f32 v134, -v134, v137, v136
	v_div_fmas_f32 v134, v134, v135, v137
	v_div_fixup_f32 v132, v134, v132, v133
	v_add_f32_e32 v131, v161, v132
	v_cmp_gt_f32_e32 vcc, s4, v131
	s_mov_b32 s4, 0x3f317217
	s_nop 0
	v_cndmask_b32_e64 v132, 0, 32, vcc
	v_ldexp_f32 v131, v131, v132
	v_log_f32_e32 v131, v131
	s_nop 0
	v_mul_f32_e32 v132, 0x3f317217, v131
	v_fma_f32 v132, v131, s4, -v132
	v_fmac_f32_e32 v132, 0x3377d1cf, v131
	s_mov_b32 s4, 0x7f800000
	v_fmac_f32_e32 v132, 0x3f317217, v131
	v_cmp_lt_f32_e64 s[12:13], |v131|, s4
	s_nop 1
	v_cndmask_b32_e64 v131, v131, v132, s[12:13]
	v_cndmask_b32_e32 v132, 0, v227, vcc
	v_sub_f32_e32 v131, v131, v132
	v_cvt_pk_bf16_f32 v141, v131, s0
	global_store_short v139, v141, s[72:73] offset:32
	v_mul_f32_e32 v132, 0xbfb8aa3b, v56
	v_exp_f32_e32 v132, v132
	v_sub_f32_e32 v133, 1.0, v162
	v_add_f32_e32 v132, 1.0, v132
	v_div_scale_f32 v134, s[4:5], v132, v132, v133
	v_rcp_f32_e32 v135, v134
	v_div_scale_f32 v136, vcc, v133, v132, v133
	s_mov_b32 s4, 0x800000
	v_fma_f32 v137, -v134, v135, 1.0
	v_fmac_f32_e32 v135, v137, v135
	v_mul_f32_e32 v137, v136, v135
	v_fma_f32 v140, -v134, v137, v136
	v_fmac_f32_e32 v137, v140, v135
	v_fma_f32 v134, -v134, v137, v136
	v_div_fmas_f32 v134, v134, v135, v137
	v_div_fixup_f32 v132, v134, v132, v133
	v_add_f32_e32 v131, v162, v132
	v_cmp_gt_f32_e32 vcc, s4, v131
	s_mov_b32 s4, 0x3f317217
	s_nop 0
	v_cndmask_b32_e64 v132, 0, 32, vcc
	v_ldexp_f32 v131, v131, v132
	v_log_f32_e32 v131, v131
	s_nop 0
	v_mul_f32_e32 v132, 0x3f317217, v131
	v_fma_f32 v132, v131, s4, -v132
	v_fmac_f32_e32 v132, 0x3377d1cf, v131
	s_mov_b32 s4, 0x7f800000
	v_fmac_f32_e32 v132, 0x3f317217, v131
	v_cmp_lt_f32_e64 s[12:13], |v131|, s4
	s_nop 1
	v_cndmask_b32_e64 v131, v131, v132, s[12:13]
	v_cndmask_b32_e32 v132, 0, v227, vcc
	v_sub_f32_e32 v131, v131, v132
	v_cvt_pk_bf16_f32 v141, v131, s0
	global_store_short v139, v141, s[72:73] offset:64
	v_mul_f32_e32 v132, 0xbfb8aa3b, v48
	v_exp_f32_e32 v132, v132
	v_sub_f32_e32 v133, 1.0, v163
	v_add_f32_e32 v132, 1.0, v132
	v_div_scale_f32 v134, s[4:5], v132, v132, v133
	v_rcp_f32_e32 v135, v134
	v_div_scale_f32 v136, vcc, v133, v132, v133
	s_mov_b32 s4, 0x800000
	v_fma_f32 v137, -v134, v135, 1.0
	v_fmac_f32_e32 v135, v137, v135
	v_mul_f32_e32 v137, v136, v135
	v_fma_f32 v140, -v134, v137, v136
	v_fmac_f32_e32 v137, v140, v135
	v_fma_f32 v134, -v134, v137, v136
	v_div_fmas_f32 v134, v134, v135, v137
	v_div_fixup_f32 v132, v134, v132, v133
	v_add_f32_e32 v131, v163, v132
	v_cmp_gt_f32_e32 vcc, s4, v131
	s_mov_b32 s4, 0x3f317217
	s_nop 0
	v_cndmask_b32_e64 v132, 0, 32, vcc
	v_ldexp_f32 v131, v131, v132
	v_log_f32_e32 v131, v131
	s_nop 0
	v_mul_f32_e32 v132, 0x3f317217, v131
	v_fma_f32 v132, v131, s4, -v132
	v_fmac_f32_e32 v132, 0x3377d1cf, v131
	s_mov_b32 s4, 0x7f800000
	v_fmac_f32_e32 v132, 0x3f317217, v131
	v_cmp_lt_f32_e64 s[12:13], |v131|, s4
	s_nop 1
	v_cndmask_b32_e64 v131, v131, v132, s[12:13]
	v_cndmask_b32_e32 v132, 0, v227, vcc
	v_sub_f32_e32 v131, v131, v132
	v_cvt_pk_bf16_f32 v141, v131, s0
	global_store_short v139, v141, s[72:73] offset:96
	v_add_u32_e32 v139, 0xa7100, v138
	v_mul_f32_e32 v132, 0xbfb8aa3b, v9
	v_exp_f32_e32 v132, v132
	v_sub_f32_e32 v133, 1.0, v160
	v_add_f32_e32 v132, 1.0, v132
	v_div_scale_f32 v134, s[4:5], v132, v132, v133
	v_rcp_f32_e32 v135, v134
; DEV u16 f2bf(float f) { return (u16)(pack2(f, 0.f) & 0xffffu); }
; DEV void phase_win(const Params& P, int l, const u16* __restrict__ xb, const u16* __restrict__ Wt, u16* __restrict__ h, char* smem) {
;     ...
;     const int mode = (cb >= C_HF && cb < C_HI) ? 1 : ((cb >= C_HG) ? 2 : 0);
; #pragma unroll
;     for (int ms = 0; ms < 8; ++ms) {
;       asm volatile("" ::: "memory");
; #pragma unroll
;       for (int ns = 0; ns < 4; ++ns)
; #pragma unroll
;         for (int j = 0; j < 4; ++j) {
;           int row = m0 + wm * 128 + ms * 16 + quad * 4 + j;
;           int col = cb + ns * 16 + l15;
;           float v = acc[ms][ns][j];
;           if (mode == 1) { float lbv = lbp[col - C_HF]; v = __logf(lbv + (1.f - lbv) / (1.f + __expf(-v))); }
;           else if (mode == 2) v = v / (1.f + __expf(-v));
;           h[(size_t)row * HS + col] = f2bf(v);
;         }
	v_div_scale_f32 v136, vcc, v133, v132, v133
	s_mov_b32 s4, 0x800000
	v_fma_f32 v137, -v134, v135, 1.0
	v_fmac_f32_e32 v135, v137, v135
	v_mul_f32_e32 v137, v136, v135
	v_fma_f32 v140, -v134, v137, v136
	v_fmac_f32_e32 v137, v140, v135
	v_fma_f32 v134, -v134, v137, v136
	v_div_fmas_f32 v134, v134, v135, v137
	v_div_fixup_f32 v132, v134, v132, v133
	v_add_f32_e32 v131, v160, v132
	v_cmp_gt_f32_e32 vcc, s4, v131
	s_mov_b32 s4, 0x3f317217
	s_nop 0
	v_cndmask_b32_e64 v132, 0, 32, vcc
	v_ldexp_f32 v131, v131, v132
	v_log_f32_e32 v131, v131
	s_nop 0
	v_mul_f32_e32 v132, 0x3f317217, v131
	v_fma_f32 v132, v131, s4, -v132
	v_fmac_f32_e32 v132, 0x3377d1cf, v131
	s_mov_b32 s4, 0x7f800000
	v_fmac_f32_e32 v132, 0x3f317217, v131
	v_cmp_lt_f32_e64 s[12:13], |v131|, s4
	s_nop 1
	v_cndmask_b32_e64 v131, v131, v132, s[12:13]
	v_cndmask_b32_e32 v132, 0, v227, vcc
	v_sub_f32_e32 v131, v131, v132
	v_cvt_pk_bf16_f32 v141, v131, s0
	global_store_short v139, v141, s[72:73]
	v_mul_f32_e32 v132, 0xbfb8aa3b, v53
	v_exp_f32_e32 v132, v132
	v_sub_f32_e32 v133, 1.0, v161
	v_add_f32_e32 v132, 1.0, v132
	v_div_scale_f32 v134, s[4:5], v132, v132, v133
	v_rcp_f32_e32 v135, v134
	v_div_scale_f32 v136, vcc, v133, v132, v133
	s_mov_b32 s4, 0x800000
	v_fma_f32 v137, -v134, v135, 1.0
	v_fmac_f32_e32 v135, v137, v135
	v_mul_f32_e32 v137, v136, v135
	v_fma_f32 v140, -v134, v137, v136
	v_fmac_f32_e32 v137, v140, v135
	v_fma_f32 v134, -v134, v137, v136
	v_div_fmas_f32 v134, v134, v135, v137
	v_div_fixup_f32 v132, v134, v132, v133
	v_add_f32_e32 v131, v161, v132
	v_cmp_gt_f32_e32 vcc, s4, v131
	s_mov_b32 s4, 0x3f317217
	s_nop 0
	v_cndmask_b32_e64 v132, 0, 32, vcc
	v_ldexp_f32 v131, v131, v132
	v_log_f32_e32 v131, v131
	s_nop 0
	v_mul_f32_e32 v132, 0x3f317217, v131
	v_fma_f32 v132, v131, s4, -v132
	v_fmac_f32_e32 v132, 0x3377d1cf, v131
	s_mov_b32 s4, 0x7f800000
	v_fmac_f32_e32 v132, 0x3f317217, v131
	v_cmp_lt_f32_e64 s[12:13], |v131|, s4
	s_nop 1
	v_cndmask_b32_e64 v131, v131, v132, s[12:13]
	v_cndmask_b32_e32 v132, 0, v227, vcc
	v_sub_f32_e32 v131, v131, v132
	v_cvt_pk_bf16_f32 v141, v131, s0
	global_store_short v139, v141, s[72:73] offset:32
	v_mul_f32_e32 v132, 0xbfb8aa3b, v57
	v_exp_f32_e32 v132, v132
	v_sub_f32_e32 v133, 1.0, v162
	v_add_f32_e32 v132, 1.0, v132
	v_div_scale_f32 v134, s[4:5], v132, v132, v133
	v_rcp_f32_e32 v135, v134
	v_div_scale_f32 v136, vcc, v133, v132, v133
	s_mov_b32 s4, 0x800000
	v_fma_f32 v137, -v134, v135, 1.0
	v_fmac_f32_e32 v135, v137, v135
	v_mul_f32_e32 v137, v136, v135
	v_fma_f32 v140, -v134, v137, v136
	v_fmac_f32_e32 v137, v140, v135
	v_fma_f32 v134, -v134, v137, v136
	v_div_fmas_f32 v134, v134, v135, v137
	v_div_fixup_f32 v132, v134, v132, v133
	v_add_f32_e32 v131, v162, v132
	v_cmp_gt_f32_e32 vcc, s4, v131
	s_mov_b32 s4, 0x3f317217
	s_nop 0
	v_cndmask_b32_e64 v132, 0, 32, vcc
	v_ldexp_f32 v131, v131, v132
	v_log_f32_e32 v131, v131
	s_nop 0
	v_mul_f32_e32 v132, 0x3f317217, v131
	v_fma_f32 v132, v131, s4, -v132
	v_fmac_f32_e32 v132, 0x3377d1cf, v131
	s_mov_b32 s4, 0x7f800000
	v_fmac_f32_e32 v132, 0x3f317217, v131
	v_cmp_lt_f32_e64 s[12:13], |v131|, s4
	s_nop 1
	v_cndmask_b32_e64 v131, v131, v132, s[12:13]
	v_cndmask_b32_e32 v132, 0, v227, vcc
	v_sub_f32_e32 v131, v131, v132
	v_cvt_pk_bf16_f32 v141, v131, s0
	global_store_short v139, v141, s[72:73] offset:64
	v_mul_f32_e32 v132, 0xbfb8aa3b, v49
	v_exp_f32_e32 v132, v132
	v_sub_f32_e32 v133, 1.0, v163
	v_add_f32_e32 v132, 1.0, v132
	v_div_scale_f32 v134, s[4:5], v132, v132, v133
	v_rcp_f32_e32 v135, v134
	v_div_scale_f32 v136, vcc, v133, v132, v133
	s_mov_b32 s4, 0x800000
	v_fma_f32 v137, -v134, v135, 1.0
	v_fmac_f32_e32 v135, v137, v135
	v_mul_f32_e32 v137, v136, v135
	v_fma_f32 v140, -v134, v137, v136
	v_fmac_f32_e32 v137, v140, v135
	v_fma_f32 v134, -v134, v137, v136
	v_div_fmas_f32 v134, v134, v135, v137
	v_div_fixup_f32 v132, v134, v132, v133
	v_add_f32_e32 v131, v163, v132
	v_cmp_gt_f32_e32 vcc, s4, v131
	s_mov_b32 s4, 0x3f317217
	s_nop 0
	v_cndmask_b32_e64 v132, 0, 32, vcc
	v_ldexp_f32 v131, v131, v132
	v_log_f32_e32 v131, v131
	s_nop 0
	v_mul_f32_e32 v132, 0x3f317217, v131
	v_fma_f32 v132, v131, s4, -v132
	v_fmac_f32_e32 v132, 0x3377d1cf, v131
	s_mov_b32 s4, 0x7f800000
	v_fmac_f32_e32 v132, 0x3f317217, v131
	v_cmp_lt_f32_e64 s[12:13], |v131|, s4
	s_nop 1
	v_cndmask_b32_e64 v131, v131, v132, s[12:13]
	v_cndmask_b32_e32 v132, 0, v227, vcc
	v_sub_f32_e32 v131, v131, v132
	v_cvt_pk_bf16_f32 v141, v131, s0
	global_store_short v139, v141, s[72:73] offset:96
	v_add_u32_e32 v139, 0xbd000, v138
	v_mul_f32_e32 v132, 0xbfb8aa3b, v2
	v_exp_f32_e32 v132, v132
	v_sub_f32_e32 v133, 1.0, v160
	v_add_f32_e32 v132, 1.0, v132
	v_div_scale_f32 v134, s[4:5], v132, v132, v133
	v_rcp_f32_e32 v135, v134
	v_div_scale_f32 v136, vcc, v133, v132, v133
	s_mov_b32 s4, 0x800000
	v_fma_f32 v137, -v134, v135, 1.0
	v_fmac_f32_e32 v135, v137, v135
	v_mul_f32_e32 v137, v136, v135
	v_fma_f32 v140, -v134, v137, v136
	v_fmac_f32_e32 v137, v140, v135
	v_fma_f32 v134, -v134, v137, v136
	v_div_fmas_f32 v134, v134, v135, v137
	v_div_fixup_f32 v132, v134, v132, v133
	v_add_f32_e32 v131, v160, v132
	v_cmp_gt_f32_e32 vcc, s4, v131
	s_mov_b32 s4, 0x3f317217
	s_nop 0
	v_cndmask_b32_e64 v132, 0, 32, vcc
	v_ldexp_f32 v131, v131, v132
	v_log_f32_e32 v131, v131
	s_nop 0
	v_mul_f32_e32 v132, 0x3f317217, v131
	v_fma_f32 v132, v131, s4, -v132
	v_fmac_f32_e32 v132, 0x3377d1cf, v131
	s_mov_b32 s4, 0x7f800000
	v_fmac_f32_e32 v132, 0x3f317217, v131
	v_cmp_lt_f32_e64 s[12:13], |v131|, s4
	s_nop 1
	v_cndmask_b32_e64 v131, v131, v132, s[12:13]
	v_cndmask_b32_e32 v132, 0, v227, vcc
	v_sub_f32_e32 v131, v131, v132
	v_cvt_pk_bf16_f32 v141, v131, s0
; DEV u16 f2bf(float f) { return (u16)(pack2(f, 0.f) & 0xffffu); }
; DEV void phase_win(const Params& P, int l, const u16* __restrict__ xb, const u16* __restrict__ Wt, u16* __restrict__ h, char* smem) {
;     ...
;     const int mode = (cb >= C_HF && cb < C_HI) ? 1 : ((cb >= C_HG) ? 2 : 0);
; #pragma unroll
;     for (int ms = 0; ms < 8; ++ms) {
;       asm volatile("" ::: "memory");
; #pragma unroll
;       for (int ns = 0; ns < 4; ++ns)
; #pragma unroll
;         for (int j = 0; j < 4; ++j) {
;           int row = m0 + wm * 128 + ms * 16 + quad * 4 + j;
;           int col = cb + ns * 16 + l15;
;           float v = acc[ms][ns][j];
;           if (mode == 1) { float lbv = lbp[col - C_HF]; v = __logf(lbv + (1.f - lbv) / (1.f + __expf(-v))); }
;           else if (mode == 2) v = v / (1.f + __expf(-v));
;           h[(size_t)row * HS + col] = f2bf(v);
;         }
	global_store_short v139, v141, s[72:73]
	v_mul_f32_e32 v132, 0xbfb8aa3b, v34
	v_exp_f32_e32 v132, v132
	v_sub_f32_e32 v133, 1.0, v161
	v_add_f32_e32 v132, 1.0, v132
	v_div_scale_f32 v134, s[4:5], v132, v132, v133
	v_rcp_f32_e32 v135, v134
	v_div_scale_f32 v136, vcc, v133, v132, v133
	s_mov_b32 s4, 0x800000
	v_fma_f32 v137, -v134, v135, 1.0
	v_fmac_f32_e32 v135, v137, v135
	v_mul_f32_e32 v137, v136, v135
	v_fma_f32 v140, -v134, v137, v136
	v_fmac_f32_e32 v137, v140, v135
	v_fma_f32 v134, -v134, v137, v136
	v_div_fmas_f32 v134, v134, v135, v137
	v_div_fixup_f32 v132, v134, v132, v133
	v_add_f32_e32 v131, v161, v132
	v_cmp_gt_f32_e32 vcc, s4, v131
	s_mov_b32 s4, 0x3f317217
	s_nop 0
	v_cndmask_b32_e64 v132, 0, 32, vcc
	v_ldexp_f32 v131, v131, v132
	v_log_f32_e32 v131, v131
	s_nop 0
	v_mul_f32_e32 v132, 0x3f317217, v131
	v_fma_f32 v132, v131, s4, -v132
	v_fmac_f32_e32 v132, 0x3377d1cf, v131
	s_mov_b32 s4, 0x7f800000
	v_fmac_f32_e32 v132, 0x3f317217, v131
	v_cmp_lt_f32_e64 s[12:13], |v131|, s4
	s_nop 1
	v_cndmask_b32_e64 v131, v131, v132, s[12:13]
	v_cndmask_b32_e32 v132, 0, v227, vcc
	v_sub_f32_e32 v131, v131, v132
	v_cvt_pk_bf16_f32 v141, v131, s0
	global_store_short v139, v141, s[72:73] offset:32
	v_mul_f32_e32 v132, 0xbfb8aa3b, v42
	v_exp_f32_e32 v132, v132
	v_sub_f32_e32 v133, 1.0, v162
	v_add_f32_e32 v132, 1.0, v132
	v_div_scale_f32 v134, s[4:5], v132, v132, v133
	v_rcp_f32_e32 v135, v134
	v_div_scale_f32 v136, vcc, v133, v132, v133
	s_mov_b32 s4, 0x800000
	v_fma_f32 v137, -v134, v135, 1.0
	v_fmac_f32_e32 v135, v137, v135
	v_mul_f32_e32 v137, v136, v135
	v_fma_f32 v140, -v134, v137, v136
	v_fmac_f32_e32 v137, v140, v135
	v_fma_f32 v134, -v134, v137, v136
	v_div_fmas_f32 v134, v134, v135, v137
	v_div_fixup_f32 v132, v134, v132, v133
	v_add_f32_e32 v131, v162, v132
	v_cmp_gt_f32_e32 vcc, s4, v131
	s_mov_b32 s4, 0x3f317217
	s_nop 0
	v_cndmask_b32_e64 v132, 0, 32, vcc
	v_ldexp_f32 v131, v131, v132
	v_log_f32_e32 v131, v131
	s_nop 0
	v_mul_f32_e32 v132, 0x3f317217, v131
	v_fma_f32 v132, v131, s4, -v132
	v_fmac_f32_e32 v132, 0x3377d1cf, v131
	s_mov_b32 s4, 0x7f800000
	v_fmac_f32_e32 v132, 0x3f317217, v131
	v_cmp_lt_f32_e64 s[12:13], |v131|, s4
	s_nop 1
	v_cndmask_b32_e64 v131, v131, v132, s[12:13]
	v_cndmask_b32_e32 v132, 0, v227, vcc
	v_sub_f32_e32 v131, v131, v132
	v_cvt_pk_bf16_f32 v141, v131, s0
	global_store_short v139, v141, s[72:73] offset:64
	v_mul_f32_e32 v132, 0xbfb8aa3b, v30
	v_exp_f32_e32 v132, v132
	v_sub_f32_e32 v133, 1.0, v163
	v_add_f32_e32 v132, 1.0, v132
	v_div_scale_f32 v134, s[4:5], v132, v132, v133
	v_rcp_f32_e32 v135, v134
	v_div_scale_f32 v136, vcc, v133, v132, v133
	s_mov_b32 s4, 0x800000
	v_fma_f32 v137, -v134, v135, 1.0
	v_fmac_f32_e32 v135, v137, v135
	v_mul_f32_e32 v137, v136, v135
	v_fma_f32 v140, -v134, v137, v136
	v_fmac_f32_e32 v137, v140, v135
	v_fma_f32 v134, -v134, v137, v136
	v_div_fmas_f32 v134, v134, v135, v137
	v_div_fixup_f32 v132, v134, v132, v133
	v_add_f32_e32 v131, v163, v132
	v_cmp_gt_f32_e32 vcc, s4, v131
	s_mov_b32 s4, 0x3f317217
	s_nop 0
	v_cndmask_b32_e64 v132, 0, 32, vcc
	v_ldexp_f32 v131, v131, v132
	v_log_f32_e32 v131, v131
	s_nop 0
	v_mul_f32_e32 v132, 0x3f317217, v131
	v_fma_f32 v132, v131, s4, -v132
	v_fmac_f32_e32 v132, 0x3377d1cf, v131
	s_mov_b32 s4, 0x7f800000
	v_fmac_f32_e32 v132, 0x3f317217, v131
	v_cmp_lt_f32_e64 s[12:13], |v131|, s4
	s_nop 1
	v_cndmask_b32_e64 v131, v131, v132, s[12:13]
	v_cndmask_b32_e32 v132, 0, v227, vcc
	v_sub_f32_e32 v131, v131, v132
	v_cvt_pk_bf16_f32 v141, v131, s0
	global_store_short v139, v141, s[72:73] offset:96
	v_add_u32_e32 v139, 0xbeb00, v138
	v_mul_f32_e32 v132, 0xbfb8aa3b, v3
	v_exp_f32_e32 v132, v132
	v_sub_f32_e32 v133, 1.0, v160
	v_add_f32_e32 v132, 1.0, v132
	v_div_scale_f32 v134, s[4:5], v132, v132, v133
	v_rcp_f32_e32 v135, v134
	v_div_scale_f32 v136, vcc, v133, v132, v133
	s_mov_b32 s4, 0x800000
	v_fma_f32 v137, -v134, v135, 1.0
	v_fmac_f32_e32 v135, v137, v135
	v_mul_f32_e32 v137, v136, v135
	v_fma_f32 v140, -v134, v137, v136
	v_fmac_f32_e32 v137, v140, v135
	v_fma_f32 v134, -v134, v137, v136
	v_div_fmas_f32 v134, v134, v135, v137
	v_div_fixup_f32 v132, v134, v132, v133
	v_add_f32_e32 v131, v160, v132
	v_cmp_gt_f32_e32 vcc, s4, v131
	s_mov_b32 s4, 0x3f317217
	s_nop 0
	v_cndmask_b32_e64 v132, 0, 32, vcc
	v_ldexp_f32 v131, v131, v132
	v_log_f32_e32 v131, v131
	s_nop 0
	v_mul_f32_e32 v132, 0x3f317217, v131
	v_fma_f32 v132, v131, s4, -v132
	v_fmac_f32_e32 v132, 0x3377d1cf, v131
	s_mov_b32 s4, 0x7f800000
	v_fmac_f32_e32 v132, 0x3f317217, v131
	v_cmp_lt_f32_e64 s[12:13], |v131|, s4
	s_nop 1
	v_cndmask_b32_e64 v131, v131, v132, s[12:13]
	v_cndmask_b32_e32 v132, 0, v227, vcc
	v_sub_f32_e32 v131, v131, v132
	v_cvt_pk_bf16_f32 v141, v131, s0
	global_store_short v139, v141, s[72:73]
	v_mul_f32_e32 v132, 0xbfb8aa3b, v35
	v_exp_f32_e32 v132, v132
	v_sub_f32_e32 v133, 1.0, v161
	v_add_f32_e32 v132, 1.0, v132
	v_div_scale_f32 v134, s[4:5], v132, v132, v133
	v_rcp_f32_e32 v135, v134
	v_div_scale_f32 v136, vcc, v133, v132, v133
	s_mov_b32 s4, 0x800000
	v_fma_f32 v137, -v134, v135, 1.0
	v_fmac_f32_e32 v135, v137, v135
	v_mul_f32_e32 v137, v136, v135
	v_fma_f32 v140, -v134, v137, v136
	v_fmac_f32_e32 v137, v140, v135
	v_fma_f32 v134, -v134, v137, v136
	v_div_fmas_f32 v134, v134, v135, v137
	v_div_fixup_f32 v132, v134, v132, v133
	v_add_f32_e32 v131, v161, v132
	v_cmp_gt_f32_e32 vcc, s4, v131
	s_mov_b32 s4, 0x3f317217
	s_nop 0
	v_cndmask_b32_e64 v132, 0, 32, vcc
	v_ldexp_f32 v131, v131, v132
	v_log_f32_e32 v131, v131
	s_nop 0
	v_mul_f32_e32 v132, 0x3f317217, v131
	v_fma_f32 v132, v131, s4, -v132
	v_fmac_f32_e32 v132, 0x3377d1cf, v131
	s_mov_b32 s4, 0x7f800000
; DEV u16 f2bf(float f) { return (u16)(pack2(f, 0.f) & 0xffffu); }
; DEV void phase_win(const Params& P, int l, const u16* __restrict__ xb, const u16* __restrict__ Wt, u16* __restrict__ h, char* smem) {
;     ...
;     const int mode = (cb >= C_HF && cb < C_HI) ? 1 : ((cb >= C_HG) ? 2 : 0);
; #pragma unroll
;     for (int ms = 0; ms < 8; ++ms) {
;       asm volatile("" ::: "memory");
; #pragma unroll
;       for (int ns = 0; ns < 4; ++ns)
; #pragma unroll
;         for (int j = 0; j < 4; ++j) {
;           int row = m0 + wm * 128 + ms * 16 + quad * 4 + j;
;           int col = cb + ns * 16 + l15;
;           float v = acc[ms][ns][j];
;           if (mode == 1) { float lbv = lbp[col - C_HF]; v = __logf(lbv + (1.f - lbv) / (1.f + __expf(-v))); }
;           else if (mode == 2) v = v / (1.f + __expf(-v));
;           h[(size_t)row * HS + col] = f2bf(v);
;         }
	v_fmac_f32_e32 v132, 0x3f317217, v131
	v_cmp_lt_f32_e64 s[12:13], |v131|, s4
	s_nop 1
	v_cndmask_b32_e64 v131, v131, v132, s[12:13]
	v_cndmask_b32_e32 v132, 0, v227, vcc
	v_sub_f32_e32 v131, v131, v132
	v_cvt_pk_bf16_f32 v141, v131, s0
	global_store_short v139, v141, s[72:73] offset:32
	v_mul_f32_e32 v132, 0xbfb8aa3b, v43
	v_exp_f32_e32 v132, v132
	v_sub_f32_e32 v133, 1.0, v162
	v_add_f32_e32 v132, 1.0, v132
	v_div_scale_f32 v134, s[4:5], v132, v132, v133
	v_rcp_f32_e32 v135, v134
	v_div_scale_f32 v136, vcc, v133, v132, v133
	s_mov_b32 s4, 0x800000
	v_fma_f32 v137, -v134, v135, 1.0
	v_fmac_f32_e32 v135, v137, v135
	v_mul_f32_e32 v137, v136, v135
	v_fma_f32 v140, -v134, v137, v136
	v_fmac_f32_e32 v137, v140, v135
	v_fma_f32 v134, -v134, v137, v136
	v_div_fmas_f32 v134, v134, v135, v137
	v_div_fixup_f32 v132, v134, v132, v133
	v_add_f32_e32 v131, v162, v132
	v_cmp_gt_f32_e32 vcc, s4, v131
	s_mov_b32 s4, 0x3f317217
	s_nop 0
	v_cndmask_b32_e64 v132, 0, 32, vcc
	v_ldexp_f32 v131, v131, v132
	v_log_f32_e32 v131, v131
	s_nop 0
	v_mul_f32_e32 v132, 0x3f317217, v131
	v_fma_f32 v132, v131, s4, -v132
	v_fmac_f32_e32 v132, 0x3377d1cf, v131
	s_mov_b32 s4, 0x7f800000
	v_fmac_f32_e32 v132, 0x3f317217, v131
	v_cmp_lt_f32_e64 s[12:13], |v131|, s4
	s_nop 1
	v_cndmask_b32_e64 v131, v131, v132, s[12:13]
	v_cndmask_b32_e32 v132, 0, v227, vcc
	v_sub_f32_e32 v131, v131, v132
	v_cvt_pk_bf16_f32 v141, v131, s0
	global_store_short v139, v141, s[72:73] offset:64
	v_mul_f32_e32 v132, 0xbfb8aa3b, v31
	v_exp_f32_e32 v132, v132
	v_sub_f32_e32 v133, 1.0, v163
	v_add_f32_e32 v132, 1.0, v132
	v_div_scale_f32 v134, s[4:5], v132, v132, v133
	v_rcp_f32_e32 v135, v134
	v_div_scale_f32 v136, vcc, v133, v132, v133
	s_mov_b32 s4, 0x800000
	v_fma_f32 v137, -v134, v135, 1.0
	v_fmac_f32_e32 v135, v137, v135
	v_mul_f32_e32 v137, v136, v135
	v_fma_f32 v140, -v134, v137, v136
	v_fmac_f32_e32 v137, v140, v135
	v_fma_f32 v134, -v134, v137, v136
	v_div_fmas_f32 v134, v134, v135, v137
	v_div_fixup_f32 v132, v134, v132, v133
	v_add_f32_e32 v131, v163, v132
	v_cmp_gt_f32_e32 vcc, s4, v131
	s_mov_b32 s4, 0x3f317217
	s_nop 0
	v_cndmask_b32_e64 v132, 0, 32, vcc
	v_ldexp_f32 v131, v131, v132
	v_log_f32_e32 v131, v131
	s_nop 0
	v_mul_f32_e32 v132, 0x3f317217, v131
	v_fma_f32 v132, v131, s4, -v132
	v_fmac_f32_e32 v132, 0x3377d1cf, v131
	s_mov_b32 s4, 0x7f800000
	v_fmac_f32_e32 v132, 0x3f317217, v131
	v_cmp_lt_f32_e64 s[12:13], |v131|, s4
	s_nop 1
	v_cndmask_b32_e64 v131, v131, v132, s[12:13]
	v_cndmask_b32_e32 v132, 0, v227, vcc
	v_sub_f32_e32 v131, v131, v132
	v_cvt_pk_bf16_f32 v141, v131, s0
	global_store_short v139, v141, s[72:73] offset:96
	v_add_u32_e32 v139, 0xc0600, v138
	v_mul_f32_e32 v132, 0xbfb8aa3b, v4
	v_exp_f32_e32 v132, v132
	v_sub_f32_e32 v133, 1.0, v160
	v_add_f32_e32 v132, 1.0, v132
	v_div_scale_f32 v134, s[4:5], v132, v132, v133
	v_rcp_f32_e32 v135, v134
	v_div_scale_f32 v136, vcc, v133, v132, v133
	s_mov_b32 s4, 0x800000
	v_fma_f32 v137, -v134, v135, 1.0
	v_fmac_f32_e32 v135, v137, v135
	v_mul_f32_e32 v137, v136, v135
	v_fma_f32 v140, -v134, v137, v136
	v_fmac_f32_e32 v137, v140, v135
	v_fma_f32 v134, -v134, v137, v136
	v_div_fmas_f32 v134, v134, v135, v137
	v_div_fixup_f32 v132, v134, v132, v133
	v_add_f32_e32 v131, v160, v132
	v_cmp_gt_f32_e32 vcc, s4, v131
	s_mov_b32 s4, 0x3f317217
	s_nop 0
	v_cndmask_b32_e64 v132, 0, 32, vcc
	v_ldexp_f32 v131, v131, v132
	v_log_f32_e32 v131, v131
	s_nop 0
	v_mul_f32_e32 v132, 0x3f317217, v131
	v_fma_f32 v132, v131, s4, -v132
	v_fmac_f32_e32 v132, 0x3377d1cf, v131
	s_mov_b32 s4, 0x7f800000
	v_fmac_f32_e32 v132, 0x3f317217, v131
	v_cmp_lt_f32_e64 s[12:13], |v131|, s4
	s_nop 1
	v_cndmask_b32_e64 v131, v131, v132, s[12:13]
	v_cndmask_b32_e32 v132, 0, v227, vcc
	v_sub_f32_e32 v131, v131, v132
	v_cvt_pk_bf16_f32 v141, v131, s0
	global_store_short v139, v141, s[72:73]
	v_mul_f32_e32 v132, 0xbfb8aa3b, v36
	v_exp_f32_e32 v132, v132
	v_sub_f32_e32 v133, 1.0, v161
	v_add_f32_e32 v132, 1.0, v132
	v_div_scale_f32 v134, s[4:5], v132, v132, v133
	v_rcp_f32_e32 v135, v134
	v_div_scale_f32 v136, vcc, v133, v132, v133
	s_mov_b32 s4, 0x800000
	v_fma_f32 v137, -v134, v135, 1.0
	v_fmac_f32_e32 v135, v137, v135
	v_mul_f32_e32 v137, v136, v135
	v_fma_f32 v140, -v134, v137, v136
	v_fmac_f32_e32 v137, v140, v135
	v_fma_f32 v134, -v134, v137, v136
	v_div_fmas_f32 v134, v134, v135, v137
	v_div_fixup_f32 v132, v134, v132, v133
	v_add_f32_e32 v131, v161, v132
	v_cmp_gt_f32_e32 vcc, s4, v131
	s_mov_b32 s4, 0x3f317217
	s_nop 0
	v_cndmask_b32_e64 v132, 0, 32, vcc
	v_ldexp_f32 v131, v131, v132
	v_log_f32_e32 v131, v131
	s_nop 0
	v_mul_f32_e32 v132, 0x3f317217, v131
	v_fma_f32 v132, v131, s4, -v132
	v_fmac_f32_e32 v132, 0x3377d1cf, v131
	s_mov_b32 s4, 0x7f800000
	v_fmac_f32_e32 v132, 0x3f317217, v131
	v_cmp_lt_f32_e64 s[12:13], |v131|, s4
	s_nop 1
	v_cndmask_b32_e64 v131, v131, v132, s[12:13]
	v_cndmask_b32_e32 v132, 0, v227, vcc
	v_sub_f32_e32 v131, v131, v132
	v_cvt_pk_bf16_f32 v141, v131, s0
	global_store_short v139, v141, s[72:73] offset:32
	v_mul_f32_e32 v132, 0xbfb8aa3b, v44
	v_exp_f32_e32 v132, v132
	v_sub_f32_e32 v133, 1.0, v162
	v_add_f32_e32 v132, 1.0, v132
	v_div_scale_f32 v134, s[4:5], v132, v132, v133
	v_rcp_f32_e32 v135, v134
	v_div_scale_f32 v136, vcc, v133, v132, v133
	s_mov_b32 s4, 0x800000
	v_fma_f32 v137, -v134, v135, 1.0
	v_fmac_f32_e32 v135, v137, v135
	v_mul_f32_e32 v137, v136, v135
	v_fma_f32 v140, -v134, v137, v136
	v_fmac_f32_e32 v137, v140, v135
	v_fma_f32 v134, -v134, v137, v136
	v_div_fmas_f32 v134, v134, v135, v137
	v_div_fixup_f32 v132, v134, v132, v133
	v_add_f32_e32 v131, v162, v132
	v_cmp_gt_f32_e32 vcc, s4, v131
	s_mov_b32 s4, 0x3f317217
; DEV u16 f2bf(float f) { return (u16)(pack2(f, 0.f) & 0xffffu); }
; DEV void phase_win(const Params& P, int l, const u16* __restrict__ xb, const u16* __restrict__ Wt, u16* __restrict__ h, char* smem) {
;     ...
;     const int mode = (cb >= C_HF && cb < C_HI) ? 1 : ((cb >= C_HG) ? 2 : 0);
; #pragma unroll
;     for (int ms = 0; ms < 8; ++ms) {
;       asm volatile("" ::: "memory");
; #pragma unroll
;       for (int ns = 0; ns < 4; ++ns)
; #pragma unroll
;         for (int j = 0; j < 4; ++j) {
;           int row = m0 + wm * 128 + ms * 16 + quad * 4 + j;
;           int col = cb + ns * 16 + l15;
;           float v = acc[ms][ns][j];
;           if (mode == 1) { float lbv = lbp[col - C_HF]; v = __logf(lbv + (1.f - lbv) / (1.f + __expf(-v))); }
;           else if (mode == 2) v = v / (1.f + __expf(-v));
;           h[(size_t)row * HS + col] = f2bf(v);
;         }
	s_nop 0
	v_cndmask_b32_e64 v132, 0, 32, vcc
	v_ldexp_f32 v131, v131, v132
	v_log_f32_e32 v131, v131
	s_nop 0
	v_mul_f32_e32 v132, 0x3f317217, v131
	v_fma_f32 v132, v131, s4, -v132
	v_fmac_f32_e32 v132, 0x3377d1cf, v131
	s_mov_b32 s4, 0x7f800000
	v_fmac_f32_e32 v132, 0x3f317217, v131
	v_cmp_lt_f32_e64 s[12:13], |v131|, s4
	s_nop 1
	v_cndmask_b32_e64 v131, v131, v132, s[12:13]
	v_cndmask_b32_e32 v132, 0, v227, vcc
	v_sub_f32_e32 v131, v131, v132
	v_cvt_pk_bf16_f32 v141, v131, s0
	global_store_short v139, v141, s[72:73] offset:64
	v_mul_f32_e32 v132, 0xbfb8aa3b, v32
	v_exp_f32_e32 v132, v132
	v_sub_f32_e32 v133, 1.0, v163
	v_add_f32_e32 v132, 1.0, v132
	v_div_scale_f32 v134, s[4:5], v132, v132, v133
	v_rcp_f32_e32 v135, v134
	v_div_scale_f32 v136, vcc, v133, v132, v133
	s_mov_b32 s4, 0x800000
	v_fma_f32 v137, -v134, v135, 1.0
	v_fmac_f32_e32 v135, v137, v135
	v_mul_f32_e32 v137, v136, v135
	v_fma_f32 v140, -v134, v137, v136
	v_fmac_f32_e32 v137, v140, v135
	v_fma_f32 v134, -v134, v137, v136
	v_div_fmas_f32 v134, v134, v135, v137
	v_div_fixup_f32 v132, v134, v132, v133
	v_add_f32_e32 v131, v163, v132
	v_cmp_gt_f32_e32 vcc, s4, v131
	s_mov_b32 s4, 0x3f317217
	s_nop 0
	v_cndmask_b32_e64 v132, 0, 32, vcc
	v_ldexp_f32 v131, v131, v132
	v_log_f32_e32 v131, v131
	s_nop 0
	v_mul_f32_e32 v132, 0x3f317217, v131
	v_fma_f32 v132, v131, s4, -v132
	v_fmac_f32_e32 v132, 0x3377d1cf, v131
	s_mov_b32 s4, 0x7f800000
	v_fmac_f32_e32 v132, 0x3f317217, v131
	v_cmp_lt_f32_e64 s[12:13], |v131|, s4
	s_nop 1
	v_cndmask_b32_e64 v131, v131, v132, s[12:13]
	v_cndmask_b32_e32 v132, 0, v227, vcc
	v_sub_f32_e32 v131, v131, v132
	v_cvt_pk_bf16_f32 v141, v131, s0
	global_store_short v139, v141, s[72:73] offset:96
	v_add_u32_e32 v139, 0xc2100, v138
	v_mul_f32_e32 v132, 0xbfb8aa3b, v5
	v_exp_f32_e32 v132, v132
	v_sub_f32_e32 v133, 1.0, v160
	v_add_f32_e32 v132, 1.0, v132
	v_div_scale_f32 v134, s[4:5], v132, v132, v133
	v_rcp_f32_e32 v135, v134
	v_div_scale_f32 v136, vcc, v133, v132, v133
	s_mov_b32 s4, 0x800000
	v_fma_f32 v137, -v134, v135, 1.0
	v_fmac_f32_e32 v135, v137, v135
	v_mul_f32_e32 v137, v136, v135
	v_fma_f32 v140, -v134, v137, v136
	v_fmac_f32_e32 v137, v140, v135
	v_fma_f32 v134, -v134, v137, v136
	v_div_fmas_f32 v134, v134, v135, v137
	v_div_fixup_f32 v132, v134, v132, v133
	v_add_f32_e32 v131, v160, v132
	v_cmp_gt_f32_e32 vcc, s4, v131
	s_mov_b32 s4, 0x3f317217
	s_nop 0
	v_cndmask_b32_e64 v132, 0, 32, vcc
	v_ldexp_f32 v131, v131, v132
	v_log_f32_e32 v131, v131
	s_nop 0
	v_mul_f32_e32 v132, 0x3f317217, v131
	v_fma_f32 v132, v131, s4, -v132
	v_fmac_f32_e32 v132, 0x3377d1cf, v131
	s_mov_b32 s4, 0x7f800000
	v_fmac_f32_e32 v132, 0x3f317217, v131
	v_cmp_lt_f32_e64 s[12:13], |v131|, s4
	s_nop 1
	v_cndmask_b32_e64 v131, v131, v132, s[12:13]
	v_cndmask_b32_e32 v132, 0, v227, vcc
	v_sub_f32_e32 v131, v131, v132
	v_cvt_pk_bf16_f32 v141, v131, s0
	global_store_short v139, v141, s[72:73]
	v_mul_f32_e32 v132, 0xbfb8aa3b, v37
	v_exp_f32_e32 v132, v132
	v_sub_f32_e32 v133, 1.0, v161
	v_add_f32_e32 v132, 1.0, v132
	v_div_scale_f32 v134, s[4:5], v132, v132, v133
	v_rcp_f32_e32 v135, v134
	v_div_scale_f32 v136, vcc, v133, v132, v133
	s_mov_b32 s4, 0x800000
	v_fma_f32 v137, -v134, v135, 1.0
	v_fmac_f32_e32 v135, v137, v135
	v_mul_f32_e32 v137, v136, v135
	v_fma_f32 v140, -v134, v137, v136
	v_fmac_f32_e32 v137, v140, v135
	v_fma_f32 v134, -v134, v137, v136
	v_div_fmas_f32 v134, v134, v135, v137
	v_div_fixup_f32 v132, v134, v132, v133
	v_add_f32_e32 v131, v161, v132
	v_cmp_gt_f32_e32 vcc, s4, v131
	s_mov_b32 s4, 0x3f317217
	s_nop 0
	v_cndmask_b32_e64 v132, 0, 32, vcc
	v_ldexp_f32 v131, v131, v132
	v_log_f32_e32 v131, v131
	s_nop 0
	v_mul_f32_e32 v132, 0x3f317217, v131
	v_fma_f32 v132, v131, s4, -v132
	v_fmac_f32_e32 v132, 0x3377d1cf, v131
	s_mov_b32 s4, 0x7f800000
	v_fmac_f32_e32 v132, 0x3f317217, v131
	v_cmp_lt_f32_e64 s[12:13], |v131|, s4
	s_nop 1
	v_cndmask_b32_e64 v131, v131, v132, s[12:13]
	v_cndmask_b32_e32 v132, 0, v227, vcc
	v_sub_f32_e32 v131, v131, v132
	v_cvt_pk_bf16_f32 v141, v131, s0
	global_store_short v139, v141, s[72:73] offset:32
	v_mul_f32_e32 v132, 0xbfb8aa3b, v45
	v_exp_f32_e32 v132, v132
	v_sub_f32_e32 v133, 1.0, v162
	v_add_f32_e32 v132, 1.0, v132
	v_div_scale_f32 v134, s[4:5], v132, v132, v133
	v_rcp_f32_e32 v135, v134
	v_div_scale_f32 v136, vcc, v133, v132, v133
	s_mov_b32 s4, 0x800000
	v_fma_f32 v137, -v134, v135, 1.0
	v_fmac_f32_e32 v135, v137, v135
	v_mul_f32_e32 v137, v136, v135
	v_fma_f32 v140, -v134, v137, v136
	v_fmac_f32_e32 v137, v140, v135
	v_fma_f32 v134, -v134, v137, v136
	v_div_fmas_f32 v134, v134, v135, v137
	v_div_fixup_f32 v132, v134, v132, v133
	v_add_f32_e32 v131, v162, v132
	v_cmp_gt_f32_e32 vcc, s4, v131
	s_mov_b32 s4, 0x3f317217
	s_nop 0
	v_cndmask_b32_e64 v132, 0, 32, vcc
	v_ldexp_f32 v131, v131, v132
	v_log_f32_e32 v131, v131
	s_nop 0
	v_mul_f32_e32 v132, 0x3f317217, v131
	v_fma_f32 v132, v131, s4, -v132
	v_fmac_f32_e32 v132, 0x3377d1cf, v131
	s_mov_b32 s4, 0x7f800000
	v_fmac_f32_e32 v132, 0x3f317217, v131
	v_cmp_lt_f32_e64 s[12:13], |v131|, s4
	s_nop 1
	v_cndmask_b32_e64 v131, v131, v132, s[12:13]
	v_cndmask_b32_e32 v132, 0, v227, vcc
	v_sub_f32_e32 v131, v131, v132
	v_cvt_pk_bf16_f32 v141, v131, s0
	global_store_short v139, v141, s[72:73] offset:64
	v_mul_f32_e32 v132, 0xbfb8aa3b, v33
	v_exp_f32_e32 v132, v132
	v_sub_f32_e32 v133, 1.0, v163
	v_add_f32_e32 v132, 1.0, v132
	v_div_scale_f32 v134, s[4:5], v132, v132, v133
	v_rcp_f32_e32 v135, v134
	v_div_scale_f32 v136, vcc, v133, v132, v133
	s_mov_b32 s4, 0x800000
	v_fma_f32 v137, -v134, v135, 1.0
	v_fmac_f32_e32 v135, v137, v135
	v_mul_f32_e32 v137, v136, v135
	v_fma_f32 v140, -v134, v137, v136
	v_fmac_f32_e32 v137, v140, v135
	v_fma_f32 v134, -v134, v137, v136
	v_div_fmas_f32 v134, v134, v135, v137
	v_div_fixup_f32 v132, v134, v132, v133
	v_add_f32_e32 v131, v163, v132
	v_cmp_gt_f32_e32 vcc, s4, v131
	s_mov_b32 s4, 0x3f317217
	s_nop 0
	v_cndmask_b32_e64 v132, 0, 32, vcc
	v_ldexp_f32 v131, v131, v132
	v_log_f32_e32 v131, v131
	s_nop 0
	v_mul_f32_e32 v132, 0x3f317217, v131
	v_fma_f32 v132, v131, s4, -v132
	v_fmac_f32_e32 v132, 0x3377d1cf, v131
	s_mov_b32 s4, 0x7f800000
	v_fmac_f32_e32 v132, 0x3f317217, v131
	v_cmp_lt_f32_e64 s[12:13], |v131|, s4
	s_nop 1
	v_cndmask_b32_e64 v131, v131, v132, s[12:13]
	v_cndmask_b32_e32 v132, 0, v227, vcc
	v_sub_f32_e32 v131, v131, v132
	v_cvt_pk_bf16_f32 v141, v131, s0
	global_store_short v139, v141, s[72:73] offset:96
	s_branch .LBB0_2075
